# P4 patch + 20-quad stream ring + stream-item prologue de-serialised: v piece requested before the 8 state quads, prologue waits vmcnt(8) so the state quads stay in flight through the prologue
# baseline (speedup 1.0000x reference)
; #define LAS __attribute__((address_space(3)))
; #define LBAR() do { asm volatile("s_waitcnt lgkmcnt(0)" ::: "memory"); __builtin_amdgcn_s_barrier(); asm volatile("" ::: "memory"); } while (0)
; __device__ __forceinline__ void ret_sample_item(Frame& F, int item) {
;     ...
;     const int r0 = MP + 8 * b;
;     LAS float* qs = (LAS float*)(F.lds + SQ_OFF); LAS float* kt = (LAS float*)(F.lds + SK_OFF); LAS float* vs = (LAS float*)(F.lds + SV_OFF);
;     LAS float* part = (LAS float*)(F.lds + SPART_OFF); LAS float* pm = (LAS float*)(F.lds + SPM_OFF);
;     const int e4 = 64 * w + 4 * fr;
;     const float* S0 = F.state_ret + ((size_t)(b * NH + h) * DK + fq) * DV + e4;
;     float* S1 = F.sr_s + ((size_t)(b * NH + h) * DK + fq) * DV + e4;
;     f32x4 sa[8], sb[8];
;     const int tq8 = (tid & 255) >> 5, d0 = 8 * (tid & 31); const bool isq = tid < 256;
;     const u32x4 rawqk = *(const u32x4*)((isq ? WSP(bf16, WS_Q) : WSP(bf16, WS_K)) + (size_t)(r0 + tq8) * D + h * DK + d0);
;     const int tv = tid >> 6, e0 = 8 * (tid & 63);
;     const u32x4 rawv = *(const u32x4*)(WSP(bf16, WS_V) + (size_t)(r0 + tv) * HV + h * DV + e0);
; #pragma unroll
;     for (int u = 0; u < 8; ++u) sa[u] = __builtin_nontemporal_load((const f32x4*)(S0 + (size_t)(4 * u) * DV));
;     LBAR();
;     { float f[8];
; #pragma unroll
;       for (int i = 0; i < 4; ++i) { f[2 * i] = __uint_as_float(rawqk[i] << 16); f[2 * i + 1] = __uint_as_float(rawqk[i] & 0xffff0000u); }
;       if (isq) { *(LAS f32x4*)(qs + tq8 * 260 + d0) = (f32x4){f[0], f[1], f[2], f[3]}; *(LAS f32x4*)(qs + tq8 * 260 + d0 + 4) = (f32x4){f[4], f[5], f[6], f[7]}; }
;       else {
; #pragma unroll
;           for (int i = 0; i < 8; ++i) kt[(d0 + i) * 8 + tq8] = f[i]; } }
.LBB0_576:
	s_ashr_i32 s59, s58, 31
	s_and_b32 s91, s58, -8
	s_lshl_b64 s[68:69], s[58:59], 19
	s_addk_i32 s91, 0x2000
	v_lshl_or_b32 v2, v118, 2, s68
	v_mov_b32_e32 v3, s69
	v_lshl_add_u64 v[136:137], v[124:125], 0, v[2:3]
	v_or_b32_e32 v2, s91, v182
	v_ashrrev_i32_e32 v3, 31, v2
	s_and_b32 s10, s58, 7
	v_lshlrev_b64 v[2:3], 12, v[2:3]
	v_lshl_add_u64 v[2:3], v[126:127], 0, v[2:3]
	s_lshl_b32 s76, s10, 9
	s_mov_b32 s77, s23
	v_lshl_add_u64 v[2:3], v[2:3], 0, s[76:77]
	v_lshl_add_u64 v[2:3], v[2:3], 0, v[120:121]
	global_load_dwordx4 v[10:13], v[2:3], off
	v_add_u32_e32 v238, s91, v183
	v_ashrrev_i32_e32 v239, 31, v238
	v_lshlrev_b64 v[238:239], 13, v[238:239]
	v_lshl_add_u64 v[238:239], s[20:21], 0, v[238:239]
	s_lshl_b32 s22, s10, 10
	v_lshl_add_u64 v[238:239], v[238:239], 0, s[22:23]
	v_lshl_add_u64 v[238:239], v[238:239], 0, v[132:133]
	global_load_dwordx4 v[2:5], v[238:239], off
	global_load_dwordx4 v[70:73], v[136:137], off nt
	v_add_co_u32_e32 v210, vcc, s35, v136
	s_nop 0
	v_addc_co_u32_e32 v211, vcc, 0, v137, vcc
	global_load_dwordx4 v[62:65], v[210:211], off nt
	v_add_co_u32_e32 v214, vcc, s70, v136
	s_nop 0
	v_addc_co_u32_e32 v215, vcc, 0, v137, vcc
	global_load_dwordx4 v[54:57], v[214:215], off nt
	v_add_co_u32_e32 v210, vcc, s71, v136
	s_nop 0
	v_addc_co_u32_e32 v211, vcc, 0, v137, vcc
	global_load_dwordx4 v[50:53], v[210:211], off nt
	v_add_co_u32_e32 v214, vcc, s72, v136
	s_nop 0
	v_addc_co_u32_e32 v215, vcc, 0, v137, vcc
	global_load_dwordx4 v[46:49], v[214:215], off nt
	v_add_co_u32_e32 v210, vcc, s73, v136
	s_nop 0
	v_addc_co_u32_e32 v211, vcc, 0, v137, vcc
	global_load_dwordx4 v[42:45], v[210:211], off nt
	v_add_co_u32_e32 v214, vcc, s80, v136
	s_nop 0
	v_addc_co_u32_e32 v215, vcc, 0, v137, vcc
	global_load_dwordx4 v[38:41], v[214:215], off nt
	v_add_co_u32_e32 v210, vcc, s81, v136
	s_nop 0
	v_addc_co_u32_e32 v211, vcc, 0, v137, vcc
	global_load_dwordx4 v[34:37], v[210:211], off nt
	s_waitcnt lgkmcnt(0)
	s_barrier
	s_waitcnt vmcnt(9)
	v_lshlrev_b32_e32 v6, 16, v10
	v_and_b32_e32 v7, 0xffff0000, v10
	v_lshlrev_b32_e32 v8, 16, v11
	v_and_b32_e32 v9, 0xffff0000, v11
	v_lshlrev_b32_e32 v10, 16, v12
	v_and_b32_e32 v11, 0xffff0000, v12
	v_lshlrev_b32_e32 v12, 16, v13
	v_and_b32_e32 v13, 0xffff0000, v13
	s_and_saveexec_b64 s[68:69], s[4:5]
	s_xor_b64 s[78:79], exec, s[68:69]
	s_cbranch_execz .LBB0_578
	v_add_u32_e32 v14, 0x2000, v162
	ds_write2_b32 v14, v6, v7 offset0:32 offset1:40
	ds_write2_b32 v14, v8, v9 offset0:48 offset1:56
	ds_write2_b32 v14, v10, v11 offset0:64 offset1:72
	ds_write2_b32 v14, v12, v13 offset0:80 offset1:88

; #define LAS __attribute__((address_space(3)))
; #define LBAR() do { asm volatile("s_waitcnt lgkmcnt(0)" ::: "memory"); __builtin_amdgcn_s_barrier(); asm volatile("" ::: "memory"); } while (0)
; __device__ __forceinline__ void ret_sample_item(Frame& F, int item) {
;     ...
;     { f32x4 lo, hi;
; #pragma unroll
;       for (int i = 0; i < 2; ++i) { lo[2 * i] = __uint_as_float(rawv[i] << 16); lo[2 * i + 1] = __uint_as_float(rawv[i] & 0xffff0000u); hi[2 * i] = __uint_as_float(rawv[i + 2] << 16); hi[2 * i + 1] = __uint_as_float(rawv[i + 2] & 0xffff0000u); }
;       *(LAS f32x4*)(vs + tv * 512 + e0) = lo; *(LAS f32x4*)(vs + tv * 512 + e0 + 4) = hi; }
;     LBAR();
.LBB0_580:
	s_or_b64 exec, exec, s[78:79]
	s_waitcnt vmcnt(8)
	v_lshlrev_b32_e32 v6, 16, v2
	v_and_b32_e32 v7, 0xffff0000, v2
	v_lshlrev_b32_e32 v8, 16, v3
	v_and_b32_e32 v9, 0xffff0000, v3
	v_lshlrev_b32_e32 v10, 16, v4
	v_and_b32_e32 v11, 0xffff0000, v4
	v_lshlrev_b32_e32 v12, 16, v5
	v_and_b32_e32 v13, 0xffff0000, v5
	ds_write_b128 v164, v[6:9] offset:16512
	ds_write_b128 v164, v[10:13] offset:16528
	s_waitcnt lgkmcnt(0)
	s_barrier
	v_mov_b32_e32 v2, 0
	s_mov_b32 s22, 0
	v_mov_b32_e32 v3, v158

; #define LAS __attribute__((address_space(3)))
; #define RS_LOAD(dst, it0) do { _Pragma("unroll") for (int u = 0; u < 8; ++u) dst[u] = __builtin_nontemporal_load((const f32x4*)(S0 + (size_t)(4 * ((it0) + u)) * DV)); } while (0)
; __device__ __forceinline__ void ret_sample_item(Frame& F, int item) {
;     ...
;     const float gam = 1.0f - exp2f(-5.0f - (float)h);
;     const float g7 = exp2f(7.0f * log2f(gam)), g8 = g7 * gam;
;     ...
;     f32x4 v4[8];
; #pragma unroll
;     for (int m = 0; m < 8; ++m) v4[m] = *(const LAS f32x4*)(vs + m * 512 + e4);
;     f32x4 oacc[4];
; #pragma unroll
;     for (int i = 0; i < 4; ++i) oacc[i] = (f32x4){0.f, 0.f, 0.f, 0.f};
;     ...
;     for (int it0 = 0; it0 < 64; it0 += 16) {
;         RS_LOAD(sb, it0 + 8);
;         RS_PROC(sa, it0);
;         { const int itn = it0 + 16 < 64 ? it0 + 16 : it0; RS_LOAD(sa, itn); }
;         RS_PROC(sb, it0 + 8);
.LBB0_584:
	s_or_b64 exec, exec, s[78:79]
	v_cvt_f32_ubyte0_e32 v2, s10
	v_sub_f32_e32 v2, 0xc0a00000, v2
	v_cmp_gt_f32_e32 vcc, s82, v2
	s_and_b64 s[68:69], vcc, exec
	s_cselect_b32 s10, 0xffffffc0, 0
	v_cndmask_b32_e32 v3, 0, v169, vcc
	v_add_f32_e32 v2, v2, v3
	v_exp_f32_e32 v2, v2
	s_waitcnt lgkmcnt(0)
	s_barrier
	v_ldexp_f32 v2, v2, s10
	v_sub_f32_e32 v138, 1.0, v2
	v_cmp_gt_f32_e32 vcc, s83, v138
	s_and_b64 s[68:69], vcc, exec
	s_cselect_b32 s10, 32, 0
	v_ldexp_f32 v3, v138, s10
	v_log_f32_e32 v3, v3
	v_cndmask_b32_e32 v2, 0, v170, vcc
	v_mov_b32_e32 v98, 0
	s_mov_b32 s10, 0
	v_sub_f32_e32 v2, v3, v2
	v_mul_f32_e32 v3, 0x40e00000, v2
	v_cmp_gt_f32_e32 vcc, s82, v3
	s_and_b64 s[68:69], vcc, exec
	s_cselect_b32 s22, 0xffffffc0, 0
	v_cndmask_b32_e32 v3, 0, v169, vcc
	v_fmac_f32_e32 v3, 0x40e00000, v2
	v_exp_f32_e32 v2, v3
	v_mov_b64_e32 v[148:149], v[130:131]
	v_mov_b64_e32 v[150:151], v[128:129]
	v_mov_b32_e32 v171, v161
	v_ldexp_f32 v140, v2, s22
	ds_read_b128 v[30:33], v139 offset:16512
	ds_read_b128 v[26:29], v139 offset:18560
	ds_read_b128 v[22:25], v139 offset:20608
	ds_read_b128 v[18:21], v139 offset:22656
	ds_read_b128 v[14:17], v139 offset:24704
	ds_read_b128 v[10:13], v139 offset:26752
	ds_read_b128 v[6:9], v139 offset:28800
	ds_read_b128 v[2:5], v139 offset:30848
	v_mul_f32_e32 v142, v138, v140
	v_mov_b32_e32 v144, v142
	v_mov_b32_e32 v145, v142
	v_mov_b32_e32 v146, v140
	v_mov_b32_e32 v147, v140
	v_mov_b32_e32 v172, v160
	v_mov_b32_e32 v99, v98
	v_mov_b32_e32 v100, v98
	v_mov_b32_e32 v101, v98
	v_mov_b32_e32 v102, v98
	v_mov_b32_e32 v103, v98
	v_mov_b32_e32 v104, v98
	v_mov_b32_e32 v105, v98
	v_mov_b32_e32 v106, v98
	v_mov_b32_e32 v107, v98
	v_mov_b32_e32 v108, v98
	v_mov_b32_e32 v109, v98
	v_mov_b32_e32 v110, v98
	v_mov_b32_e32 v111, v98
	v_mov_b32_e32 v112, v98
	v_mov_b32_e32 v113, v98
	v_lshl_add_u64 v[148:149], v[130:131], 0, v[122:123]
	v_lshl_add_u64 v[150:151], v[128:129], 0, v[122:123]
	s_mov_b32 s74, 0x10000
	s_mov_b32 s75, 0
	v_add_co_u32_e32 v150, vcc, 0x5878000, v150
	v_lshl_add_u64 v[148:149], v[148:149], 0, s[74:75]
	s_mov_b32 s74, 0x2000
	v_addc_co_u32_e32 v151, vcc, 0, v151, vcc
	ds_read_b32 v141, v160
	ds_read_b128 v[114:117], v161
	ds_read_b128 v[176:179], v161 offset:16
	global_load_dwordx4 v[58:61], v[148:149], off nt
	v_lshl_add_u64 v[148:149], v[148:149], 0, s[74:75]
	global_load_dwordx4 v[66:69], v[148:149], off nt
	v_lshl_add_u64 v[148:149], v[148:149], 0, s[74:75]
	global_load_dwordx4 v[74:77], v[148:149], off nt
	v_lshl_add_u64 v[148:149], v[148:149], 0, s[74:75]
	global_load_dwordx4 v[78:81], v[148:149], off nt
	v_lshl_add_u64 v[148:149], v[148:149], 0, s[74:75]
	global_load_dwordx4 v[82:85], v[148:149], off nt
	v_lshl_add_u64 v[148:149], v[148:149], 0, s[74:75]
	global_load_dwordx4 v[86:89], v[148:149], off nt
	v_lshl_add_u64 v[148:149], v[148:149], 0, s[74:75]
	global_load_dwordx4 v[90:93], v[148:149], off nt
	v_lshl_add_u64 v[148:149], v[148:149], 0, s[74:75]
	global_load_dwordx4 v[94:97], v[148:149], off nt
	v_lshl_add_u64 v[148:149], v[148:149], 0, s[74:75]
	global_load_dwordx4 v[212:215], v[148:149], off nt
	v_lshl_add_u64 v[148:149], v[148:149], 0, s[74:75]
	global_load_dwordx4 v[216:219], v[148:149], off nt
	v_lshl_add_u64 v[148:149], v[148:149], 0, s[74:75]
	global_load_dwordx4 v[224:227], v[148:149], off nt
	v_lshl_add_u64 v[148:149], v[148:149], 0, s[74:75]
	global_load_dwordx4 v[228:231], v[148:149], off nt
	v_lshl_add_u64 v[148:149], v[148:149], 0, s[74:75]
	ds_read_b32 v143, v160 offset:16
	ds_read_b128 v[172:175], v161 offset:128
	ds_read_b128 v[232:235], v161 offset:144
	s_waitcnt vmcnt(19)
	s_waitcnt lgkmcnt(3)
	v_cndmask_b32_e64 v141, 0, v141, s[8:9]
	v_pk_mul_f32 v[180:181], v[26:27], v[114:115] op_sel:[0,1]
	v_pk_mul_f32 v[192:193], v[28:29], v[114:115] op_sel:[0,1]
	v_mfma_f32_16x16x4_f32 v[110:113], v141, v70, v[110:113]
	v_pk_fma_f32 v[180:181], v[30:31], v[114:115], v[180:181] op_sel_hi:[1,0,1]
	v_pk_fma_f32 v[192:193], v[32:33], v[114:115], v[192:193] op_sel_hi:[1,0,1]
	v_pk_fma_f32 v[180:181], v[22:23], v[116:117], v[180:181] op_sel_hi:[1,0,1]
	v_pk_fma_f32 v[192:193], v[24:25], v[116:117], v[192:193] op_sel_hi:[1,0,1]
	v_mfma_f32_16x16x4_f32 v[106:109], v141, v71, v[106:109]
	v_pk_fma_f32 v[180:181], v[18:19], v[116:117], v[180:181] op_sel:[0,1,0]
	v_pk_fma_f32 v[192:193], v[20:21], v[116:117], v[192:193] op_sel:[0,1,0]
	v_pk_fma_f32 v[180:181], v[14:15], v[176:177], v[180:181] op_sel_hi:[1,0,1]
	v_pk_fma_f32 v[192:193], v[16:17], v[176:177], v[192:193] op_sel_hi:[1,0,1]
	v_mfma_f32_16x16x4_f32 v[102:105], v141, v72, v[102:105]
	v_pk_fma_f32 v[180:181], v[10:11], v[176:177], v[180:181] op_sel:[0,1,0]
	v_pk_fma_f32 v[192:193], v[12:13], v[176:177], v[192:193] op_sel:[0,1,0]
	v_pk_fma_f32 v[180:181], v[6:7], v[178:179], v[180:181] op_sel_hi:[1,0,1]
	v_pk_fma_f32 v[192:193], v[8:9], v[178:179], v[192:193] op_sel_hi:[1,0,1]
	v_mfma_f32_16x16x4_f32 v[98:101], v141, v73, v[98:101]
	v_pk_fma_f32 v[180:181], v[2:3], v[178:179], v[180:181] op_sel:[0,1,0]
	v_pk_fma_f32 v[192:193], v[4:5], v[178:179], v[192:193] op_sel:[0,1,0]
	v_pk_mul_f32 v[180:181], v[146:147], v[180:181]
	v_pk_mul_f32 v[192:193], v[146:147], v[192:193]
	v_pk_fma_f32 v[236:237], v[144:145], v[70:71], v[180:181]
	v_pk_fma_f32 v[238:239], v[144:145], v[72:73], v[192:193]
	global_store_dwordx4 v[150:151], v[236:239], off nt
	v_lshl_add_u64 v[150:151], v[150:151], 0, s[74:75]
	global_load_dwordx4 v[70:73], v[148:149], off nt
	v_lshl_add_u64 v[148:149], v[148:149], 0, s[74:75]
	ds_read_b32 v141, v160 offset:32
	ds_read_b128 v[114:117], v161 offset:256
	ds_read_b128 v[176:179], v161 offset:272
	s_waitcnt vmcnt(20)
; #define RS_LOAD(dst, it0) do { _Pragma("unroll") for (int u = 0; u < 8; ++u) dst[u] = __builtin_nontemporal_load((const f32x4*)(S0 + (size_t)(4 * ((it0) + u)) * DV)); } while (0)
; __device__ __forceinline__ void ret_sample_item(Frame& F, int item) {
;     ...
;     for (int it0 = 0; it0 < 64; it0 += 16) {
;         RS_LOAD(sb, it0 + 8);
;         RS_PROC(sa, it0);
;         { const int itn = it0 + 16 < 64 ? it0 + 16 : it0; RS_LOAD(sa, itn); }
;         RS_PROC(sb, it0 + 8);
	s_waitcnt lgkmcnt(3)
	v_cndmask_b32_e64 v143, 0, v143, s[8:9]
	v_pk_mul_f32 v[180:181], v[26:27], v[172:173] op_sel:[0,1]
	v_pk_mul_f32 v[192:193], v[28:29], v[172:173] op_sel:[0,1]
	v_mfma_f32_16x16x4_f32 v[110:113], v143, v62, v[110:113]
	v_pk_fma_f32 v[180:181], v[30:31], v[172:173], v[180:181] op_sel_hi:[1,0,1]
	v_pk_fma_f32 v[192:193], v[32:33], v[172:173], v[192:193] op_sel_hi:[1,0,1]
	v_pk_fma_f32 v[180:181], v[22:23], v[174:175], v[180:181] op_sel_hi:[1,0,1]
	v_pk_fma_f32 v[192:193], v[24:25], v[174:175], v[192:193] op_sel_hi:[1,0,1]
	v_mfma_f32_16x16x4_f32 v[106:109], v143, v63, v[106:109]
	v_pk_fma_f32 v[180:181], v[18:19], v[174:175], v[180:181] op_sel:[0,1,0]
	v_pk_fma_f32 v[192:193], v[20:21], v[174:175], v[192:193] op_sel:[0,1,0]
	v_pk_fma_f32 v[180:181], v[14:15], v[232:233], v[180:181] op_sel_hi:[1,0,1]
	v_pk_fma_f32 v[192:193], v[16:17], v[232:233], v[192:193] op_sel_hi:[1,0,1]
	v_mfma_f32_16x16x4_f32 v[102:105], v143, v64, v[102:105]
	v_pk_fma_f32 v[180:181], v[10:11], v[232:233], v[180:181] op_sel:[0,1,0]
	v_pk_fma_f32 v[192:193], v[12:13], v[232:233], v[192:193] op_sel:[0,1,0]
	v_pk_fma_f32 v[180:181], v[6:7], v[234:235], v[180:181] op_sel_hi:[1,0,1]
	v_pk_fma_f32 v[192:193], v[8:9], v[234:235], v[192:193] op_sel_hi:[1,0,1]
	v_mfma_f32_16x16x4_f32 v[98:101], v143, v65, v[98:101]
	v_pk_fma_f32 v[180:181], v[2:3], v[234:235], v[180:181] op_sel:[0,1,0]
	v_pk_fma_f32 v[192:193], v[4:5], v[234:235], v[192:193] op_sel:[0,1,0]
	v_pk_mul_f32 v[180:181], v[146:147], v[180:181]
	v_pk_mul_f32 v[192:193], v[146:147], v[192:193]
	v_pk_fma_f32 v[236:237], v[144:145], v[62:63], v[180:181]
	v_pk_fma_f32 v[238:239], v[144:145], v[64:65], v[192:193]
	global_store_dwordx4 v[150:151], v[236:239], off nt
	v_lshl_add_u64 v[150:151], v[150:151], 0, s[74:75]
	global_load_dwordx4 v[62:65], v[148:149], off nt
	v_lshl_add_u64 v[148:149], v[148:149], 0, s[74:75]
	ds_read_b32 v143, v160 offset:48
	ds_read_b128 v[172:175], v161 offset:384
	ds_read_b128 v[232:235], v161 offset:400
	s_waitcnt vmcnt(21)
	s_waitcnt lgkmcnt(3)
	v_cndmask_b32_e64 v141, 0, v141, s[8:9]
	v_pk_mul_f32 v[180:181], v[26:27], v[114:115] op_sel:[0,1]
	v_pk_mul_f32 v[192:193], v[28:29], v[114:115] op_sel:[0,1]
	v_mfma_f32_16x16x4_f32 v[110:113], v141, v54, v[110:113]
	v_pk_fma_f32 v[180:181], v[30:31], v[114:115], v[180:181] op_sel_hi:[1,0,1]
	v_pk_fma_f32 v[192:193], v[32:33], v[114:115], v[192:193] op_sel_hi:[1,0,1]
	v_pk_fma_f32 v[180:181], v[22:23], v[116:117], v[180:181] op_sel_hi:[1,0,1]
	v_pk_fma_f32 v[192:193], v[24:25], v[116:117], v[192:193] op_sel_hi:[1,0,1]
	v_mfma_f32_16x16x4_f32 v[106:109], v141, v55, v[106:109]
	v_pk_fma_f32 v[180:181], v[18:19], v[116:117], v[180:181] op_sel:[0,1,0]
	v_pk_fma_f32 v[192:193], v[20:21], v[116:117], v[192:193] op_sel:[0,1,0]
	v_pk_fma_f32 v[180:181], v[14:15], v[176:177], v[180:181] op_sel_hi:[1,0,1]
	v_pk_fma_f32 v[192:193], v[16:17], v[176:177], v[192:193] op_sel_hi:[1,0,1]
	v_mfma_f32_16x16x4_f32 v[102:105], v141, v56, v[102:105]
	v_pk_fma_f32 v[180:181], v[10:11], v[176:177], v[180:181] op_sel:[0,1,0]
	v_pk_fma_f32 v[192:193], v[12:13], v[176:177], v[192:193] op_sel:[0,1,0]
	v_pk_fma_f32 v[180:181], v[6:7], v[178:179], v[180:181] op_sel_hi:[1,0,1]
	v_pk_fma_f32 v[192:193], v[8:9], v[178:179], v[192:193] op_sel_hi:[1,0,1]
	v_mfma_f32_16x16x4_f32 v[98:101], v141, v57, v[98:101]
	v_pk_fma_f32 v[180:181], v[2:3], v[178:179], v[180:181] op_sel:[0,1,0]
	v_pk_fma_f32 v[192:193], v[4:5], v[178:179], v[192:193] op_sel:[0,1,0]
	v_pk_mul_f32 v[180:181], v[146:147], v[180:181]
	v_pk_mul_f32 v[192:193], v[146:147], v[192:193]
	v_pk_fma_f32 v[236:237], v[144:145], v[54:55], v[180:181]
	v_pk_fma_f32 v[238:239], v[144:145], v[56:57], v[192:193]
	global_store_dwordx4 v[150:151], v[236:239], off nt
	v_lshl_add_u64 v[150:151], v[150:151], 0, s[74:75]
	global_load_dwordx4 v[54:57], v[148:149], off nt
	v_lshl_add_u64 v[148:149], v[148:149], 0, s[74:75]
	ds_read_b32 v141, v160 offset:64
	ds_read_b128 v[114:117], v161 offset:512
	ds_read_b128 v[176:179], v161 offset:528
	s_waitcnt vmcnt(22)
	s_waitcnt lgkmcnt(3)
	v_cndmask_b32_e64 v143, 0, v143, s[8:9]
	v_pk_mul_f32 v[180:181], v[26:27], v[172:173] op_sel:[0,1]
	v_pk_mul_f32 v[192:193], v[28:29], v[172:173] op_sel:[0,1]
	v_mfma_f32_16x16x4_f32 v[110:113], v143, v50, v[110:113]
	v_pk_fma_f32 v[180:181], v[30:31], v[172:173], v[180:181] op_sel_hi:[1,0,1]
	v_pk_fma_f32 v[192:193], v[32:33], v[172:173], v[192:193] op_sel_hi:[1,0,1]
	v_pk_fma_f32 v[180:181], v[22:23], v[174:175], v[180:181] op_sel_hi:[1,0,1]
	v_pk_fma_f32 v[192:193], v[24:25], v[174:175], v[192:193] op_sel_hi:[1,0,1]
	v_mfma_f32_16x16x4_f32 v[106:109], v143, v51, v[106:109]
	v_pk_fma_f32 v[180:181], v[18:19], v[174:175], v[180:181] op_sel:[0,1,0]
	v_pk_fma_f32 v[192:193], v[20:21], v[174:175], v[192:193] op_sel:[0,1,0]
	v_pk_fma_f32 v[180:181], v[14:15], v[232:233], v[180:181] op_sel_hi:[1,0,1]
	v_pk_fma_f32 v[192:193], v[16:17], v[232:233], v[192:193] op_sel_hi:[1,0,1]
	v_mfma_f32_16x16x4_f32 v[102:105], v143, v52, v[102:105]
	v_pk_fma_f32 v[180:181], v[10:11], v[232:233], v[180:181] op_sel:[0,1,0]
	v_pk_fma_f32 v[192:193], v[12:13], v[232:233], v[192:193] op_sel:[0,1,0]
	v_pk_fma_f32 v[180:181], v[6:7], v[234:235], v[180:181] op_sel_hi:[1,0,1]
	v_pk_fma_f32 v[192:193], v[8:9], v[234:235], v[192:193] op_sel_hi:[1,0,1]
	v_mfma_f32_16x16x4_f32 v[98:101], v143, v53, v[98:101]
	v_pk_fma_f32 v[180:181], v[2:3], v[234:235], v[180:181] op_sel:[0,1,0]
	v_pk_fma_f32 v[192:193], v[4:5], v[234:235], v[192:193] op_sel:[0,1,0]
	v_pk_mul_f32 v[180:181], v[146:147], v[180:181]
	v_pk_mul_f32 v[192:193], v[146:147], v[192:193]
	v_pk_fma_f32 v[236:237], v[144:145], v[50:51], v[180:181]
	v_pk_fma_f32 v[238:239], v[144:145], v[52:53], v[192:193]
	global_store_dwordx4 v[150:151], v[236:239], off nt
	v_lshl_add_u64 v[150:151], v[150:151], 0, s[74:75]
	global_load_dwordx4 v[50:53], v[148:149], off nt
	v_lshl_add_u64 v[148:149], v[148:149], 0, s[74:75]
	ds_read_b32 v143, v160 offset:80
	ds_read_b128 v[172:175], v161 offset:640
	ds_read_b128 v[232:235], v161 offset:656
	s_waitcnt vmcnt(23)
; #define RS_LOAD(dst, it0) do { _Pragma("unroll") for (int u = 0; u < 8; ++u) dst[u] = __builtin_nontemporal_load((const f32x4*)(S0 + (size_t)(4 * ((it0) + u)) * DV)); } while (0)
; __device__ __forceinline__ void ret_sample_item(Frame& F, int item) {
;     ...
;     for (int it0 = 0; it0 < 64; it0 += 16) {
;         RS_LOAD(sb, it0 + 8);
;         RS_PROC(sa, it0);
;         { const int itn = it0 + 16 < 64 ? it0 + 16 : it0; RS_LOAD(sa, itn); }
;         RS_PROC(sb, it0 + 8);
	s_waitcnt lgkmcnt(3)
	v_cndmask_b32_e64 v141, 0, v141, s[8:9]
	v_pk_mul_f32 v[180:181], v[26:27], v[114:115] op_sel:[0,1]
	v_pk_mul_f32 v[192:193], v[28:29], v[114:115] op_sel:[0,1]
	v_mfma_f32_16x16x4_f32 v[110:113], v141, v46, v[110:113]
	v_pk_fma_f32 v[180:181], v[30:31], v[114:115], v[180:181] op_sel_hi:[1,0,1]
	v_pk_fma_f32 v[192:193], v[32:33], v[114:115], v[192:193] op_sel_hi:[1,0,1]
	v_pk_fma_f32 v[180:181], v[22:23], v[116:117], v[180:181] op_sel_hi:[1,0,1]
	v_pk_fma_f32 v[192:193], v[24:25], v[116:117], v[192:193] op_sel_hi:[1,0,1]
	v_mfma_f32_16x16x4_f32 v[106:109], v141, v47, v[106:109]
	v_pk_fma_f32 v[180:181], v[18:19], v[116:117], v[180:181] op_sel:[0,1,0]
	v_pk_fma_f32 v[192:193], v[20:21], v[116:117], v[192:193] op_sel:[0,1,0]
	v_pk_fma_f32 v[180:181], v[14:15], v[176:177], v[180:181] op_sel_hi:[1,0,1]
	v_pk_fma_f32 v[192:193], v[16:17], v[176:177], v[192:193] op_sel_hi:[1,0,1]
	v_mfma_f32_16x16x4_f32 v[102:105], v141, v48, v[102:105]
	v_pk_fma_f32 v[180:181], v[10:11], v[176:177], v[180:181] op_sel:[0,1,0]
	v_pk_fma_f32 v[192:193], v[12:13], v[176:177], v[192:193] op_sel:[0,1,0]
	v_pk_fma_f32 v[180:181], v[6:7], v[178:179], v[180:181] op_sel_hi:[1,0,1]
	v_pk_fma_f32 v[192:193], v[8:9], v[178:179], v[192:193] op_sel_hi:[1,0,1]
	v_mfma_f32_16x16x4_f32 v[98:101], v141, v49, v[98:101]
	v_pk_fma_f32 v[180:181], v[2:3], v[178:179], v[180:181] op_sel:[0,1,0]
	v_pk_fma_f32 v[192:193], v[4:5], v[178:179], v[192:193] op_sel:[0,1,0]
	v_pk_mul_f32 v[180:181], v[146:147], v[180:181]
	v_pk_mul_f32 v[192:193], v[146:147], v[192:193]
	v_pk_fma_f32 v[236:237], v[144:145], v[46:47], v[180:181]
	v_pk_fma_f32 v[238:239], v[144:145], v[48:49], v[192:193]
	global_store_dwordx4 v[150:151], v[236:239], off nt
	v_lshl_add_u64 v[150:151], v[150:151], 0, s[74:75]
	global_load_dwordx4 v[46:49], v[148:149], off nt
	v_lshl_add_u64 v[148:149], v[148:149], 0, s[74:75]
	ds_read_b32 v141, v160 offset:96
	ds_read_b128 v[114:117], v161 offset:768
	ds_read_b128 v[176:179], v161 offset:784
	s_waitcnt vmcnt(24)
	s_waitcnt lgkmcnt(3)
	v_cndmask_b32_e64 v143, 0, v143, s[8:9]
	v_pk_mul_f32 v[180:181], v[26:27], v[172:173] op_sel:[0,1]
	v_pk_mul_f32 v[192:193], v[28:29], v[172:173] op_sel:[0,1]
	v_mfma_f32_16x16x4_f32 v[110:113], v143, v42, v[110:113]
	v_pk_fma_f32 v[180:181], v[30:31], v[172:173], v[180:181] op_sel_hi:[1,0,1]
	v_pk_fma_f32 v[192:193], v[32:33], v[172:173], v[192:193] op_sel_hi:[1,0,1]
	v_pk_fma_f32 v[180:181], v[22:23], v[174:175], v[180:181] op_sel_hi:[1,0,1]
	v_pk_fma_f32 v[192:193], v[24:25], v[174:175], v[192:193] op_sel_hi:[1,0,1]
	v_mfma_f32_16x16x4_f32 v[106:109], v143, v43, v[106:109]
	v_pk_fma_f32 v[180:181], v[18:19], v[174:175], v[180:181] op_sel:[0,1,0]
	v_pk_fma_f32 v[192:193], v[20:21], v[174:175], v[192:193] op_sel:[0,1,0]
	v_pk_fma_f32 v[180:181], v[14:15], v[232:233], v[180:181] op_sel_hi:[1,0,1]
	v_pk_fma_f32 v[192:193], v[16:17], v[232:233], v[192:193] op_sel_hi:[1,0,1]
	v_mfma_f32_16x16x4_f32 v[102:105], v143, v44, v[102:105]
	v_pk_fma_f32 v[180:181], v[10:11], v[232:233], v[180:181] op_sel:[0,1,0]
	v_pk_fma_f32 v[192:193], v[12:13], v[232:233], v[192:193] op_sel:[0,1,0]
	v_pk_fma_f32 v[180:181], v[6:7], v[234:235], v[180:181] op_sel_hi:[1,0,1]
	v_pk_fma_f32 v[192:193], v[8:9], v[234:235], v[192:193] op_sel_hi:[1,0,1]
	v_mfma_f32_16x16x4_f32 v[98:101], v143, v45, v[98:101]
	v_pk_fma_f32 v[180:181], v[2:3], v[234:235], v[180:181] op_sel:[0,1,0]
	v_pk_fma_f32 v[192:193], v[4:5], v[234:235], v[192:193] op_sel:[0,1,0]
	v_pk_mul_f32 v[180:181], v[146:147], v[180:181]
	v_pk_mul_f32 v[192:193], v[146:147], v[192:193]
	v_pk_fma_f32 v[236:237], v[144:145], v[42:43], v[180:181]
	v_pk_fma_f32 v[238:239], v[144:145], v[44:45], v[192:193]
	global_store_dwordx4 v[150:151], v[236:239], off nt
	v_lshl_add_u64 v[150:151], v[150:151], 0, s[74:75]
	global_load_dwordx4 v[42:45], v[148:149], off nt
	v_lshl_add_u64 v[148:149], v[148:149], 0, s[74:75]
	ds_read_b32 v143, v160 offset:112
	ds_read_b128 v[172:175], v161 offset:896
	ds_read_b128 v[232:235], v161 offset:912
	s_waitcnt vmcnt(25)
	s_waitcnt lgkmcnt(3)
	v_cndmask_b32_e64 v141, 0, v141, s[8:9]
	v_pk_mul_f32 v[180:181], v[26:27], v[114:115] op_sel:[0,1]
	v_pk_mul_f32 v[192:193], v[28:29], v[114:115] op_sel:[0,1]
	v_mfma_f32_16x16x4_f32 v[110:113], v141, v38, v[110:113]
	v_pk_fma_f32 v[180:181], v[30:31], v[114:115], v[180:181] op_sel_hi:[1,0,1]
	v_pk_fma_f32 v[192:193], v[32:33], v[114:115], v[192:193] op_sel_hi:[1,0,1]
	v_pk_fma_f32 v[180:181], v[22:23], v[116:117], v[180:181] op_sel_hi:[1,0,1]
	v_pk_fma_f32 v[192:193], v[24:25], v[116:117], v[192:193] op_sel_hi:[1,0,1]
	v_mfma_f32_16x16x4_f32 v[106:109], v141, v39, v[106:109]
	v_pk_fma_f32 v[180:181], v[18:19], v[116:117], v[180:181] op_sel:[0,1,0]
	v_pk_fma_f32 v[192:193], v[20:21], v[116:117], v[192:193] op_sel:[0,1,0]
	v_pk_fma_f32 v[180:181], v[14:15], v[176:177], v[180:181] op_sel_hi:[1,0,1]
	v_pk_fma_f32 v[192:193], v[16:17], v[176:177], v[192:193] op_sel_hi:[1,0,1]
	v_mfma_f32_16x16x4_f32 v[102:105], v141, v40, v[102:105]
	v_pk_fma_f32 v[180:181], v[10:11], v[176:177], v[180:181] op_sel:[0,1,0]
	v_pk_fma_f32 v[192:193], v[12:13], v[176:177], v[192:193] op_sel:[0,1,0]
	v_pk_fma_f32 v[180:181], v[6:7], v[178:179], v[180:181] op_sel_hi:[1,0,1]
	v_pk_fma_f32 v[192:193], v[8:9], v[178:179], v[192:193] op_sel_hi:[1,0,1]
	v_mfma_f32_16x16x4_f32 v[98:101], v141, v41, v[98:101]
	v_pk_fma_f32 v[180:181], v[2:3], v[178:179], v[180:181] op_sel:[0,1,0]
	v_pk_fma_f32 v[192:193], v[4:5], v[178:179], v[192:193] op_sel:[0,1,0]
	v_pk_mul_f32 v[180:181], v[146:147], v[180:181]
	v_pk_mul_f32 v[192:193], v[146:147], v[192:193]
	v_pk_fma_f32 v[236:237], v[144:145], v[38:39], v[180:181]
	v_pk_fma_f32 v[238:239], v[144:145], v[40:41], v[192:193]
	global_store_dwordx4 v[150:151], v[236:239], off nt
	v_lshl_add_u64 v[150:151], v[150:151], 0, s[74:75]
	global_load_dwordx4 v[38:41], v[148:149], off nt
	v_lshl_add_u64 v[148:149], v[148:149], 0, s[74:75]
	ds_read_b32 v141, v160 offset:128
	ds_read_b128 v[114:117], v161 offset:1024
	ds_read_b128 v[176:179], v161 offset:1040
	s_waitcnt vmcnt(26)
; #define RS_LOAD(dst, it0) do { _Pragma("unroll") for (int u = 0; u < 8; ++u) dst[u] = __builtin_nontemporal_load((const f32x4*)(S0 + (size_t)(4 * ((it0) + u)) * DV)); } while (0)
; __device__ __forceinline__ void ret_sample_item(Frame& F, int item) {
;     ...
;     for (int it0 = 0; it0 < 64; it0 += 16) {
;         RS_LOAD(sb, it0 + 8);
;         RS_PROC(sa, it0);
;         { const int itn = it0 + 16 < 64 ? it0 + 16 : it0; RS_LOAD(sa, itn); }
;         RS_PROC(sb, it0 + 8);
	s_waitcnt lgkmcnt(3)
	v_cndmask_b32_e64 v143, 0, v143, s[8:9]
	v_pk_mul_f32 v[180:181], v[26:27], v[172:173] op_sel:[0,1]
	v_pk_mul_f32 v[192:193], v[28:29], v[172:173] op_sel:[0,1]
	v_mfma_f32_16x16x4_f32 v[110:113], v143, v34, v[110:113]
	v_pk_fma_f32 v[180:181], v[30:31], v[172:173], v[180:181] op_sel_hi:[1,0,1]
	v_pk_fma_f32 v[192:193], v[32:33], v[172:173], v[192:193] op_sel_hi:[1,0,1]
	v_pk_fma_f32 v[180:181], v[22:23], v[174:175], v[180:181] op_sel_hi:[1,0,1]
	v_pk_fma_f32 v[192:193], v[24:25], v[174:175], v[192:193] op_sel_hi:[1,0,1]
	v_mfma_f32_16x16x4_f32 v[106:109], v143, v35, v[106:109]
	v_pk_fma_f32 v[180:181], v[18:19], v[174:175], v[180:181] op_sel:[0,1,0]
	v_pk_fma_f32 v[192:193], v[20:21], v[174:175], v[192:193] op_sel:[0,1,0]
	v_pk_fma_f32 v[180:181], v[14:15], v[232:233], v[180:181] op_sel_hi:[1,0,1]
	v_pk_fma_f32 v[192:193], v[16:17], v[232:233], v[192:193] op_sel_hi:[1,0,1]
	v_mfma_f32_16x16x4_f32 v[102:105], v143, v36, v[102:105]
	v_pk_fma_f32 v[180:181], v[10:11], v[232:233], v[180:181] op_sel:[0,1,0]
	v_pk_fma_f32 v[192:193], v[12:13], v[232:233], v[192:193] op_sel:[0,1,0]
	v_pk_fma_f32 v[180:181], v[6:7], v[234:235], v[180:181] op_sel_hi:[1,0,1]
	v_pk_fma_f32 v[192:193], v[8:9], v[234:235], v[192:193] op_sel_hi:[1,0,1]
	v_mfma_f32_16x16x4_f32 v[98:101], v143, v37, v[98:101]
	v_pk_fma_f32 v[180:181], v[2:3], v[234:235], v[180:181] op_sel:[0,1,0]
	v_pk_fma_f32 v[192:193], v[4:5], v[234:235], v[192:193] op_sel:[0,1,0]
	v_pk_mul_f32 v[180:181], v[146:147], v[180:181]
	v_pk_mul_f32 v[192:193], v[146:147], v[192:193]
	v_pk_fma_f32 v[236:237], v[144:145], v[34:35], v[180:181]
	v_pk_fma_f32 v[238:239], v[144:145], v[36:37], v[192:193]
	global_store_dwordx4 v[150:151], v[236:239], off nt
	v_lshl_add_u64 v[150:151], v[150:151], 0, s[74:75]
	global_load_dwordx4 v[34:37], v[148:149], off nt
	v_lshl_add_u64 v[148:149], v[148:149], 0, s[74:75]
	ds_read_b32 v143, v160 offset:144
	ds_read_b128 v[172:175], v161 offset:1152
	ds_read_b128 v[232:235], v161 offset:1168
	s_waitcnt vmcnt(27)
	s_waitcnt lgkmcnt(3)
	v_cndmask_b32_e64 v141, 0, v141, s[8:9]
	v_pk_mul_f32 v[180:181], v[26:27], v[114:115] op_sel:[0,1]
	v_pk_mul_f32 v[192:193], v[28:29], v[114:115] op_sel:[0,1]
	v_mfma_f32_16x16x4_f32 v[110:113], v141, v58, v[110:113]
	v_pk_fma_f32 v[180:181], v[30:31], v[114:115], v[180:181] op_sel_hi:[1,0,1]
	v_pk_fma_f32 v[192:193], v[32:33], v[114:115], v[192:193] op_sel_hi:[1,0,1]
	v_pk_fma_f32 v[180:181], v[22:23], v[116:117], v[180:181] op_sel_hi:[1,0,1]
	v_pk_fma_f32 v[192:193], v[24:25], v[116:117], v[192:193] op_sel_hi:[1,0,1]
	v_mfma_f32_16x16x4_f32 v[106:109], v141, v59, v[106:109]
	v_pk_fma_f32 v[180:181], v[18:19], v[116:117], v[180:181] op_sel:[0,1,0]
	v_pk_fma_f32 v[192:193], v[20:21], v[116:117], v[192:193] op_sel:[0,1,0]
	v_pk_fma_f32 v[180:181], v[14:15], v[176:177], v[180:181] op_sel_hi:[1,0,1]
	v_pk_fma_f32 v[192:193], v[16:17], v[176:177], v[192:193] op_sel_hi:[1,0,1]
	v_mfma_f32_16x16x4_f32 v[102:105], v141, v60, v[102:105]
	v_pk_fma_f32 v[180:181], v[10:11], v[176:177], v[180:181] op_sel:[0,1,0]
	v_pk_fma_f32 v[192:193], v[12:13], v[176:177], v[192:193] op_sel:[0,1,0]
	v_pk_fma_f32 v[180:181], v[6:7], v[178:179], v[180:181] op_sel_hi:[1,0,1]
	v_pk_fma_f32 v[192:193], v[8:9], v[178:179], v[192:193] op_sel_hi:[1,0,1]
	v_mfma_f32_16x16x4_f32 v[98:101], v141, v61, v[98:101]
	v_pk_fma_f32 v[180:181], v[2:3], v[178:179], v[180:181] op_sel:[0,1,0]
	v_pk_fma_f32 v[192:193], v[4:5], v[178:179], v[192:193] op_sel:[0,1,0]
	v_pk_mul_f32 v[180:181], v[146:147], v[180:181]
	v_pk_mul_f32 v[192:193], v[146:147], v[192:193]
	v_pk_fma_f32 v[236:237], v[144:145], v[58:59], v[180:181]
	v_pk_fma_f32 v[238:239], v[144:145], v[60:61], v[192:193]
	global_store_dwordx4 v[150:151], v[236:239], off nt
	v_lshl_add_u64 v[150:151], v[150:151], 0, s[74:75]
	global_load_dwordx4 v[58:61], v[148:149], off nt
	v_lshl_add_u64 v[148:149], v[148:149], 0, s[74:75]
	ds_read_b32 v141, v160 offset:160
	ds_read_b128 v[114:117], v161 offset:1280
	ds_read_b128 v[176:179], v161 offset:1296
	s_waitcnt vmcnt(28)
	s_waitcnt lgkmcnt(3)
	v_cndmask_b32_e64 v143, 0, v143, s[8:9]
	v_pk_mul_f32 v[180:181], v[26:27], v[172:173] op_sel:[0,1]
	v_pk_mul_f32 v[192:193], v[28:29], v[172:173] op_sel:[0,1]
	v_mfma_f32_16x16x4_f32 v[110:113], v143, v66, v[110:113]
	v_pk_fma_f32 v[180:181], v[30:31], v[172:173], v[180:181] op_sel_hi:[1,0,1]
	v_pk_fma_f32 v[192:193], v[32:33], v[172:173], v[192:193] op_sel_hi:[1,0,1]
	v_pk_fma_f32 v[180:181], v[22:23], v[174:175], v[180:181] op_sel_hi:[1,0,1]
	v_pk_fma_f32 v[192:193], v[24:25], v[174:175], v[192:193] op_sel_hi:[1,0,1]
	v_mfma_f32_16x16x4_f32 v[106:109], v143, v67, v[106:109]
	v_pk_fma_f32 v[180:181], v[18:19], v[174:175], v[180:181] op_sel:[0,1,0]
	v_pk_fma_f32 v[192:193], v[20:21], v[174:175], v[192:193] op_sel:[0,1,0]
	v_pk_fma_f32 v[180:181], v[14:15], v[232:233], v[180:181] op_sel_hi:[1,0,1]
	v_pk_fma_f32 v[192:193], v[16:17], v[232:233], v[192:193] op_sel_hi:[1,0,1]
	v_mfma_f32_16x16x4_f32 v[102:105], v143, v68, v[102:105]
	v_pk_fma_f32 v[180:181], v[10:11], v[232:233], v[180:181] op_sel:[0,1,0]
	v_pk_fma_f32 v[192:193], v[12:13], v[232:233], v[192:193] op_sel:[0,1,0]
	v_pk_fma_f32 v[180:181], v[6:7], v[234:235], v[180:181] op_sel_hi:[1,0,1]
	v_pk_fma_f32 v[192:193], v[8:9], v[234:235], v[192:193] op_sel_hi:[1,0,1]
	v_mfma_f32_16x16x4_f32 v[98:101], v143, v69, v[98:101]
	v_pk_fma_f32 v[180:181], v[2:3], v[234:235], v[180:181] op_sel:[0,1,0]
	v_pk_fma_f32 v[192:193], v[4:5], v[234:235], v[192:193] op_sel:[0,1,0]
	v_pk_mul_f32 v[180:181], v[146:147], v[180:181]
	v_pk_mul_f32 v[192:193], v[146:147], v[192:193]
	v_pk_fma_f32 v[236:237], v[144:145], v[66:67], v[180:181]
	v_pk_fma_f32 v[238:239], v[144:145], v[68:69], v[192:193]
	global_store_dwordx4 v[150:151], v[236:239], off nt
	v_lshl_add_u64 v[150:151], v[150:151], 0, s[74:75]
	global_load_dwordx4 v[66:69], v[148:149], off nt
	v_lshl_add_u64 v[148:149], v[148:149], 0, s[74:75]
	ds_read_b32 v143, v160 offset:176
	ds_read_b128 v[172:175], v161 offset:1408
	ds_read_b128 v[232:235], v161 offset:1424
	s_waitcnt vmcnt(29)
; #define RS_LOAD(dst, it0) do { _Pragma("unroll") for (int u = 0; u < 8; ++u) dst[u] = __builtin_nontemporal_load((const f32x4*)(S0 + (size_t)(4 * ((it0) + u)) * DV)); } while (0)
; __device__ __forceinline__ void ret_sample_item(Frame& F, int item) {
;     ...
;     for (int it0 = 0; it0 < 64; it0 += 16) {
;         RS_LOAD(sb, it0 + 8);
;         RS_PROC(sa, it0);
;         { const int itn = it0 + 16 < 64 ? it0 + 16 : it0; RS_LOAD(sa, itn); }
;         RS_PROC(sb, it0 + 8);
	s_waitcnt lgkmcnt(3)
	v_cndmask_b32_e64 v141, 0, v141, s[8:9]
	v_pk_mul_f32 v[180:181], v[26:27], v[114:115] op_sel:[0,1]
	v_pk_mul_f32 v[192:193], v[28:29], v[114:115] op_sel:[0,1]
	v_mfma_f32_16x16x4_f32 v[110:113], v141, v74, v[110:113]
	v_pk_fma_f32 v[180:181], v[30:31], v[114:115], v[180:181] op_sel_hi:[1,0,1]
	v_pk_fma_f32 v[192:193], v[32:33], v[114:115], v[192:193] op_sel_hi:[1,0,1]
	v_pk_fma_f32 v[180:181], v[22:23], v[116:117], v[180:181] op_sel_hi:[1,0,1]
	v_pk_fma_f32 v[192:193], v[24:25], v[116:117], v[192:193] op_sel_hi:[1,0,1]
	v_mfma_f32_16x16x4_f32 v[106:109], v141, v75, v[106:109]
	v_pk_fma_f32 v[180:181], v[18:19], v[116:117], v[180:181] op_sel:[0,1,0]
	v_pk_fma_f32 v[192:193], v[20:21], v[116:117], v[192:193] op_sel:[0,1,0]
	v_pk_fma_f32 v[180:181], v[14:15], v[176:177], v[180:181] op_sel_hi:[1,0,1]
	v_pk_fma_f32 v[192:193], v[16:17], v[176:177], v[192:193] op_sel_hi:[1,0,1]
	v_mfma_f32_16x16x4_f32 v[102:105], v141, v76, v[102:105]
	v_pk_fma_f32 v[180:181], v[10:11], v[176:177], v[180:181] op_sel:[0,1,0]
	v_pk_fma_f32 v[192:193], v[12:13], v[176:177], v[192:193] op_sel:[0,1,0]
	v_pk_fma_f32 v[180:181], v[6:7], v[178:179], v[180:181] op_sel_hi:[1,0,1]
	v_pk_fma_f32 v[192:193], v[8:9], v[178:179], v[192:193] op_sel_hi:[1,0,1]
	v_mfma_f32_16x16x4_f32 v[98:101], v141, v77, v[98:101]
	v_pk_fma_f32 v[180:181], v[2:3], v[178:179], v[180:181] op_sel:[0,1,0]
	v_pk_fma_f32 v[192:193], v[4:5], v[178:179], v[192:193] op_sel:[0,1,0]
	v_pk_mul_f32 v[180:181], v[146:147], v[180:181]
	v_pk_mul_f32 v[192:193], v[146:147], v[192:193]
	v_pk_fma_f32 v[236:237], v[144:145], v[74:75], v[180:181]
	v_pk_fma_f32 v[238:239], v[144:145], v[76:77], v[192:193]
	global_store_dwordx4 v[150:151], v[236:239], off nt
	v_lshl_add_u64 v[150:151], v[150:151], 0, s[74:75]
	global_load_dwordx4 v[74:77], v[148:149], off nt
	v_lshl_add_u64 v[148:149], v[148:149], 0, s[74:75]
	ds_read_b32 v141, v160 offset:192
	ds_read_b128 v[114:117], v161 offset:1536
	ds_read_b128 v[176:179], v161 offset:1552
	s_waitcnt vmcnt(30)
	s_waitcnt lgkmcnt(3)
	v_cndmask_b32_e64 v143, 0, v143, s[8:9]
	v_pk_mul_f32 v[180:181], v[26:27], v[172:173] op_sel:[0,1]
	v_pk_mul_f32 v[192:193], v[28:29], v[172:173] op_sel:[0,1]
	v_mfma_f32_16x16x4_f32 v[110:113], v143, v78, v[110:113]
	v_pk_fma_f32 v[180:181], v[30:31], v[172:173], v[180:181] op_sel_hi:[1,0,1]
	v_pk_fma_f32 v[192:193], v[32:33], v[172:173], v[192:193] op_sel_hi:[1,0,1]
	v_pk_fma_f32 v[180:181], v[22:23], v[174:175], v[180:181] op_sel_hi:[1,0,1]
	v_pk_fma_f32 v[192:193], v[24:25], v[174:175], v[192:193] op_sel_hi:[1,0,1]
	v_mfma_f32_16x16x4_f32 v[106:109], v143, v79, v[106:109]
	v_pk_fma_f32 v[180:181], v[18:19], v[174:175], v[180:181] op_sel:[0,1,0]
	v_pk_fma_f32 v[192:193], v[20:21], v[174:175], v[192:193] op_sel:[0,1,0]
	v_pk_fma_f32 v[180:181], v[14:15], v[232:233], v[180:181] op_sel_hi:[1,0,1]
	v_pk_fma_f32 v[192:193], v[16:17], v[232:233], v[192:193] op_sel_hi:[1,0,1]
	v_mfma_f32_16x16x4_f32 v[102:105], v143, v80, v[102:105]
	v_pk_fma_f32 v[180:181], v[10:11], v[232:233], v[180:181] op_sel:[0,1,0]
	v_pk_fma_f32 v[192:193], v[12:13], v[232:233], v[192:193] op_sel:[0,1,0]
	v_pk_fma_f32 v[180:181], v[6:7], v[234:235], v[180:181] op_sel_hi:[1,0,1]
	v_pk_fma_f32 v[192:193], v[8:9], v[234:235], v[192:193] op_sel_hi:[1,0,1]
	v_mfma_f32_16x16x4_f32 v[98:101], v143, v81, v[98:101]
	v_pk_fma_f32 v[180:181], v[2:3], v[234:235], v[180:181] op_sel:[0,1,0]
	v_pk_fma_f32 v[192:193], v[4:5], v[234:235], v[192:193] op_sel:[0,1,0]
	v_pk_mul_f32 v[180:181], v[146:147], v[180:181]
	v_pk_mul_f32 v[192:193], v[146:147], v[192:193]
	v_pk_fma_f32 v[236:237], v[144:145], v[78:79], v[180:181]
	v_pk_fma_f32 v[238:239], v[144:145], v[80:81], v[192:193]
	global_store_dwordx4 v[150:151], v[236:239], off nt
	v_lshl_add_u64 v[150:151], v[150:151], 0, s[74:75]
	global_load_dwordx4 v[78:81], v[148:149], off nt
	v_lshl_add_u64 v[148:149], v[148:149], 0, s[74:75]
	ds_read_b32 v143, v160 offset:208
	ds_read_b128 v[172:175], v161 offset:1664
	ds_read_b128 v[232:235], v161 offset:1680
	s_waitcnt vmcnt(31)
	s_waitcnt lgkmcnt(3)
	v_cndmask_b32_e64 v141, 0, v141, s[8:9]
	v_pk_mul_f32 v[180:181], v[26:27], v[114:115] op_sel:[0,1]
	v_pk_mul_f32 v[192:193], v[28:29], v[114:115] op_sel:[0,1]
	v_mfma_f32_16x16x4_f32 v[110:113], v141, v82, v[110:113]
	v_pk_fma_f32 v[180:181], v[30:31], v[114:115], v[180:181] op_sel_hi:[1,0,1]
	v_pk_fma_f32 v[192:193], v[32:33], v[114:115], v[192:193] op_sel_hi:[1,0,1]
	v_pk_fma_f32 v[180:181], v[22:23], v[116:117], v[180:181] op_sel_hi:[1,0,1]
	v_pk_fma_f32 v[192:193], v[24:25], v[116:117], v[192:193] op_sel_hi:[1,0,1]
	v_mfma_f32_16x16x4_f32 v[106:109], v141, v83, v[106:109]
	v_pk_fma_f32 v[180:181], v[18:19], v[116:117], v[180:181] op_sel:[0,1,0]
	v_pk_fma_f32 v[192:193], v[20:21], v[116:117], v[192:193] op_sel:[0,1,0]
	v_pk_fma_f32 v[180:181], v[14:15], v[176:177], v[180:181] op_sel_hi:[1,0,1]
	v_pk_fma_f32 v[192:193], v[16:17], v[176:177], v[192:193] op_sel_hi:[1,0,1]
	v_mfma_f32_16x16x4_f32 v[102:105], v141, v84, v[102:105]
	v_pk_fma_f32 v[180:181], v[10:11], v[176:177], v[180:181] op_sel:[0,1,0]
	v_pk_fma_f32 v[192:193], v[12:13], v[176:177], v[192:193] op_sel:[0,1,0]
	v_pk_fma_f32 v[180:181], v[6:7], v[178:179], v[180:181] op_sel_hi:[1,0,1]
	v_pk_fma_f32 v[192:193], v[8:9], v[178:179], v[192:193] op_sel_hi:[1,0,1]
	v_mfma_f32_16x16x4_f32 v[98:101], v141, v85, v[98:101]
	v_pk_fma_f32 v[180:181], v[2:3], v[178:179], v[180:181] op_sel:[0,1,0]
	v_pk_fma_f32 v[192:193], v[4:5], v[178:179], v[192:193] op_sel:[0,1,0]
	v_pk_mul_f32 v[180:181], v[146:147], v[180:181]
	v_pk_mul_f32 v[192:193], v[146:147], v[192:193]
	v_pk_fma_f32 v[236:237], v[144:145], v[82:83], v[180:181]
	v_pk_fma_f32 v[238:239], v[144:145], v[84:85], v[192:193]
	global_store_dwordx4 v[150:151], v[236:239], off nt
	v_lshl_add_u64 v[150:151], v[150:151], 0, s[74:75]
	global_load_dwordx4 v[82:85], v[148:149], off nt
	v_lshl_add_u64 v[148:149], v[148:149], 0, s[74:75]
	ds_read_b32 v141, v160 offset:224
	ds_read_b128 v[114:117], v161 offset:1792
	ds_read_b128 v[176:179], v161 offset:1808
	s_waitcnt vmcnt(32)
; #define RS_LOAD(dst, it0) do { _Pragma("unroll") for (int u = 0; u < 8; ++u) dst[u] = __builtin_nontemporal_load((const f32x4*)(S0 + (size_t)(4 * ((it0) + u)) * DV)); } while (0)
; __device__ __forceinline__ void ret_sample_item(Frame& F, int item) {
;     ...
;     for (int it0 = 0; it0 < 64; it0 += 16) {
;         RS_LOAD(sb, it0 + 8);
;         RS_PROC(sa, it0);
;         { const int itn = it0 + 16 < 64 ? it0 + 16 : it0; RS_LOAD(sa, itn); }
;         RS_PROC(sb, it0 + 8);
	s_waitcnt lgkmcnt(3)
	v_cndmask_b32_e64 v143, 0, v143, s[8:9]
	v_pk_mul_f32 v[180:181], v[26:27], v[172:173] op_sel:[0,1]
	v_pk_mul_f32 v[192:193], v[28:29], v[172:173] op_sel:[0,1]
	v_mfma_f32_16x16x4_f32 v[110:113], v143, v86, v[110:113]
	v_pk_fma_f32 v[180:181], v[30:31], v[172:173], v[180:181] op_sel_hi:[1,0,1]
	v_pk_fma_f32 v[192:193], v[32:33], v[172:173], v[192:193] op_sel_hi:[1,0,1]
	v_pk_fma_f32 v[180:181], v[22:23], v[174:175], v[180:181] op_sel_hi:[1,0,1]
	v_pk_fma_f32 v[192:193], v[24:25], v[174:175], v[192:193] op_sel_hi:[1,0,1]
	v_mfma_f32_16x16x4_f32 v[106:109], v143, v87, v[106:109]
	v_pk_fma_f32 v[180:181], v[18:19], v[174:175], v[180:181] op_sel:[0,1,0]
	v_pk_fma_f32 v[192:193], v[20:21], v[174:175], v[192:193] op_sel:[0,1,0]
	v_pk_fma_f32 v[180:181], v[14:15], v[232:233], v[180:181] op_sel_hi:[1,0,1]
	v_pk_fma_f32 v[192:193], v[16:17], v[232:233], v[192:193] op_sel_hi:[1,0,1]
	v_mfma_f32_16x16x4_f32 v[102:105], v143, v88, v[102:105]
	v_pk_fma_f32 v[180:181], v[10:11], v[232:233], v[180:181] op_sel:[0,1,0]
	v_pk_fma_f32 v[192:193], v[12:13], v[232:233], v[192:193] op_sel:[0,1,0]
	v_pk_fma_f32 v[180:181], v[6:7], v[234:235], v[180:181] op_sel_hi:[1,0,1]
	v_pk_fma_f32 v[192:193], v[8:9], v[234:235], v[192:193] op_sel_hi:[1,0,1]
	v_mfma_f32_16x16x4_f32 v[98:101], v143, v89, v[98:101]
	v_pk_fma_f32 v[180:181], v[2:3], v[234:235], v[180:181] op_sel:[0,1,0]
	v_pk_fma_f32 v[192:193], v[4:5], v[234:235], v[192:193] op_sel:[0,1,0]
	v_pk_mul_f32 v[180:181], v[146:147], v[180:181]
	v_pk_mul_f32 v[192:193], v[146:147], v[192:193]
	v_pk_fma_f32 v[236:237], v[144:145], v[86:87], v[180:181]
	v_pk_fma_f32 v[238:239], v[144:145], v[88:89], v[192:193]
	global_store_dwordx4 v[150:151], v[236:239], off nt
	v_lshl_add_u64 v[150:151], v[150:151], 0, s[74:75]
	global_load_dwordx4 v[86:89], v[148:149], off nt
	v_lshl_add_u64 v[148:149], v[148:149], 0, s[74:75]
	ds_read_b32 v143, v160 offset:240
	ds_read_b128 v[172:175], v161 offset:1920
	ds_read_b128 v[232:235], v161 offset:1936
	s_waitcnt vmcnt(33)
	s_waitcnt lgkmcnt(3)
	v_cndmask_b32_e64 v141, 0, v141, s[8:9]
	v_pk_mul_f32 v[180:181], v[26:27], v[114:115] op_sel:[0,1]
	v_pk_mul_f32 v[192:193], v[28:29], v[114:115] op_sel:[0,1]
	v_mfma_f32_16x16x4_f32 v[110:113], v141, v90, v[110:113]
	v_pk_fma_f32 v[180:181], v[30:31], v[114:115], v[180:181] op_sel_hi:[1,0,1]
	v_pk_fma_f32 v[192:193], v[32:33], v[114:115], v[192:193] op_sel_hi:[1,0,1]
	v_pk_fma_f32 v[180:181], v[22:23], v[116:117], v[180:181] op_sel_hi:[1,0,1]
	v_pk_fma_f32 v[192:193], v[24:25], v[116:117], v[192:193] op_sel_hi:[1,0,1]
	v_mfma_f32_16x16x4_f32 v[106:109], v141, v91, v[106:109]
	v_pk_fma_f32 v[180:181], v[18:19], v[116:117], v[180:181] op_sel:[0,1,0]
	v_pk_fma_f32 v[192:193], v[20:21], v[116:117], v[192:193] op_sel:[0,1,0]
	v_pk_fma_f32 v[180:181], v[14:15], v[176:177], v[180:181] op_sel_hi:[1,0,1]
	v_pk_fma_f32 v[192:193], v[16:17], v[176:177], v[192:193] op_sel_hi:[1,0,1]
	v_mfma_f32_16x16x4_f32 v[102:105], v141, v92, v[102:105]
	v_pk_fma_f32 v[180:181], v[10:11], v[176:177], v[180:181] op_sel:[0,1,0]
	v_pk_fma_f32 v[192:193], v[12:13], v[176:177], v[192:193] op_sel:[0,1,0]
	v_pk_fma_f32 v[180:181], v[6:7], v[178:179], v[180:181] op_sel_hi:[1,0,1]
	v_pk_fma_f32 v[192:193], v[8:9], v[178:179], v[192:193] op_sel_hi:[1,0,1]
	v_mfma_f32_16x16x4_f32 v[98:101], v141, v93, v[98:101]
	v_pk_fma_f32 v[180:181], v[2:3], v[178:179], v[180:181] op_sel:[0,1,0]
	v_pk_fma_f32 v[192:193], v[4:5], v[178:179], v[192:193] op_sel:[0,1,0]
	v_pk_mul_f32 v[180:181], v[146:147], v[180:181]
	v_pk_mul_f32 v[192:193], v[146:147], v[192:193]
	v_pk_fma_f32 v[236:237], v[144:145], v[90:91], v[180:181]
	v_pk_fma_f32 v[238:239], v[144:145], v[92:93], v[192:193]
	global_store_dwordx4 v[150:151], v[236:239], off nt
	v_lshl_add_u64 v[150:151], v[150:151], 0, s[74:75]
	global_load_dwordx4 v[90:93], v[148:149], off nt
	v_lshl_add_u64 v[148:149], v[148:149], 0, s[74:75]
	ds_read_b32 v141, v160 offset:256
	ds_read_b128 v[114:117], v161 offset:2048
	ds_read_b128 v[176:179], v161 offset:2064
	s_waitcnt vmcnt(34)
	s_waitcnt lgkmcnt(3)
	v_cndmask_b32_e64 v143, 0, v143, s[8:9]
	v_pk_mul_f32 v[180:181], v[26:27], v[172:173] op_sel:[0,1]
	v_pk_mul_f32 v[192:193], v[28:29], v[172:173] op_sel:[0,1]
	v_mfma_f32_16x16x4_f32 v[110:113], v143, v94, v[110:113]
	v_pk_fma_f32 v[180:181], v[30:31], v[172:173], v[180:181] op_sel_hi:[1,0,1]
	v_pk_fma_f32 v[192:193], v[32:33], v[172:173], v[192:193] op_sel_hi:[1,0,1]
	v_pk_fma_f32 v[180:181], v[22:23], v[174:175], v[180:181] op_sel_hi:[1,0,1]
	v_pk_fma_f32 v[192:193], v[24:25], v[174:175], v[192:193] op_sel_hi:[1,0,1]
	v_mfma_f32_16x16x4_f32 v[106:109], v143, v95, v[106:109]
	v_pk_fma_f32 v[180:181], v[18:19], v[174:175], v[180:181] op_sel:[0,1,0]
	v_pk_fma_f32 v[192:193], v[20:21], v[174:175], v[192:193] op_sel:[0,1,0]
	v_pk_fma_f32 v[180:181], v[14:15], v[232:233], v[180:181] op_sel_hi:[1,0,1]
	v_pk_fma_f32 v[192:193], v[16:17], v[232:233], v[192:193] op_sel_hi:[1,0,1]
	v_mfma_f32_16x16x4_f32 v[102:105], v143, v96, v[102:105]
	v_pk_fma_f32 v[180:181], v[10:11], v[232:233], v[180:181] op_sel:[0,1,0]
	v_pk_fma_f32 v[192:193], v[12:13], v[232:233], v[192:193] op_sel:[0,1,0]
	v_pk_fma_f32 v[180:181], v[6:7], v[234:235], v[180:181] op_sel_hi:[1,0,1]
	v_pk_fma_f32 v[192:193], v[8:9], v[234:235], v[192:193] op_sel_hi:[1,0,1]
	v_mfma_f32_16x16x4_f32 v[98:101], v143, v97, v[98:101]
	v_pk_fma_f32 v[180:181], v[2:3], v[234:235], v[180:181] op_sel:[0,1,0]
	v_pk_fma_f32 v[192:193], v[4:5], v[234:235], v[192:193] op_sel:[0,1,0]
	v_pk_mul_f32 v[180:181], v[146:147], v[180:181]
	v_pk_mul_f32 v[192:193], v[146:147], v[192:193]
	v_pk_fma_f32 v[236:237], v[144:145], v[94:95], v[180:181]
	v_pk_fma_f32 v[238:239], v[144:145], v[96:97], v[192:193]
	global_store_dwordx4 v[150:151], v[236:239], off nt
	v_lshl_add_u64 v[150:151], v[150:151], 0, s[74:75]
	global_load_dwordx4 v[94:97], v[148:149], off nt
	v_lshl_add_u64 v[148:149], v[148:149], 0, s[74:75]
	ds_read_b32 v143, v160 offset:272
	ds_read_b128 v[172:175], v161 offset:2176
	ds_read_b128 v[232:235], v161 offset:2192
	s_waitcnt vmcnt(35)
; #define RS_LOAD(dst, it0) do { _Pragma("unroll") for (int u = 0; u < 8; ++u) dst[u] = __builtin_nontemporal_load((const f32x4*)(S0 + (size_t)(4 * ((it0) + u)) * DV)); } while (0)
; __device__ __forceinline__ void ret_sample_item(Frame& F, int item) {
;     ...
;     for (int it0 = 0; it0 < 64; it0 += 16) {
;         RS_LOAD(sb, it0 + 8);
;         RS_PROC(sa, it0);
;         { const int itn = it0 + 16 < 64 ? it0 + 16 : it0; RS_LOAD(sa, itn); }
;         RS_PROC(sb, it0 + 8);
	s_waitcnt lgkmcnt(3)
	v_cndmask_b32_e64 v141, 0, v141, s[8:9]
	v_pk_mul_f32 v[180:181], v[26:27], v[114:115] op_sel:[0,1]
	v_pk_mul_f32 v[192:193], v[28:29], v[114:115] op_sel:[0,1]
	v_mfma_f32_16x16x4_f32 v[110:113], v141, v212, v[110:113]
	v_pk_fma_f32 v[180:181], v[30:31], v[114:115], v[180:181] op_sel_hi:[1,0,1]
	v_pk_fma_f32 v[192:193], v[32:33], v[114:115], v[192:193] op_sel_hi:[1,0,1]
	v_pk_fma_f32 v[180:181], v[22:23], v[116:117], v[180:181] op_sel_hi:[1,0,1]
	v_pk_fma_f32 v[192:193], v[24:25], v[116:117], v[192:193] op_sel_hi:[1,0,1]
	v_mfma_f32_16x16x4_f32 v[106:109], v141, v213, v[106:109]
	v_pk_fma_f32 v[180:181], v[18:19], v[116:117], v[180:181] op_sel:[0,1,0]
	v_pk_fma_f32 v[192:193], v[20:21], v[116:117], v[192:193] op_sel:[0,1,0]
	v_pk_fma_f32 v[180:181], v[14:15], v[176:177], v[180:181] op_sel_hi:[1,0,1]
	v_pk_fma_f32 v[192:193], v[16:17], v[176:177], v[192:193] op_sel_hi:[1,0,1]
	v_mfma_f32_16x16x4_f32 v[102:105], v141, v214, v[102:105]
	v_pk_fma_f32 v[180:181], v[10:11], v[176:177], v[180:181] op_sel:[0,1,0]
	v_pk_fma_f32 v[192:193], v[12:13], v[176:177], v[192:193] op_sel:[0,1,0]
	v_pk_fma_f32 v[180:181], v[6:7], v[178:179], v[180:181] op_sel_hi:[1,0,1]
	v_pk_fma_f32 v[192:193], v[8:9], v[178:179], v[192:193] op_sel_hi:[1,0,1]
	v_mfma_f32_16x16x4_f32 v[98:101], v141, v215, v[98:101]
	v_pk_fma_f32 v[180:181], v[2:3], v[178:179], v[180:181] op_sel:[0,1,0]
	v_pk_fma_f32 v[192:193], v[4:5], v[178:179], v[192:193] op_sel:[0,1,0]
	v_pk_mul_f32 v[180:181], v[146:147], v[180:181]
	v_pk_mul_f32 v[192:193], v[146:147], v[192:193]
	v_pk_fma_f32 v[236:237], v[144:145], v[212:213], v[180:181]
	v_pk_fma_f32 v[238:239], v[144:145], v[214:215], v[192:193]
	global_store_dwordx4 v[150:151], v[236:239], off nt
	v_lshl_add_u64 v[150:151], v[150:151], 0, s[74:75]
	global_load_dwordx4 v[212:215], v[148:149], off nt
	v_lshl_add_u64 v[148:149], v[148:149], 0, s[74:75]
	ds_read_b32 v141, v160 offset:288
	ds_read_b128 v[114:117], v161 offset:2304
	ds_read_b128 v[176:179], v161 offset:2320
	s_waitcnt vmcnt(36)
	s_waitcnt lgkmcnt(3)
	v_cndmask_b32_e64 v143, 0, v143, s[8:9]
	v_pk_mul_f32 v[180:181], v[26:27], v[172:173] op_sel:[0,1]
	v_pk_mul_f32 v[192:193], v[28:29], v[172:173] op_sel:[0,1]
	v_mfma_f32_16x16x4_f32 v[110:113], v143, v216, v[110:113]
	v_pk_fma_f32 v[180:181], v[30:31], v[172:173], v[180:181] op_sel_hi:[1,0,1]
	v_pk_fma_f32 v[192:193], v[32:33], v[172:173], v[192:193] op_sel_hi:[1,0,1]
	v_pk_fma_f32 v[180:181], v[22:23], v[174:175], v[180:181] op_sel_hi:[1,0,1]
	v_pk_fma_f32 v[192:193], v[24:25], v[174:175], v[192:193] op_sel_hi:[1,0,1]
	v_mfma_f32_16x16x4_f32 v[106:109], v143, v217, v[106:109]
	v_pk_fma_f32 v[180:181], v[18:19], v[174:175], v[180:181] op_sel:[0,1,0]
	v_pk_fma_f32 v[192:193], v[20:21], v[174:175], v[192:193] op_sel:[0,1,0]
	v_pk_fma_f32 v[180:181], v[14:15], v[232:233], v[180:181] op_sel_hi:[1,0,1]
	v_pk_fma_f32 v[192:193], v[16:17], v[232:233], v[192:193] op_sel_hi:[1,0,1]
	v_mfma_f32_16x16x4_f32 v[102:105], v143, v218, v[102:105]
	v_pk_fma_f32 v[180:181], v[10:11], v[232:233], v[180:181] op_sel:[0,1,0]
	v_pk_fma_f32 v[192:193], v[12:13], v[232:233], v[192:193] op_sel:[0,1,0]
	v_pk_fma_f32 v[180:181], v[6:7], v[234:235], v[180:181] op_sel_hi:[1,0,1]
	v_pk_fma_f32 v[192:193], v[8:9], v[234:235], v[192:193] op_sel_hi:[1,0,1]
	v_mfma_f32_16x16x4_f32 v[98:101], v143, v219, v[98:101]
	v_pk_fma_f32 v[180:181], v[2:3], v[234:235], v[180:181] op_sel:[0,1,0]
	v_pk_fma_f32 v[192:193], v[4:5], v[234:235], v[192:193] op_sel:[0,1,0]
	v_pk_mul_f32 v[180:181], v[146:147], v[180:181]
	v_pk_mul_f32 v[192:193], v[146:147], v[192:193]
	v_pk_fma_f32 v[236:237], v[144:145], v[216:217], v[180:181]
	v_pk_fma_f32 v[238:239], v[144:145], v[218:219], v[192:193]
	global_store_dwordx4 v[150:151], v[236:239], off nt
	v_lshl_add_u64 v[150:151], v[150:151], 0, s[74:75]
	global_load_dwordx4 v[216:219], v[148:149], off nt
	v_lshl_add_u64 v[148:149], v[148:149], 0, s[74:75]
	ds_read_b32 v143, v160 offset:304
	ds_read_b128 v[172:175], v161 offset:2432
	ds_read_b128 v[232:235], v161 offset:2448
	s_waitcnt vmcnt(37)
	s_waitcnt lgkmcnt(3)
	v_cndmask_b32_e64 v141, 0, v141, s[8:9]
	v_pk_mul_f32 v[180:181], v[26:27], v[114:115] op_sel:[0,1]
	v_pk_mul_f32 v[192:193], v[28:29], v[114:115] op_sel:[0,1]
	v_mfma_f32_16x16x4_f32 v[110:113], v141, v224, v[110:113]
	v_pk_fma_f32 v[180:181], v[30:31], v[114:115], v[180:181] op_sel_hi:[1,0,1]
	v_pk_fma_f32 v[192:193], v[32:33], v[114:115], v[192:193] op_sel_hi:[1,0,1]
	v_pk_fma_f32 v[180:181], v[22:23], v[116:117], v[180:181] op_sel_hi:[1,0,1]
	v_pk_fma_f32 v[192:193], v[24:25], v[116:117], v[192:193] op_sel_hi:[1,0,1]
	v_mfma_f32_16x16x4_f32 v[106:109], v141, v225, v[106:109]
	v_pk_fma_f32 v[180:181], v[18:19], v[116:117], v[180:181] op_sel:[0,1,0]
	v_pk_fma_f32 v[192:193], v[20:21], v[116:117], v[192:193] op_sel:[0,1,0]
	v_pk_fma_f32 v[180:181], v[14:15], v[176:177], v[180:181] op_sel_hi:[1,0,1]
	v_pk_fma_f32 v[192:193], v[16:17], v[176:177], v[192:193] op_sel_hi:[1,0,1]
	v_mfma_f32_16x16x4_f32 v[102:105], v141, v226, v[102:105]
	v_pk_fma_f32 v[180:181], v[10:11], v[176:177], v[180:181] op_sel:[0,1,0]
	v_pk_fma_f32 v[192:193], v[12:13], v[176:177], v[192:193] op_sel:[0,1,0]
	v_pk_fma_f32 v[180:181], v[6:7], v[178:179], v[180:181] op_sel_hi:[1,0,1]
	v_pk_fma_f32 v[192:193], v[8:9], v[178:179], v[192:193] op_sel_hi:[1,0,1]
	v_mfma_f32_16x16x4_f32 v[98:101], v141, v227, v[98:101]
	v_pk_fma_f32 v[180:181], v[2:3], v[178:179], v[180:181] op_sel:[0,1,0]
	v_pk_fma_f32 v[192:193], v[4:5], v[178:179], v[192:193] op_sel:[0,1,0]
	v_pk_mul_f32 v[180:181], v[146:147], v[180:181]
	v_pk_mul_f32 v[192:193], v[146:147], v[192:193]
	v_pk_fma_f32 v[236:237], v[144:145], v[224:225], v[180:181]
	v_pk_fma_f32 v[238:239], v[144:145], v[226:227], v[192:193]
	global_store_dwordx4 v[150:151], v[236:239], off nt
	v_lshl_add_u64 v[150:151], v[150:151], 0, s[74:75]
	global_load_dwordx4 v[224:227], v[148:149], off nt
	v_lshl_add_u64 v[148:149], v[148:149], 0, s[74:75]
	ds_read_b32 v141, v160 offset:320
	ds_read_b128 v[114:117], v161 offset:2560
	ds_read_b128 v[176:179], v161 offset:2576
	s_waitcnt vmcnt(38)
; #define RS_LOAD(dst, it0) do { _Pragma("unroll") for (int u = 0; u < 8; ++u) dst[u] = __builtin_nontemporal_load((const f32x4*)(S0 + (size_t)(4 * ((it0) + u)) * DV)); } while (0)
; __device__ __forceinline__ void ret_sample_item(Frame& F, int item) {
;     ...
;     for (int it0 = 0; it0 < 64; it0 += 16) {
;         RS_LOAD(sb, it0 + 8);
;         RS_PROC(sa, it0);
;         { const int itn = it0 + 16 < 64 ? it0 + 16 : it0; RS_LOAD(sa, itn); }
;         RS_PROC(sb, it0 + 8);
;     }
	s_waitcnt lgkmcnt(3)
	v_cndmask_b32_e64 v143, 0, v143, s[8:9]
	v_pk_mul_f32 v[180:181], v[26:27], v[172:173] op_sel:[0,1]
	v_pk_mul_f32 v[192:193], v[28:29], v[172:173] op_sel:[0,1]
	v_mfma_f32_16x16x4_f32 v[110:113], v143, v228, v[110:113]
	v_pk_fma_f32 v[180:181], v[30:31], v[172:173], v[180:181] op_sel_hi:[1,0,1]
	v_pk_fma_f32 v[192:193], v[32:33], v[172:173], v[192:193] op_sel_hi:[1,0,1]
	v_pk_fma_f32 v[180:181], v[22:23], v[174:175], v[180:181] op_sel_hi:[1,0,1]
	v_pk_fma_f32 v[192:193], v[24:25], v[174:175], v[192:193] op_sel_hi:[1,0,1]
	v_mfma_f32_16x16x4_f32 v[106:109], v143, v229, v[106:109]
	v_pk_fma_f32 v[180:181], v[18:19], v[174:175], v[180:181] op_sel:[0,1,0]
	v_pk_fma_f32 v[192:193], v[20:21], v[174:175], v[192:193] op_sel:[0,1,0]
	v_pk_fma_f32 v[180:181], v[14:15], v[232:233], v[180:181] op_sel_hi:[1,0,1]
	v_pk_fma_f32 v[192:193], v[16:17], v[232:233], v[192:193] op_sel_hi:[1,0,1]
	v_mfma_f32_16x16x4_f32 v[102:105], v143, v230, v[102:105]
	v_pk_fma_f32 v[180:181], v[10:11], v[232:233], v[180:181] op_sel:[0,1,0]
	v_pk_fma_f32 v[192:193], v[12:13], v[232:233], v[192:193] op_sel:[0,1,0]
	v_pk_fma_f32 v[180:181], v[6:7], v[234:235], v[180:181] op_sel_hi:[1,0,1]
	v_pk_fma_f32 v[192:193], v[8:9], v[234:235], v[192:193] op_sel_hi:[1,0,1]
	v_mfma_f32_16x16x4_f32 v[98:101], v143, v231, v[98:101]
	v_pk_fma_f32 v[180:181], v[2:3], v[234:235], v[180:181] op_sel:[0,1,0]
	v_pk_fma_f32 v[192:193], v[4:5], v[234:235], v[192:193] op_sel:[0,1,0]
	v_pk_mul_f32 v[180:181], v[146:147], v[180:181]
	v_pk_mul_f32 v[192:193], v[146:147], v[192:193]
	v_pk_fma_f32 v[236:237], v[144:145], v[228:229], v[180:181]
	v_pk_fma_f32 v[238:239], v[144:145], v[230:231], v[192:193]
	global_store_dwordx4 v[150:151], v[236:239], off nt
	v_lshl_add_u64 v[150:151], v[150:151], 0, s[74:75]
	global_load_dwordx4 v[228:231], v[148:149], off nt
	v_lshl_add_u64 v[148:149], v[148:149], 0, s[74:75]
	ds_read_b32 v143, v160 offset:336
	ds_read_b128 v[172:175], v161 offset:2688
	ds_read_b128 v[232:235], v161 offset:2704
	s_waitcnt vmcnt(38)
	s_waitcnt lgkmcnt(3)
	v_cndmask_b32_e64 v141, 0, v141, s[8:9]
	v_pk_mul_f32 v[180:181], v[26:27], v[114:115] op_sel:[0,1]
	v_pk_mul_f32 v[192:193], v[28:29], v[114:115] op_sel:[0,1]
	v_mfma_f32_16x16x4_f32 v[110:113], v141, v70, v[110:113]
	v_pk_fma_f32 v[180:181], v[30:31], v[114:115], v[180:181] op_sel_hi:[1,0,1]
	v_pk_fma_f32 v[192:193], v[32:33], v[114:115], v[192:193] op_sel_hi:[1,0,1]
	v_pk_fma_f32 v[180:181], v[22:23], v[116:117], v[180:181] op_sel_hi:[1,0,1]
	v_pk_fma_f32 v[192:193], v[24:25], v[116:117], v[192:193] op_sel_hi:[1,0,1]
	v_mfma_f32_16x16x4_f32 v[106:109], v141, v71, v[106:109]
	v_pk_fma_f32 v[180:181], v[18:19], v[116:117], v[180:181] op_sel:[0,1,0]
	v_pk_fma_f32 v[192:193], v[20:21], v[116:117], v[192:193] op_sel:[0,1,0]
	v_pk_fma_f32 v[180:181], v[14:15], v[176:177], v[180:181] op_sel_hi:[1,0,1]
	v_pk_fma_f32 v[192:193], v[16:17], v[176:177], v[192:193] op_sel_hi:[1,0,1]
	v_mfma_f32_16x16x4_f32 v[102:105], v141, v72, v[102:105]
	v_pk_fma_f32 v[180:181], v[10:11], v[176:177], v[180:181] op_sel:[0,1,0]
	v_pk_fma_f32 v[192:193], v[12:13], v[176:177], v[192:193] op_sel:[0,1,0]
	v_pk_fma_f32 v[180:181], v[6:7], v[178:179], v[180:181] op_sel_hi:[1,0,1]
	v_pk_fma_f32 v[192:193], v[8:9], v[178:179], v[192:193] op_sel_hi:[1,0,1]
	v_mfma_f32_16x16x4_f32 v[98:101], v141, v73, v[98:101]
	v_pk_fma_f32 v[180:181], v[2:3], v[178:179], v[180:181] op_sel:[0,1,0]
	v_pk_fma_f32 v[192:193], v[4:5], v[178:179], v[192:193] op_sel:[0,1,0]
	v_pk_mul_f32 v[180:181], v[146:147], v[180:181]
	v_pk_mul_f32 v[192:193], v[146:147], v[192:193]
	v_pk_fma_f32 v[236:237], v[144:145], v[70:71], v[180:181]
	v_pk_fma_f32 v[238:239], v[144:145], v[72:73], v[192:193]
	global_store_dwordx4 v[150:151], v[236:239], off nt
	v_lshl_add_u64 v[150:151], v[150:151], 0, s[74:75]
	global_load_dwordx4 v[70:73], v[148:149], off nt
	v_lshl_add_u64 v[148:149], v[148:149], 0, s[74:75]
	ds_read_b32 v141, v160 offset:352
	ds_read_b128 v[114:117], v161 offset:2816
	ds_read_b128 v[176:179], v161 offset:2832
	s_waitcnt vmcnt(38)
	s_waitcnt lgkmcnt(3)
	v_cndmask_b32_e64 v143, 0, v143, s[8:9]
	v_pk_mul_f32 v[180:181], v[26:27], v[172:173] op_sel:[0,1]
	v_pk_mul_f32 v[192:193], v[28:29], v[172:173] op_sel:[0,1]
	v_mfma_f32_16x16x4_f32 v[110:113], v143, v62, v[110:113]
	v_pk_fma_f32 v[180:181], v[30:31], v[172:173], v[180:181] op_sel_hi:[1,0,1]
	v_pk_fma_f32 v[192:193], v[32:33], v[172:173], v[192:193] op_sel_hi:[1,0,1]
	v_pk_fma_f32 v[180:181], v[22:23], v[174:175], v[180:181] op_sel_hi:[1,0,1]
	v_pk_fma_f32 v[192:193], v[24:25], v[174:175], v[192:193] op_sel_hi:[1,0,1]
	v_mfma_f32_16x16x4_f32 v[106:109], v143, v63, v[106:109]
	v_pk_fma_f32 v[180:181], v[18:19], v[174:175], v[180:181] op_sel:[0,1,0]
	v_pk_fma_f32 v[192:193], v[20:21], v[174:175], v[192:193] op_sel:[0,1,0]
	v_pk_fma_f32 v[180:181], v[14:15], v[232:233], v[180:181] op_sel_hi:[1,0,1]
	v_pk_fma_f32 v[192:193], v[16:17], v[232:233], v[192:193] op_sel_hi:[1,0,1]
	v_mfma_f32_16x16x4_f32 v[102:105], v143, v64, v[102:105]
	v_pk_fma_f32 v[180:181], v[10:11], v[232:233], v[180:181] op_sel:[0,1,0]
	v_pk_fma_f32 v[192:193], v[12:13], v[232:233], v[192:193] op_sel:[0,1,0]
	v_pk_fma_f32 v[180:181], v[6:7], v[234:235], v[180:181] op_sel_hi:[1,0,1]
	v_pk_fma_f32 v[192:193], v[8:9], v[234:235], v[192:193] op_sel_hi:[1,0,1]
	v_mfma_f32_16x16x4_f32 v[98:101], v143, v65, v[98:101]
	v_pk_fma_f32 v[180:181], v[2:3], v[234:235], v[180:181] op_sel:[0,1,0]
	v_pk_fma_f32 v[192:193], v[4:5], v[234:235], v[192:193] op_sel:[0,1,0]
	v_pk_mul_f32 v[180:181], v[146:147], v[180:181]
	v_pk_mul_f32 v[192:193], v[146:147], v[192:193]
	v_pk_fma_f32 v[236:237], v[144:145], v[62:63], v[180:181]
	v_pk_fma_f32 v[238:239], v[144:145], v[64:65], v[192:193]
	global_store_dwordx4 v[150:151], v[236:239], off nt
	v_lshl_add_u64 v[150:151], v[150:151], 0, s[74:75]
	global_load_dwordx4 v[62:65], v[148:149], off nt
	v_lshl_add_u64 v[148:149], v[148:149], 0, s[74:75]
	ds_read_b32 v143, v160 offset:368
	ds_read_b128 v[172:175], v161 offset:2944
	ds_read_b128 v[232:235], v161 offset:2960
	s_waitcnt vmcnt(38)
; #define RS_LOAD(dst, it0) do { _Pragma("unroll") for (int u = 0; u < 8; ++u) dst[u] = __builtin_nontemporal_load((const f32x4*)(S0 + (size_t)(4 * ((it0) + u)) * DV)); } while (0)
; __device__ __forceinline__ void ret_sample_item(Frame& F, int item) {
;     ...
;     for (int it0 = 0; it0 < 64; it0 += 16) {
;         RS_LOAD(sb, it0 + 8);
;         RS_PROC(sa, it0);
;         { const int itn = it0 + 16 < 64 ? it0 + 16 : it0; RS_LOAD(sa, itn); }
;         RS_PROC(sb, it0 + 8);
;     }
	s_waitcnt lgkmcnt(3)
	v_cndmask_b32_e64 v141, 0, v141, s[8:9]
	v_pk_mul_f32 v[180:181], v[26:27], v[114:115] op_sel:[0,1]
	v_pk_mul_f32 v[192:193], v[28:29], v[114:115] op_sel:[0,1]
	v_mfma_f32_16x16x4_f32 v[110:113], v141, v54, v[110:113]
	v_pk_fma_f32 v[180:181], v[30:31], v[114:115], v[180:181] op_sel_hi:[1,0,1]
	v_pk_fma_f32 v[192:193], v[32:33], v[114:115], v[192:193] op_sel_hi:[1,0,1]
	v_pk_fma_f32 v[180:181], v[22:23], v[116:117], v[180:181] op_sel_hi:[1,0,1]
	v_pk_fma_f32 v[192:193], v[24:25], v[116:117], v[192:193] op_sel_hi:[1,0,1]
	v_mfma_f32_16x16x4_f32 v[106:109], v141, v55, v[106:109]
	v_pk_fma_f32 v[180:181], v[18:19], v[116:117], v[180:181] op_sel:[0,1,0]
	v_pk_fma_f32 v[192:193], v[20:21], v[116:117], v[192:193] op_sel:[0,1,0]
	v_pk_fma_f32 v[180:181], v[14:15], v[176:177], v[180:181] op_sel_hi:[1,0,1]
	v_pk_fma_f32 v[192:193], v[16:17], v[176:177], v[192:193] op_sel_hi:[1,0,1]
	v_mfma_f32_16x16x4_f32 v[102:105], v141, v56, v[102:105]
	v_pk_fma_f32 v[180:181], v[10:11], v[176:177], v[180:181] op_sel:[0,1,0]
	v_pk_fma_f32 v[192:193], v[12:13], v[176:177], v[192:193] op_sel:[0,1,0]
	v_pk_fma_f32 v[180:181], v[6:7], v[178:179], v[180:181] op_sel_hi:[1,0,1]
	v_pk_fma_f32 v[192:193], v[8:9], v[178:179], v[192:193] op_sel_hi:[1,0,1]
	v_mfma_f32_16x16x4_f32 v[98:101], v141, v57, v[98:101]
	v_pk_fma_f32 v[180:181], v[2:3], v[178:179], v[180:181] op_sel:[0,1,0]
	v_pk_fma_f32 v[192:193], v[4:5], v[178:179], v[192:193] op_sel:[0,1,0]
	v_pk_mul_f32 v[180:181], v[146:147], v[180:181]
	v_pk_mul_f32 v[192:193], v[146:147], v[192:193]
	v_pk_fma_f32 v[236:237], v[144:145], v[54:55], v[180:181]
	v_pk_fma_f32 v[238:239], v[144:145], v[56:57], v[192:193]
	global_store_dwordx4 v[150:151], v[236:239], off nt
	v_lshl_add_u64 v[150:151], v[150:151], 0, s[74:75]
	global_load_dwordx4 v[54:57], v[148:149], off nt
	v_lshl_add_u64 v[148:149], v[148:149], 0, s[74:75]
	ds_read_b32 v141, v160 offset:384
	ds_read_b128 v[114:117], v161 offset:3072
	ds_read_b128 v[176:179], v161 offset:3088
	s_waitcnt vmcnt(38)
	s_waitcnt lgkmcnt(3)
	v_cndmask_b32_e64 v143, 0, v143, s[8:9]
	v_pk_mul_f32 v[180:181], v[26:27], v[172:173] op_sel:[0,1]
	v_pk_mul_f32 v[192:193], v[28:29], v[172:173] op_sel:[0,1]
	v_mfma_f32_16x16x4_f32 v[110:113], v143, v50, v[110:113]
	v_pk_fma_f32 v[180:181], v[30:31], v[172:173], v[180:181] op_sel_hi:[1,0,1]
	v_pk_fma_f32 v[192:193], v[32:33], v[172:173], v[192:193] op_sel_hi:[1,0,1]
	v_pk_fma_f32 v[180:181], v[22:23], v[174:175], v[180:181] op_sel_hi:[1,0,1]
	v_pk_fma_f32 v[192:193], v[24:25], v[174:175], v[192:193] op_sel_hi:[1,0,1]
	v_mfma_f32_16x16x4_f32 v[106:109], v143, v51, v[106:109]
	v_pk_fma_f32 v[180:181], v[18:19], v[174:175], v[180:181] op_sel:[0,1,0]
	v_pk_fma_f32 v[192:193], v[20:21], v[174:175], v[192:193] op_sel:[0,1,0]
	v_pk_fma_f32 v[180:181], v[14:15], v[232:233], v[180:181] op_sel_hi:[1,0,1]
	v_pk_fma_f32 v[192:193], v[16:17], v[232:233], v[192:193] op_sel_hi:[1,0,1]
	v_mfma_f32_16x16x4_f32 v[102:105], v143, v52, v[102:105]
	v_pk_fma_f32 v[180:181], v[10:11], v[232:233], v[180:181] op_sel:[0,1,0]
	v_pk_fma_f32 v[192:193], v[12:13], v[232:233], v[192:193] op_sel:[0,1,0]
	v_pk_fma_f32 v[180:181], v[6:7], v[234:235], v[180:181] op_sel_hi:[1,0,1]
	v_pk_fma_f32 v[192:193], v[8:9], v[234:235], v[192:193] op_sel_hi:[1,0,1]
	v_mfma_f32_16x16x4_f32 v[98:101], v143, v53, v[98:101]
	v_pk_fma_f32 v[180:181], v[2:3], v[234:235], v[180:181] op_sel:[0,1,0]
	v_pk_fma_f32 v[192:193], v[4:5], v[234:235], v[192:193] op_sel:[0,1,0]
	v_pk_mul_f32 v[180:181], v[146:147], v[180:181]
	v_pk_mul_f32 v[192:193], v[146:147], v[192:193]
	v_pk_fma_f32 v[236:237], v[144:145], v[50:51], v[180:181]
	v_pk_fma_f32 v[238:239], v[144:145], v[52:53], v[192:193]
	global_store_dwordx4 v[150:151], v[236:239], off nt
	v_lshl_add_u64 v[150:151], v[150:151], 0, s[74:75]
	global_load_dwordx4 v[50:53], v[148:149], off nt
	v_lshl_add_u64 v[148:149], v[148:149], 0, s[74:75]
	ds_read_b32 v143, v160 offset:400
	ds_read_b128 v[172:175], v161 offset:3200
	ds_read_b128 v[232:235], v161 offset:3216
	s_waitcnt vmcnt(38)
	s_waitcnt lgkmcnt(3)
	v_cndmask_b32_e64 v141, 0, v141, s[8:9]
	v_pk_mul_f32 v[180:181], v[26:27], v[114:115] op_sel:[0,1]
	v_pk_mul_f32 v[192:193], v[28:29], v[114:115] op_sel:[0,1]
	v_mfma_f32_16x16x4_f32 v[110:113], v141, v46, v[110:113]
	v_pk_fma_f32 v[180:181], v[30:31], v[114:115], v[180:181] op_sel_hi:[1,0,1]
	v_pk_fma_f32 v[192:193], v[32:33], v[114:115], v[192:193] op_sel_hi:[1,0,1]
	v_pk_fma_f32 v[180:181], v[22:23], v[116:117], v[180:181] op_sel_hi:[1,0,1]
	v_pk_fma_f32 v[192:193], v[24:25], v[116:117], v[192:193] op_sel_hi:[1,0,1]
	v_mfma_f32_16x16x4_f32 v[106:109], v141, v47, v[106:109]
	v_pk_fma_f32 v[180:181], v[18:19], v[116:117], v[180:181] op_sel:[0,1,0]
	v_pk_fma_f32 v[192:193], v[20:21], v[116:117], v[192:193] op_sel:[0,1,0]
	v_pk_fma_f32 v[180:181], v[14:15], v[176:177], v[180:181] op_sel_hi:[1,0,1]
	v_pk_fma_f32 v[192:193], v[16:17], v[176:177], v[192:193] op_sel_hi:[1,0,1]
	v_mfma_f32_16x16x4_f32 v[102:105], v141, v48, v[102:105]
	v_pk_fma_f32 v[180:181], v[10:11], v[176:177], v[180:181] op_sel:[0,1,0]
	v_pk_fma_f32 v[192:193], v[12:13], v[176:177], v[192:193] op_sel:[0,1,0]
	v_pk_fma_f32 v[180:181], v[6:7], v[178:179], v[180:181] op_sel_hi:[1,0,1]
	v_pk_fma_f32 v[192:193], v[8:9], v[178:179], v[192:193] op_sel_hi:[1,0,1]
	v_mfma_f32_16x16x4_f32 v[98:101], v141, v49, v[98:101]
	v_pk_fma_f32 v[180:181], v[2:3], v[178:179], v[180:181] op_sel:[0,1,0]
	v_pk_fma_f32 v[192:193], v[4:5], v[178:179], v[192:193] op_sel:[0,1,0]
	v_pk_mul_f32 v[180:181], v[146:147], v[180:181]
	v_pk_mul_f32 v[192:193], v[146:147], v[192:193]
	v_pk_fma_f32 v[236:237], v[144:145], v[46:47], v[180:181]
	v_pk_fma_f32 v[238:239], v[144:145], v[48:49], v[192:193]
	global_store_dwordx4 v[150:151], v[236:239], off nt
	v_lshl_add_u64 v[150:151], v[150:151], 0, s[74:75]
	global_load_dwordx4 v[46:49], v[148:149], off nt
	v_lshl_add_u64 v[148:149], v[148:149], 0, s[74:75]
	ds_read_b32 v141, v160 offset:416
	ds_read_b128 v[114:117], v161 offset:3328
	ds_read_b128 v[176:179], v161 offset:3344
	s_waitcnt vmcnt(38)
; #define RS_LOAD(dst, it0) do { _Pragma("unroll") for (int u = 0; u < 8; ++u) dst[u] = __builtin_nontemporal_load((const f32x4*)(S0 + (size_t)(4 * ((it0) + u)) * DV)); } while (0)
; __device__ __forceinline__ void ret_sample_item(Frame& F, int item) {
;     ...
;     for (int it0 = 0; it0 < 64; it0 += 16) {
;         RS_LOAD(sb, it0 + 8);
;         RS_PROC(sa, it0);
;         { const int itn = it0 + 16 < 64 ? it0 + 16 : it0; RS_LOAD(sa, itn); }
;         RS_PROC(sb, it0 + 8);
;     }
	s_waitcnt lgkmcnt(3)
	v_cndmask_b32_e64 v143, 0, v143, s[8:9]
	v_pk_mul_f32 v[180:181], v[26:27], v[172:173] op_sel:[0,1]
	v_pk_mul_f32 v[192:193], v[28:29], v[172:173] op_sel:[0,1]
	v_mfma_f32_16x16x4_f32 v[110:113], v143, v42, v[110:113]
	v_pk_fma_f32 v[180:181], v[30:31], v[172:173], v[180:181] op_sel_hi:[1,0,1]
	v_pk_fma_f32 v[192:193], v[32:33], v[172:173], v[192:193] op_sel_hi:[1,0,1]
	v_pk_fma_f32 v[180:181], v[22:23], v[174:175], v[180:181] op_sel_hi:[1,0,1]
	v_pk_fma_f32 v[192:193], v[24:25], v[174:175], v[192:193] op_sel_hi:[1,0,1]
	v_mfma_f32_16x16x4_f32 v[106:109], v143, v43, v[106:109]
	v_pk_fma_f32 v[180:181], v[18:19], v[174:175], v[180:181] op_sel:[0,1,0]
	v_pk_fma_f32 v[192:193], v[20:21], v[174:175], v[192:193] op_sel:[0,1,0]
	v_pk_fma_f32 v[180:181], v[14:15], v[232:233], v[180:181] op_sel_hi:[1,0,1]
	v_pk_fma_f32 v[192:193], v[16:17], v[232:233], v[192:193] op_sel_hi:[1,0,1]
	v_mfma_f32_16x16x4_f32 v[102:105], v143, v44, v[102:105]
	v_pk_fma_f32 v[180:181], v[10:11], v[232:233], v[180:181] op_sel:[0,1,0]
	v_pk_fma_f32 v[192:193], v[12:13], v[232:233], v[192:193] op_sel:[0,1,0]
	v_pk_fma_f32 v[180:181], v[6:7], v[234:235], v[180:181] op_sel_hi:[1,0,1]
	v_pk_fma_f32 v[192:193], v[8:9], v[234:235], v[192:193] op_sel_hi:[1,0,1]
	v_mfma_f32_16x16x4_f32 v[98:101], v143, v45, v[98:101]
	v_pk_fma_f32 v[180:181], v[2:3], v[234:235], v[180:181] op_sel:[0,1,0]
	v_pk_fma_f32 v[192:193], v[4:5], v[234:235], v[192:193] op_sel:[0,1,0]
	v_pk_mul_f32 v[180:181], v[146:147], v[180:181]
	v_pk_mul_f32 v[192:193], v[146:147], v[192:193]
	v_pk_fma_f32 v[236:237], v[144:145], v[42:43], v[180:181]
	v_pk_fma_f32 v[238:239], v[144:145], v[44:45], v[192:193]
	global_store_dwordx4 v[150:151], v[236:239], off nt
	v_lshl_add_u64 v[150:151], v[150:151], 0, s[74:75]
	global_load_dwordx4 v[42:45], v[148:149], off nt
	v_lshl_add_u64 v[148:149], v[148:149], 0, s[74:75]
	ds_read_b32 v143, v160 offset:432
	ds_read_b128 v[172:175], v161 offset:3456
	ds_read_b128 v[232:235], v161 offset:3472
	s_waitcnt vmcnt(38)
	s_waitcnt lgkmcnt(3)
	v_cndmask_b32_e64 v141, 0, v141, s[8:9]
	v_pk_mul_f32 v[180:181], v[26:27], v[114:115] op_sel:[0,1]
	v_pk_mul_f32 v[192:193], v[28:29], v[114:115] op_sel:[0,1]
	v_mfma_f32_16x16x4_f32 v[110:113], v141, v38, v[110:113]
	v_pk_fma_f32 v[180:181], v[30:31], v[114:115], v[180:181] op_sel_hi:[1,0,1]
	v_pk_fma_f32 v[192:193], v[32:33], v[114:115], v[192:193] op_sel_hi:[1,0,1]
	v_pk_fma_f32 v[180:181], v[22:23], v[116:117], v[180:181] op_sel_hi:[1,0,1]
	v_pk_fma_f32 v[192:193], v[24:25], v[116:117], v[192:193] op_sel_hi:[1,0,1]
	v_mfma_f32_16x16x4_f32 v[106:109], v141, v39, v[106:109]
	v_pk_fma_f32 v[180:181], v[18:19], v[116:117], v[180:181] op_sel:[0,1,0]
	v_pk_fma_f32 v[192:193], v[20:21], v[116:117], v[192:193] op_sel:[0,1,0]
	v_pk_fma_f32 v[180:181], v[14:15], v[176:177], v[180:181] op_sel_hi:[1,0,1]
	v_pk_fma_f32 v[192:193], v[16:17], v[176:177], v[192:193] op_sel_hi:[1,0,1]
	v_mfma_f32_16x16x4_f32 v[102:105], v141, v40, v[102:105]
	v_pk_fma_f32 v[180:181], v[10:11], v[176:177], v[180:181] op_sel:[0,1,0]
	v_pk_fma_f32 v[192:193], v[12:13], v[176:177], v[192:193] op_sel:[0,1,0]
	v_pk_fma_f32 v[180:181], v[6:7], v[178:179], v[180:181] op_sel_hi:[1,0,1]
	v_pk_fma_f32 v[192:193], v[8:9], v[178:179], v[192:193] op_sel_hi:[1,0,1]
	v_mfma_f32_16x16x4_f32 v[98:101], v141, v41, v[98:101]
	v_pk_fma_f32 v[180:181], v[2:3], v[178:179], v[180:181] op_sel:[0,1,0]
	v_pk_fma_f32 v[192:193], v[4:5], v[178:179], v[192:193] op_sel:[0,1,0]
	v_pk_mul_f32 v[180:181], v[146:147], v[180:181]
	v_pk_mul_f32 v[192:193], v[146:147], v[192:193]
	v_pk_fma_f32 v[236:237], v[144:145], v[38:39], v[180:181]
	v_pk_fma_f32 v[238:239], v[144:145], v[40:41], v[192:193]
	global_store_dwordx4 v[150:151], v[236:239], off nt
	v_lshl_add_u64 v[150:151], v[150:151], 0, s[74:75]
	global_load_dwordx4 v[38:41], v[148:149], off nt
	v_lshl_add_u64 v[148:149], v[148:149], 0, s[74:75]
	ds_read_b32 v141, v160 offset:448
	ds_read_b128 v[114:117], v161 offset:3584
	ds_read_b128 v[176:179], v161 offset:3600
	s_waitcnt vmcnt(38)
	s_waitcnt lgkmcnt(3)
	v_cndmask_b32_e64 v143, 0, v143, s[8:9]
	v_pk_mul_f32 v[180:181], v[26:27], v[172:173] op_sel:[0,1]
	v_pk_mul_f32 v[192:193], v[28:29], v[172:173] op_sel:[0,1]
	v_mfma_f32_16x16x4_f32 v[110:113], v143, v34, v[110:113]
	v_pk_fma_f32 v[180:181], v[30:31], v[172:173], v[180:181] op_sel_hi:[1,0,1]
	v_pk_fma_f32 v[192:193], v[32:33], v[172:173], v[192:193] op_sel_hi:[1,0,1]
	v_pk_fma_f32 v[180:181], v[22:23], v[174:175], v[180:181] op_sel_hi:[1,0,1]
	v_pk_fma_f32 v[192:193], v[24:25], v[174:175], v[192:193] op_sel_hi:[1,0,1]
	v_mfma_f32_16x16x4_f32 v[106:109], v143, v35, v[106:109]
	v_pk_fma_f32 v[180:181], v[18:19], v[174:175], v[180:181] op_sel:[0,1,0]
	v_pk_fma_f32 v[192:193], v[20:21], v[174:175], v[192:193] op_sel:[0,1,0]
	v_pk_fma_f32 v[180:181], v[14:15], v[232:233], v[180:181] op_sel_hi:[1,0,1]
	v_pk_fma_f32 v[192:193], v[16:17], v[232:233], v[192:193] op_sel_hi:[1,0,1]
	v_mfma_f32_16x16x4_f32 v[102:105], v143, v36, v[102:105]
	v_pk_fma_f32 v[180:181], v[10:11], v[232:233], v[180:181] op_sel:[0,1,0]
	v_pk_fma_f32 v[192:193], v[12:13], v[232:233], v[192:193] op_sel:[0,1,0]
	v_pk_fma_f32 v[180:181], v[6:7], v[234:235], v[180:181] op_sel_hi:[1,0,1]
	v_pk_fma_f32 v[192:193], v[8:9], v[234:235], v[192:193] op_sel_hi:[1,0,1]
	v_mfma_f32_16x16x4_f32 v[98:101], v143, v37, v[98:101]
	v_pk_fma_f32 v[180:181], v[2:3], v[234:235], v[180:181] op_sel:[0,1,0]
	v_pk_fma_f32 v[192:193], v[4:5], v[234:235], v[192:193] op_sel:[0,1,0]
	v_pk_mul_f32 v[180:181], v[146:147], v[180:181]
	v_pk_mul_f32 v[192:193], v[146:147], v[192:193]
	v_pk_fma_f32 v[236:237], v[144:145], v[34:35], v[180:181]
	v_pk_fma_f32 v[238:239], v[144:145], v[36:37], v[192:193]
	global_store_dwordx4 v[150:151], v[236:239], off nt
	v_lshl_add_u64 v[150:151], v[150:151], 0, s[74:75]
	global_load_dwordx4 v[34:37], v[148:149], off nt
	v_lshl_add_u64 v[148:149], v[148:149], 0, s[74:75]
	ds_read_b32 v143, v160 offset:464
	ds_read_b128 v[172:175], v161 offset:3712
	ds_read_b128 v[232:235], v161 offset:3728
	s_waitcnt vmcnt(38)
; #define RS_LOAD(dst, it0) do { _Pragma("unroll") for (int u = 0; u < 8; ++u) dst[u] = __builtin_nontemporal_load((const f32x4*)(S0 + (size_t)(4 * ((it0) + u)) * DV)); } while (0)
; __device__ __forceinline__ void ret_sample_item(Frame& F, int item) {
;     ...
;     for (int it0 = 0; it0 < 64; it0 += 16) {
;         RS_LOAD(sb, it0 + 8);
;         RS_PROC(sa, it0);
;         { const int itn = it0 + 16 < 64 ? it0 + 16 : it0; RS_LOAD(sa, itn); }
;         RS_PROC(sb, it0 + 8);
;     }
	s_waitcnt lgkmcnt(3)
	v_cndmask_b32_e64 v141, 0, v141, s[8:9]
	v_pk_mul_f32 v[180:181], v[26:27], v[114:115] op_sel:[0,1]
	v_pk_mul_f32 v[192:193], v[28:29], v[114:115] op_sel:[0,1]
	v_mfma_f32_16x16x4_f32 v[110:113], v141, v58, v[110:113]
	v_pk_fma_f32 v[180:181], v[30:31], v[114:115], v[180:181] op_sel_hi:[1,0,1]
	v_pk_fma_f32 v[192:193], v[32:33], v[114:115], v[192:193] op_sel_hi:[1,0,1]
	v_pk_fma_f32 v[180:181], v[22:23], v[116:117], v[180:181] op_sel_hi:[1,0,1]
	v_pk_fma_f32 v[192:193], v[24:25], v[116:117], v[192:193] op_sel_hi:[1,0,1]
	v_mfma_f32_16x16x4_f32 v[106:109], v141, v59, v[106:109]
	v_pk_fma_f32 v[180:181], v[18:19], v[116:117], v[180:181] op_sel:[0,1,0]
	v_pk_fma_f32 v[192:193], v[20:21], v[116:117], v[192:193] op_sel:[0,1,0]
	v_pk_fma_f32 v[180:181], v[14:15], v[176:177], v[180:181] op_sel_hi:[1,0,1]
	v_pk_fma_f32 v[192:193], v[16:17], v[176:177], v[192:193] op_sel_hi:[1,0,1]
	v_mfma_f32_16x16x4_f32 v[102:105], v141, v60, v[102:105]
	v_pk_fma_f32 v[180:181], v[10:11], v[176:177], v[180:181] op_sel:[0,1,0]
	v_pk_fma_f32 v[192:193], v[12:13], v[176:177], v[192:193] op_sel:[0,1,0]
	v_pk_fma_f32 v[180:181], v[6:7], v[178:179], v[180:181] op_sel_hi:[1,0,1]
	v_pk_fma_f32 v[192:193], v[8:9], v[178:179], v[192:193] op_sel_hi:[1,0,1]
	v_mfma_f32_16x16x4_f32 v[98:101], v141, v61, v[98:101]
	v_pk_fma_f32 v[180:181], v[2:3], v[178:179], v[180:181] op_sel:[0,1,0]
	v_pk_fma_f32 v[192:193], v[4:5], v[178:179], v[192:193] op_sel:[0,1,0]
	v_pk_mul_f32 v[180:181], v[146:147], v[180:181]
	v_pk_mul_f32 v[192:193], v[146:147], v[192:193]
	v_pk_fma_f32 v[236:237], v[144:145], v[58:59], v[180:181]
	v_pk_fma_f32 v[238:239], v[144:145], v[60:61], v[192:193]
	global_store_dwordx4 v[150:151], v[236:239], off nt
	v_lshl_add_u64 v[150:151], v[150:151], 0, s[74:75]
	global_load_dwordx4 v[58:61], v[148:149], off nt
	v_lshl_add_u64 v[148:149], v[148:149], 0, s[74:75]
	ds_read_b32 v141, v160 offset:480
	ds_read_b128 v[114:117], v161 offset:3840
	ds_read_b128 v[176:179], v161 offset:3856
	s_waitcnt vmcnt(38)
	s_waitcnt lgkmcnt(3)
	v_cndmask_b32_e64 v143, 0, v143, s[8:9]
	v_pk_mul_f32 v[180:181], v[26:27], v[172:173] op_sel:[0,1]
	v_pk_mul_f32 v[192:193], v[28:29], v[172:173] op_sel:[0,1]
	v_mfma_f32_16x16x4_f32 v[110:113], v143, v66, v[110:113]
	v_pk_fma_f32 v[180:181], v[30:31], v[172:173], v[180:181] op_sel_hi:[1,0,1]
	v_pk_fma_f32 v[192:193], v[32:33], v[172:173], v[192:193] op_sel_hi:[1,0,1]
	v_pk_fma_f32 v[180:181], v[22:23], v[174:175], v[180:181] op_sel_hi:[1,0,1]
	v_pk_fma_f32 v[192:193], v[24:25], v[174:175], v[192:193] op_sel_hi:[1,0,1]
	v_mfma_f32_16x16x4_f32 v[106:109], v143, v67, v[106:109]
	v_pk_fma_f32 v[180:181], v[18:19], v[174:175], v[180:181] op_sel:[0,1,0]
	v_pk_fma_f32 v[192:193], v[20:21], v[174:175], v[192:193] op_sel:[0,1,0]
	v_pk_fma_f32 v[180:181], v[14:15], v[232:233], v[180:181] op_sel_hi:[1,0,1]
	v_pk_fma_f32 v[192:193], v[16:17], v[232:233], v[192:193] op_sel_hi:[1,0,1]
	v_mfma_f32_16x16x4_f32 v[102:105], v143, v68, v[102:105]
	v_pk_fma_f32 v[180:181], v[10:11], v[232:233], v[180:181] op_sel:[0,1,0]
	v_pk_fma_f32 v[192:193], v[12:13], v[232:233], v[192:193] op_sel:[0,1,0]
	v_pk_fma_f32 v[180:181], v[6:7], v[234:235], v[180:181] op_sel_hi:[1,0,1]
	v_pk_fma_f32 v[192:193], v[8:9], v[234:235], v[192:193] op_sel_hi:[1,0,1]
	v_mfma_f32_16x16x4_f32 v[98:101], v143, v69, v[98:101]
	v_pk_fma_f32 v[180:181], v[2:3], v[234:235], v[180:181] op_sel:[0,1,0]
	v_pk_fma_f32 v[192:193], v[4:5], v[234:235], v[192:193] op_sel:[0,1,0]
	v_pk_mul_f32 v[180:181], v[146:147], v[180:181]
	v_pk_mul_f32 v[192:193], v[146:147], v[192:193]
	v_pk_fma_f32 v[236:237], v[144:145], v[66:67], v[180:181]
	v_pk_fma_f32 v[238:239], v[144:145], v[68:69], v[192:193]
	global_store_dwordx4 v[150:151], v[236:239], off nt
	v_lshl_add_u64 v[150:151], v[150:151], 0, s[74:75]
	global_load_dwordx4 v[66:69], v[148:149], off nt
	v_lshl_add_u64 v[148:149], v[148:149], 0, s[74:75]
	ds_read_b32 v143, v160 offset:496
	ds_read_b128 v[172:175], v161 offset:3968
	ds_read_b128 v[232:235], v161 offset:3984
	s_waitcnt vmcnt(38)
	s_waitcnt lgkmcnt(3)
	v_cndmask_b32_e64 v141, 0, v141, s[8:9]
	v_pk_mul_f32 v[180:181], v[26:27], v[114:115] op_sel:[0,1]
	v_pk_mul_f32 v[192:193], v[28:29], v[114:115] op_sel:[0,1]
	v_mfma_f32_16x16x4_f32 v[110:113], v141, v74, v[110:113]
	v_pk_fma_f32 v[180:181], v[30:31], v[114:115], v[180:181] op_sel_hi:[1,0,1]
	v_pk_fma_f32 v[192:193], v[32:33], v[114:115], v[192:193] op_sel_hi:[1,0,1]
	v_pk_fma_f32 v[180:181], v[22:23], v[116:117], v[180:181] op_sel_hi:[1,0,1]
	v_pk_fma_f32 v[192:193], v[24:25], v[116:117], v[192:193] op_sel_hi:[1,0,1]
	v_mfma_f32_16x16x4_f32 v[106:109], v141, v75, v[106:109]
	v_pk_fma_f32 v[180:181], v[18:19], v[116:117], v[180:181] op_sel:[0,1,0]
	v_pk_fma_f32 v[192:193], v[20:21], v[116:117], v[192:193] op_sel:[0,1,0]
	v_pk_fma_f32 v[180:181], v[14:15], v[176:177], v[180:181] op_sel_hi:[1,0,1]
	v_pk_fma_f32 v[192:193], v[16:17], v[176:177], v[192:193] op_sel_hi:[1,0,1]
	v_mfma_f32_16x16x4_f32 v[102:105], v141, v76, v[102:105]
	v_pk_fma_f32 v[180:181], v[10:11], v[176:177], v[180:181] op_sel:[0,1,0]
	v_pk_fma_f32 v[192:193], v[12:13], v[176:177], v[192:193] op_sel:[0,1,0]
	v_pk_fma_f32 v[180:181], v[6:7], v[178:179], v[180:181] op_sel_hi:[1,0,1]
	v_pk_fma_f32 v[192:193], v[8:9], v[178:179], v[192:193] op_sel_hi:[1,0,1]
	v_mfma_f32_16x16x4_f32 v[98:101], v141, v77, v[98:101]
	v_pk_fma_f32 v[180:181], v[2:3], v[178:179], v[180:181] op_sel:[0,1,0]
	v_pk_fma_f32 v[192:193], v[4:5], v[178:179], v[192:193] op_sel:[0,1,0]
	v_pk_mul_f32 v[180:181], v[146:147], v[180:181]
	v_pk_mul_f32 v[192:193], v[146:147], v[192:193]
	v_pk_fma_f32 v[236:237], v[144:145], v[74:75], v[180:181]
	v_pk_fma_f32 v[238:239], v[144:145], v[76:77], v[192:193]
	global_store_dwordx4 v[150:151], v[236:239], off nt
	v_lshl_add_u64 v[150:151], v[150:151], 0, s[74:75]
	global_load_dwordx4 v[74:77], v[148:149], off nt
	v_lshl_add_u64 v[148:149], v[148:149], 0, s[74:75]
	ds_read_b32 v141, v160 offset:512
	ds_read_b128 v[114:117], v161 offset:4096
	ds_read_b128 v[176:179], v161 offset:4112
	s_waitcnt vmcnt(38)
; #define RS_LOAD(dst, it0) do { _Pragma("unroll") for (int u = 0; u < 8; ++u) dst[u] = __builtin_nontemporal_load((const f32x4*)(S0 + (size_t)(4 * ((it0) + u)) * DV)); } while (0)
; __device__ __forceinline__ void ret_sample_item(Frame& F, int item) {
;     ...
;     for (int it0 = 0; it0 < 64; it0 += 16) {
;         RS_LOAD(sb, it0 + 8);
;         RS_PROC(sa, it0);
;         { const int itn = it0 + 16 < 64 ? it0 + 16 : it0; RS_LOAD(sa, itn); }
;         RS_PROC(sb, it0 + 8);
;     }
	s_waitcnt lgkmcnt(3)
	v_cndmask_b32_e64 v143, 0, v143, s[8:9]
	v_pk_mul_f32 v[180:181], v[26:27], v[172:173] op_sel:[0,1]
	v_pk_mul_f32 v[192:193], v[28:29], v[172:173] op_sel:[0,1]
	v_mfma_f32_16x16x4_f32 v[110:113], v143, v78, v[110:113]
	v_pk_fma_f32 v[180:181], v[30:31], v[172:173], v[180:181] op_sel_hi:[1,0,1]
	v_pk_fma_f32 v[192:193], v[32:33], v[172:173], v[192:193] op_sel_hi:[1,0,1]
	v_pk_fma_f32 v[180:181], v[22:23], v[174:175], v[180:181] op_sel_hi:[1,0,1]
	v_pk_fma_f32 v[192:193], v[24:25], v[174:175], v[192:193] op_sel_hi:[1,0,1]
	v_mfma_f32_16x16x4_f32 v[106:109], v143, v79, v[106:109]
	v_pk_fma_f32 v[180:181], v[18:19], v[174:175], v[180:181] op_sel:[0,1,0]
	v_pk_fma_f32 v[192:193], v[20:21], v[174:175], v[192:193] op_sel:[0,1,0]
	v_pk_fma_f32 v[180:181], v[14:15], v[232:233], v[180:181] op_sel_hi:[1,0,1]
	v_pk_fma_f32 v[192:193], v[16:17], v[232:233], v[192:193] op_sel_hi:[1,0,1]
	v_mfma_f32_16x16x4_f32 v[102:105], v143, v80, v[102:105]
	v_pk_fma_f32 v[180:181], v[10:11], v[232:233], v[180:181] op_sel:[0,1,0]
	v_pk_fma_f32 v[192:193], v[12:13], v[232:233], v[192:193] op_sel:[0,1,0]
	v_pk_fma_f32 v[180:181], v[6:7], v[234:235], v[180:181] op_sel_hi:[1,0,1]
	v_pk_fma_f32 v[192:193], v[8:9], v[234:235], v[192:193] op_sel_hi:[1,0,1]
	v_mfma_f32_16x16x4_f32 v[98:101], v143, v81, v[98:101]
	v_pk_fma_f32 v[180:181], v[2:3], v[234:235], v[180:181] op_sel:[0,1,0]
	v_pk_fma_f32 v[192:193], v[4:5], v[234:235], v[192:193] op_sel:[0,1,0]
	v_pk_mul_f32 v[180:181], v[146:147], v[180:181]
	v_pk_mul_f32 v[192:193], v[146:147], v[192:193]
	v_pk_fma_f32 v[236:237], v[144:145], v[78:79], v[180:181]
	v_pk_fma_f32 v[238:239], v[144:145], v[80:81], v[192:193]
	global_store_dwordx4 v[150:151], v[236:239], off nt
	v_lshl_add_u64 v[150:151], v[150:151], 0, s[74:75]
	global_load_dwordx4 v[78:81], v[148:149], off nt
	v_lshl_add_u64 v[148:149], v[148:149], 0, s[74:75]
	ds_read_b32 v143, v160 offset:528
	ds_read_b128 v[172:175], v161 offset:4224
	ds_read_b128 v[232:235], v161 offset:4240
	s_waitcnt vmcnt(38)
	s_waitcnt lgkmcnt(3)
	v_cndmask_b32_e64 v141, 0, v141, s[8:9]
	v_pk_mul_f32 v[180:181], v[26:27], v[114:115] op_sel:[0,1]
	v_pk_mul_f32 v[192:193], v[28:29], v[114:115] op_sel:[0,1]
	v_mfma_f32_16x16x4_f32 v[110:113], v141, v82, v[110:113]
	v_pk_fma_f32 v[180:181], v[30:31], v[114:115], v[180:181] op_sel_hi:[1,0,1]
	v_pk_fma_f32 v[192:193], v[32:33], v[114:115], v[192:193] op_sel_hi:[1,0,1]
	v_pk_fma_f32 v[180:181], v[22:23], v[116:117], v[180:181] op_sel_hi:[1,0,1]
	v_pk_fma_f32 v[192:193], v[24:25], v[116:117], v[192:193] op_sel_hi:[1,0,1]
	v_mfma_f32_16x16x4_f32 v[106:109], v141, v83, v[106:109]
	v_pk_fma_f32 v[180:181], v[18:19], v[116:117], v[180:181] op_sel:[0,1,0]
	v_pk_fma_f32 v[192:193], v[20:21], v[116:117], v[192:193] op_sel:[0,1,0]
	v_pk_fma_f32 v[180:181], v[14:15], v[176:177], v[180:181] op_sel_hi:[1,0,1]
	v_pk_fma_f32 v[192:193], v[16:17], v[176:177], v[192:193] op_sel_hi:[1,0,1]
	v_mfma_f32_16x16x4_f32 v[102:105], v141, v84, v[102:105]
	v_pk_fma_f32 v[180:181], v[10:11], v[176:177], v[180:181] op_sel:[0,1,0]
	v_pk_fma_f32 v[192:193], v[12:13], v[176:177], v[192:193] op_sel:[0,1,0]
	v_pk_fma_f32 v[180:181], v[6:7], v[178:179], v[180:181] op_sel_hi:[1,0,1]
	v_pk_fma_f32 v[192:193], v[8:9], v[178:179], v[192:193] op_sel_hi:[1,0,1]
	v_mfma_f32_16x16x4_f32 v[98:101], v141, v85, v[98:101]
	v_pk_fma_f32 v[180:181], v[2:3], v[178:179], v[180:181] op_sel:[0,1,0]
	v_pk_fma_f32 v[192:193], v[4:5], v[178:179], v[192:193] op_sel:[0,1,0]
	v_pk_mul_f32 v[180:181], v[146:147], v[180:181]
	v_pk_mul_f32 v[192:193], v[146:147], v[192:193]
	v_pk_fma_f32 v[236:237], v[144:145], v[82:83], v[180:181]
	v_pk_fma_f32 v[238:239], v[144:145], v[84:85], v[192:193]
	global_store_dwordx4 v[150:151], v[236:239], off nt
	v_lshl_add_u64 v[150:151], v[150:151], 0, s[74:75]
	global_load_dwordx4 v[82:85], v[148:149], off nt
	v_lshl_add_u64 v[148:149], v[148:149], 0, s[74:75]
	ds_read_b32 v141, v160 offset:544
	ds_read_b128 v[114:117], v161 offset:4352
	ds_read_b128 v[176:179], v161 offset:4368
	s_waitcnt vmcnt(38)
	s_waitcnt lgkmcnt(3)
	v_cndmask_b32_e64 v143, 0, v143, s[8:9]
	v_pk_mul_f32 v[180:181], v[26:27], v[172:173] op_sel:[0,1]
	v_pk_mul_f32 v[192:193], v[28:29], v[172:173] op_sel:[0,1]
	v_mfma_f32_16x16x4_f32 v[110:113], v143, v86, v[110:113]
	v_pk_fma_f32 v[180:181], v[30:31], v[172:173], v[180:181] op_sel_hi:[1,0,1]
	v_pk_fma_f32 v[192:193], v[32:33], v[172:173], v[192:193] op_sel_hi:[1,0,1]
	v_pk_fma_f32 v[180:181], v[22:23], v[174:175], v[180:181] op_sel_hi:[1,0,1]
	v_pk_fma_f32 v[192:193], v[24:25], v[174:175], v[192:193] op_sel_hi:[1,0,1]
	v_mfma_f32_16x16x4_f32 v[106:109], v143, v87, v[106:109]
	v_pk_fma_f32 v[180:181], v[18:19], v[174:175], v[180:181] op_sel:[0,1,0]
	v_pk_fma_f32 v[192:193], v[20:21], v[174:175], v[192:193] op_sel:[0,1,0]
	v_pk_fma_f32 v[180:181], v[14:15], v[232:233], v[180:181] op_sel_hi:[1,0,1]
	v_pk_fma_f32 v[192:193], v[16:17], v[232:233], v[192:193] op_sel_hi:[1,0,1]
	v_mfma_f32_16x16x4_f32 v[102:105], v143, v88, v[102:105]
	v_pk_fma_f32 v[180:181], v[10:11], v[232:233], v[180:181] op_sel:[0,1,0]
	v_pk_fma_f32 v[192:193], v[12:13], v[232:233], v[192:193] op_sel:[0,1,0]
	v_pk_fma_f32 v[180:181], v[6:7], v[234:235], v[180:181] op_sel_hi:[1,0,1]
	v_pk_fma_f32 v[192:193], v[8:9], v[234:235], v[192:193] op_sel_hi:[1,0,1]
	v_mfma_f32_16x16x4_f32 v[98:101], v143, v89, v[98:101]
	v_pk_fma_f32 v[180:181], v[2:3], v[234:235], v[180:181] op_sel:[0,1,0]
	v_pk_fma_f32 v[192:193], v[4:5], v[234:235], v[192:193] op_sel:[0,1,0]
	v_pk_mul_f32 v[180:181], v[146:147], v[180:181]
	v_pk_mul_f32 v[192:193], v[146:147], v[192:193]
	v_pk_fma_f32 v[236:237], v[144:145], v[86:87], v[180:181]
	v_pk_fma_f32 v[238:239], v[144:145], v[88:89], v[192:193]
	global_store_dwordx4 v[150:151], v[236:239], off nt
	v_lshl_add_u64 v[150:151], v[150:151], 0, s[74:75]
	global_load_dwordx4 v[86:89], v[148:149], off nt
	v_lshl_add_u64 v[148:149], v[148:149], 0, s[74:75]
	ds_read_b32 v143, v160 offset:560
	ds_read_b128 v[172:175], v161 offset:4480
	ds_read_b128 v[232:235], v161 offset:4496
	s_waitcnt vmcnt(38)
; #define RS_LOAD(dst, it0) do { _Pragma("unroll") for (int u = 0; u < 8; ++u) dst[u] = __builtin_nontemporal_load((const f32x4*)(S0 + (size_t)(4 * ((it0) + u)) * DV)); } while (0)
; __device__ __forceinline__ void ret_sample_item(Frame& F, int item) {
;     ...
;     for (int it0 = 0; it0 < 64; it0 += 16) {
;         RS_LOAD(sb, it0 + 8);
;         RS_PROC(sa, it0);
;         { const int itn = it0 + 16 < 64 ? it0 + 16 : it0; RS_LOAD(sa, itn); }
;         RS_PROC(sb, it0 + 8);
;     }
	s_waitcnt lgkmcnt(3)
	v_cndmask_b32_e64 v141, 0, v141, s[8:9]
	v_pk_mul_f32 v[180:181], v[26:27], v[114:115] op_sel:[0,1]
	v_pk_mul_f32 v[192:193], v[28:29], v[114:115] op_sel:[0,1]
	v_mfma_f32_16x16x4_f32 v[110:113], v141, v90, v[110:113]
	v_pk_fma_f32 v[180:181], v[30:31], v[114:115], v[180:181] op_sel_hi:[1,0,1]
	v_pk_fma_f32 v[192:193], v[32:33], v[114:115], v[192:193] op_sel_hi:[1,0,1]
	v_pk_fma_f32 v[180:181], v[22:23], v[116:117], v[180:181] op_sel_hi:[1,0,1]
	v_pk_fma_f32 v[192:193], v[24:25], v[116:117], v[192:193] op_sel_hi:[1,0,1]
	v_mfma_f32_16x16x4_f32 v[106:109], v141, v91, v[106:109]
	v_pk_fma_f32 v[180:181], v[18:19], v[116:117], v[180:181] op_sel:[0,1,0]
	v_pk_fma_f32 v[192:193], v[20:21], v[116:117], v[192:193] op_sel:[0,1,0]
	v_pk_fma_f32 v[180:181], v[14:15], v[176:177], v[180:181] op_sel_hi:[1,0,1]
	v_pk_fma_f32 v[192:193], v[16:17], v[176:177], v[192:193] op_sel_hi:[1,0,1]
	v_mfma_f32_16x16x4_f32 v[102:105], v141, v92, v[102:105]
	v_pk_fma_f32 v[180:181], v[10:11], v[176:177], v[180:181] op_sel:[0,1,0]
	v_pk_fma_f32 v[192:193], v[12:13], v[176:177], v[192:193] op_sel:[0,1,0]
	v_pk_fma_f32 v[180:181], v[6:7], v[178:179], v[180:181] op_sel_hi:[1,0,1]
	v_pk_fma_f32 v[192:193], v[8:9], v[178:179], v[192:193] op_sel_hi:[1,0,1]
	v_mfma_f32_16x16x4_f32 v[98:101], v141, v93, v[98:101]
	v_pk_fma_f32 v[180:181], v[2:3], v[178:179], v[180:181] op_sel:[0,1,0]
	v_pk_fma_f32 v[192:193], v[4:5], v[178:179], v[192:193] op_sel:[0,1,0]
	v_pk_mul_f32 v[180:181], v[146:147], v[180:181]
	v_pk_mul_f32 v[192:193], v[146:147], v[192:193]
	v_pk_fma_f32 v[236:237], v[144:145], v[90:91], v[180:181]
	v_pk_fma_f32 v[238:239], v[144:145], v[92:93], v[192:193]
	global_store_dwordx4 v[150:151], v[236:239], off nt
	v_lshl_add_u64 v[150:151], v[150:151], 0, s[74:75]
	global_load_dwordx4 v[90:93], v[148:149], off nt
	v_lshl_add_u64 v[148:149], v[148:149], 0, s[74:75]
	ds_read_b32 v141, v160 offset:576
	ds_read_b128 v[114:117], v161 offset:4608
	ds_read_b128 v[176:179], v161 offset:4624
	s_waitcnt vmcnt(38)
	s_waitcnt lgkmcnt(3)
	v_cndmask_b32_e64 v143, 0, v143, s[8:9]
	v_pk_mul_f32 v[180:181], v[26:27], v[172:173] op_sel:[0,1]
	v_pk_mul_f32 v[192:193], v[28:29], v[172:173] op_sel:[0,1]
	v_mfma_f32_16x16x4_f32 v[110:113], v143, v94, v[110:113]
	v_pk_fma_f32 v[180:181], v[30:31], v[172:173], v[180:181] op_sel_hi:[1,0,1]
	v_pk_fma_f32 v[192:193], v[32:33], v[172:173], v[192:193] op_sel_hi:[1,0,1]
	v_pk_fma_f32 v[180:181], v[22:23], v[174:175], v[180:181] op_sel_hi:[1,0,1]
	v_pk_fma_f32 v[192:193], v[24:25], v[174:175], v[192:193] op_sel_hi:[1,0,1]
	v_mfma_f32_16x16x4_f32 v[106:109], v143, v95, v[106:109]
	v_pk_fma_f32 v[180:181], v[18:19], v[174:175], v[180:181] op_sel:[0,1,0]
	v_pk_fma_f32 v[192:193], v[20:21], v[174:175], v[192:193] op_sel:[0,1,0]
	v_pk_fma_f32 v[180:181], v[14:15], v[232:233], v[180:181] op_sel_hi:[1,0,1]
	v_pk_fma_f32 v[192:193], v[16:17], v[232:233], v[192:193] op_sel_hi:[1,0,1]
	v_mfma_f32_16x16x4_f32 v[102:105], v143, v96, v[102:105]
	v_pk_fma_f32 v[180:181], v[10:11], v[232:233], v[180:181] op_sel:[0,1,0]
	v_pk_fma_f32 v[192:193], v[12:13], v[232:233], v[192:193] op_sel:[0,1,0]
	v_pk_fma_f32 v[180:181], v[6:7], v[234:235], v[180:181] op_sel_hi:[1,0,1]
	v_pk_fma_f32 v[192:193], v[8:9], v[234:235], v[192:193] op_sel_hi:[1,0,1]
	v_mfma_f32_16x16x4_f32 v[98:101], v143, v97, v[98:101]
	v_pk_fma_f32 v[180:181], v[2:3], v[234:235], v[180:181] op_sel:[0,1,0]
	v_pk_fma_f32 v[192:193], v[4:5], v[234:235], v[192:193] op_sel:[0,1,0]
	v_pk_mul_f32 v[180:181], v[146:147], v[180:181]
	v_pk_mul_f32 v[192:193], v[146:147], v[192:193]
	v_pk_fma_f32 v[236:237], v[144:145], v[94:95], v[180:181]
	v_pk_fma_f32 v[238:239], v[144:145], v[96:97], v[192:193]
	global_store_dwordx4 v[150:151], v[236:239], off nt
	v_lshl_add_u64 v[150:151], v[150:151], 0, s[74:75]
	global_load_dwordx4 v[94:97], v[148:149], off nt
	v_lshl_add_u64 v[148:149], v[148:149], 0, s[74:75]
	ds_read_b32 v143, v160 offset:592
	ds_read_b128 v[172:175], v161 offset:4736
	ds_read_b128 v[232:235], v161 offset:4752
	s_waitcnt vmcnt(38)
	s_waitcnt lgkmcnt(3)
	v_cndmask_b32_e64 v141, 0, v141, s[8:9]
	v_pk_mul_f32 v[180:181], v[26:27], v[114:115] op_sel:[0,1]
	v_pk_mul_f32 v[192:193], v[28:29], v[114:115] op_sel:[0,1]
	v_mfma_f32_16x16x4_f32 v[110:113], v141, v212, v[110:113]
	v_pk_fma_f32 v[180:181], v[30:31], v[114:115], v[180:181] op_sel_hi:[1,0,1]
	v_pk_fma_f32 v[192:193], v[32:33], v[114:115], v[192:193] op_sel_hi:[1,0,1]
	v_pk_fma_f32 v[180:181], v[22:23], v[116:117], v[180:181] op_sel_hi:[1,0,1]
	v_pk_fma_f32 v[192:193], v[24:25], v[116:117], v[192:193] op_sel_hi:[1,0,1]
	v_mfma_f32_16x16x4_f32 v[106:109], v141, v213, v[106:109]
	v_pk_fma_f32 v[180:181], v[18:19], v[116:117], v[180:181] op_sel:[0,1,0]
	v_pk_fma_f32 v[192:193], v[20:21], v[116:117], v[192:193] op_sel:[0,1,0]
	v_pk_fma_f32 v[180:181], v[14:15], v[176:177], v[180:181] op_sel_hi:[1,0,1]
	v_pk_fma_f32 v[192:193], v[16:17], v[176:177], v[192:193] op_sel_hi:[1,0,1]
	v_mfma_f32_16x16x4_f32 v[102:105], v141, v214, v[102:105]
	v_pk_fma_f32 v[180:181], v[10:11], v[176:177], v[180:181] op_sel:[0,1,0]
	v_pk_fma_f32 v[192:193], v[12:13], v[176:177], v[192:193] op_sel:[0,1,0]
	v_pk_fma_f32 v[180:181], v[6:7], v[178:179], v[180:181] op_sel_hi:[1,0,1]
	v_pk_fma_f32 v[192:193], v[8:9], v[178:179], v[192:193] op_sel_hi:[1,0,1]
	v_mfma_f32_16x16x4_f32 v[98:101], v141, v215, v[98:101]
	v_pk_fma_f32 v[180:181], v[2:3], v[178:179], v[180:181] op_sel:[0,1,0]
	v_pk_fma_f32 v[192:193], v[4:5], v[178:179], v[192:193] op_sel:[0,1,0]
	v_pk_mul_f32 v[180:181], v[146:147], v[180:181]
	v_pk_mul_f32 v[192:193], v[146:147], v[192:193]
	v_pk_fma_f32 v[236:237], v[144:145], v[212:213], v[180:181]
	v_pk_fma_f32 v[238:239], v[144:145], v[214:215], v[192:193]
	global_store_dwordx4 v[150:151], v[236:239], off nt
	v_lshl_add_u64 v[150:151], v[150:151], 0, s[74:75]
	global_load_dwordx4 v[212:215], v[148:149], off nt
	v_lshl_add_u64 v[148:149], v[148:149], 0, s[74:75]
	ds_read_b32 v141, v160 offset:608
	ds_read_b128 v[114:117], v161 offset:4864
	ds_read_b128 v[176:179], v161 offset:4880
	s_waitcnt vmcnt(38)
; #define RS_LOAD(dst, it0) do { _Pragma("unroll") for (int u = 0; u < 8; ++u) dst[u] = __builtin_nontemporal_load((const f32x4*)(S0 + (size_t)(4 * ((it0) + u)) * DV)); } while (0)
; __device__ __forceinline__ void ret_sample_item(Frame& F, int item) {
;     ...
;     for (int it0 = 0; it0 < 64; it0 += 16) {
;         RS_LOAD(sb, it0 + 8);
;         RS_PROC(sa, it0);
;         { const int itn = it0 + 16 < 64 ? it0 + 16 : it0; RS_LOAD(sa, itn); }
;         RS_PROC(sb, it0 + 8);
;     }
	s_waitcnt lgkmcnt(3)
	v_cndmask_b32_e64 v143, 0, v143, s[8:9]
	v_pk_mul_f32 v[180:181], v[26:27], v[172:173] op_sel:[0,1]
	v_pk_mul_f32 v[192:193], v[28:29], v[172:173] op_sel:[0,1]
	v_mfma_f32_16x16x4_f32 v[110:113], v143, v216, v[110:113]
	v_pk_fma_f32 v[180:181], v[30:31], v[172:173], v[180:181] op_sel_hi:[1,0,1]
	v_pk_fma_f32 v[192:193], v[32:33], v[172:173], v[192:193] op_sel_hi:[1,0,1]
	v_pk_fma_f32 v[180:181], v[22:23], v[174:175], v[180:181] op_sel_hi:[1,0,1]
	v_pk_fma_f32 v[192:193], v[24:25], v[174:175], v[192:193] op_sel_hi:[1,0,1]
	v_mfma_f32_16x16x4_f32 v[106:109], v143, v217, v[106:109]
	v_pk_fma_f32 v[180:181], v[18:19], v[174:175], v[180:181] op_sel:[0,1,0]
	v_pk_fma_f32 v[192:193], v[20:21], v[174:175], v[192:193] op_sel:[0,1,0]
	v_pk_fma_f32 v[180:181], v[14:15], v[232:233], v[180:181] op_sel_hi:[1,0,1]
	v_pk_fma_f32 v[192:193], v[16:17], v[232:233], v[192:193] op_sel_hi:[1,0,1]
	v_mfma_f32_16x16x4_f32 v[102:105], v143, v218, v[102:105]
	v_pk_fma_f32 v[180:181], v[10:11], v[232:233], v[180:181] op_sel:[0,1,0]
	v_pk_fma_f32 v[192:193], v[12:13], v[232:233], v[192:193] op_sel:[0,1,0]
	v_pk_fma_f32 v[180:181], v[6:7], v[234:235], v[180:181] op_sel_hi:[1,0,1]
	v_pk_fma_f32 v[192:193], v[8:9], v[234:235], v[192:193] op_sel_hi:[1,0,1]
	v_mfma_f32_16x16x4_f32 v[98:101], v143, v219, v[98:101]
	v_pk_fma_f32 v[180:181], v[2:3], v[234:235], v[180:181] op_sel:[0,1,0]
	v_pk_fma_f32 v[192:193], v[4:5], v[234:235], v[192:193] op_sel:[0,1,0]
	v_pk_mul_f32 v[180:181], v[146:147], v[180:181]
	v_pk_mul_f32 v[192:193], v[146:147], v[192:193]
	v_pk_fma_f32 v[236:237], v[144:145], v[216:217], v[180:181]
	v_pk_fma_f32 v[238:239], v[144:145], v[218:219], v[192:193]
	global_store_dwordx4 v[150:151], v[236:239], off nt
	v_lshl_add_u64 v[150:151], v[150:151], 0, s[74:75]
	global_load_dwordx4 v[216:219], v[148:149], off nt
	v_lshl_add_u64 v[148:149], v[148:149], 0, s[74:75]
	ds_read_b32 v143, v160 offset:624
	ds_read_b128 v[172:175], v161 offset:4992
	ds_read_b128 v[232:235], v161 offset:5008
	s_waitcnt vmcnt(38)
	s_waitcnt lgkmcnt(3)
	v_cndmask_b32_e64 v141, 0, v141, s[8:9]
	v_pk_mul_f32 v[180:181], v[26:27], v[114:115] op_sel:[0,1]
	v_pk_mul_f32 v[192:193], v[28:29], v[114:115] op_sel:[0,1]
	v_mfma_f32_16x16x4_f32 v[110:113], v141, v224, v[110:113]
	v_pk_fma_f32 v[180:181], v[30:31], v[114:115], v[180:181] op_sel_hi:[1,0,1]
	v_pk_fma_f32 v[192:193], v[32:33], v[114:115], v[192:193] op_sel_hi:[1,0,1]
	v_pk_fma_f32 v[180:181], v[22:23], v[116:117], v[180:181] op_sel_hi:[1,0,1]
	v_pk_fma_f32 v[192:193], v[24:25], v[116:117], v[192:193] op_sel_hi:[1,0,1]
	v_mfma_f32_16x16x4_f32 v[106:109], v141, v225, v[106:109]
	v_pk_fma_f32 v[180:181], v[18:19], v[116:117], v[180:181] op_sel:[0,1,0]
	v_pk_fma_f32 v[192:193], v[20:21], v[116:117], v[192:193] op_sel:[0,1,0]
	v_pk_fma_f32 v[180:181], v[14:15], v[176:177], v[180:181] op_sel_hi:[1,0,1]
	v_pk_fma_f32 v[192:193], v[16:17], v[176:177], v[192:193] op_sel_hi:[1,0,1]
	v_mfma_f32_16x16x4_f32 v[102:105], v141, v226, v[102:105]
	v_pk_fma_f32 v[180:181], v[10:11], v[176:177], v[180:181] op_sel:[0,1,0]
	v_pk_fma_f32 v[192:193], v[12:13], v[176:177], v[192:193] op_sel:[0,1,0]
	v_pk_fma_f32 v[180:181], v[6:7], v[178:179], v[180:181] op_sel_hi:[1,0,1]
	v_pk_fma_f32 v[192:193], v[8:9], v[178:179], v[192:193] op_sel_hi:[1,0,1]
	v_mfma_f32_16x16x4_f32 v[98:101], v141, v227, v[98:101]
	v_pk_fma_f32 v[180:181], v[2:3], v[178:179], v[180:181] op_sel:[0,1,0]
	v_pk_fma_f32 v[192:193], v[4:5], v[178:179], v[192:193] op_sel:[0,1,0]
	v_pk_mul_f32 v[180:181], v[146:147], v[180:181]
	v_pk_mul_f32 v[192:193], v[146:147], v[192:193]
	v_pk_fma_f32 v[236:237], v[144:145], v[224:225], v[180:181]
	v_pk_fma_f32 v[238:239], v[144:145], v[226:227], v[192:193]
	global_store_dwordx4 v[150:151], v[236:239], off nt
	v_lshl_add_u64 v[150:151], v[150:151], 0, s[74:75]
	global_load_dwordx4 v[224:227], v[148:149], off nt
	v_lshl_add_u64 v[148:149], v[148:149], 0, s[74:75]
	ds_read_b32 v141, v160 offset:640
	ds_read_b128 v[114:117], v161 offset:5120
	ds_read_b128 v[176:179], v161 offset:5136
	s_waitcnt vmcnt(38)
	s_waitcnt lgkmcnt(3)
	v_cndmask_b32_e64 v143, 0, v143, s[8:9]
	v_pk_mul_f32 v[180:181], v[26:27], v[172:173] op_sel:[0,1]
	v_pk_mul_f32 v[192:193], v[28:29], v[172:173] op_sel:[0,1]
	v_mfma_f32_16x16x4_f32 v[110:113], v143, v228, v[110:113]
	v_pk_fma_f32 v[180:181], v[30:31], v[172:173], v[180:181] op_sel_hi:[1,0,1]
	v_pk_fma_f32 v[192:193], v[32:33], v[172:173], v[192:193] op_sel_hi:[1,0,1]
	v_pk_fma_f32 v[180:181], v[22:23], v[174:175], v[180:181] op_sel_hi:[1,0,1]
	v_pk_fma_f32 v[192:193], v[24:25], v[174:175], v[192:193] op_sel_hi:[1,0,1]
	v_mfma_f32_16x16x4_f32 v[106:109], v143, v229, v[106:109]
	v_pk_fma_f32 v[180:181], v[18:19], v[174:175], v[180:181] op_sel:[0,1,0]
	v_pk_fma_f32 v[192:193], v[20:21], v[174:175], v[192:193] op_sel:[0,1,0]
	v_pk_fma_f32 v[180:181], v[14:15], v[232:233], v[180:181] op_sel_hi:[1,0,1]
	v_pk_fma_f32 v[192:193], v[16:17], v[232:233], v[192:193] op_sel_hi:[1,0,1]
	v_mfma_f32_16x16x4_f32 v[102:105], v143, v230, v[102:105]
	v_pk_fma_f32 v[180:181], v[10:11], v[232:233], v[180:181] op_sel:[0,1,0]
	v_pk_fma_f32 v[192:193], v[12:13], v[232:233], v[192:193] op_sel:[0,1,0]
	v_pk_fma_f32 v[180:181], v[6:7], v[234:235], v[180:181] op_sel_hi:[1,0,1]
	v_pk_fma_f32 v[192:193], v[8:9], v[234:235], v[192:193] op_sel_hi:[1,0,1]
	v_mfma_f32_16x16x4_f32 v[98:101], v143, v231, v[98:101]
	v_pk_fma_f32 v[180:181], v[2:3], v[234:235], v[180:181] op_sel:[0,1,0]
	v_pk_fma_f32 v[192:193], v[4:5], v[234:235], v[192:193] op_sel:[0,1,0]
	v_pk_mul_f32 v[180:181], v[146:147], v[180:181]
	v_pk_mul_f32 v[192:193], v[146:147], v[192:193]
	v_pk_fma_f32 v[236:237], v[144:145], v[228:229], v[180:181]
	v_pk_fma_f32 v[238:239], v[144:145], v[230:231], v[192:193]
	global_store_dwordx4 v[150:151], v[236:239], off nt
	v_lshl_add_u64 v[150:151], v[150:151], 0, s[74:75]
	global_load_dwordx4 v[228:231], v[148:149], off nt
	v_lshl_add_u64 v[148:149], v[148:149], 0, s[74:75]
	ds_read_b32 v143, v160 offset:656
	ds_read_b128 v[172:175], v161 offset:5248
	ds_read_b128 v[232:235], v161 offset:5264
	s_waitcnt vmcnt(38)
; #define RS_LOAD(dst, it0) do { _Pragma("unroll") for (int u = 0; u < 8; ++u) dst[u] = __builtin_nontemporal_load((const f32x4*)(S0 + (size_t)(4 * ((it0) + u)) * DV)); } while (0)
; __device__ __forceinline__ void ret_sample_item(Frame& F, int item) {
;     ...
;     for (int it0 = 0; it0 < 64; it0 += 16) {
;         RS_LOAD(sb, it0 + 8);
;         RS_PROC(sa, it0);
;         { const int itn = it0 + 16 < 64 ? it0 + 16 : it0; RS_LOAD(sa, itn); }
;         RS_PROC(sb, it0 + 8);
;     }
	s_waitcnt lgkmcnt(3)
	v_cndmask_b32_e64 v141, 0, v141, s[8:9]
	v_pk_mul_f32 v[180:181], v[26:27], v[114:115] op_sel:[0,1]
	v_pk_mul_f32 v[192:193], v[28:29], v[114:115] op_sel:[0,1]
	v_mfma_f32_16x16x4_f32 v[110:113], v141, v70, v[110:113]
	v_pk_fma_f32 v[180:181], v[30:31], v[114:115], v[180:181] op_sel_hi:[1,0,1]
	v_pk_fma_f32 v[192:193], v[32:33], v[114:115], v[192:193] op_sel_hi:[1,0,1]
	v_pk_fma_f32 v[180:181], v[22:23], v[116:117], v[180:181] op_sel_hi:[1,0,1]
	v_pk_fma_f32 v[192:193], v[24:25], v[116:117], v[192:193] op_sel_hi:[1,0,1]
	v_mfma_f32_16x16x4_f32 v[106:109], v141, v71, v[106:109]
	v_pk_fma_f32 v[180:181], v[18:19], v[116:117], v[180:181] op_sel:[0,1,0]
	v_pk_fma_f32 v[192:193], v[20:21], v[116:117], v[192:193] op_sel:[0,1,0]
	v_pk_fma_f32 v[180:181], v[14:15], v[176:177], v[180:181] op_sel_hi:[1,0,1]
	v_pk_fma_f32 v[192:193], v[16:17], v[176:177], v[192:193] op_sel_hi:[1,0,1]
	v_mfma_f32_16x16x4_f32 v[102:105], v141, v72, v[102:105]
	v_pk_fma_f32 v[180:181], v[10:11], v[176:177], v[180:181] op_sel:[0,1,0]
	v_pk_fma_f32 v[192:193], v[12:13], v[176:177], v[192:193] op_sel:[0,1,0]
	v_pk_fma_f32 v[180:181], v[6:7], v[178:179], v[180:181] op_sel_hi:[1,0,1]
	v_pk_fma_f32 v[192:193], v[8:9], v[178:179], v[192:193] op_sel_hi:[1,0,1]
	v_mfma_f32_16x16x4_f32 v[98:101], v141, v73, v[98:101]
	v_pk_fma_f32 v[180:181], v[2:3], v[178:179], v[180:181] op_sel:[0,1,0]
	v_pk_fma_f32 v[192:193], v[4:5], v[178:179], v[192:193] op_sel:[0,1,0]
	v_pk_mul_f32 v[180:181], v[146:147], v[180:181]
	v_pk_mul_f32 v[192:193], v[146:147], v[192:193]
	v_pk_fma_f32 v[236:237], v[144:145], v[70:71], v[180:181]
	v_pk_fma_f32 v[238:239], v[144:145], v[72:73], v[192:193]
	global_store_dwordx4 v[150:151], v[236:239], off nt
	v_lshl_add_u64 v[150:151], v[150:151], 0, s[74:75]
	global_load_dwordx4 v[70:73], v[148:149], off nt
	v_lshl_add_u64 v[148:149], v[148:149], 0, s[74:75]
	ds_read_b32 v141, v160 offset:672
	ds_read_b128 v[114:117], v161 offset:5376
	ds_read_b128 v[176:179], v161 offset:5392
	s_waitcnt vmcnt(38)
	s_waitcnt lgkmcnt(3)
	v_cndmask_b32_e64 v143, 0, v143, s[8:9]
	v_pk_mul_f32 v[180:181], v[26:27], v[172:173] op_sel:[0,1]
	v_pk_mul_f32 v[192:193], v[28:29], v[172:173] op_sel:[0,1]
	v_mfma_f32_16x16x4_f32 v[110:113], v143, v62, v[110:113]
	v_pk_fma_f32 v[180:181], v[30:31], v[172:173], v[180:181] op_sel_hi:[1,0,1]
	v_pk_fma_f32 v[192:193], v[32:33], v[172:173], v[192:193] op_sel_hi:[1,0,1]
	v_pk_fma_f32 v[180:181], v[22:23], v[174:175], v[180:181] op_sel_hi:[1,0,1]
	v_pk_fma_f32 v[192:193], v[24:25], v[174:175], v[192:193] op_sel_hi:[1,0,1]
	v_mfma_f32_16x16x4_f32 v[106:109], v143, v63, v[106:109]
	v_pk_fma_f32 v[180:181], v[18:19], v[174:175], v[180:181] op_sel:[0,1,0]
	v_pk_fma_f32 v[192:193], v[20:21], v[174:175], v[192:193] op_sel:[0,1,0]
	v_pk_fma_f32 v[180:181], v[14:15], v[232:233], v[180:181] op_sel_hi:[1,0,1]
	v_pk_fma_f32 v[192:193], v[16:17], v[232:233], v[192:193] op_sel_hi:[1,0,1]
	v_mfma_f32_16x16x4_f32 v[102:105], v143, v64, v[102:105]
	v_pk_fma_f32 v[180:181], v[10:11], v[232:233], v[180:181] op_sel:[0,1,0]
	v_pk_fma_f32 v[192:193], v[12:13], v[232:233], v[192:193] op_sel:[0,1,0]
	v_pk_fma_f32 v[180:181], v[6:7], v[234:235], v[180:181] op_sel_hi:[1,0,1]
	v_pk_fma_f32 v[192:193], v[8:9], v[234:235], v[192:193] op_sel_hi:[1,0,1]
	v_mfma_f32_16x16x4_f32 v[98:101], v143, v65, v[98:101]
	v_pk_fma_f32 v[180:181], v[2:3], v[234:235], v[180:181] op_sel:[0,1,0]
	v_pk_fma_f32 v[192:193], v[4:5], v[234:235], v[192:193] op_sel:[0,1,0]
	v_pk_mul_f32 v[180:181], v[146:147], v[180:181]
	v_pk_mul_f32 v[192:193], v[146:147], v[192:193]
	v_pk_fma_f32 v[236:237], v[144:145], v[62:63], v[180:181]
	v_pk_fma_f32 v[238:239], v[144:145], v[64:65], v[192:193]
	global_store_dwordx4 v[150:151], v[236:239], off nt
	v_lshl_add_u64 v[150:151], v[150:151], 0, s[74:75]
	global_load_dwordx4 v[62:65], v[148:149], off nt
	v_lshl_add_u64 v[148:149], v[148:149], 0, s[74:75]
	ds_read_b32 v143, v160 offset:688
	ds_read_b128 v[172:175], v161 offset:5504
	ds_read_b128 v[232:235], v161 offset:5520
	s_waitcnt vmcnt(38)
	s_waitcnt lgkmcnt(3)
	v_cndmask_b32_e64 v141, 0, v141, s[8:9]
	v_pk_mul_f32 v[180:181], v[26:27], v[114:115] op_sel:[0,1]
	v_pk_mul_f32 v[192:193], v[28:29], v[114:115] op_sel:[0,1]
	v_mfma_f32_16x16x4_f32 v[110:113], v141, v54, v[110:113]
	v_pk_fma_f32 v[180:181], v[30:31], v[114:115], v[180:181] op_sel_hi:[1,0,1]
	v_pk_fma_f32 v[192:193], v[32:33], v[114:115], v[192:193] op_sel_hi:[1,0,1]
	v_pk_fma_f32 v[180:181], v[22:23], v[116:117], v[180:181] op_sel_hi:[1,0,1]
	v_pk_fma_f32 v[192:193], v[24:25], v[116:117], v[192:193] op_sel_hi:[1,0,1]
	v_mfma_f32_16x16x4_f32 v[106:109], v141, v55, v[106:109]
	v_pk_fma_f32 v[180:181], v[18:19], v[116:117], v[180:181] op_sel:[0,1,0]
	v_pk_fma_f32 v[192:193], v[20:21], v[116:117], v[192:193] op_sel:[0,1,0]
	v_pk_fma_f32 v[180:181], v[14:15], v[176:177], v[180:181] op_sel_hi:[1,0,1]
	v_pk_fma_f32 v[192:193], v[16:17], v[176:177], v[192:193] op_sel_hi:[1,0,1]
	v_mfma_f32_16x16x4_f32 v[102:105], v141, v56, v[102:105]
	v_pk_fma_f32 v[180:181], v[10:11], v[176:177], v[180:181] op_sel:[0,1,0]
	v_pk_fma_f32 v[192:193], v[12:13], v[176:177], v[192:193] op_sel:[0,1,0]
	v_pk_fma_f32 v[180:181], v[6:7], v[178:179], v[180:181] op_sel_hi:[1,0,1]
	v_pk_fma_f32 v[192:193], v[8:9], v[178:179], v[192:193] op_sel_hi:[1,0,1]
	v_mfma_f32_16x16x4_f32 v[98:101], v141, v57, v[98:101]
	v_pk_fma_f32 v[180:181], v[2:3], v[178:179], v[180:181] op_sel:[0,1,0]
	v_pk_fma_f32 v[192:193], v[4:5], v[178:179], v[192:193] op_sel:[0,1,0]
	v_pk_mul_f32 v[180:181], v[146:147], v[180:181]
	v_pk_mul_f32 v[192:193], v[146:147], v[192:193]
	v_pk_fma_f32 v[236:237], v[144:145], v[54:55], v[180:181]
	v_pk_fma_f32 v[238:239], v[144:145], v[56:57], v[192:193]
	global_store_dwordx4 v[150:151], v[236:239], off nt
	v_lshl_add_u64 v[150:151], v[150:151], 0, s[74:75]
	global_load_dwordx4 v[54:57], v[148:149], off nt
	v_lshl_add_u64 v[148:149], v[148:149], 0, s[74:75]
	ds_read_b32 v141, v160 offset:704
	ds_read_b128 v[114:117], v161 offset:5632
	ds_read_b128 v[176:179], v161 offset:5648
	s_waitcnt vmcnt(38)
; #define RS_LOAD(dst, it0) do { _Pragma("unroll") for (int u = 0; u < 8; ++u) dst[u] = __builtin_nontemporal_load((const f32x4*)(S0 + (size_t)(4 * ((it0) + u)) * DV)); } while (0)
; __device__ __forceinline__ void ret_sample_item(Frame& F, int item) {
;     ...
;     for (int it0 = 0; it0 < 64; it0 += 16) {
;         RS_LOAD(sb, it0 + 8);
;         RS_PROC(sa, it0);
;         { const int itn = it0 + 16 < 64 ? it0 + 16 : it0; RS_LOAD(sa, itn); }
;         RS_PROC(sb, it0 + 8);
;     }
	s_waitcnt lgkmcnt(3)
	v_cndmask_b32_e64 v143, 0, v143, s[8:9]
	v_pk_mul_f32 v[180:181], v[26:27], v[172:173] op_sel:[0,1]
	v_pk_mul_f32 v[192:193], v[28:29], v[172:173] op_sel:[0,1]
	v_mfma_f32_16x16x4_f32 v[110:113], v143, v50, v[110:113]
	v_pk_fma_f32 v[180:181], v[30:31], v[172:173], v[180:181] op_sel_hi:[1,0,1]
	v_pk_fma_f32 v[192:193], v[32:33], v[172:173], v[192:193] op_sel_hi:[1,0,1]
	v_pk_fma_f32 v[180:181], v[22:23], v[174:175], v[180:181] op_sel_hi:[1,0,1]
	v_pk_fma_f32 v[192:193], v[24:25], v[174:175], v[192:193] op_sel_hi:[1,0,1]
	v_mfma_f32_16x16x4_f32 v[106:109], v143, v51, v[106:109]
	v_pk_fma_f32 v[180:181], v[18:19], v[174:175], v[180:181] op_sel:[0,1,0]
	v_pk_fma_f32 v[192:193], v[20:21], v[174:175], v[192:193] op_sel:[0,1,0]
	v_pk_fma_f32 v[180:181], v[14:15], v[232:233], v[180:181] op_sel_hi:[1,0,1]
	v_pk_fma_f32 v[192:193], v[16:17], v[232:233], v[192:193] op_sel_hi:[1,0,1]
	v_mfma_f32_16x16x4_f32 v[102:105], v143, v52, v[102:105]
	v_pk_fma_f32 v[180:181], v[10:11], v[232:233], v[180:181] op_sel:[0,1,0]
	v_pk_fma_f32 v[192:193], v[12:13], v[232:233], v[192:193] op_sel:[0,1,0]
	v_pk_fma_f32 v[180:181], v[6:7], v[234:235], v[180:181] op_sel_hi:[1,0,1]
	v_pk_fma_f32 v[192:193], v[8:9], v[234:235], v[192:193] op_sel_hi:[1,0,1]
	v_mfma_f32_16x16x4_f32 v[98:101], v143, v53, v[98:101]
	v_pk_fma_f32 v[180:181], v[2:3], v[234:235], v[180:181] op_sel:[0,1,0]
	v_pk_fma_f32 v[192:193], v[4:5], v[234:235], v[192:193] op_sel:[0,1,0]
	v_pk_mul_f32 v[180:181], v[146:147], v[180:181]
	v_pk_mul_f32 v[192:193], v[146:147], v[192:193]
	v_pk_fma_f32 v[236:237], v[144:145], v[50:51], v[180:181]
	v_pk_fma_f32 v[238:239], v[144:145], v[52:53], v[192:193]
	global_store_dwordx4 v[150:151], v[236:239], off nt
	v_lshl_add_u64 v[150:151], v[150:151], 0, s[74:75]
	global_load_dwordx4 v[50:53], v[148:149], off nt
	v_lshl_add_u64 v[148:149], v[148:149], 0, s[74:75]
	ds_read_b32 v143, v160 offset:720
	ds_read_b128 v[172:175], v161 offset:5760
	ds_read_b128 v[232:235], v161 offset:5776
	s_waitcnt vmcnt(38)
	s_waitcnt lgkmcnt(3)
	v_cndmask_b32_e64 v141, 0, v141, s[8:9]
	v_pk_mul_f32 v[180:181], v[26:27], v[114:115] op_sel:[0,1]
	v_pk_mul_f32 v[192:193], v[28:29], v[114:115] op_sel:[0,1]
	v_mfma_f32_16x16x4_f32 v[110:113], v141, v46, v[110:113]
	v_pk_fma_f32 v[180:181], v[30:31], v[114:115], v[180:181] op_sel_hi:[1,0,1]
	v_pk_fma_f32 v[192:193], v[32:33], v[114:115], v[192:193] op_sel_hi:[1,0,1]
	v_pk_fma_f32 v[180:181], v[22:23], v[116:117], v[180:181] op_sel_hi:[1,0,1]
	v_pk_fma_f32 v[192:193], v[24:25], v[116:117], v[192:193] op_sel_hi:[1,0,1]
	v_mfma_f32_16x16x4_f32 v[106:109], v141, v47, v[106:109]
	v_pk_fma_f32 v[180:181], v[18:19], v[116:117], v[180:181] op_sel:[0,1,0]
	v_pk_fma_f32 v[192:193], v[20:21], v[116:117], v[192:193] op_sel:[0,1,0]
	v_pk_fma_f32 v[180:181], v[14:15], v[176:177], v[180:181] op_sel_hi:[1,0,1]
	v_pk_fma_f32 v[192:193], v[16:17], v[176:177], v[192:193] op_sel_hi:[1,0,1]
	v_mfma_f32_16x16x4_f32 v[102:105], v141, v48, v[102:105]
	v_pk_fma_f32 v[180:181], v[10:11], v[176:177], v[180:181] op_sel:[0,1,0]
	v_pk_fma_f32 v[192:193], v[12:13], v[176:177], v[192:193] op_sel:[0,1,0]
	v_pk_fma_f32 v[180:181], v[6:7], v[178:179], v[180:181] op_sel_hi:[1,0,1]
	v_pk_fma_f32 v[192:193], v[8:9], v[178:179], v[192:193] op_sel_hi:[1,0,1]
	v_mfma_f32_16x16x4_f32 v[98:101], v141, v49, v[98:101]
	v_pk_fma_f32 v[180:181], v[2:3], v[178:179], v[180:181] op_sel:[0,1,0]
	v_pk_fma_f32 v[192:193], v[4:5], v[178:179], v[192:193] op_sel:[0,1,0]
	v_pk_mul_f32 v[180:181], v[146:147], v[180:181]
	v_pk_mul_f32 v[192:193], v[146:147], v[192:193]
	v_pk_fma_f32 v[236:237], v[144:145], v[46:47], v[180:181]
	v_pk_fma_f32 v[238:239], v[144:145], v[48:49], v[192:193]
	global_store_dwordx4 v[150:151], v[236:239], off nt
	v_lshl_add_u64 v[150:151], v[150:151], 0, s[74:75]
	ds_read_b32 v141, v160 offset:736
	ds_read_b128 v[114:117], v161 offset:5888
	ds_read_b128 v[176:179], v161 offset:5904
	s_waitcnt vmcnt(37)
	s_waitcnt lgkmcnt(3)
	v_cndmask_b32_e64 v143, 0, v143, s[8:9]
	v_pk_mul_f32 v[180:181], v[26:27], v[172:173] op_sel:[0,1]
	v_pk_mul_f32 v[192:193], v[28:29], v[172:173] op_sel:[0,1]
	v_mfma_f32_16x16x4_f32 v[110:113], v143, v42, v[110:113]
	v_pk_fma_f32 v[180:181], v[30:31], v[172:173], v[180:181] op_sel_hi:[1,0,1]
	v_pk_fma_f32 v[192:193], v[32:33], v[172:173], v[192:193] op_sel_hi:[1,0,1]
	v_pk_fma_f32 v[180:181], v[22:23], v[174:175], v[180:181] op_sel_hi:[1,0,1]
	v_pk_fma_f32 v[192:193], v[24:25], v[174:175], v[192:193] op_sel_hi:[1,0,1]
	v_mfma_f32_16x16x4_f32 v[106:109], v143, v43, v[106:109]
	v_pk_fma_f32 v[180:181], v[18:19], v[174:175], v[180:181] op_sel:[0,1,0]
	v_pk_fma_f32 v[192:193], v[20:21], v[174:175], v[192:193] op_sel:[0,1,0]
	v_pk_fma_f32 v[180:181], v[14:15], v[232:233], v[180:181] op_sel_hi:[1,0,1]
	v_pk_fma_f32 v[192:193], v[16:17], v[232:233], v[192:193] op_sel_hi:[1,0,1]
	v_mfma_f32_16x16x4_f32 v[102:105], v143, v44, v[102:105]
	v_pk_fma_f32 v[180:181], v[10:11], v[232:233], v[180:181] op_sel:[0,1,0]
	v_pk_fma_f32 v[192:193], v[12:13], v[232:233], v[192:193] op_sel:[0,1,0]
	v_pk_fma_f32 v[180:181], v[6:7], v[234:235], v[180:181] op_sel_hi:[1,0,1]
	v_pk_fma_f32 v[192:193], v[8:9], v[234:235], v[192:193] op_sel_hi:[1,0,1]
	v_mfma_f32_16x16x4_f32 v[98:101], v143, v45, v[98:101]
	v_pk_fma_f32 v[180:181], v[2:3], v[234:235], v[180:181] op_sel:[0,1,0]
	v_pk_fma_f32 v[192:193], v[4:5], v[234:235], v[192:193] op_sel:[0,1,0]
	v_pk_mul_f32 v[180:181], v[146:147], v[180:181]
	v_pk_mul_f32 v[192:193], v[146:147], v[192:193]
	v_pk_fma_f32 v[236:237], v[144:145], v[42:43], v[180:181]
	v_pk_fma_f32 v[238:239], v[144:145], v[44:45], v[192:193]
	global_store_dwordx4 v[150:151], v[236:239], off nt
	v_lshl_add_u64 v[150:151], v[150:151], 0, s[74:75]
	ds_read_b32 v143, v160 offset:752
	ds_read_b128 v[172:175], v161 offset:6016
	ds_read_b128 v[232:235], v161 offset:6032
	s_waitcnt vmcnt(36)
; #define RS_LOAD(dst, it0) do { _Pragma("unroll") for (int u = 0; u < 8; ++u) dst[u] = __builtin_nontemporal_load((const f32x4*)(S0 + (size_t)(4 * ((it0) + u)) * DV)); } while (0)
; __device__ __forceinline__ void ret_sample_item(Frame& F, int item) {
;     ...
;     for (int it0 = 0; it0 < 64; it0 += 16) {
;         RS_LOAD(sb, it0 + 8);
;         RS_PROC(sa, it0);
;         { const int itn = it0 + 16 < 64 ? it0 + 16 : it0; RS_LOAD(sa, itn); }
;         RS_PROC(sb, it0 + 8);
;     }
	s_waitcnt lgkmcnt(3)
	v_cndmask_b32_e64 v141, 0, v141, s[8:9]
	v_pk_mul_f32 v[180:181], v[26:27], v[114:115] op_sel:[0,1]
	v_pk_mul_f32 v[192:193], v[28:29], v[114:115] op_sel:[0,1]
	v_mfma_f32_16x16x4_f32 v[110:113], v141, v38, v[110:113]
	v_pk_fma_f32 v[180:181], v[30:31], v[114:115], v[180:181] op_sel_hi:[1,0,1]
	v_pk_fma_f32 v[192:193], v[32:33], v[114:115], v[192:193] op_sel_hi:[1,0,1]
	v_pk_fma_f32 v[180:181], v[22:23], v[116:117], v[180:181] op_sel_hi:[1,0,1]
	v_pk_fma_f32 v[192:193], v[24:25], v[116:117], v[192:193] op_sel_hi:[1,0,1]
	v_mfma_f32_16x16x4_f32 v[106:109], v141, v39, v[106:109]
	v_pk_fma_f32 v[180:181], v[18:19], v[116:117], v[180:181] op_sel:[0,1,0]
	v_pk_fma_f32 v[192:193], v[20:21], v[116:117], v[192:193] op_sel:[0,1,0]
	v_pk_fma_f32 v[180:181], v[14:15], v[176:177], v[180:181] op_sel_hi:[1,0,1]
	v_pk_fma_f32 v[192:193], v[16:17], v[176:177], v[192:193] op_sel_hi:[1,0,1]
	v_mfma_f32_16x16x4_f32 v[102:105], v141, v40, v[102:105]
	v_pk_fma_f32 v[180:181], v[10:11], v[176:177], v[180:181] op_sel:[0,1,0]
	v_pk_fma_f32 v[192:193], v[12:13], v[176:177], v[192:193] op_sel:[0,1,0]
	v_pk_fma_f32 v[180:181], v[6:7], v[178:179], v[180:181] op_sel_hi:[1,0,1]
	v_pk_fma_f32 v[192:193], v[8:9], v[178:179], v[192:193] op_sel_hi:[1,0,1]
	v_mfma_f32_16x16x4_f32 v[98:101], v141, v41, v[98:101]
	v_pk_fma_f32 v[180:181], v[2:3], v[178:179], v[180:181] op_sel:[0,1,0]
	v_pk_fma_f32 v[192:193], v[4:5], v[178:179], v[192:193] op_sel:[0,1,0]
	v_pk_mul_f32 v[180:181], v[146:147], v[180:181]
	v_pk_mul_f32 v[192:193], v[146:147], v[192:193]
	v_pk_fma_f32 v[236:237], v[144:145], v[38:39], v[180:181]
	v_pk_fma_f32 v[238:239], v[144:145], v[40:41], v[192:193]
	global_store_dwordx4 v[150:151], v[236:239], off nt
	v_lshl_add_u64 v[150:151], v[150:151], 0, s[74:75]
	ds_read_b32 v141, v160 offset:768
	ds_read_b128 v[114:117], v161 offset:6144
	ds_read_b128 v[176:179], v161 offset:6160
	s_waitcnt vmcnt(35)
	s_waitcnt lgkmcnt(3)
	v_cndmask_b32_e64 v143, 0, v143, s[8:9]
	v_pk_mul_f32 v[180:181], v[26:27], v[172:173] op_sel:[0,1]
	v_pk_mul_f32 v[192:193], v[28:29], v[172:173] op_sel:[0,1]
	v_mfma_f32_16x16x4_f32 v[110:113], v143, v34, v[110:113]
	v_pk_fma_f32 v[180:181], v[30:31], v[172:173], v[180:181] op_sel_hi:[1,0,1]
	v_pk_fma_f32 v[192:193], v[32:33], v[172:173], v[192:193] op_sel_hi:[1,0,1]
	v_pk_fma_f32 v[180:181], v[22:23], v[174:175], v[180:181] op_sel_hi:[1,0,1]
	v_pk_fma_f32 v[192:193], v[24:25], v[174:175], v[192:193] op_sel_hi:[1,0,1]
	v_mfma_f32_16x16x4_f32 v[106:109], v143, v35, v[106:109]
	v_pk_fma_f32 v[180:181], v[18:19], v[174:175], v[180:181] op_sel:[0,1,0]
	v_pk_fma_f32 v[192:193], v[20:21], v[174:175], v[192:193] op_sel:[0,1,0]
	v_pk_fma_f32 v[180:181], v[14:15], v[232:233], v[180:181] op_sel_hi:[1,0,1]
	v_pk_fma_f32 v[192:193], v[16:17], v[232:233], v[192:193] op_sel_hi:[1,0,1]
	v_mfma_f32_16x16x4_f32 v[102:105], v143, v36, v[102:105]
	v_pk_fma_f32 v[180:181], v[10:11], v[232:233], v[180:181] op_sel:[0,1,0]
	v_pk_fma_f32 v[192:193], v[12:13], v[232:233], v[192:193] op_sel:[0,1,0]
	v_pk_fma_f32 v[180:181], v[6:7], v[234:235], v[180:181] op_sel_hi:[1,0,1]
	v_pk_fma_f32 v[192:193], v[8:9], v[234:235], v[192:193] op_sel_hi:[1,0,1]
	v_mfma_f32_16x16x4_f32 v[98:101], v143, v37, v[98:101]
	v_pk_fma_f32 v[180:181], v[2:3], v[234:235], v[180:181] op_sel:[0,1,0]
	v_pk_fma_f32 v[192:193], v[4:5], v[234:235], v[192:193] op_sel:[0,1,0]
	v_pk_mul_f32 v[180:181], v[146:147], v[180:181]
	v_pk_mul_f32 v[192:193], v[146:147], v[192:193]
	v_pk_fma_f32 v[236:237], v[144:145], v[34:35], v[180:181]
	v_pk_fma_f32 v[238:239], v[144:145], v[36:37], v[192:193]
	global_store_dwordx4 v[150:151], v[236:239], off nt
	v_lshl_add_u64 v[150:151], v[150:151], 0, s[74:75]
	ds_read_b32 v143, v160 offset:784
	ds_read_b128 v[172:175], v161 offset:6272
	ds_read_b128 v[232:235], v161 offset:6288
	s_waitcnt vmcnt(34)
	s_waitcnt lgkmcnt(3)
	v_cndmask_b32_e64 v141, 0, v141, s[8:9]
	v_pk_mul_f32 v[180:181], v[26:27], v[114:115] op_sel:[0,1]
	v_pk_mul_f32 v[192:193], v[28:29], v[114:115] op_sel:[0,1]
	v_mfma_f32_16x16x4_f32 v[110:113], v141, v58, v[110:113]
	v_pk_fma_f32 v[180:181], v[30:31], v[114:115], v[180:181] op_sel_hi:[1,0,1]
	v_pk_fma_f32 v[192:193], v[32:33], v[114:115], v[192:193] op_sel_hi:[1,0,1]
	v_pk_fma_f32 v[180:181], v[22:23], v[116:117], v[180:181] op_sel_hi:[1,0,1]
	v_pk_fma_f32 v[192:193], v[24:25], v[116:117], v[192:193] op_sel_hi:[1,0,1]
	v_mfma_f32_16x16x4_f32 v[106:109], v141, v59, v[106:109]
	v_pk_fma_f32 v[180:181], v[18:19], v[116:117], v[180:181] op_sel:[0,1,0]
	v_pk_fma_f32 v[192:193], v[20:21], v[116:117], v[192:193] op_sel:[0,1,0]
	v_pk_fma_f32 v[180:181], v[14:15], v[176:177], v[180:181] op_sel_hi:[1,0,1]
	v_pk_fma_f32 v[192:193], v[16:17], v[176:177], v[192:193] op_sel_hi:[1,0,1]
	v_mfma_f32_16x16x4_f32 v[102:105], v141, v60, v[102:105]
	v_pk_fma_f32 v[180:181], v[10:11], v[176:177], v[180:181] op_sel:[0,1,0]
	v_pk_fma_f32 v[192:193], v[12:13], v[176:177], v[192:193] op_sel:[0,1,0]
	v_pk_fma_f32 v[180:181], v[6:7], v[178:179], v[180:181] op_sel_hi:[1,0,1]
	v_pk_fma_f32 v[192:193], v[8:9], v[178:179], v[192:193] op_sel_hi:[1,0,1]
	v_mfma_f32_16x16x4_f32 v[98:101], v141, v61, v[98:101]
	v_pk_fma_f32 v[180:181], v[2:3], v[178:179], v[180:181] op_sel:[0,1,0]
	v_pk_fma_f32 v[192:193], v[4:5], v[178:179], v[192:193] op_sel:[0,1,0]
	v_pk_mul_f32 v[180:181], v[146:147], v[180:181]
	v_pk_mul_f32 v[192:193], v[146:147], v[192:193]
	v_pk_fma_f32 v[236:237], v[144:145], v[58:59], v[180:181]
	v_pk_fma_f32 v[238:239], v[144:145], v[60:61], v[192:193]
	global_store_dwordx4 v[150:151], v[236:239], off nt
	v_lshl_add_u64 v[150:151], v[150:151], 0, s[74:75]
	ds_read_b32 v141, v160 offset:800
	ds_read_b128 v[114:117], v161 offset:6400
	ds_read_b128 v[176:179], v161 offset:6416
	s_waitcnt vmcnt(33)
; #define RS_LOAD(dst, it0) do { _Pragma("unroll") for (int u = 0; u < 8; ++u) dst[u] = __builtin_nontemporal_load((const f32x4*)(S0 + (size_t)(4 * ((it0) + u)) * DV)); } while (0)
; __device__ __forceinline__ void ret_sample_item(Frame& F, int item) {
;     ...
;     for (int it0 = 0; it0 < 64; it0 += 16) {
;         RS_LOAD(sb, it0 + 8);
;         RS_PROC(sa, it0);
;         { const int itn = it0 + 16 < 64 ? it0 + 16 : it0; RS_LOAD(sa, itn); }
;         RS_PROC(sb, it0 + 8);
;     }
	s_waitcnt lgkmcnt(3)
	v_cndmask_b32_e64 v143, 0, v143, s[8:9]
	v_pk_mul_f32 v[180:181], v[26:27], v[172:173] op_sel:[0,1]
	v_pk_mul_f32 v[192:193], v[28:29], v[172:173] op_sel:[0,1]
	v_mfma_f32_16x16x4_f32 v[110:113], v143, v66, v[110:113]
	v_pk_fma_f32 v[180:181], v[30:31], v[172:173], v[180:181] op_sel_hi:[1,0,1]
	v_pk_fma_f32 v[192:193], v[32:33], v[172:173], v[192:193] op_sel_hi:[1,0,1]
	v_pk_fma_f32 v[180:181], v[22:23], v[174:175], v[180:181] op_sel_hi:[1,0,1]
	v_pk_fma_f32 v[192:193], v[24:25], v[174:175], v[192:193] op_sel_hi:[1,0,1]
	v_mfma_f32_16x16x4_f32 v[106:109], v143, v67, v[106:109]
	v_pk_fma_f32 v[180:181], v[18:19], v[174:175], v[180:181] op_sel:[0,1,0]
	v_pk_fma_f32 v[192:193], v[20:21], v[174:175], v[192:193] op_sel:[0,1,0]
	v_pk_fma_f32 v[180:181], v[14:15], v[232:233], v[180:181] op_sel_hi:[1,0,1]
	v_pk_fma_f32 v[192:193], v[16:17], v[232:233], v[192:193] op_sel_hi:[1,0,1]
	v_mfma_f32_16x16x4_f32 v[102:105], v143, v68, v[102:105]
	v_pk_fma_f32 v[180:181], v[10:11], v[232:233], v[180:181] op_sel:[0,1,0]
	v_pk_fma_f32 v[192:193], v[12:13], v[232:233], v[192:193] op_sel:[0,1,0]
	v_pk_fma_f32 v[180:181], v[6:7], v[234:235], v[180:181] op_sel_hi:[1,0,1]
	v_pk_fma_f32 v[192:193], v[8:9], v[234:235], v[192:193] op_sel_hi:[1,0,1]
	v_mfma_f32_16x16x4_f32 v[98:101], v143, v69, v[98:101]
	v_pk_fma_f32 v[180:181], v[2:3], v[234:235], v[180:181] op_sel:[0,1,0]
	v_pk_fma_f32 v[192:193], v[4:5], v[234:235], v[192:193] op_sel:[0,1,0]
	v_pk_mul_f32 v[180:181], v[146:147], v[180:181]
	v_pk_mul_f32 v[192:193], v[146:147], v[192:193]
	v_pk_fma_f32 v[236:237], v[144:145], v[66:67], v[180:181]
	v_pk_fma_f32 v[238:239], v[144:145], v[68:69], v[192:193]
	global_store_dwordx4 v[150:151], v[236:239], off nt
	v_lshl_add_u64 v[150:151], v[150:151], 0, s[74:75]
	ds_read_b32 v143, v160 offset:816
	ds_read_b128 v[172:175], v161 offset:6528
	ds_read_b128 v[232:235], v161 offset:6544
	s_waitcnt vmcnt(32)
	s_waitcnt lgkmcnt(3)
	v_cndmask_b32_e64 v141, 0, v141, s[8:9]
	v_pk_mul_f32 v[180:181], v[26:27], v[114:115] op_sel:[0,1]
	v_pk_mul_f32 v[192:193], v[28:29], v[114:115] op_sel:[0,1]
	v_mfma_f32_16x16x4_f32 v[110:113], v141, v74, v[110:113]
	v_pk_fma_f32 v[180:181], v[30:31], v[114:115], v[180:181] op_sel_hi:[1,0,1]
	v_pk_fma_f32 v[192:193], v[32:33], v[114:115], v[192:193] op_sel_hi:[1,0,1]
	v_pk_fma_f32 v[180:181], v[22:23], v[116:117], v[180:181] op_sel_hi:[1,0,1]
	v_pk_fma_f32 v[192:193], v[24:25], v[116:117], v[192:193] op_sel_hi:[1,0,1]
	v_mfma_f32_16x16x4_f32 v[106:109], v141, v75, v[106:109]
	v_pk_fma_f32 v[180:181], v[18:19], v[116:117], v[180:181] op_sel:[0,1,0]
	v_pk_fma_f32 v[192:193], v[20:21], v[116:117], v[192:193] op_sel:[0,1,0]
	v_pk_fma_f32 v[180:181], v[14:15], v[176:177], v[180:181] op_sel_hi:[1,0,1]
	v_pk_fma_f32 v[192:193], v[16:17], v[176:177], v[192:193] op_sel_hi:[1,0,1]
	v_mfma_f32_16x16x4_f32 v[102:105], v141, v76, v[102:105]
	v_pk_fma_f32 v[180:181], v[10:11], v[176:177], v[180:181] op_sel:[0,1,0]
	v_pk_fma_f32 v[192:193], v[12:13], v[176:177], v[192:193] op_sel:[0,1,0]
	v_pk_fma_f32 v[180:181], v[6:7], v[178:179], v[180:181] op_sel_hi:[1,0,1]
	v_pk_fma_f32 v[192:193], v[8:9], v[178:179], v[192:193] op_sel_hi:[1,0,1]
	v_mfma_f32_16x16x4_f32 v[98:101], v141, v77, v[98:101]
	v_pk_fma_f32 v[180:181], v[2:3], v[178:179], v[180:181] op_sel:[0,1,0]
	v_pk_fma_f32 v[192:193], v[4:5], v[178:179], v[192:193] op_sel:[0,1,0]
	v_pk_mul_f32 v[180:181], v[146:147], v[180:181]
	v_pk_mul_f32 v[192:193], v[146:147], v[192:193]
	v_pk_fma_f32 v[236:237], v[144:145], v[74:75], v[180:181]
	v_pk_fma_f32 v[238:239], v[144:145], v[76:77], v[192:193]
	global_store_dwordx4 v[150:151], v[236:239], off nt
	v_lshl_add_u64 v[150:151], v[150:151], 0, s[74:75]
	ds_read_b32 v141, v160 offset:832
	ds_read_b128 v[114:117], v161 offset:6656
	ds_read_b128 v[176:179], v161 offset:6672
	s_waitcnt vmcnt(31)
	s_waitcnt lgkmcnt(3)
	v_cndmask_b32_e64 v143, 0, v143, s[8:9]
	v_pk_mul_f32 v[180:181], v[26:27], v[172:173] op_sel:[0,1]
	v_pk_mul_f32 v[192:193], v[28:29], v[172:173] op_sel:[0,1]
	v_mfma_f32_16x16x4_f32 v[110:113], v143, v78, v[110:113]
	v_pk_fma_f32 v[180:181], v[30:31], v[172:173], v[180:181] op_sel_hi:[1,0,1]
	v_pk_fma_f32 v[192:193], v[32:33], v[172:173], v[192:193] op_sel_hi:[1,0,1]
	v_pk_fma_f32 v[180:181], v[22:23], v[174:175], v[180:181] op_sel_hi:[1,0,1]
	v_pk_fma_f32 v[192:193], v[24:25], v[174:175], v[192:193] op_sel_hi:[1,0,1]
	v_mfma_f32_16x16x4_f32 v[106:109], v143, v79, v[106:109]
	v_pk_fma_f32 v[180:181], v[18:19], v[174:175], v[180:181] op_sel:[0,1,0]
	v_pk_fma_f32 v[192:193], v[20:21], v[174:175], v[192:193] op_sel:[0,1,0]
	v_pk_fma_f32 v[180:181], v[14:15], v[232:233], v[180:181] op_sel_hi:[1,0,1]
	v_pk_fma_f32 v[192:193], v[16:17], v[232:233], v[192:193] op_sel_hi:[1,0,1]
	v_mfma_f32_16x16x4_f32 v[102:105], v143, v80, v[102:105]
	v_pk_fma_f32 v[180:181], v[10:11], v[232:233], v[180:181] op_sel:[0,1,0]
	v_pk_fma_f32 v[192:193], v[12:13], v[232:233], v[192:193] op_sel:[0,1,0]
	v_pk_fma_f32 v[180:181], v[6:7], v[234:235], v[180:181] op_sel_hi:[1,0,1]
	v_pk_fma_f32 v[192:193], v[8:9], v[234:235], v[192:193] op_sel_hi:[1,0,1]
	v_mfma_f32_16x16x4_f32 v[98:101], v143, v81, v[98:101]
	v_pk_fma_f32 v[180:181], v[2:3], v[234:235], v[180:181] op_sel:[0,1,0]
	v_pk_fma_f32 v[192:193], v[4:5], v[234:235], v[192:193] op_sel:[0,1,0]
	v_pk_mul_f32 v[180:181], v[146:147], v[180:181]
	v_pk_mul_f32 v[192:193], v[146:147], v[192:193]
	v_pk_fma_f32 v[236:237], v[144:145], v[78:79], v[180:181]
	v_pk_fma_f32 v[238:239], v[144:145], v[80:81], v[192:193]
	global_store_dwordx4 v[150:151], v[236:239], off nt
	v_lshl_add_u64 v[150:151], v[150:151], 0, s[74:75]
	ds_read_b32 v143, v160 offset:848
	ds_read_b128 v[172:175], v161 offset:6784
	ds_read_b128 v[232:235], v161 offset:6800
	s_waitcnt vmcnt(30)
; #define RS_LOAD(dst, it0) do { _Pragma("unroll") for (int u = 0; u < 8; ++u) dst[u] = __builtin_nontemporal_load((const f32x4*)(S0 + (size_t)(4 * ((it0) + u)) * DV)); } while (0)
; __device__ __forceinline__ void ret_sample_item(Frame& F, int item) {
;     ...
;     for (int it0 = 0; it0 < 64; it0 += 16) {
;         RS_LOAD(sb, it0 + 8);
;         RS_PROC(sa, it0);
;         { const int itn = it0 + 16 < 64 ? it0 + 16 : it0; RS_LOAD(sa, itn); }
;         RS_PROC(sb, it0 + 8);
;     }
	s_waitcnt lgkmcnt(3)
	v_cndmask_b32_e64 v141, 0, v141, s[8:9]
	v_pk_mul_f32 v[180:181], v[26:27], v[114:115] op_sel:[0,1]
	v_pk_mul_f32 v[192:193], v[28:29], v[114:115] op_sel:[0,1]
	v_mfma_f32_16x16x4_f32 v[110:113], v141, v82, v[110:113]
	v_pk_fma_f32 v[180:181], v[30:31], v[114:115], v[180:181] op_sel_hi:[1,0,1]
	v_pk_fma_f32 v[192:193], v[32:33], v[114:115], v[192:193] op_sel_hi:[1,0,1]
	v_pk_fma_f32 v[180:181], v[22:23], v[116:117], v[180:181] op_sel_hi:[1,0,1]
	v_pk_fma_f32 v[192:193], v[24:25], v[116:117], v[192:193] op_sel_hi:[1,0,1]
	v_mfma_f32_16x16x4_f32 v[106:109], v141, v83, v[106:109]
	v_pk_fma_f32 v[180:181], v[18:19], v[116:117], v[180:181] op_sel:[0,1,0]
	v_pk_fma_f32 v[192:193], v[20:21], v[116:117], v[192:193] op_sel:[0,1,0]
	v_pk_fma_f32 v[180:181], v[14:15], v[176:177], v[180:181] op_sel_hi:[1,0,1]
	v_pk_fma_f32 v[192:193], v[16:17], v[176:177], v[192:193] op_sel_hi:[1,0,1]
	v_mfma_f32_16x16x4_f32 v[102:105], v141, v84, v[102:105]
	v_pk_fma_f32 v[180:181], v[10:11], v[176:177], v[180:181] op_sel:[0,1,0]
	v_pk_fma_f32 v[192:193], v[12:13], v[176:177], v[192:193] op_sel:[0,1,0]
	v_pk_fma_f32 v[180:181], v[6:7], v[178:179], v[180:181] op_sel_hi:[1,0,1]
	v_pk_fma_f32 v[192:193], v[8:9], v[178:179], v[192:193] op_sel_hi:[1,0,1]
	v_mfma_f32_16x16x4_f32 v[98:101], v141, v85, v[98:101]
	v_pk_fma_f32 v[180:181], v[2:3], v[178:179], v[180:181] op_sel:[0,1,0]
	v_pk_fma_f32 v[192:193], v[4:5], v[178:179], v[192:193] op_sel:[0,1,0]
	v_pk_mul_f32 v[180:181], v[146:147], v[180:181]
	v_pk_mul_f32 v[192:193], v[146:147], v[192:193]
	v_pk_fma_f32 v[236:237], v[144:145], v[82:83], v[180:181]
	v_pk_fma_f32 v[238:239], v[144:145], v[84:85], v[192:193]
	global_store_dwordx4 v[150:151], v[236:239], off nt
	v_lshl_add_u64 v[150:151], v[150:151], 0, s[74:75]
	ds_read_b32 v141, v160 offset:864
	ds_read_b128 v[114:117], v161 offset:6912
	ds_read_b128 v[176:179], v161 offset:6928
	s_waitcnt vmcnt(29)
	s_waitcnt lgkmcnt(3)
	v_cndmask_b32_e64 v143, 0, v143, s[8:9]
	v_pk_mul_f32 v[180:181], v[26:27], v[172:173] op_sel:[0,1]
	v_pk_mul_f32 v[192:193], v[28:29], v[172:173] op_sel:[0,1]
	v_mfma_f32_16x16x4_f32 v[110:113], v143, v86, v[110:113]
	v_pk_fma_f32 v[180:181], v[30:31], v[172:173], v[180:181] op_sel_hi:[1,0,1]
	v_pk_fma_f32 v[192:193], v[32:33], v[172:173], v[192:193] op_sel_hi:[1,0,1]
	v_pk_fma_f32 v[180:181], v[22:23], v[174:175], v[180:181] op_sel_hi:[1,0,1]
	v_pk_fma_f32 v[192:193], v[24:25], v[174:175], v[192:193] op_sel_hi:[1,0,1]
	v_mfma_f32_16x16x4_f32 v[106:109], v143, v87, v[106:109]
	v_pk_fma_f32 v[180:181], v[18:19], v[174:175], v[180:181] op_sel:[0,1,0]
	v_pk_fma_f32 v[192:193], v[20:21], v[174:175], v[192:193] op_sel:[0,1,0]
	v_pk_fma_f32 v[180:181], v[14:15], v[232:233], v[180:181] op_sel_hi:[1,0,1]
	v_pk_fma_f32 v[192:193], v[16:17], v[232:233], v[192:193] op_sel_hi:[1,0,1]
	v_mfma_f32_16x16x4_f32 v[102:105], v143, v88, v[102:105]
	v_pk_fma_f32 v[180:181], v[10:11], v[232:233], v[180:181] op_sel:[0,1,0]
	v_pk_fma_f32 v[192:193], v[12:13], v[232:233], v[192:193] op_sel:[0,1,0]
	v_pk_fma_f32 v[180:181], v[6:7], v[234:235], v[180:181] op_sel_hi:[1,0,1]
	v_pk_fma_f32 v[192:193], v[8:9], v[234:235], v[192:193] op_sel_hi:[1,0,1]
	v_mfma_f32_16x16x4_f32 v[98:101], v143, v89, v[98:101]
	v_pk_fma_f32 v[180:181], v[2:3], v[234:235], v[180:181] op_sel:[0,1,0]
	v_pk_fma_f32 v[192:193], v[4:5], v[234:235], v[192:193] op_sel:[0,1,0]
	v_pk_mul_f32 v[180:181], v[146:147], v[180:181]
	v_pk_mul_f32 v[192:193], v[146:147], v[192:193]
	v_pk_fma_f32 v[236:237], v[144:145], v[86:87], v[180:181]
	v_pk_fma_f32 v[238:239], v[144:145], v[88:89], v[192:193]
	global_store_dwordx4 v[150:151], v[236:239], off nt
	v_lshl_add_u64 v[150:151], v[150:151], 0, s[74:75]
	ds_read_b32 v143, v160 offset:880
	ds_read_b128 v[172:175], v161 offset:7040
	ds_read_b128 v[232:235], v161 offset:7056
	s_waitcnt vmcnt(28)
	s_waitcnt lgkmcnt(3)
	v_cndmask_b32_e64 v141, 0, v141, s[8:9]
	v_pk_mul_f32 v[180:181], v[26:27], v[114:115] op_sel:[0,1]
	v_pk_mul_f32 v[192:193], v[28:29], v[114:115] op_sel:[0,1]
	v_mfma_f32_16x16x4_f32 v[110:113], v141, v90, v[110:113]
	v_pk_fma_f32 v[180:181], v[30:31], v[114:115], v[180:181] op_sel_hi:[1,0,1]
	v_pk_fma_f32 v[192:193], v[32:33], v[114:115], v[192:193] op_sel_hi:[1,0,1]
	v_pk_fma_f32 v[180:181], v[22:23], v[116:117], v[180:181] op_sel_hi:[1,0,1]
	v_pk_fma_f32 v[192:193], v[24:25], v[116:117], v[192:193] op_sel_hi:[1,0,1]
	v_mfma_f32_16x16x4_f32 v[106:109], v141, v91, v[106:109]
	v_pk_fma_f32 v[180:181], v[18:19], v[116:117], v[180:181] op_sel:[0,1,0]
	v_pk_fma_f32 v[192:193], v[20:21], v[116:117], v[192:193] op_sel:[0,1,0]
	v_pk_fma_f32 v[180:181], v[14:15], v[176:177], v[180:181] op_sel_hi:[1,0,1]
	v_pk_fma_f32 v[192:193], v[16:17], v[176:177], v[192:193] op_sel_hi:[1,0,1]
	v_mfma_f32_16x16x4_f32 v[102:105], v141, v92, v[102:105]
	v_pk_fma_f32 v[180:181], v[10:11], v[176:177], v[180:181] op_sel:[0,1,0]
	v_pk_fma_f32 v[192:193], v[12:13], v[176:177], v[192:193] op_sel:[0,1,0]
	v_pk_fma_f32 v[180:181], v[6:7], v[178:179], v[180:181] op_sel_hi:[1,0,1]
	v_pk_fma_f32 v[192:193], v[8:9], v[178:179], v[192:193] op_sel_hi:[1,0,1]
	v_mfma_f32_16x16x4_f32 v[98:101], v141, v93, v[98:101]
	v_pk_fma_f32 v[180:181], v[2:3], v[178:179], v[180:181] op_sel:[0,1,0]
	v_pk_fma_f32 v[192:193], v[4:5], v[178:179], v[192:193] op_sel:[0,1,0]
	v_pk_mul_f32 v[180:181], v[146:147], v[180:181]
	v_pk_mul_f32 v[192:193], v[146:147], v[192:193]
	v_pk_fma_f32 v[236:237], v[144:145], v[90:91], v[180:181]
	v_pk_fma_f32 v[238:239], v[144:145], v[92:93], v[192:193]
	global_store_dwordx4 v[150:151], v[236:239], off nt
	v_lshl_add_u64 v[150:151], v[150:151], 0, s[74:75]
	ds_read_b32 v141, v160 offset:896
	ds_read_b128 v[114:117], v161 offset:7168
	ds_read_b128 v[176:179], v161 offset:7184
	s_waitcnt vmcnt(27)
; #define RS_LOAD(dst, it0) do { _Pragma("unroll") for (int u = 0; u < 8; ++u) dst[u] = __builtin_nontemporal_load((const f32x4*)(S0 + (size_t)(4 * ((it0) + u)) * DV)); } while (0)
; __device__ __forceinline__ void ret_sample_item(Frame& F, int item) {
;     ...
;     for (int it0 = 0; it0 < 64; it0 += 16) {
;         RS_LOAD(sb, it0 + 8);
;         RS_PROC(sa, it0);
;         { const int itn = it0 + 16 < 64 ? it0 + 16 : it0; RS_LOAD(sa, itn); }
;         RS_PROC(sb, it0 + 8);
;     }
	s_waitcnt lgkmcnt(3)
	v_cndmask_b32_e64 v143, 0, v143, s[8:9]
	v_pk_mul_f32 v[180:181], v[26:27], v[172:173] op_sel:[0,1]
	v_pk_mul_f32 v[192:193], v[28:29], v[172:173] op_sel:[0,1]
	v_mfma_f32_16x16x4_f32 v[110:113], v143, v94, v[110:113]
	v_pk_fma_f32 v[180:181], v[30:31], v[172:173], v[180:181] op_sel_hi:[1,0,1]
	v_pk_fma_f32 v[192:193], v[32:33], v[172:173], v[192:193] op_sel_hi:[1,0,1]
	v_pk_fma_f32 v[180:181], v[22:23], v[174:175], v[180:181] op_sel_hi:[1,0,1]
	v_pk_fma_f32 v[192:193], v[24:25], v[174:175], v[192:193] op_sel_hi:[1,0,1]
	v_mfma_f32_16x16x4_f32 v[106:109], v143, v95, v[106:109]
	v_pk_fma_f32 v[180:181], v[18:19], v[174:175], v[180:181] op_sel:[0,1,0]
	v_pk_fma_f32 v[192:193], v[20:21], v[174:175], v[192:193] op_sel:[0,1,0]
	v_pk_fma_f32 v[180:181], v[14:15], v[232:233], v[180:181] op_sel_hi:[1,0,1]
	v_pk_fma_f32 v[192:193], v[16:17], v[232:233], v[192:193] op_sel_hi:[1,0,1]
	v_mfma_f32_16x16x4_f32 v[102:105], v143, v96, v[102:105]
	v_pk_fma_f32 v[180:181], v[10:11], v[232:233], v[180:181] op_sel:[0,1,0]
	v_pk_fma_f32 v[192:193], v[12:13], v[232:233], v[192:193] op_sel:[0,1,0]
	v_pk_fma_f32 v[180:181], v[6:7], v[234:235], v[180:181] op_sel_hi:[1,0,1]
	v_pk_fma_f32 v[192:193], v[8:9], v[234:235], v[192:193] op_sel_hi:[1,0,1]
	v_mfma_f32_16x16x4_f32 v[98:101], v143, v97, v[98:101]
	v_pk_fma_f32 v[180:181], v[2:3], v[234:235], v[180:181] op_sel:[0,1,0]
	v_pk_fma_f32 v[192:193], v[4:5], v[234:235], v[192:193] op_sel:[0,1,0]
	v_pk_mul_f32 v[180:181], v[146:147], v[180:181]
	v_pk_mul_f32 v[192:193], v[146:147], v[192:193]
	v_pk_fma_f32 v[236:237], v[144:145], v[94:95], v[180:181]
	v_pk_fma_f32 v[238:239], v[144:145], v[96:97], v[192:193]
	global_store_dwordx4 v[150:151], v[236:239], off nt
	v_lshl_add_u64 v[150:151], v[150:151], 0, s[74:75]
	ds_read_b32 v143, v160 offset:912
	ds_read_b128 v[172:175], v161 offset:7296
	ds_read_b128 v[232:235], v161 offset:7312
	s_waitcnt vmcnt(26)
	s_waitcnt lgkmcnt(3)
	v_cndmask_b32_e64 v141, 0, v141, s[8:9]
	v_pk_mul_f32 v[180:181], v[26:27], v[114:115] op_sel:[0,1]
	v_pk_mul_f32 v[192:193], v[28:29], v[114:115] op_sel:[0,1]
	v_mfma_f32_16x16x4_f32 v[110:113], v141, v212, v[110:113]
	v_pk_fma_f32 v[180:181], v[30:31], v[114:115], v[180:181] op_sel_hi:[1,0,1]
	v_pk_fma_f32 v[192:193], v[32:33], v[114:115], v[192:193] op_sel_hi:[1,0,1]
	v_pk_fma_f32 v[180:181], v[22:23], v[116:117], v[180:181] op_sel_hi:[1,0,1]
	v_pk_fma_f32 v[192:193], v[24:25], v[116:117], v[192:193] op_sel_hi:[1,0,1]
	v_mfma_f32_16x16x4_f32 v[106:109], v141, v213, v[106:109]
	v_pk_fma_f32 v[180:181], v[18:19], v[116:117], v[180:181] op_sel:[0,1,0]
	v_pk_fma_f32 v[192:193], v[20:21], v[116:117], v[192:193] op_sel:[0,1,0]
	v_pk_fma_f32 v[180:181], v[14:15], v[176:177], v[180:181] op_sel_hi:[1,0,1]
	v_pk_fma_f32 v[192:193], v[16:17], v[176:177], v[192:193] op_sel_hi:[1,0,1]
	v_mfma_f32_16x16x4_f32 v[102:105], v141, v214, v[102:105]
	v_pk_fma_f32 v[180:181], v[10:11], v[176:177], v[180:181] op_sel:[0,1,0]
	v_pk_fma_f32 v[192:193], v[12:13], v[176:177], v[192:193] op_sel:[0,1,0]
	v_pk_fma_f32 v[180:181], v[6:7], v[178:179], v[180:181] op_sel_hi:[1,0,1]
	v_pk_fma_f32 v[192:193], v[8:9], v[178:179], v[192:193] op_sel_hi:[1,0,1]
	v_mfma_f32_16x16x4_f32 v[98:101], v141, v215, v[98:101]
	v_pk_fma_f32 v[180:181], v[2:3], v[178:179], v[180:181] op_sel:[0,1,0]
	v_pk_fma_f32 v[192:193], v[4:5], v[178:179], v[192:193] op_sel:[0,1,0]
	v_pk_mul_f32 v[180:181], v[146:147], v[180:181]
	v_pk_mul_f32 v[192:193], v[146:147], v[192:193]
	v_pk_fma_f32 v[236:237], v[144:145], v[212:213], v[180:181]
	v_pk_fma_f32 v[238:239], v[144:145], v[214:215], v[192:193]
	global_store_dwordx4 v[150:151], v[236:239], off nt
	v_lshl_add_u64 v[150:151], v[150:151], 0, s[74:75]
	ds_read_b32 v141, v160 offset:928
	ds_read_b128 v[114:117], v161 offset:7424
	ds_read_b128 v[176:179], v161 offset:7440
	s_waitcnt vmcnt(25)
	s_waitcnt lgkmcnt(3)
	v_cndmask_b32_e64 v143, 0, v143, s[8:9]
	v_pk_mul_f32 v[180:181], v[26:27], v[172:173] op_sel:[0,1]
	v_pk_mul_f32 v[192:193], v[28:29], v[172:173] op_sel:[0,1]
	v_mfma_f32_16x16x4_f32 v[110:113], v143, v216, v[110:113]
	v_pk_fma_f32 v[180:181], v[30:31], v[172:173], v[180:181] op_sel_hi:[1,0,1]
	v_pk_fma_f32 v[192:193], v[32:33], v[172:173], v[192:193] op_sel_hi:[1,0,1]
	v_pk_fma_f32 v[180:181], v[22:23], v[174:175], v[180:181] op_sel_hi:[1,0,1]
	v_pk_fma_f32 v[192:193], v[24:25], v[174:175], v[192:193] op_sel_hi:[1,0,1]
	v_mfma_f32_16x16x4_f32 v[106:109], v143, v217, v[106:109]
	v_pk_fma_f32 v[180:181], v[18:19], v[174:175], v[180:181] op_sel:[0,1,0]
	v_pk_fma_f32 v[192:193], v[20:21], v[174:175], v[192:193] op_sel:[0,1,0]
	v_pk_fma_f32 v[180:181], v[14:15], v[232:233], v[180:181] op_sel_hi:[1,0,1]
	v_pk_fma_f32 v[192:193], v[16:17], v[232:233], v[192:193] op_sel_hi:[1,0,1]
	v_mfma_f32_16x16x4_f32 v[102:105], v143, v218, v[102:105]
	v_pk_fma_f32 v[180:181], v[10:11], v[232:233], v[180:181] op_sel:[0,1,0]
	v_pk_fma_f32 v[192:193], v[12:13], v[232:233], v[192:193] op_sel:[0,1,0]
	v_pk_fma_f32 v[180:181], v[6:7], v[234:235], v[180:181] op_sel_hi:[1,0,1]
	v_pk_fma_f32 v[192:193], v[8:9], v[234:235], v[192:193] op_sel_hi:[1,0,1]
	v_mfma_f32_16x16x4_f32 v[98:101], v143, v219, v[98:101]
	v_pk_fma_f32 v[180:181], v[2:3], v[234:235], v[180:181] op_sel:[0,1,0]
	v_pk_fma_f32 v[192:193], v[4:5], v[234:235], v[192:193] op_sel:[0,1,0]
	v_pk_mul_f32 v[180:181], v[146:147], v[180:181]
	v_pk_mul_f32 v[192:193], v[146:147], v[192:193]
	v_pk_fma_f32 v[236:237], v[144:145], v[216:217], v[180:181]
	v_pk_fma_f32 v[238:239], v[144:145], v[218:219], v[192:193]
	global_store_dwordx4 v[150:151], v[236:239], off nt
	v_lshl_add_u64 v[150:151], v[150:151], 0, s[74:75]
	ds_read_b32 v143, v160 offset:944
	ds_read_b128 v[172:175], v161 offset:7552
	ds_read_b128 v[232:235], v161 offset:7568
	s_waitcnt vmcnt(24)
; #define RS_LOAD(dst, it0) do { _Pragma("unroll") for (int u = 0; u < 8; ++u) dst[u] = __builtin_nontemporal_load((const f32x4*)(S0 + (size_t)(4 * ((it0) + u)) * DV)); } while (0)
; __device__ __forceinline__ void ret_sample_item(Frame& F, int item) {
;     ...
;     for (int it0 = 0; it0 < 64; it0 += 16) {
;         RS_LOAD(sb, it0 + 8);
;         RS_PROC(sa, it0);
;         { const int itn = it0 + 16 < 64 ? it0 + 16 : it0; RS_LOAD(sa, itn); }
;         RS_PROC(sb, it0 + 8);
;     }
	s_waitcnt lgkmcnt(3)
	v_cndmask_b32_e64 v141, 0, v141, s[8:9]
	v_pk_mul_f32 v[180:181], v[26:27], v[114:115] op_sel:[0,1]
	v_pk_mul_f32 v[192:193], v[28:29], v[114:115] op_sel:[0,1]
	v_mfma_f32_16x16x4_f32 v[110:113], v141, v224, v[110:113]
	v_pk_fma_f32 v[180:181], v[30:31], v[114:115], v[180:181] op_sel_hi:[1,0,1]
	v_pk_fma_f32 v[192:193], v[32:33], v[114:115], v[192:193] op_sel_hi:[1,0,1]
	v_pk_fma_f32 v[180:181], v[22:23], v[116:117], v[180:181] op_sel_hi:[1,0,1]
	v_pk_fma_f32 v[192:193], v[24:25], v[116:117], v[192:193] op_sel_hi:[1,0,1]
	v_mfma_f32_16x16x4_f32 v[106:109], v141, v225, v[106:109]
	v_pk_fma_f32 v[180:181], v[18:19], v[116:117], v[180:181] op_sel:[0,1,0]
	v_pk_fma_f32 v[192:193], v[20:21], v[116:117], v[192:193] op_sel:[0,1,0]
	v_pk_fma_f32 v[180:181], v[14:15], v[176:177], v[180:181] op_sel_hi:[1,0,1]
	v_pk_fma_f32 v[192:193], v[16:17], v[176:177], v[192:193] op_sel_hi:[1,0,1]
	v_mfma_f32_16x16x4_f32 v[102:105], v141, v226, v[102:105]
	v_pk_fma_f32 v[180:181], v[10:11], v[176:177], v[180:181] op_sel:[0,1,0]
	v_pk_fma_f32 v[192:193], v[12:13], v[176:177], v[192:193] op_sel:[0,1,0]
	v_pk_fma_f32 v[180:181], v[6:7], v[178:179], v[180:181] op_sel_hi:[1,0,1]
	v_pk_fma_f32 v[192:193], v[8:9], v[178:179], v[192:193] op_sel_hi:[1,0,1]
	v_mfma_f32_16x16x4_f32 v[98:101], v141, v227, v[98:101]
	v_pk_fma_f32 v[180:181], v[2:3], v[178:179], v[180:181] op_sel:[0,1,0]
	v_pk_fma_f32 v[192:193], v[4:5], v[178:179], v[192:193] op_sel:[0,1,0]
	v_pk_mul_f32 v[180:181], v[146:147], v[180:181]
	v_pk_mul_f32 v[192:193], v[146:147], v[192:193]
	v_pk_fma_f32 v[236:237], v[144:145], v[224:225], v[180:181]
	v_pk_fma_f32 v[238:239], v[144:145], v[226:227], v[192:193]
	global_store_dwordx4 v[150:151], v[236:239], off nt
	v_lshl_add_u64 v[150:151], v[150:151], 0, s[74:75]
	ds_read_b32 v141, v160 offset:960
	ds_read_b128 v[114:117], v161 offset:7680
	ds_read_b128 v[176:179], v161 offset:7696
	s_waitcnt vmcnt(23)
	s_waitcnt lgkmcnt(3)
	v_cndmask_b32_e64 v143, 0, v143, s[8:9]
	v_pk_mul_f32 v[180:181], v[26:27], v[172:173] op_sel:[0,1]
	v_pk_mul_f32 v[192:193], v[28:29], v[172:173] op_sel:[0,1]
	v_mfma_f32_16x16x4_f32 v[110:113], v143, v228, v[110:113]
	v_pk_fma_f32 v[180:181], v[30:31], v[172:173], v[180:181] op_sel_hi:[1,0,1]
	v_pk_fma_f32 v[192:193], v[32:33], v[172:173], v[192:193] op_sel_hi:[1,0,1]
	v_pk_fma_f32 v[180:181], v[22:23], v[174:175], v[180:181] op_sel_hi:[1,0,1]
	v_pk_fma_f32 v[192:193], v[24:25], v[174:175], v[192:193] op_sel_hi:[1,0,1]
	v_mfma_f32_16x16x4_f32 v[106:109], v143, v229, v[106:109]
	v_pk_fma_f32 v[180:181], v[18:19], v[174:175], v[180:181] op_sel:[0,1,0]
	v_pk_fma_f32 v[192:193], v[20:21], v[174:175], v[192:193] op_sel:[0,1,0]
	v_pk_fma_f32 v[180:181], v[14:15], v[232:233], v[180:181] op_sel_hi:[1,0,1]
	v_pk_fma_f32 v[192:193], v[16:17], v[232:233], v[192:193] op_sel_hi:[1,0,1]
	v_mfma_f32_16x16x4_f32 v[102:105], v143, v230, v[102:105]
	v_pk_fma_f32 v[180:181], v[10:11], v[232:233], v[180:181] op_sel:[0,1,0]
	v_pk_fma_f32 v[192:193], v[12:13], v[232:233], v[192:193] op_sel:[0,1,0]
	v_pk_fma_f32 v[180:181], v[6:7], v[234:235], v[180:181] op_sel_hi:[1,0,1]
	v_pk_fma_f32 v[192:193], v[8:9], v[234:235], v[192:193] op_sel_hi:[1,0,1]
	v_mfma_f32_16x16x4_f32 v[98:101], v143, v231, v[98:101]
	v_pk_fma_f32 v[180:181], v[2:3], v[234:235], v[180:181] op_sel:[0,1,0]
	v_pk_fma_f32 v[192:193], v[4:5], v[234:235], v[192:193] op_sel:[0,1,0]
	v_pk_mul_f32 v[180:181], v[146:147], v[180:181]
	v_pk_mul_f32 v[192:193], v[146:147], v[192:193]
	v_pk_fma_f32 v[236:237], v[144:145], v[228:229], v[180:181]
	v_pk_fma_f32 v[238:239], v[144:145], v[230:231], v[192:193]
	global_store_dwordx4 v[150:151], v[236:239], off nt
	v_lshl_add_u64 v[150:151], v[150:151], 0, s[74:75]
	ds_read_b32 v143, v160 offset:976
	ds_read_b128 v[172:175], v161 offset:7808
	ds_read_b128 v[232:235], v161 offset:7824
	s_waitcnt vmcnt(22)
	s_waitcnt lgkmcnt(3)
	v_cndmask_b32_e64 v141, 0, v141, s[8:9]
	v_pk_mul_f32 v[180:181], v[26:27], v[114:115] op_sel:[0,1]
	v_pk_mul_f32 v[192:193], v[28:29], v[114:115] op_sel:[0,1]
	v_mfma_f32_16x16x4_f32 v[110:113], v141, v70, v[110:113]
	v_pk_fma_f32 v[180:181], v[30:31], v[114:115], v[180:181] op_sel_hi:[1,0,1]
	v_pk_fma_f32 v[192:193], v[32:33], v[114:115], v[192:193] op_sel_hi:[1,0,1]
	v_pk_fma_f32 v[180:181], v[22:23], v[116:117], v[180:181] op_sel_hi:[1,0,1]
	v_pk_fma_f32 v[192:193], v[24:25], v[116:117], v[192:193] op_sel_hi:[1,0,1]
	v_mfma_f32_16x16x4_f32 v[106:109], v141, v71, v[106:109]
	v_pk_fma_f32 v[180:181], v[18:19], v[116:117], v[180:181] op_sel:[0,1,0]
	v_pk_fma_f32 v[192:193], v[20:21], v[116:117], v[192:193] op_sel:[0,1,0]
	v_pk_fma_f32 v[180:181], v[14:15], v[176:177], v[180:181] op_sel_hi:[1,0,1]
	v_pk_fma_f32 v[192:193], v[16:17], v[176:177], v[192:193] op_sel_hi:[1,0,1]
	v_mfma_f32_16x16x4_f32 v[102:105], v141, v72, v[102:105]
	v_pk_fma_f32 v[180:181], v[10:11], v[176:177], v[180:181] op_sel:[0,1,0]
	v_pk_fma_f32 v[192:193], v[12:13], v[176:177], v[192:193] op_sel:[0,1,0]
	v_pk_fma_f32 v[180:181], v[6:7], v[178:179], v[180:181] op_sel_hi:[1,0,1]
	v_pk_fma_f32 v[192:193], v[8:9], v[178:179], v[192:193] op_sel_hi:[1,0,1]
	v_mfma_f32_16x16x4_f32 v[98:101], v141, v73, v[98:101]
	v_pk_fma_f32 v[180:181], v[2:3], v[178:179], v[180:181] op_sel:[0,1,0]
	v_pk_fma_f32 v[192:193], v[4:5], v[178:179], v[192:193] op_sel:[0,1,0]
	v_pk_mul_f32 v[180:181], v[146:147], v[180:181]
	v_pk_mul_f32 v[192:193], v[146:147], v[192:193]
	v_pk_fma_f32 v[236:237], v[144:145], v[70:71], v[180:181]
	v_pk_fma_f32 v[238:239], v[144:145], v[72:73], v[192:193]
	global_store_dwordx4 v[150:151], v[236:239], off nt
	v_lshl_add_u64 v[150:151], v[150:151], 0, s[74:75]
	ds_read_b32 v141, v160 offset:992
	ds_read_b128 v[114:117], v161 offset:7936
	ds_read_b128 v[176:179], v161 offset:7952
	s_waitcnt vmcnt(21)
; #define RS_LOAD(dst, it0) do { _Pragma("unroll") for (int u = 0; u < 8; ++u) dst[u] = __builtin_nontemporal_load((const f32x4*)(S0 + (size_t)(4 * ((it0) + u)) * DV)); } while (0)
; __device__ __forceinline__ void ret_sample_item(Frame& F, int item) {
;     ...
;     for (int it0 = 0; it0 < 64; it0 += 16) {
;         RS_LOAD(sb, it0 + 8);
;         RS_PROC(sa, it0);
;         { const int itn = it0 + 16 < 64 ? it0 + 16 : it0; RS_LOAD(sa, itn); }
;         RS_PROC(sb, it0 + 8);
;     }
	s_waitcnt lgkmcnt(3)
	v_cndmask_b32_e64 v143, 0, v143, s[8:9]
	v_pk_mul_f32 v[180:181], v[26:27], v[172:173] op_sel:[0,1]
	v_pk_mul_f32 v[192:193], v[28:29], v[172:173] op_sel:[0,1]
	v_mfma_f32_16x16x4_f32 v[110:113], v143, v62, v[110:113]
	v_pk_fma_f32 v[180:181], v[30:31], v[172:173], v[180:181] op_sel_hi:[1,0,1]
	v_pk_fma_f32 v[192:193], v[32:33], v[172:173], v[192:193] op_sel_hi:[1,0,1]
	v_pk_fma_f32 v[180:181], v[22:23], v[174:175], v[180:181] op_sel_hi:[1,0,1]
	v_pk_fma_f32 v[192:193], v[24:25], v[174:175], v[192:193] op_sel_hi:[1,0,1]
	v_mfma_f32_16x16x4_f32 v[106:109], v143, v63, v[106:109]
	v_pk_fma_f32 v[180:181], v[18:19], v[174:175], v[180:181] op_sel:[0,1,0]
	v_pk_fma_f32 v[192:193], v[20:21], v[174:175], v[192:193] op_sel:[0,1,0]
	v_pk_fma_f32 v[180:181], v[14:15], v[232:233], v[180:181] op_sel_hi:[1,0,1]
	v_pk_fma_f32 v[192:193], v[16:17], v[232:233], v[192:193] op_sel_hi:[1,0,1]
	v_mfma_f32_16x16x4_f32 v[102:105], v143, v64, v[102:105]
	v_pk_fma_f32 v[180:181], v[10:11], v[232:233], v[180:181] op_sel:[0,1,0]
	v_pk_fma_f32 v[192:193], v[12:13], v[232:233], v[192:193] op_sel:[0,1,0]
	v_pk_fma_f32 v[180:181], v[6:7], v[234:235], v[180:181] op_sel_hi:[1,0,1]
	v_pk_fma_f32 v[192:193], v[8:9], v[234:235], v[192:193] op_sel_hi:[1,0,1]
	v_mfma_f32_16x16x4_f32 v[98:101], v143, v65, v[98:101]
	v_pk_fma_f32 v[180:181], v[2:3], v[234:235], v[180:181] op_sel:[0,1,0]
	v_pk_fma_f32 v[192:193], v[4:5], v[234:235], v[192:193] op_sel:[0,1,0]
	v_pk_mul_f32 v[180:181], v[146:147], v[180:181]
	v_pk_mul_f32 v[192:193], v[146:147], v[192:193]
	v_pk_fma_f32 v[236:237], v[144:145], v[62:63], v[180:181]
	v_pk_fma_f32 v[238:239], v[144:145], v[64:65], v[192:193]
	global_store_dwordx4 v[150:151], v[236:239], off nt
	v_lshl_add_u64 v[150:151], v[150:151], 0, s[74:75]
	ds_read_b32 v143, v160 offset:1008
	ds_read_b128 v[172:175], v161 offset:8064
	ds_read_b128 v[232:235], v161 offset:8080
	s_waitcnt vmcnt(20)
	s_waitcnt lgkmcnt(3)
	v_cndmask_b32_e64 v141, 0, v141, s[8:9]
	v_pk_mul_f32 v[180:181], v[26:27], v[114:115] op_sel:[0,1]
	v_pk_mul_f32 v[192:193], v[28:29], v[114:115] op_sel:[0,1]
	v_mfma_f32_16x16x4_f32 v[110:113], v141, v54, v[110:113]
	v_pk_fma_f32 v[180:181], v[30:31], v[114:115], v[180:181] op_sel_hi:[1,0,1]
	v_pk_fma_f32 v[192:193], v[32:33], v[114:115], v[192:193] op_sel_hi:[1,0,1]
	v_pk_fma_f32 v[180:181], v[22:23], v[116:117], v[180:181] op_sel_hi:[1,0,1]
	v_pk_fma_f32 v[192:193], v[24:25], v[116:117], v[192:193] op_sel_hi:[1,0,1]
	v_mfma_f32_16x16x4_f32 v[106:109], v141, v55, v[106:109]
	v_pk_fma_f32 v[180:181], v[18:19], v[116:117], v[180:181] op_sel:[0,1,0]
	v_pk_fma_f32 v[192:193], v[20:21], v[116:117], v[192:193] op_sel:[0,1,0]
	v_pk_fma_f32 v[180:181], v[14:15], v[176:177], v[180:181] op_sel_hi:[1,0,1]
	v_pk_fma_f32 v[192:193], v[16:17], v[176:177], v[192:193] op_sel_hi:[1,0,1]
	v_mfma_f32_16x16x4_f32 v[102:105], v141, v56, v[102:105]
	v_pk_fma_f32 v[180:181], v[10:11], v[176:177], v[180:181] op_sel:[0,1,0]
	v_pk_fma_f32 v[192:193], v[12:13], v[176:177], v[192:193] op_sel:[0,1,0]
	v_pk_fma_f32 v[180:181], v[6:7], v[178:179], v[180:181] op_sel_hi:[1,0,1]
	v_pk_fma_f32 v[192:193], v[8:9], v[178:179], v[192:193] op_sel_hi:[1,0,1]
	v_mfma_f32_16x16x4_f32 v[98:101], v141, v57, v[98:101]
	v_pk_fma_f32 v[180:181], v[2:3], v[178:179], v[180:181] op_sel:[0,1,0]
	v_pk_fma_f32 v[192:193], v[4:5], v[178:179], v[192:193] op_sel:[0,1,0]
	v_pk_mul_f32 v[180:181], v[146:147], v[180:181]
	v_pk_mul_f32 v[192:193], v[146:147], v[192:193]
	v_pk_fma_f32 v[236:237], v[144:145], v[54:55], v[180:181]
	v_pk_fma_f32 v[238:239], v[144:145], v[56:57], v[192:193]
	global_store_dwordx4 v[150:151], v[236:239], off nt
	v_lshl_add_u64 v[150:151], v[150:151], 0, s[74:75]
	s_waitcnt vmcnt(19)
	s_waitcnt lgkmcnt(0)
	v_cndmask_b32_e64 v143, 0, v143, s[8:9]
	v_pk_mul_f32 v[180:181], v[26:27], v[172:173] op_sel:[0,1]
	v_pk_mul_f32 v[192:193], v[28:29], v[172:173] op_sel:[0,1]
	v_mfma_f32_16x16x4_f32 v[110:113], v143, v50, v[110:113]
	v_pk_fma_f32 v[180:181], v[30:31], v[172:173], v[180:181] op_sel_hi:[1,0,1]
	v_pk_fma_f32 v[192:193], v[32:33], v[172:173], v[192:193] op_sel_hi:[1,0,1]
	v_pk_fma_f32 v[180:181], v[22:23], v[174:175], v[180:181] op_sel_hi:[1,0,1]
	v_pk_fma_f32 v[192:193], v[24:25], v[174:175], v[192:193] op_sel_hi:[1,0,1]
	v_mfma_f32_16x16x4_f32 v[106:109], v143, v51, v[106:109]
	v_pk_fma_f32 v[180:181], v[18:19], v[174:175], v[180:181] op_sel:[0,1,0]
	v_pk_fma_f32 v[192:193], v[20:21], v[174:175], v[192:193] op_sel:[0,1,0]
	v_pk_fma_f32 v[180:181], v[14:15], v[232:233], v[180:181] op_sel_hi:[1,0,1]
	v_pk_fma_f32 v[192:193], v[16:17], v[232:233], v[192:193] op_sel_hi:[1,0,1]
	v_mfma_f32_16x16x4_f32 v[102:105], v143, v52, v[102:105]
	v_pk_fma_f32 v[180:181], v[10:11], v[232:233], v[180:181] op_sel:[0,1,0]
	v_pk_fma_f32 v[192:193], v[12:13], v[232:233], v[192:193] op_sel:[0,1,0]
	v_pk_fma_f32 v[180:181], v[6:7], v[234:235], v[180:181] op_sel_hi:[1,0,1]
	v_pk_fma_f32 v[192:193], v[8:9], v[234:235], v[192:193] op_sel_hi:[1,0,1]
	v_mfma_f32_16x16x4_f32 v[98:101], v143, v53, v[98:101]
	v_pk_fma_f32 v[180:181], v[2:3], v[234:235], v[180:181] op_sel:[0,1,0]
	v_pk_fma_f32 v[192:193], v[4:5], v[234:235], v[192:193] op_sel:[0,1,0]
	v_pk_mul_f32 v[180:181], v[146:147], v[180:181]
	v_pk_mul_f32 v[192:193], v[146:147], v[192:193]
	v_pk_fma_f32 v[236:237], v[144:145], v[50:51], v[180:181]
	v_pk_fma_f32 v[238:239], v[144:145], v[52:53], v[192:193]
	global_store_dwordx4 v[150:151], v[236:239], off nt
	v_lshl_add_u64 v[150:151], v[150:151], 0, s[74:75]
	s_nop 7
	s_nop 3
	s_branch .LBB0_618
	s_nop 0
	s_nop 0
	s_nop 0
	s_nop 0
	s_nop 0
	s_nop 0
	s_nop 0
	s_nop 0
	s_nop 0
	s_nop 0
	s_nop 0
	s_nop 0
	s_nop 0
	s_nop 0
	s_nop 0
	s_nop 0
	s_nop 0
	s_nop 0
	s_nop 0
	s_nop 0
	s_nop 0
	s_nop 0
	s_nop 0
	s_nop 0
	s_nop 0
	s_nop 0
	s_nop 0
	s_nop 0
	s_nop 0
	s_nop 0
	s_nop 0
	s_nop 0
	s_nop 0
	s_nop 0
	s_nop 0
	s_nop 0
	s_nop 0
	s_nop 0
	s_nop 0
	s_nop 0
	s_nop 0
	s_nop 0
	s_nop 0
	s_nop 0
	s_nop 0
	s_nop 0
	s_nop 0
	s_nop 0
	s_nop 0
	s_nop 0
	s_nop 0
	s_nop 0
	s_nop 0
	s_nop 0
	s_nop 0
	s_nop 0
	s_nop 0
	s_nop 0
	s_nop 0
	s_nop 0
	s_nop 0

; #define LAS __attribute__((address_space(3)))
; #define LBAR() do { asm volatile("s_waitcnt lgkmcnt(0)" ::: "memory"); __builtin_amdgcn_s_barrier(); asm volatile("" ::: "memory"); } while (0)
; __device__ __forceinline__ void ret_sample_item(Frame& F, int item) {
;     ...
;     const int tq8 = (tid & 255) >> 5, d0 = 8 * (tid & 31); const bool isq = tid < 256;
;     const u32x4 rawqk = *(const u32x4*)((isq ? WSP(bf16, WS_Q) : WSP(bf16, WS_K)) + (size_t)(r0 + tq8) * D + h * DK + d0);
;     const int tv = tid >> 6, e0 = 8 * (tid & 63);
;     const u32x4 rawv = *(const u32x4*)(WSP(bf16, WS_V) + (size_t)(r0 + tv) * HV + h * DV + e0);
; #pragma unroll
;     for (int u = 0; u < 8; ++u) sa[u] = __builtin_nontemporal_load((const f32x4*)(S0 + (size_t)(4 * u) * DV));
;     LBAR();
;     { float f[8];
; #pragma unroll
;       for (int i = 0; i < 4; ++i) { f[2 * i] = __uint_as_float(rawqk[i] << 16); f[2 * i + 1] = __uint_as_float(rawqk[i] & 0xffff0000u); }
;       if (isq) { *(LAS f32x4*)(qs + tq8 * 260 + d0) = (f32x4){f[0], f[1], f[2], f[3]}; *(LAS f32x4*)(qs + tq8 * 260 + d0 + 4) = (f32x4){f[4], f[5], f[6], f[7]}; }
;       else {
; #pragma unroll
;           for (int i = 0; i < 8; ++i) kt[(d0 + i) * 8 + tq8] = f[i]; } }
;     { f32x4 lo, hi;
; #pragma unroll
;       for (int i = 0; i < 2; ++i) { lo[2 * i] = __uint_as_float(rawv[i] << 16); lo[2 * i + 1] = __uint_as_float(rawv[i] & 0xffff0000u); hi[2 * i] = __uint_as_float(rawv[i + 2] << 16); hi[2 * i + 1] = __uint_as_float(rawv[i + 2] & 0xffff0000u); }
;       *(LAS f32x4*)(vs + tv * 512 + e0) = lo; *(LAS f32x4*)(vs + tv * 512 + e0 + 4) = hi; }
;     LBAR();
.LBB0_635:
	s_ashr_i32 s39, s38, 31
	s_and_b32 s84, s38, -8
	s_lshl_b64 s[56:57], s[38:39], 19
	s_addk_i32 s84, 0x2000
	v_lshl_or_b32 v2, v118, 2, s56
	v_mov_b32_e32 v3, s57
	v_lshl_add_u64 v[136:137], v[124:125], 0, v[2:3]
	v_or_b32_e32 v2, s84, v182
	v_ashrrev_i32_e32 v3, 31, v2
	s_and_b32 s10, s38, 7
	v_lshlrev_b64 v[2:3], 12, v[2:3]
	v_lshl_add_u64 v[2:3], v[126:127], 0, v[2:3]
	s_lshl_b32 s56, s10, 9
	s_mov_b32 s57, s19
	v_lshl_add_u64 v[2:3], v[2:3], 0, s[56:57]
	v_lshl_add_u64 v[2:3], v[2:3], 0, v[120:121]
	global_load_dwordx4 v[10:13], v[2:3], off
	v_add_u32_e32 v238, s84, v183
	v_ashrrev_i32_e32 v239, 31, v238
	v_lshlrev_b64 v[238:239], 13, v[238:239]
	v_lshl_add_u64 v[238:239], s[16:17], 0, v[238:239]
	s_lshl_b32 s18, s10, 10
	v_lshl_add_u64 v[238:239], v[238:239], 0, s[18:19]
	v_lshl_add_u64 v[238:239], v[238:239], 0, v[132:133]
	global_load_dwordx4 v[2:5], v[238:239], off
	global_load_dwordx4 v[70:73], v[136:137], off nt
	v_add_co_u32_e32 v210, vcc, s33, v136
	s_nop 0
	v_addc_co_u32_e32 v211, vcc, 0, v137, vcc
	global_load_dwordx4 v[62:65], v[210:211], off nt
	v_add_co_u32_e32 v214, vcc, s35, v136
	s_nop 0
	v_addc_co_u32_e32 v215, vcc, 0, v137, vcc
	global_load_dwordx4 v[54:57], v[214:215], off nt
	v_add_co_u32_e32 v210, vcc, s70, v136
	s_nop 0
	v_addc_co_u32_e32 v211, vcc, 0, v137, vcc
	global_load_dwordx4 v[50:53], v[210:211], off nt
	v_add_co_u32_e32 v214, vcc, s71, v136
	s_nop 0
	v_addc_co_u32_e32 v215, vcc, 0, v137, vcc
	global_load_dwordx4 v[46:49], v[214:215], off nt
	v_add_co_u32_e32 v210, vcc, s72, v136
	s_nop 0
	v_addc_co_u32_e32 v211, vcc, 0, v137, vcc
	global_load_dwordx4 v[42:45], v[210:211], off nt
	v_add_co_u32_e32 v214, vcc, s73, v136
	s_nop 0
	v_addc_co_u32_e32 v215, vcc, 0, v137, vcc
	global_load_dwordx4 v[38:41], v[214:215], off nt
	v_add_co_u32_e32 v210, vcc, s74, v136
	s_nop 0
	v_addc_co_u32_e32 v211, vcc, 0, v137, vcc
	global_load_dwordx4 v[34:37], v[210:211], off nt
	s_waitcnt lgkmcnt(0)
	s_barrier
	s_waitcnt vmcnt(9)
	v_lshlrev_b32_e32 v6, 16, v10
	v_and_b32_e32 v7, 0xffff0000, v10
	v_lshlrev_b32_e32 v8, 16, v11
	v_and_b32_e32 v9, 0xffff0000, v11
	v_lshlrev_b32_e32 v10, 16, v12
	v_and_b32_e32 v11, 0xffff0000, v12
	v_lshlrev_b32_e32 v12, 16, v13
	v_and_b32_e32 v13, 0xffff0000, v13
	s_and_saveexec_b64 s[58:59], s[0:1]
	s_xor_b64 s[58:59], exec, s[58:59]
	s_cbranch_execz .LBB0_637
	v_add_u32_e32 v14, 0x2000, v162
	ds_write2_b32 v14, v6, v7 offset0:32 offset1:40
	ds_write2_b32 v14, v8, v9 offset0:48 offset1:56
	ds_write2_b32 v14, v10, v11 offset0:64 offset1:72
	ds_write2_b32 v14, v12, v13 offset0:80 offset1:88

; #define LAS __attribute__((address_space(3)))
; #define LBAR() do { asm volatile("s_waitcnt lgkmcnt(0)" ::: "memory"); __builtin_amdgcn_s_barrier(); asm volatile("" ::: "memory"); } while (0)
; __device__ __forceinline__ void ret_sample_item(Frame& F, int item) {
;     ...
;     { f32x4 lo, hi;
; #pragma unroll
;       for (int i = 0; i < 2; ++i) { lo[2 * i] = __uint_as_float(rawv[i] << 16); lo[2 * i + 1] = __uint_as_float(rawv[i] & 0xffff0000u); hi[2 * i] = __uint_as_float(rawv[i + 2] << 16); hi[2 * i + 1] = __uint_as_float(rawv[i + 2] & 0xffff0000u); }
;       *(LAS f32x4*)(vs + tv * 512 + e0) = lo; *(LAS f32x4*)(vs + tv * 512 + e0 + 4) = hi; }
;     LBAR();
.LBB0_639:
	s_or_b64 exec, exec, s[58:59]
	s_waitcnt vmcnt(8)
	v_lshlrev_b32_e32 v6, 16, v2
	v_and_b32_e32 v7, 0xffff0000, v2
	v_lshlrev_b32_e32 v8, 16, v3
	v_and_b32_e32 v9, 0xffff0000, v3
	v_lshlrev_b32_e32 v10, 16, v4
	v_and_b32_e32 v11, 0xffff0000, v4
	v_lshlrev_b32_e32 v12, 16, v5
	v_and_b32_e32 v13, 0xffff0000, v5
	ds_write_b128 v164, v[6:9] offset:16512
	ds_write_b128 v164, v[10:13] offset:16528
	s_waitcnt lgkmcnt(0)
	s_barrier
	v_mov_b32_e32 v2, 0
	s_mov_b32 s18, 0
	v_mov_b32_e32 v3, v158

; #define LAS __attribute__((address_space(3)))
; #define LBAR() do { asm volatile("s_waitcnt lgkmcnt(0)" ::: "memory"); __builtin_amdgcn_s_barrier(); asm volatile("" ::: "memory"); } while (0)
; #define RS_LOAD(dst, it0) do { _Pragma("unroll") for (int u = 0; u < 8; ++u) dst[u] = __builtin_nontemporal_load((const f32x4*)(S0 + (size_t)(4 * ((it0) + u)) * DV)); } while (0)
; __device__ __forceinline__ void ret_sample_item(Frame& F, int item) {
;     ...
;     const float gam = 1.0f - exp2f(-5.0f - (float)h);
;     const float g7 = exp2f(7.0f * log2f(gam)), g8 = g7 * gam;
;     ...
;     { const int n = lane >> 3, m = lane & 7; float sx = 0.f;
; #pragma unroll 8
;       for (int d = 32 * w; d < 32 * w + 32; ++d) sx += qs[n * 260 + d] * kt[d * 8 + m];
;       part[w * 64 + lane] = sx; }
;     LBAR();
;     if (tid < 64) { float sx = 0.f;
; #pragma unroll
;         for (int i = 0; i < 8; ++i) sx += part[i * 64 + tid];
;         pm[tid] = (tid & 7) <= (tid >> 3) ? sx : 0.f; }
;     LBAR();
;     f32x4 v4[8];
; #pragma unroll
;     for (int m = 0; m < 8; ++m) v4[m] = *(const LAS f32x4*)(vs + m * 512 + e4);
;     f32x4 oacc[4];
; #pragma unroll
;     for (int i = 0; i < 4; ++i) oacc[i] = (f32x4){0.f, 0.f, 0.f, 0.f};
;     ...
;     for (int it0 = 0; it0 < 64; it0 += 16) {
;         RS_LOAD(sb, it0 + 8);
;         RS_PROC(sa, it0);
;         { const int itn = it0 + 16 < 64 ? it0 + 16 : it0; RS_LOAD(sa, itn); }
;         RS_PROC(sb, it0 + 8);
;     }
.LBB0_643:
	s_or_b64 exec, exec, s[58:59]
	v_cvt_f32_ubyte0_e32 v2, s10
	v_sub_f32_e32 v2, 0xc0a00000, v2
	v_cmp_gt_f32_e32 vcc, s75, v2
	s_and_b64 s[58:59], vcc, exec
	s_cselect_b32 s10, 0xffffffc0, 0
	v_cndmask_b32_e32 v3, 0, v169, vcc
	v_add_f32_e32 v2, v2, v3
	v_exp_f32_e32 v2, v2
	s_waitcnt lgkmcnt(0)
	s_barrier
	v_ldexp_f32 v2, v2, s10
	v_sub_f32_e32 v138, 1.0, v2
	v_cmp_gt_f32_e32 vcc, s76, v138
	s_and_b64 s[58:59], vcc, exec
	s_cselect_b32 s10, 32, 0
	v_ldexp_f32 v3, v138, s10
	v_log_f32_e32 v3, v3
	v_cndmask_b32_e32 v2, 0, v170, vcc
	v_mov_b32_e32 v98, 0
	s_mov_b32 s10, 0
	v_sub_f32_e32 v2, v3, v2
	v_mul_f32_e32 v3, 0x40e00000, v2
	v_cmp_gt_f32_e32 vcc, s75, v3
	s_and_b64 s[58:59], vcc, exec
	s_cselect_b32 s18, 0xffffffc0, 0
	v_cndmask_b32_e32 v3, 0, v169, vcc
	v_fmac_f32_e32 v3, 0x40e00000, v2
	v_exp_f32_e32 v2, v3
	v_mov_b64_e32 v[148:149], v[130:131]
	v_mov_b64_e32 v[150:151], v[128:129]
	v_mov_b32_e32 v171, v161
	v_ldexp_f32 v140, v2, s18
	ds_read_b128 v[30:33], v139 offset:16512
	ds_read_b128 v[26:29], v139 offset:18560
	ds_read_b128 v[22:25], v139 offset:20608
	ds_read_b128 v[18:21], v139 offset:22656
	ds_read_b128 v[14:17], v139 offset:24704
	ds_read_b128 v[10:13], v139 offset:26752
	ds_read_b128 v[6:9], v139 offset:28800
	ds_read_b128 v[2:5], v139 offset:30848
	v_mul_f32_e32 v142, v138, v140
	v_mov_b32_e32 v144, v142
	v_mov_b32_e32 v145, v142
	v_mov_b32_e32 v146, v140
	v_mov_b32_e32 v147, v140
	v_mov_b32_e32 v172, v160
	v_mov_b32_e32 v99, v98
	v_mov_b32_e32 v100, v98
	v_mov_b32_e32 v101, v98
	v_mov_b32_e32 v102, v98
	v_mov_b32_e32 v103, v98
	v_mov_b32_e32 v104, v98
	v_mov_b32_e32 v105, v98
	v_mov_b32_e32 v106, v98
	v_mov_b32_e32 v107, v98
	v_mov_b32_e32 v108, v98
	v_mov_b32_e32 v109, v98
	v_mov_b32_e32 v110, v98
	v_mov_b32_e32 v111, v98
	v_mov_b32_e32 v112, v98
	v_mov_b32_e32 v113, v98
	v_lshl_add_u64 v[148:149], v[130:131], 0, v[122:123]
	v_lshl_add_u64 v[150:151], v[128:129], 0, v[122:123]
	s_mov_b32 s58, 0x10000
	s_mov_b32 s59, 0
	v_add_co_u32_e32 v150, vcc, 0x5878000, v150
	v_lshl_add_u64 v[148:149], v[148:149], 0, s[58:59]
	s_mov_b32 s58, 0x2000
	v_addc_co_u32_e32 v151, vcc, 0, v151, vcc
	ds_read_b32 v141, v160
	ds_read_b128 v[114:117], v161
	ds_read_b128 v[176:179], v161 offset:16
	global_load_dwordx4 v[58:61], v[148:149], off nt
	v_lshl_add_u64 v[148:149], v[148:149], 0, s[58:59]
	global_load_dwordx4 v[66:69], v[148:149], off nt
	v_lshl_add_u64 v[148:149], v[148:149], 0, s[58:59]
	global_load_dwordx4 v[74:77], v[148:149], off nt
	v_lshl_add_u64 v[148:149], v[148:149], 0, s[58:59]
	global_load_dwordx4 v[78:81], v[148:149], off nt
	v_lshl_add_u64 v[148:149], v[148:149], 0, s[58:59]
	global_load_dwordx4 v[82:85], v[148:149], off nt
	v_lshl_add_u64 v[148:149], v[148:149], 0, s[58:59]
	global_load_dwordx4 v[86:89], v[148:149], off nt
	v_lshl_add_u64 v[148:149], v[148:149], 0, s[58:59]
	global_load_dwordx4 v[90:93], v[148:149], off nt
	v_lshl_add_u64 v[148:149], v[148:149], 0, s[58:59]
	global_load_dwordx4 v[94:97], v[148:149], off nt
	v_lshl_add_u64 v[148:149], v[148:149], 0, s[58:59]
	global_load_dwordx4 v[212:215], v[148:149], off nt
	v_lshl_add_u64 v[148:149], v[148:149], 0, s[58:59]
	global_load_dwordx4 v[216:219], v[148:149], off nt
	v_lshl_add_u64 v[148:149], v[148:149], 0, s[58:59]
	global_load_dwordx4 v[224:227], v[148:149], off nt
	v_lshl_add_u64 v[148:149], v[148:149], 0, s[58:59]
	global_load_dwordx4 v[228:231], v[148:149], off nt
	v_lshl_add_u64 v[148:149], v[148:149], 0, s[58:59]
	ds_read_b32 v143, v160 offset:16
	ds_read_b128 v[172:175], v161 offset:128
	ds_read_b128 v[232:235], v161 offset:144
	s_waitcnt vmcnt(19)
	s_waitcnt lgkmcnt(3)
	v_cndmask_b32_e64 v141, 0, v141, s[6:7]
	v_pk_mul_f32 v[180:181], v[26:27], v[114:115] op_sel:[0,1]
	v_pk_mul_f32 v[192:193], v[28:29], v[114:115] op_sel:[0,1]
	v_mfma_f32_16x16x4_f32 v[110:113], v141, v70, v[110:113]
	v_pk_fma_f32 v[180:181], v[30:31], v[114:115], v[180:181] op_sel_hi:[1,0,1]
	v_pk_fma_f32 v[192:193], v[32:33], v[114:115], v[192:193] op_sel_hi:[1,0,1]
	v_pk_fma_f32 v[180:181], v[22:23], v[116:117], v[180:181] op_sel_hi:[1,0,1]
	v_pk_fma_f32 v[192:193], v[24:25], v[116:117], v[192:193] op_sel_hi:[1,0,1]
	v_mfma_f32_16x16x4_f32 v[106:109], v141, v71, v[106:109]
	v_pk_fma_f32 v[180:181], v[18:19], v[116:117], v[180:181] op_sel:[0,1,0]
	v_pk_fma_f32 v[192:193], v[20:21], v[116:117], v[192:193] op_sel:[0,1,0]
	v_pk_fma_f32 v[180:181], v[14:15], v[176:177], v[180:181] op_sel_hi:[1,0,1]
	v_pk_fma_f32 v[192:193], v[16:17], v[176:177], v[192:193] op_sel_hi:[1,0,1]
	v_mfma_f32_16x16x4_f32 v[102:105], v141, v72, v[102:105]
	v_pk_fma_f32 v[180:181], v[10:11], v[176:177], v[180:181] op_sel:[0,1,0]
	v_pk_fma_f32 v[192:193], v[12:13], v[176:177], v[192:193] op_sel:[0,1,0]
	v_pk_fma_f32 v[180:181], v[6:7], v[178:179], v[180:181] op_sel_hi:[1,0,1]
	v_pk_fma_f32 v[192:193], v[8:9], v[178:179], v[192:193] op_sel_hi:[1,0,1]
	v_mfma_f32_16x16x4_f32 v[98:101], v141, v73, v[98:101]
	v_pk_fma_f32 v[180:181], v[2:3], v[178:179], v[180:181] op_sel:[0,1,0]
	v_pk_fma_f32 v[192:193], v[4:5], v[178:179], v[192:193] op_sel:[0,1,0]
	v_pk_mul_f32 v[180:181], v[146:147], v[180:181]
	v_pk_mul_f32 v[192:193], v[146:147], v[192:193]
	v_pk_fma_f32 v[236:237], v[144:145], v[70:71], v[180:181]
	v_pk_fma_f32 v[238:239], v[144:145], v[72:73], v[192:193]
	global_store_dwordx4 v[150:151], v[236:239], off nt
	v_lshl_add_u64 v[150:151], v[150:151], 0, s[58:59]
	global_load_dwordx4 v[70:73], v[148:149], off nt
	v_lshl_add_u64 v[148:149], v[148:149], 0, s[58:59]
	ds_read_b32 v141, v160 offset:32
	ds_read_b128 v[114:117], v161 offset:256
	ds_read_b128 v[176:179], v161 offset:272
	s_waitcnt vmcnt(20)
; #define RS_LOAD(dst, it0) do { _Pragma("unroll") for (int u = 0; u < 8; ++u) dst[u] = __builtin_nontemporal_load((const f32x4*)(S0 + (size_t)(4 * ((it0) + u)) * DV)); } while (0)
; __device__ __forceinline__ void ret_sample_item(Frame& F, int item) {
;     ...
;     for (int it0 = 0; it0 < 64; it0 += 16) {
;         RS_LOAD(sb, it0 + 8);
;         RS_PROC(sa, it0);
;         { const int itn = it0 + 16 < 64 ? it0 + 16 : it0; RS_LOAD(sa, itn); }
;         RS_PROC(sb, it0 + 8);
;     }
	s_waitcnt lgkmcnt(3)
	v_cndmask_b32_e64 v143, 0, v143, s[6:7]
	v_pk_mul_f32 v[180:181], v[26:27], v[172:173] op_sel:[0,1]
	v_pk_mul_f32 v[192:193], v[28:29], v[172:173] op_sel:[0,1]
	v_mfma_f32_16x16x4_f32 v[110:113], v143, v62, v[110:113]
	v_pk_fma_f32 v[180:181], v[30:31], v[172:173], v[180:181] op_sel_hi:[1,0,1]
	v_pk_fma_f32 v[192:193], v[32:33], v[172:173], v[192:193] op_sel_hi:[1,0,1]
	v_pk_fma_f32 v[180:181], v[22:23], v[174:175], v[180:181] op_sel_hi:[1,0,1]
	v_pk_fma_f32 v[192:193], v[24:25], v[174:175], v[192:193] op_sel_hi:[1,0,1]
	v_mfma_f32_16x16x4_f32 v[106:109], v143, v63, v[106:109]
	v_pk_fma_f32 v[180:181], v[18:19], v[174:175], v[180:181] op_sel:[0,1,0]
	v_pk_fma_f32 v[192:193], v[20:21], v[174:175], v[192:193] op_sel:[0,1,0]
	v_pk_fma_f32 v[180:181], v[14:15], v[232:233], v[180:181] op_sel_hi:[1,0,1]
	v_pk_fma_f32 v[192:193], v[16:17], v[232:233], v[192:193] op_sel_hi:[1,0,1]
	v_mfma_f32_16x16x4_f32 v[102:105], v143, v64, v[102:105]
	v_pk_fma_f32 v[180:181], v[10:11], v[232:233], v[180:181] op_sel:[0,1,0]
	v_pk_fma_f32 v[192:193], v[12:13], v[232:233], v[192:193] op_sel:[0,1,0]
	v_pk_fma_f32 v[180:181], v[6:7], v[234:235], v[180:181] op_sel_hi:[1,0,1]
	v_pk_fma_f32 v[192:193], v[8:9], v[234:235], v[192:193] op_sel_hi:[1,0,1]
	v_mfma_f32_16x16x4_f32 v[98:101], v143, v65, v[98:101]
	v_pk_fma_f32 v[180:181], v[2:3], v[234:235], v[180:181] op_sel:[0,1,0]
	v_pk_fma_f32 v[192:193], v[4:5], v[234:235], v[192:193] op_sel:[0,1,0]
	v_pk_mul_f32 v[180:181], v[146:147], v[180:181]
	v_pk_mul_f32 v[192:193], v[146:147], v[192:193]
	v_pk_fma_f32 v[236:237], v[144:145], v[62:63], v[180:181]
	v_pk_fma_f32 v[238:239], v[144:145], v[64:65], v[192:193]
	global_store_dwordx4 v[150:151], v[236:239], off nt
	v_lshl_add_u64 v[150:151], v[150:151], 0, s[58:59]
	global_load_dwordx4 v[62:65], v[148:149], off nt
	v_lshl_add_u64 v[148:149], v[148:149], 0, s[58:59]
	ds_read_b32 v143, v160 offset:48
	ds_read_b128 v[172:175], v161 offset:384
	ds_read_b128 v[232:235], v161 offset:400
	s_waitcnt vmcnt(21)
	s_waitcnt lgkmcnt(3)
	v_cndmask_b32_e64 v141, 0, v141, s[6:7]
	v_pk_mul_f32 v[180:181], v[26:27], v[114:115] op_sel:[0,1]
	v_pk_mul_f32 v[192:193], v[28:29], v[114:115] op_sel:[0,1]
	v_mfma_f32_16x16x4_f32 v[110:113], v141, v54, v[110:113]
	v_pk_fma_f32 v[180:181], v[30:31], v[114:115], v[180:181] op_sel_hi:[1,0,1]
	v_pk_fma_f32 v[192:193], v[32:33], v[114:115], v[192:193] op_sel_hi:[1,0,1]
	v_pk_fma_f32 v[180:181], v[22:23], v[116:117], v[180:181] op_sel_hi:[1,0,1]
	v_pk_fma_f32 v[192:193], v[24:25], v[116:117], v[192:193] op_sel_hi:[1,0,1]
	v_mfma_f32_16x16x4_f32 v[106:109], v141, v55, v[106:109]
	v_pk_fma_f32 v[180:181], v[18:19], v[116:117], v[180:181] op_sel:[0,1,0]
	v_pk_fma_f32 v[192:193], v[20:21], v[116:117], v[192:193] op_sel:[0,1,0]
	v_pk_fma_f32 v[180:181], v[14:15], v[176:177], v[180:181] op_sel_hi:[1,0,1]
	v_pk_fma_f32 v[192:193], v[16:17], v[176:177], v[192:193] op_sel_hi:[1,0,1]
	v_mfma_f32_16x16x4_f32 v[102:105], v141, v56, v[102:105]
	v_pk_fma_f32 v[180:181], v[10:11], v[176:177], v[180:181] op_sel:[0,1,0]
	v_pk_fma_f32 v[192:193], v[12:13], v[176:177], v[192:193] op_sel:[0,1,0]
	v_pk_fma_f32 v[180:181], v[6:7], v[178:179], v[180:181] op_sel_hi:[1,0,1]
	v_pk_fma_f32 v[192:193], v[8:9], v[178:179], v[192:193] op_sel_hi:[1,0,1]
	v_mfma_f32_16x16x4_f32 v[98:101], v141, v57, v[98:101]
	v_pk_fma_f32 v[180:181], v[2:3], v[178:179], v[180:181] op_sel:[0,1,0]
	v_pk_fma_f32 v[192:193], v[4:5], v[178:179], v[192:193] op_sel:[0,1,0]
	v_pk_mul_f32 v[180:181], v[146:147], v[180:181]
	v_pk_mul_f32 v[192:193], v[146:147], v[192:193]
	v_pk_fma_f32 v[236:237], v[144:145], v[54:55], v[180:181]
	v_pk_fma_f32 v[238:239], v[144:145], v[56:57], v[192:193]
	global_store_dwordx4 v[150:151], v[236:239], off nt
	v_lshl_add_u64 v[150:151], v[150:151], 0, s[58:59]
	global_load_dwordx4 v[54:57], v[148:149], off nt
	v_lshl_add_u64 v[148:149], v[148:149], 0, s[58:59]
	ds_read_b32 v141, v160 offset:64
	ds_read_b128 v[114:117], v161 offset:512
	ds_read_b128 v[176:179], v161 offset:528
	s_waitcnt vmcnt(22)
	s_waitcnt lgkmcnt(3)
	v_cndmask_b32_e64 v143, 0, v143, s[6:7]
	v_pk_mul_f32 v[180:181], v[26:27], v[172:173] op_sel:[0,1]
	v_pk_mul_f32 v[192:193], v[28:29], v[172:173] op_sel:[0,1]
	v_mfma_f32_16x16x4_f32 v[110:113], v143, v50, v[110:113]
	v_pk_fma_f32 v[180:181], v[30:31], v[172:173], v[180:181] op_sel_hi:[1,0,1]
	v_pk_fma_f32 v[192:193], v[32:33], v[172:173], v[192:193] op_sel_hi:[1,0,1]
	v_pk_fma_f32 v[180:181], v[22:23], v[174:175], v[180:181] op_sel_hi:[1,0,1]
	v_pk_fma_f32 v[192:193], v[24:25], v[174:175], v[192:193] op_sel_hi:[1,0,1]
	v_mfma_f32_16x16x4_f32 v[106:109], v143, v51, v[106:109]
	v_pk_fma_f32 v[180:181], v[18:19], v[174:175], v[180:181] op_sel:[0,1,0]
	v_pk_fma_f32 v[192:193], v[20:21], v[174:175], v[192:193] op_sel:[0,1,0]
	v_pk_fma_f32 v[180:181], v[14:15], v[232:233], v[180:181] op_sel_hi:[1,0,1]
	v_pk_fma_f32 v[192:193], v[16:17], v[232:233], v[192:193] op_sel_hi:[1,0,1]
	v_mfma_f32_16x16x4_f32 v[102:105], v143, v52, v[102:105]
	v_pk_fma_f32 v[180:181], v[10:11], v[232:233], v[180:181] op_sel:[0,1,0]
	v_pk_fma_f32 v[192:193], v[12:13], v[232:233], v[192:193] op_sel:[0,1,0]
	v_pk_fma_f32 v[180:181], v[6:7], v[234:235], v[180:181] op_sel_hi:[1,0,1]
	v_pk_fma_f32 v[192:193], v[8:9], v[234:235], v[192:193] op_sel_hi:[1,0,1]
	v_mfma_f32_16x16x4_f32 v[98:101], v143, v53, v[98:101]
	v_pk_fma_f32 v[180:181], v[2:3], v[234:235], v[180:181] op_sel:[0,1,0]
	v_pk_fma_f32 v[192:193], v[4:5], v[234:235], v[192:193] op_sel:[0,1,0]
	v_pk_mul_f32 v[180:181], v[146:147], v[180:181]
	v_pk_mul_f32 v[192:193], v[146:147], v[192:193]
	v_pk_fma_f32 v[236:237], v[144:145], v[50:51], v[180:181]
	v_pk_fma_f32 v[238:239], v[144:145], v[52:53], v[192:193]
	global_store_dwordx4 v[150:151], v[236:239], off nt
	v_lshl_add_u64 v[150:151], v[150:151], 0, s[58:59]
	global_load_dwordx4 v[50:53], v[148:149], off nt
	v_lshl_add_u64 v[148:149], v[148:149], 0, s[58:59]
	ds_read_b32 v143, v160 offset:80
	ds_read_b128 v[172:175], v161 offset:640
	ds_read_b128 v[232:235], v161 offset:656
	s_waitcnt vmcnt(23)
; #define RS_LOAD(dst, it0) do { _Pragma("unroll") for (int u = 0; u < 8; ++u) dst[u] = __builtin_nontemporal_load((const f32x4*)(S0 + (size_t)(4 * ((it0) + u)) * DV)); } while (0)
; __device__ __forceinline__ void ret_sample_item(Frame& F, int item) {
;     ...
;     for (int it0 = 0; it0 < 64; it0 += 16) {
;         RS_LOAD(sb, it0 + 8);
;         RS_PROC(sa, it0);
;         { const int itn = it0 + 16 < 64 ? it0 + 16 : it0; RS_LOAD(sa, itn); }
;         RS_PROC(sb, it0 + 8);
;     }
	s_waitcnt lgkmcnt(3)
	v_cndmask_b32_e64 v141, 0, v141, s[6:7]
	v_pk_mul_f32 v[180:181], v[26:27], v[114:115] op_sel:[0,1]
	v_pk_mul_f32 v[192:193], v[28:29], v[114:115] op_sel:[0,1]
	v_mfma_f32_16x16x4_f32 v[110:113], v141, v46, v[110:113]
	v_pk_fma_f32 v[180:181], v[30:31], v[114:115], v[180:181] op_sel_hi:[1,0,1]
	v_pk_fma_f32 v[192:193], v[32:33], v[114:115], v[192:193] op_sel_hi:[1,0,1]
	v_pk_fma_f32 v[180:181], v[22:23], v[116:117], v[180:181] op_sel_hi:[1,0,1]
	v_pk_fma_f32 v[192:193], v[24:25], v[116:117], v[192:193] op_sel_hi:[1,0,1]
	v_mfma_f32_16x16x4_f32 v[106:109], v141, v47, v[106:109]
	v_pk_fma_f32 v[180:181], v[18:19], v[116:117], v[180:181] op_sel:[0,1,0]
	v_pk_fma_f32 v[192:193], v[20:21], v[116:117], v[192:193] op_sel:[0,1,0]
	v_pk_fma_f32 v[180:181], v[14:15], v[176:177], v[180:181] op_sel_hi:[1,0,1]
	v_pk_fma_f32 v[192:193], v[16:17], v[176:177], v[192:193] op_sel_hi:[1,0,1]
	v_mfma_f32_16x16x4_f32 v[102:105], v141, v48, v[102:105]
	v_pk_fma_f32 v[180:181], v[10:11], v[176:177], v[180:181] op_sel:[0,1,0]
	v_pk_fma_f32 v[192:193], v[12:13], v[176:177], v[192:193] op_sel:[0,1,0]
	v_pk_fma_f32 v[180:181], v[6:7], v[178:179], v[180:181] op_sel_hi:[1,0,1]
	v_pk_fma_f32 v[192:193], v[8:9], v[178:179], v[192:193] op_sel_hi:[1,0,1]
	v_mfma_f32_16x16x4_f32 v[98:101], v141, v49, v[98:101]
	v_pk_fma_f32 v[180:181], v[2:3], v[178:179], v[180:181] op_sel:[0,1,0]
	v_pk_fma_f32 v[192:193], v[4:5], v[178:179], v[192:193] op_sel:[0,1,0]
	v_pk_mul_f32 v[180:181], v[146:147], v[180:181]
	v_pk_mul_f32 v[192:193], v[146:147], v[192:193]
	v_pk_fma_f32 v[236:237], v[144:145], v[46:47], v[180:181]
	v_pk_fma_f32 v[238:239], v[144:145], v[48:49], v[192:193]
	global_store_dwordx4 v[150:151], v[236:239], off nt
	v_lshl_add_u64 v[150:151], v[150:151], 0, s[58:59]
	global_load_dwordx4 v[46:49], v[148:149], off nt
	v_lshl_add_u64 v[148:149], v[148:149], 0, s[58:59]
	ds_read_b32 v141, v160 offset:96
	ds_read_b128 v[114:117], v161 offset:768
	ds_read_b128 v[176:179], v161 offset:784
	s_waitcnt vmcnt(24)
	s_waitcnt lgkmcnt(3)
	v_cndmask_b32_e64 v143, 0, v143, s[6:7]
	v_pk_mul_f32 v[180:181], v[26:27], v[172:173] op_sel:[0,1]
	v_pk_mul_f32 v[192:193], v[28:29], v[172:173] op_sel:[0,1]
	v_mfma_f32_16x16x4_f32 v[110:113], v143, v42, v[110:113]
	v_pk_fma_f32 v[180:181], v[30:31], v[172:173], v[180:181] op_sel_hi:[1,0,1]
	v_pk_fma_f32 v[192:193], v[32:33], v[172:173], v[192:193] op_sel_hi:[1,0,1]
	v_pk_fma_f32 v[180:181], v[22:23], v[174:175], v[180:181] op_sel_hi:[1,0,1]
	v_pk_fma_f32 v[192:193], v[24:25], v[174:175], v[192:193] op_sel_hi:[1,0,1]
	v_mfma_f32_16x16x4_f32 v[106:109], v143, v43, v[106:109]
	v_pk_fma_f32 v[180:181], v[18:19], v[174:175], v[180:181] op_sel:[0,1,0]
	v_pk_fma_f32 v[192:193], v[20:21], v[174:175], v[192:193] op_sel:[0,1,0]
	v_pk_fma_f32 v[180:181], v[14:15], v[232:233], v[180:181] op_sel_hi:[1,0,1]
	v_pk_fma_f32 v[192:193], v[16:17], v[232:233], v[192:193] op_sel_hi:[1,0,1]
	v_mfma_f32_16x16x4_f32 v[102:105], v143, v44, v[102:105]
	v_pk_fma_f32 v[180:181], v[10:11], v[232:233], v[180:181] op_sel:[0,1,0]
	v_pk_fma_f32 v[192:193], v[12:13], v[232:233], v[192:193] op_sel:[0,1,0]
	v_pk_fma_f32 v[180:181], v[6:7], v[234:235], v[180:181] op_sel_hi:[1,0,1]
	v_pk_fma_f32 v[192:193], v[8:9], v[234:235], v[192:193] op_sel_hi:[1,0,1]
	v_mfma_f32_16x16x4_f32 v[98:101], v143, v45, v[98:101]
	v_pk_fma_f32 v[180:181], v[2:3], v[234:235], v[180:181] op_sel:[0,1,0]
	v_pk_fma_f32 v[192:193], v[4:5], v[234:235], v[192:193] op_sel:[0,1,0]
	v_pk_mul_f32 v[180:181], v[146:147], v[180:181]
	v_pk_mul_f32 v[192:193], v[146:147], v[192:193]
	v_pk_fma_f32 v[236:237], v[144:145], v[42:43], v[180:181]
	v_pk_fma_f32 v[238:239], v[144:145], v[44:45], v[192:193]
	global_store_dwordx4 v[150:151], v[236:239], off nt
	v_lshl_add_u64 v[150:151], v[150:151], 0, s[58:59]
	global_load_dwordx4 v[42:45], v[148:149], off nt
	v_lshl_add_u64 v[148:149], v[148:149], 0, s[58:59]
	ds_read_b32 v143, v160 offset:112
	ds_read_b128 v[172:175], v161 offset:896
	ds_read_b128 v[232:235], v161 offset:912
	s_waitcnt vmcnt(25)
	s_waitcnt lgkmcnt(3)
	v_cndmask_b32_e64 v141, 0, v141, s[6:7]
	v_pk_mul_f32 v[180:181], v[26:27], v[114:115] op_sel:[0,1]
	v_pk_mul_f32 v[192:193], v[28:29], v[114:115] op_sel:[0,1]
	v_mfma_f32_16x16x4_f32 v[110:113], v141, v38, v[110:113]
	v_pk_fma_f32 v[180:181], v[30:31], v[114:115], v[180:181] op_sel_hi:[1,0,1]
	v_pk_fma_f32 v[192:193], v[32:33], v[114:115], v[192:193] op_sel_hi:[1,0,1]
	v_pk_fma_f32 v[180:181], v[22:23], v[116:117], v[180:181] op_sel_hi:[1,0,1]
	v_pk_fma_f32 v[192:193], v[24:25], v[116:117], v[192:193] op_sel_hi:[1,0,1]
	v_mfma_f32_16x16x4_f32 v[106:109], v141, v39, v[106:109]
	v_pk_fma_f32 v[180:181], v[18:19], v[116:117], v[180:181] op_sel:[0,1,0]
	v_pk_fma_f32 v[192:193], v[20:21], v[116:117], v[192:193] op_sel:[0,1,0]
	v_pk_fma_f32 v[180:181], v[14:15], v[176:177], v[180:181] op_sel_hi:[1,0,1]
	v_pk_fma_f32 v[192:193], v[16:17], v[176:177], v[192:193] op_sel_hi:[1,0,1]
	v_mfma_f32_16x16x4_f32 v[102:105], v141, v40, v[102:105]
	v_pk_fma_f32 v[180:181], v[10:11], v[176:177], v[180:181] op_sel:[0,1,0]
	v_pk_fma_f32 v[192:193], v[12:13], v[176:177], v[192:193] op_sel:[0,1,0]
	v_pk_fma_f32 v[180:181], v[6:7], v[178:179], v[180:181] op_sel_hi:[1,0,1]
	v_pk_fma_f32 v[192:193], v[8:9], v[178:179], v[192:193] op_sel_hi:[1,0,1]
	v_mfma_f32_16x16x4_f32 v[98:101], v141, v41, v[98:101]
	v_pk_fma_f32 v[180:181], v[2:3], v[178:179], v[180:181] op_sel:[0,1,0]
	v_pk_fma_f32 v[192:193], v[4:5], v[178:179], v[192:193] op_sel:[0,1,0]
	v_pk_mul_f32 v[180:181], v[146:147], v[180:181]
	v_pk_mul_f32 v[192:193], v[146:147], v[192:193]
	v_pk_fma_f32 v[236:237], v[144:145], v[38:39], v[180:181]
	v_pk_fma_f32 v[238:239], v[144:145], v[40:41], v[192:193]
	global_store_dwordx4 v[150:151], v[236:239], off nt
	v_lshl_add_u64 v[150:151], v[150:151], 0, s[58:59]
	global_load_dwordx4 v[38:41], v[148:149], off nt
	v_lshl_add_u64 v[148:149], v[148:149], 0, s[58:59]
	ds_read_b32 v141, v160 offset:128
	ds_read_b128 v[114:117], v161 offset:1024
	ds_read_b128 v[176:179], v161 offset:1040
	s_waitcnt vmcnt(26)
; #define RS_LOAD(dst, it0) do { _Pragma("unroll") for (int u = 0; u < 8; ++u) dst[u] = __builtin_nontemporal_load((const f32x4*)(S0 + (size_t)(4 * ((it0) + u)) * DV)); } while (0)
; __device__ __forceinline__ void ret_sample_item(Frame& F, int item) {
;     ...
;     for (int it0 = 0; it0 < 64; it0 += 16) {
;         RS_LOAD(sb, it0 + 8);
;         RS_PROC(sa, it0);
;         { const int itn = it0 + 16 < 64 ? it0 + 16 : it0; RS_LOAD(sa, itn); }
;         RS_PROC(sb, it0 + 8);
;     }
	s_waitcnt lgkmcnt(3)
	v_cndmask_b32_e64 v143, 0, v143, s[6:7]
	v_pk_mul_f32 v[180:181], v[26:27], v[172:173] op_sel:[0,1]
	v_pk_mul_f32 v[192:193], v[28:29], v[172:173] op_sel:[0,1]
	v_mfma_f32_16x16x4_f32 v[110:113], v143, v34, v[110:113]
	v_pk_fma_f32 v[180:181], v[30:31], v[172:173], v[180:181] op_sel_hi:[1,0,1]
	v_pk_fma_f32 v[192:193], v[32:33], v[172:173], v[192:193] op_sel_hi:[1,0,1]
	v_pk_fma_f32 v[180:181], v[22:23], v[174:175], v[180:181] op_sel_hi:[1,0,1]
	v_pk_fma_f32 v[192:193], v[24:25], v[174:175], v[192:193] op_sel_hi:[1,0,1]
	v_mfma_f32_16x16x4_f32 v[106:109], v143, v35, v[106:109]
	v_pk_fma_f32 v[180:181], v[18:19], v[174:175], v[180:181] op_sel:[0,1,0]
	v_pk_fma_f32 v[192:193], v[20:21], v[174:175], v[192:193] op_sel:[0,1,0]
	v_pk_fma_f32 v[180:181], v[14:15], v[232:233], v[180:181] op_sel_hi:[1,0,1]
	v_pk_fma_f32 v[192:193], v[16:17], v[232:233], v[192:193] op_sel_hi:[1,0,1]
	v_mfma_f32_16x16x4_f32 v[102:105], v143, v36, v[102:105]
	v_pk_fma_f32 v[180:181], v[10:11], v[232:233], v[180:181] op_sel:[0,1,0]
	v_pk_fma_f32 v[192:193], v[12:13], v[232:233], v[192:193] op_sel:[0,1,0]
	v_pk_fma_f32 v[180:181], v[6:7], v[234:235], v[180:181] op_sel_hi:[1,0,1]
	v_pk_fma_f32 v[192:193], v[8:9], v[234:235], v[192:193] op_sel_hi:[1,0,1]
	v_mfma_f32_16x16x4_f32 v[98:101], v143, v37, v[98:101]
	v_pk_fma_f32 v[180:181], v[2:3], v[234:235], v[180:181] op_sel:[0,1,0]
	v_pk_fma_f32 v[192:193], v[4:5], v[234:235], v[192:193] op_sel:[0,1,0]
	v_pk_mul_f32 v[180:181], v[146:147], v[180:181]
	v_pk_mul_f32 v[192:193], v[146:147], v[192:193]
	v_pk_fma_f32 v[236:237], v[144:145], v[34:35], v[180:181]
	v_pk_fma_f32 v[238:239], v[144:145], v[36:37], v[192:193]
	global_store_dwordx4 v[150:151], v[236:239], off nt
	v_lshl_add_u64 v[150:151], v[150:151], 0, s[58:59]
	global_load_dwordx4 v[34:37], v[148:149], off nt
	v_lshl_add_u64 v[148:149], v[148:149], 0, s[58:59]
	ds_read_b32 v143, v160 offset:144
	ds_read_b128 v[172:175], v161 offset:1152
	ds_read_b128 v[232:235], v161 offset:1168
	s_waitcnt vmcnt(27)
	s_waitcnt lgkmcnt(3)
	v_cndmask_b32_e64 v141, 0, v141, s[6:7]
	v_pk_mul_f32 v[180:181], v[26:27], v[114:115] op_sel:[0,1]
	v_pk_mul_f32 v[192:193], v[28:29], v[114:115] op_sel:[0,1]
	v_mfma_f32_16x16x4_f32 v[110:113], v141, v58, v[110:113]
	v_pk_fma_f32 v[180:181], v[30:31], v[114:115], v[180:181] op_sel_hi:[1,0,1]
	v_pk_fma_f32 v[192:193], v[32:33], v[114:115], v[192:193] op_sel_hi:[1,0,1]
	v_pk_fma_f32 v[180:181], v[22:23], v[116:117], v[180:181] op_sel_hi:[1,0,1]
	v_pk_fma_f32 v[192:193], v[24:25], v[116:117], v[192:193] op_sel_hi:[1,0,1]
	v_mfma_f32_16x16x4_f32 v[106:109], v141, v59, v[106:109]
	v_pk_fma_f32 v[180:181], v[18:19], v[116:117], v[180:181] op_sel:[0,1,0]
	v_pk_fma_f32 v[192:193], v[20:21], v[116:117], v[192:193] op_sel:[0,1,0]
	v_pk_fma_f32 v[180:181], v[14:15], v[176:177], v[180:181] op_sel_hi:[1,0,1]
	v_pk_fma_f32 v[192:193], v[16:17], v[176:177], v[192:193] op_sel_hi:[1,0,1]
	v_mfma_f32_16x16x4_f32 v[102:105], v141, v60, v[102:105]
	v_pk_fma_f32 v[180:181], v[10:11], v[176:177], v[180:181] op_sel:[0,1,0]
	v_pk_fma_f32 v[192:193], v[12:13], v[176:177], v[192:193] op_sel:[0,1,0]
	v_pk_fma_f32 v[180:181], v[6:7], v[178:179], v[180:181] op_sel_hi:[1,0,1]
	v_pk_fma_f32 v[192:193], v[8:9], v[178:179], v[192:193] op_sel_hi:[1,0,1]
	v_mfma_f32_16x16x4_f32 v[98:101], v141, v61, v[98:101]
	v_pk_fma_f32 v[180:181], v[2:3], v[178:179], v[180:181] op_sel:[0,1,0]
	v_pk_fma_f32 v[192:193], v[4:5], v[178:179], v[192:193] op_sel:[0,1,0]
	v_pk_mul_f32 v[180:181], v[146:147], v[180:181]
	v_pk_mul_f32 v[192:193], v[146:147], v[192:193]
	v_pk_fma_f32 v[236:237], v[144:145], v[58:59], v[180:181]
	v_pk_fma_f32 v[238:239], v[144:145], v[60:61], v[192:193]
	global_store_dwordx4 v[150:151], v[236:239], off nt
	v_lshl_add_u64 v[150:151], v[150:151], 0, s[58:59]
	global_load_dwordx4 v[58:61], v[148:149], off nt
	v_lshl_add_u64 v[148:149], v[148:149], 0, s[58:59]
	ds_read_b32 v141, v160 offset:160
	ds_read_b128 v[114:117], v161 offset:1280
	ds_read_b128 v[176:179], v161 offset:1296
	s_waitcnt vmcnt(28)
	s_waitcnt lgkmcnt(3)
	v_cndmask_b32_e64 v143, 0, v143, s[6:7]
	v_pk_mul_f32 v[180:181], v[26:27], v[172:173] op_sel:[0,1]
	v_pk_mul_f32 v[192:193], v[28:29], v[172:173] op_sel:[0,1]
	v_mfma_f32_16x16x4_f32 v[110:113], v143, v66, v[110:113]
	v_pk_fma_f32 v[180:181], v[30:31], v[172:173], v[180:181] op_sel_hi:[1,0,1]
	v_pk_fma_f32 v[192:193], v[32:33], v[172:173], v[192:193] op_sel_hi:[1,0,1]
	v_pk_fma_f32 v[180:181], v[22:23], v[174:175], v[180:181] op_sel_hi:[1,0,1]
	v_pk_fma_f32 v[192:193], v[24:25], v[174:175], v[192:193] op_sel_hi:[1,0,1]
	v_mfma_f32_16x16x4_f32 v[106:109], v143, v67, v[106:109]
	v_pk_fma_f32 v[180:181], v[18:19], v[174:175], v[180:181] op_sel:[0,1,0]
	v_pk_fma_f32 v[192:193], v[20:21], v[174:175], v[192:193] op_sel:[0,1,0]
	v_pk_fma_f32 v[180:181], v[14:15], v[232:233], v[180:181] op_sel_hi:[1,0,1]
	v_pk_fma_f32 v[192:193], v[16:17], v[232:233], v[192:193] op_sel_hi:[1,0,1]
	v_mfma_f32_16x16x4_f32 v[102:105], v143, v68, v[102:105]
	v_pk_fma_f32 v[180:181], v[10:11], v[232:233], v[180:181] op_sel:[0,1,0]
	v_pk_fma_f32 v[192:193], v[12:13], v[232:233], v[192:193] op_sel:[0,1,0]
	v_pk_fma_f32 v[180:181], v[6:7], v[234:235], v[180:181] op_sel_hi:[1,0,1]
	v_pk_fma_f32 v[192:193], v[8:9], v[234:235], v[192:193] op_sel_hi:[1,0,1]
	v_mfma_f32_16x16x4_f32 v[98:101], v143, v69, v[98:101]
	v_pk_fma_f32 v[180:181], v[2:3], v[234:235], v[180:181] op_sel:[0,1,0]
	v_pk_fma_f32 v[192:193], v[4:5], v[234:235], v[192:193] op_sel:[0,1,0]
	v_pk_mul_f32 v[180:181], v[146:147], v[180:181]
	v_pk_mul_f32 v[192:193], v[146:147], v[192:193]
	v_pk_fma_f32 v[236:237], v[144:145], v[66:67], v[180:181]
	v_pk_fma_f32 v[238:239], v[144:145], v[68:69], v[192:193]
	global_store_dwordx4 v[150:151], v[236:239], off nt
	v_lshl_add_u64 v[150:151], v[150:151], 0, s[58:59]
	global_load_dwordx4 v[66:69], v[148:149], off nt
	v_lshl_add_u64 v[148:149], v[148:149], 0, s[58:59]
	ds_read_b32 v143, v160 offset:176
	ds_read_b128 v[172:175], v161 offset:1408
	ds_read_b128 v[232:235], v161 offset:1424
	s_waitcnt vmcnt(29)
; #define RS_LOAD(dst, it0) do { _Pragma("unroll") for (int u = 0; u < 8; ++u) dst[u] = __builtin_nontemporal_load((const f32x4*)(S0 + (size_t)(4 * ((it0) + u)) * DV)); } while (0)
; __device__ __forceinline__ void ret_sample_item(Frame& F, int item) {
;     ...
;     for (int it0 = 0; it0 < 64; it0 += 16) {
;         RS_LOAD(sb, it0 + 8);
;         RS_PROC(sa, it0);
;         { const int itn = it0 + 16 < 64 ? it0 + 16 : it0; RS_LOAD(sa, itn); }
;         RS_PROC(sb, it0 + 8);
;     }
	s_waitcnt lgkmcnt(3)
	v_cndmask_b32_e64 v141, 0, v141, s[6:7]
	v_pk_mul_f32 v[180:181], v[26:27], v[114:115] op_sel:[0,1]
	v_pk_mul_f32 v[192:193], v[28:29], v[114:115] op_sel:[0,1]
	v_mfma_f32_16x16x4_f32 v[110:113], v141, v74, v[110:113]
	v_pk_fma_f32 v[180:181], v[30:31], v[114:115], v[180:181] op_sel_hi:[1,0,1]
	v_pk_fma_f32 v[192:193], v[32:33], v[114:115], v[192:193] op_sel_hi:[1,0,1]
	v_pk_fma_f32 v[180:181], v[22:23], v[116:117], v[180:181] op_sel_hi:[1,0,1]
	v_pk_fma_f32 v[192:193], v[24:25], v[116:117], v[192:193] op_sel_hi:[1,0,1]
	v_mfma_f32_16x16x4_f32 v[106:109], v141, v75, v[106:109]
	v_pk_fma_f32 v[180:181], v[18:19], v[116:117], v[180:181] op_sel:[0,1,0]
	v_pk_fma_f32 v[192:193], v[20:21], v[116:117], v[192:193] op_sel:[0,1,0]
	v_pk_fma_f32 v[180:181], v[14:15], v[176:177], v[180:181] op_sel_hi:[1,0,1]
	v_pk_fma_f32 v[192:193], v[16:17], v[176:177], v[192:193] op_sel_hi:[1,0,1]
	v_mfma_f32_16x16x4_f32 v[102:105], v141, v76, v[102:105]
	v_pk_fma_f32 v[180:181], v[10:11], v[176:177], v[180:181] op_sel:[0,1,0]
	v_pk_fma_f32 v[192:193], v[12:13], v[176:177], v[192:193] op_sel:[0,1,0]
	v_pk_fma_f32 v[180:181], v[6:7], v[178:179], v[180:181] op_sel_hi:[1,0,1]
	v_pk_fma_f32 v[192:193], v[8:9], v[178:179], v[192:193] op_sel_hi:[1,0,1]
	v_mfma_f32_16x16x4_f32 v[98:101], v141, v77, v[98:101]
	v_pk_fma_f32 v[180:181], v[2:3], v[178:179], v[180:181] op_sel:[0,1,0]
	v_pk_fma_f32 v[192:193], v[4:5], v[178:179], v[192:193] op_sel:[0,1,0]
	v_pk_mul_f32 v[180:181], v[146:147], v[180:181]
	v_pk_mul_f32 v[192:193], v[146:147], v[192:193]
	v_pk_fma_f32 v[236:237], v[144:145], v[74:75], v[180:181]
	v_pk_fma_f32 v[238:239], v[144:145], v[76:77], v[192:193]
	global_store_dwordx4 v[150:151], v[236:239], off nt
	v_lshl_add_u64 v[150:151], v[150:151], 0, s[58:59]
	global_load_dwordx4 v[74:77], v[148:149], off nt
	v_lshl_add_u64 v[148:149], v[148:149], 0, s[58:59]
	ds_read_b32 v141, v160 offset:192
	ds_read_b128 v[114:117], v161 offset:1536
	ds_read_b128 v[176:179], v161 offset:1552
	s_waitcnt vmcnt(30)
	s_waitcnt lgkmcnt(3)
	v_cndmask_b32_e64 v143, 0, v143, s[6:7]
	v_pk_mul_f32 v[180:181], v[26:27], v[172:173] op_sel:[0,1]
	v_pk_mul_f32 v[192:193], v[28:29], v[172:173] op_sel:[0,1]
	v_mfma_f32_16x16x4_f32 v[110:113], v143, v78, v[110:113]
	v_pk_fma_f32 v[180:181], v[30:31], v[172:173], v[180:181] op_sel_hi:[1,0,1]
	v_pk_fma_f32 v[192:193], v[32:33], v[172:173], v[192:193] op_sel_hi:[1,0,1]
	v_pk_fma_f32 v[180:181], v[22:23], v[174:175], v[180:181] op_sel_hi:[1,0,1]
	v_pk_fma_f32 v[192:193], v[24:25], v[174:175], v[192:193] op_sel_hi:[1,0,1]
	v_mfma_f32_16x16x4_f32 v[106:109], v143, v79, v[106:109]
	v_pk_fma_f32 v[180:181], v[18:19], v[174:175], v[180:181] op_sel:[0,1,0]
	v_pk_fma_f32 v[192:193], v[20:21], v[174:175], v[192:193] op_sel:[0,1,0]
	v_pk_fma_f32 v[180:181], v[14:15], v[232:233], v[180:181] op_sel_hi:[1,0,1]
	v_pk_fma_f32 v[192:193], v[16:17], v[232:233], v[192:193] op_sel_hi:[1,0,1]
	v_mfma_f32_16x16x4_f32 v[102:105], v143, v80, v[102:105]
	v_pk_fma_f32 v[180:181], v[10:11], v[232:233], v[180:181] op_sel:[0,1,0]
	v_pk_fma_f32 v[192:193], v[12:13], v[232:233], v[192:193] op_sel:[0,1,0]
	v_pk_fma_f32 v[180:181], v[6:7], v[234:235], v[180:181] op_sel_hi:[1,0,1]
	v_pk_fma_f32 v[192:193], v[8:9], v[234:235], v[192:193] op_sel_hi:[1,0,1]
	v_mfma_f32_16x16x4_f32 v[98:101], v143, v81, v[98:101]
	v_pk_fma_f32 v[180:181], v[2:3], v[234:235], v[180:181] op_sel:[0,1,0]
	v_pk_fma_f32 v[192:193], v[4:5], v[234:235], v[192:193] op_sel:[0,1,0]
	v_pk_mul_f32 v[180:181], v[146:147], v[180:181]
	v_pk_mul_f32 v[192:193], v[146:147], v[192:193]
	v_pk_fma_f32 v[236:237], v[144:145], v[78:79], v[180:181]
	v_pk_fma_f32 v[238:239], v[144:145], v[80:81], v[192:193]
	global_store_dwordx4 v[150:151], v[236:239], off nt
	v_lshl_add_u64 v[150:151], v[150:151], 0, s[58:59]
	global_load_dwordx4 v[78:81], v[148:149], off nt
	v_lshl_add_u64 v[148:149], v[148:149], 0, s[58:59]
	ds_read_b32 v143, v160 offset:208
	ds_read_b128 v[172:175], v161 offset:1664
	ds_read_b128 v[232:235], v161 offset:1680
	s_waitcnt vmcnt(31)
	s_waitcnt lgkmcnt(3)
	v_cndmask_b32_e64 v141, 0, v141, s[6:7]
	v_pk_mul_f32 v[180:181], v[26:27], v[114:115] op_sel:[0,1]
	v_pk_mul_f32 v[192:193], v[28:29], v[114:115] op_sel:[0,1]
	v_mfma_f32_16x16x4_f32 v[110:113], v141, v82, v[110:113]
	v_pk_fma_f32 v[180:181], v[30:31], v[114:115], v[180:181] op_sel_hi:[1,0,1]
	v_pk_fma_f32 v[192:193], v[32:33], v[114:115], v[192:193] op_sel_hi:[1,0,1]
	v_pk_fma_f32 v[180:181], v[22:23], v[116:117], v[180:181] op_sel_hi:[1,0,1]
	v_pk_fma_f32 v[192:193], v[24:25], v[116:117], v[192:193] op_sel_hi:[1,0,1]
	v_mfma_f32_16x16x4_f32 v[106:109], v141, v83, v[106:109]
	v_pk_fma_f32 v[180:181], v[18:19], v[116:117], v[180:181] op_sel:[0,1,0]
	v_pk_fma_f32 v[192:193], v[20:21], v[116:117], v[192:193] op_sel:[0,1,0]
	v_pk_fma_f32 v[180:181], v[14:15], v[176:177], v[180:181] op_sel_hi:[1,0,1]
	v_pk_fma_f32 v[192:193], v[16:17], v[176:177], v[192:193] op_sel_hi:[1,0,1]
	v_mfma_f32_16x16x4_f32 v[102:105], v141, v84, v[102:105]
	v_pk_fma_f32 v[180:181], v[10:11], v[176:177], v[180:181] op_sel:[0,1,0]
	v_pk_fma_f32 v[192:193], v[12:13], v[176:177], v[192:193] op_sel:[0,1,0]
	v_pk_fma_f32 v[180:181], v[6:7], v[178:179], v[180:181] op_sel_hi:[1,0,1]
	v_pk_fma_f32 v[192:193], v[8:9], v[178:179], v[192:193] op_sel_hi:[1,0,1]
	v_mfma_f32_16x16x4_f32 v[98:101], v141, v85, v[98:101]
	v_pk_fma_f32 v[180:181], v[2:3], v[178:179], v[180:181] op_sel:[0,1,0]
	v_pk_fma_f32 v[192:193], v[4:5], v[178:179], v[192:193] op_sel:[0,1,0]
	v_pk_mul_f32 v[180:181], v[146:147], v[180:181]
	v_pk_mul_f32 v[192:193], v[146:147], v[192:193]
	v_pk_fma_f32 v[236:237], v[144:145], v[82:83], v[180:181]
	v_pk_fma_f32 v[238:239], v[144:145], v[84:85], v[192:193]
	global_store_dwordx4 v[150:151], v[236:239], off nt
	v_lshl_add_u64 v[150:151], v[150:151], 0, s[58:59]
	global_load_dwordx4 v[82:85], v[148:149], off nt
	v_lshl_add_u64 v[148:149], v[148:149], 0, s[58:59]
	ds_read_b32 v141, v160 offset:224
	ds_read_b128 v[114:117], v161 offset:1792
	ds_read_b128 v[176:179], v161 offset:1808
	s_waitcnt vmcnt(32)
; #define RS_LOAD(dst, it0) do { _Pragma("unroll") for (int u = 0; u < 8; ++u) dst[u] = __builtin_nontemporal_load((const f32x4*)(S0 + (size_t)(4 * ((it0) + u)) * DV)); } while (0)
; __device__ __forceinline__ void ret_sample_item(Frame& F, int item) {
;     ...
;     for (int it0 = 0; it0 < 64; it0 += 16) {
;         RS_LOAD(sb, it0 + 8);
;         RS_PROC(sa, it0);
;         { const int itn = it0 + 16 < 64 ? it0 + 16 : it0; RS_LOAD(sa, itn); }
;         RS_PROC(sb, it0 + 8);
;     }
	s_waitcnt lgkmcnt(3)
	v_cndmask_b32_e64 v143, 0, v143, s[6:7]
	v_pk_mul_f32 v[180:181], v[26:27], v[172:173] op_sel:[0,1]
	v_pk_mul_f32 v[192:193], v[28:29], v[172:173] op_sel:[0,1]
	v_mfma_f32_16x16x4_f32 v[110:113], v143, v86, v[110:113]
	v_pk_fma_f32 v[180:181], v[30:31], v[172:173], v[180:181] op_sel_hi:[1,0,1]
	v_pk_fma_f32 v[192:193], v[32:33], v[172:173], v[192:193] op_sel_hi:[1,0,1]
	v_pk_fma_f32 v[180:181], v[22:23], v[174:175], v[180:181] op_sel_hi:[1,0,1]
	v_pk_fma_f32 v[192:193], v[24:25], v[174:175], v[192:193] op_sel_hi:[1,0,1]
	v_mfma_f32_16x16x4_f32 v[106:109], v143, v87, v[106:109]
	v_pk_fma_f32 v[180:181], v[18:19], v[174:175], v[180:181] op_sel:[0,1,0]
	v_pk_fma_f32 v[192:193], v[20:21], v[174:175], v[192:193] op_sel:[0,1,0]
	v_pk_fma_f32 v[180:181], v[14:15], v[232:233], v[180:181] op_sel_hi:[1,0,1]
	v_pk_fma_f32 v[192:193], v[16:17], v[232:233], v[192:193] op_sel_hi:[1,0,1]
	v_mfma_f32_16x16x4_f32 v[102:105], v143, v88, v[102:105]
	v_pk_fma_f32 v[180:181], v[10:11], v[232:233], v[180:181] op_sel:[0,1,0]
	v_pk_fma_f32 v[192:193], v[12:13], v[232:233], v[192:193] op_sel:[0,1,0]
	v_pk_fma_f32 v[180:181], v[6:7], v[234:235], v[180:181] op_sel_hi:[1,0,1]
	v_pk_fma_f32 v[192:193], v[8:9], v[234:235], v[192:193] op_sel_hi:[1,0,1]
	v_mfma_f32_16x16x4_f32 v[98:101], v143, v89, v[98:101]
	v_pk_fma_f32 v[180:181], v[2:3], v[234:235], v[180:181] op_sel:[0,1,0]
	v_pk_fma_f32 v[192:193], v[4:5], v[234:235], v[192:193] op_sel:[0,1,0]
	v_pk_mul_f32 v[180:181], v[146:147], v[180:181]
	v_pk_mul_f32 v[192:193], v[146:147], v[192:193]
	v_pk_fma_f32 v[236:237], v[144:145], v[86:87], v[180:181]
	v_pk_fma_f32 v[238:239], v[144:145], v[88:89], v[192:193]
	global_store_dwordx4 v[150:151], v[236:239], off nt
	v_lshl_add_u64 v[150:151], v[150:151], 0, s[58:59]
	global_load_dwordx4 v[86:89], v[148:149], off nt
	v_lshl_add_u64 v[148:149], v[148:149], 0, s[58:59]
	ds_read_b32 v143, v160 offset:240
	ds_read_b128 v[172:175], v161 offset:1920
	ds_read_b128 v[232:235], v161 offset:1936
	s_waitcnt vmcnt(33)
	s_waitcnt lgkmcnt(3)
	v_cndmask_b32_e64 v141, 0, v141, s[6:7]
	v_pk_mul_f32 v[180:181], v[26:27], v[114:115] op_sel:[0,1]
	v_pk_mul_f32 v[192:193], v[28:29], v[114:115] op_sel:[0,1]
	v_mfma_f32_16x16x4_f32 v[110:113], v141, v90, v[110:113]
	v_pk_fma_f32 v[180:181], v[30:31], v[114:115], v[180:181] op_sel_hi:[1,0,1]
	v_pk_fma_f32 v[192:193], v[32:33], v[114:115], v[192:193] op_sel_hi:[1,0,1]
	v_pk_fma_f32 v[180:181], v[22:23], v[116:117], v[180:181] op_sel_hi:[1,0,1]
	v_pk_fma_f32 v[192:193], v[24:25], v[116:117], v[192:193] op_sel_hi:[1,0,1]
	v_mfma_f32_16x16x4_f32 v[106:109], v141, v91, v[106:109]
	v_pk_fma_f32 v[180:181], v[18:19], v[116:117], v[180:181] op_sel:[0,1,0]
	v_pk_fma_f32 v[192:193], v[20:21], v[116:117], v[192:193] op_sel:[0,1,0]
	v_pk_fma_f32 v[180:181], v[14:15], v[176:177], v[180:181] op_sel_hi:[1,0,1]
	v_pk_fma_f32 v[192:193], v[16:17], v[176:177], v[192:193] op_sel_hi:[1,0,1]
	v_mfma_f32_16x16x4_f32 v[102:105], v141, v92, v[102:105]
	v_pk_fma_f32 v[180:181], v[10:11], v[176:177], v[180:181] op_sel:[0,1,0]
	v_pk_fma_f32 v[192:193], v[12:13], v[176:177], v[192:193] op_sel:[0,1,0]
	v_pk_fma_f32 v[180:181], v[6:7], v[178:179], v[180:181] op_sel_hi:[1,0,1]
	v_pk_fma_f32 v[192:193], v[8:9], v[178:179], v[192:193] op_sel_hi:[1,0,1]
	v_mfma_f32_16x16x4_f32 v[98:101], v141, v93, v[98:101]
	v_pk_fma_f32 v[180:181], v[2:3], v[178:179], v[180:181] op_sel:[0,1,0]
	v_pk_fma_f32 v[192:193], v[4:5], v[178:179], v[192:193] op_sel:[0,1,0]
	v_pk_mul_f32 v[180:181], v[146:147], v[180:181]
	v_pk_mul_f32 v[192:193], v[146:147], v[192:193]
	v_pk_fma_f32 v[236:237], v[144:145], v[90:91], v[180:181]
	v_pk_fma_f32 v[238:239], v[144:145], v[92:93], v[192:193]
	global_store_dwordx4 v[150:151], v[236:239], off nt
	v_lshl_add_u64 v[150:151], v[150:151], 0, s[58:59]
	global_load_dwordx4 v[90:93], v[148:149], off nt
	v_lshl_add_u64 v[148:149], v[148:149], 0, s[58:59]
	ds_read_b32 v141, v160 offset:256
	ds_read_b128 v[114:117], v161 offset:2048
	ds_read_b128 v[176:179], v161 offset:2064
	s_waitcnt vmcnt(34)
	s_waitcnt lgkmcnt(3)
	v_cndmask_b32_e64 v143, 0, v143, s[6:7]
	v_pk_mul_f32 v[180:181], v[26:27], v[172:173] op_sel:[0,1]
	v_pk_mul_f32 v[192:193], v[28:29], v[172:173] op_sel:[0,1]
	v_mfma_f32_16x16x4_f32 v[110:113], v143, v94, v[110:113]
	v_pk_fma_f32 v[180:181], v[30:31], v[172:173], v[180:181] op_sel_hi:[1,0,1]
	v_pk_fma_f32 v[192:193], v[32:33], v[172:173], v[192:193] op_sel_hi:[1,0,1]
	v_pk_fma_f32 v[180:181], v[22:23], v[174:175], v[180:181] op_sel_hi:[1,0,1]
	v_pk_fma_f32 v[192:193], v[24:25], v[174:175], v[192:193] op_sel_hi:[1,0,1]
	v_mfma_f32_16x16x4_f32 v[106:109], v143, v95, v[106:109]
	v_pk_fma_f32 v[180:181], v[18:19], v[174:175], v[180:181] op_sel:[0,1,0]
	v_pk_fma_f32 v[192:193], v[20:21], v[174:175], v[192:193] op_sel:[0,1,0]
	v_pk_fma_f32 v[180:181], v[14:15], v[232:233], v[180:181] op_sel_hi:[1,0,1]
	v_pk_fma_f32 v[192:193], v[16:17], v[232:233], v[192:193] op_sel_hi:[1,0,1]
	v_mfma_f32_16x16x4_f32 v[102:105], v143, v96, v[102:105]
	v_pk_fma_f32 v[180:181], v[10:11], v[232:233], v[180:181] op_sel:[0,1,0]
	v_pk_fma_f32 v[192:193], v[12:13], v[232:233], v[192:193] op_sel:[0,1,0]
	v_pk_fma_f32 v[180:181], v[6:7], v[234:235], v[180:181] op_sel_hi:[1,0,1]
	v_pk_fma_f32 v[192:193], v[8:9], v[234:235], v[192:193] op_sel_hi:[1,0,1]
	v_mfma_f32_16x16x4_f32 v[98:101], v143, v97, v[98:101]
	v_pk_fma_f32 v[180:181], v[2:3], v[234:235], v[180:181] op_sel:[0,1,0]
	v_pk_fma_f32 v[192:193], v[4:5], v[234:235], v[192:193] op_sel:[0,1,0]
	v_pk_mul_f32 v[180:181], v[146:147], v[180:181]
	v_pk_mul_f32 v[192:193], v[146:147], v[192:193]
	v_pk_fma_f32 v[236:237], v[144:145], v[94:95], v[180:181]
	v_pk_fma_f32 v[238:239], v[144:145], v[96:97], v[192:193]
	global_store_dwordx4 v[150:151], v[236:239], off nt
	v_lshl_add_u64 v[150:151], v[150:151], 0, s[58:59]
	global_load_dwordx4 v[94:97], v[148:149], off nt
	v_lshl_add_u64 v[148:149], v[148:149], 0, s[58:59]
	ds_read_b32 v143, v160 offset:272
	ds_read_b128 v[172:175], v161 offset:2176
	ds_read_b128 v[232:235], v161 offset:2192
	s_waitcnt vmcnt(35)
; #define RS_LOAD(dst, it0) do { _Pragma("unroll") for (int u = 0; u < 8; ++u) dst[u] = __builtin_nontemporal_load((const f32x4*)(S0 + (size_t)(4 * ((it0) + u)) * DV)); } while (0)
; __device__ __forceinline__ void ret_sample_item(Frame& F, int item) {
;     ...
;     for (int it0 = 0; it0 < 64; it0 += 16) {
;         RS_LOAD(sb, it0 + 8);
;         RS_PROC(sa, it0);
;         { const int itn = it0 + 16 < 64 ? it0 + 16 : it0; RS_LOAD(sa, itn); }
;         RS_PROC(sb, it0 + 8);
;     }
	s_waitcnt lgkmcnt(3)
	v_cndmask_b32_e64 v141, 0, v141, s[6:7]
	v_pk_mul_f32 v[180:181], v[26:27], v[114:115] op_sel:[0,1]
	v_pk_mul_f32 v[192:193], v[28:29], v[114:115] op_sel:[0,1]
	v_mfma_f32_16x16x4_f32 v[110:113], v141, v212, v[110:113]
	v_pk_fma_f32 v[180:181], v[30:31], v[114:115], v[180:181] op_sel_hi:[1,0,1]
	v_pk_fma_f32 v[192:193], v[32:33], v[114:115], v[192:193] op_sel_hi:[1,0,1]
	v_pk_fma_f32 v[180:181], v[22:23], v[116:117], v[180:181] op_sel_hi:[1,0,1]
	v_pk_fma_f32 v[192:193], v[24:25], v[116:117], v[192:193] op_sel_hi:[1,0,1]
	v_mfma_f32_16x16x4_f32 v[106:109], v141, v213, v[106:109]
	v_pk_fma_f32 v[180:181], v[18:19], v[116:117], v[180:181] op_sel:[0,1,0]
	v_pk_fma_f32 v[192:193], v[20:21], v[116:117], v[192:193] op_sel:[0,1,0]
	v_pk_fma_f32 v[180:181], v[14:15], v[176:177], v[180:181] op_sel_hi:[1,0,1]
	v_pk_fma_f32 v[192:193], v[16:17], v[176:177], v[192:193] op_sel_hi:[1,0,1]
	v_mfma_f32_16x16x4_f32 v[102:105], v141, v214, v[102:105]
	v_pk_fma_f32 v[180:181], v[10:11], v[176:177], v[180:181] op_sel:[0,1,0]
	v_pk_fma_f32 v[192:193], v[12:13], v[176:177], v[192:193] op_sel:[0,1,0]
	v_pk_fma_f32 v[180:181], v[6:7], v[178:179], v[180:181] op_sel_hi:[1,0,1]
	v_pk_fma_f32 v[192:193], v[8:9], v[178:179], v[192:193] op_sel_hi:[1,0,1]
	v_mfma_f32_16x16x4_f32 v[98:101], v141, v215, v[98:101]
	v_pk_fma_f32 v[180:181], v[2:3], v[178:179], v[180:181] op_sel:[0,1,0]
	v_pk_fma_f32 v[192:193], v[4:5], v[178:179], v[192:193] op_sel:[0,1,0]
	v_pk_mul_f32 v[180:181], v[146:147], v[180:181]
	v_pk_mul_f32 v[192:193], v[146:147], v[192:193]
	v_pk_fma_f32 v[236:237], v[144:145], v[212:213], v[180:181]
	v_pk_fma_f32 v[238:239], v[144:145], v[214:215], v[192:193]
	global_store_dwordx4 v[150:151], v[236:239], off nt
	v_lshl_add_u64 v[150:151], v[150:151], 0, s[58:59]
	global_load_dwordx4 v[212:215], v[148:149], off nt
	v_lshl_add_u64 v[148:149], v[148:149], 0, s[58:59]
	ds_read_b32 v141, v160 offset:288
	ds_read_b128 v[114:117], v161 offset:2304
	ds_read_b128 v[176:179], v161 offset:2320
	s_waitcnt vmcnt(36)
	s_waitcnt lgkmcnt(3)
	v_cndmask_b32_e64 v143, 0, v143, s[6:7]
	v_pk_mul_f32 v[180:181], v[26:27], v[172:173] op_sel:[0,1]
	v_pk_mul_f32 v[192:193], v[28:29], v[172:173] op_sel:[0,1]
	v_mfma_f32_16x16x4_f32 v[110:113], v143, v216, v[110:113]
	v_pk_fma_f32 v[180:181], v[30:31], v[172:173], v[180:181] op_sel_hi:[1,0,1]
	v_pk_fma_f32 v[192:193], v[32:33], v[172:173], v[192:193] op_sel_hi:[1,0,1]
	v_pk_fma_f32 v[180:181], v[22:23], v[174:175], v[180:181] op_sel_hi:[1,0,1]
	v_pk_fma_f32 v[192:193], v[24:25], v[174:175], v[192:193] op_sel_hi:[1,0,1]
	v_mfma_f32_16x16x4_f32 v[106:109], v143, v217, v[106:109]
	v_pk_fma_f32 v[180:181], v[18:19], v[174:175], v[180:181] op_sel:[0,1,0]
	v_pk_fma_f32 v[192:193], v[20:21], v[174:175], v[192:193] op_sel:[0,1,0]
	v_pk_fma_f32 v[180:181], v[14:15], v[232:233], v[180:181] op_sel_hi:[1,0,1]
	v_pk_fma_f32 v[192:193], v[16:17], v[232:233], v[192:193] op_sel_hi:[1,0,1]
	v_mfma_f32_16x16x4_f32 v[102:105], v143, v218, v[102:105]
	v_pk_fma_f32 v[180:181], v[10:11], v[232:233], v[180:181] op_sel:[0,1,0]
	v_pk_fma_f32 v[192:193], v[12:13], v[232:233], v[192:193] op_sel:[0,1,0]
	v_pk_fma_f32 v[180:181], v[6:7], v[234:235], v[180:181] op_sel_hi:[1,0,1]
	v_pk_fma_f32 v[192:193], v[8:9], v[234:235], v[192:193] op_sel_hi:[1,0,1]
	v_mfma_f32_16x16x4_f32 v[98:101], v143, v219, v[98:101]
	v_pk_fma_f32 v[180:181], v[2:3], v[234:235], v[180:181] op_sel:[0,1,0]
	v_pk_fma_f32 v[192:193], v[4:5], v[234:235], v[192:193] op_sel:[0,1,0]
	v_pk_mul_f32 v[180:181], v[146:147], v[180:181]
	v_pk_mul_f32 v[192:193], v[146:147], v[192:193]
	v_pk_fma_f32 v[236:237], v[144:145], v[216:217], v[180:181]
	v_pk_fma_f32 v[238:239], v[144:145], v[218:219], v[192:193]
	global_store_dwordx4 v[150:151], v[236:239], off nt
	v_lshl_add_u64 v[150:151], v[150:151], 0, s[58:59]
	global_load_dwordx4 v[216:219], v[148:149], off nt
	v_lshl_add_u64 v[148:149], v[148:149], 0, s[58:59]
	ds_read_b32 v143, v160 offset:304
	ds_read_b128 v[172:175], v161 offset:2432
	ds_read_b128 v[232:235], v161 offset:2448
	s_waitcnt vmcnt(37)
	s_waitcnt lgkmcnt(3)
	v_cndmask_b32_e64 v141, 0, v141, s[6:7]
	v_pk_mul_f32 v[180:181], v[26:27], v[114:115] op_sel:[0,1]
	v_pk_mul_f32 v[192:193], v[28:29], v[114:115] op_sel:[0,1]
	v_mfma_f32_16x16x4_f32 v[110:113], v141, v224, v[110:113]
	v_pk_fma_f32 v[180:181], v[30:31], v[114:115], v[180:181] op_sel_hi:[1,0,1]
	v_pk_fma_f32 v[192:193], v[32:33], v[114:115], v[192:193] op_sel_hi:[1,0,1]
	v_pk_fma_f32 v[180:181], v[22:23], v[116:117], v[180:181] op_sel_hi:[1,0,1]
	v_pk_fma_f32 v[192:193], v[24:25], v[116:117], v[192:193] op_sel_hi:[1,0,1]
	v_mfma_f32_16x16x4_f32 v[106:109], v141, v225, v[106:109]
	v_pk_fma_f32 v[180:181], v[18:19], v[116:117], v[180:181] op_sel:[0,1,0]
	v_pk_fma_f32 v[192:193], v[20:21], v[116:117], v[192:193] op_sel:[0,1,0]
	v_pk_fma_f32 v[180:181], v[14:15], v[176:177], v[180:181] op_sel_hi:[1,0,1]
	v_pk_fma_f32 v[192:193], v[16:17], v[176:177], v[192:193] op_sel_hi:[1,0,1]
	v_mfma_f32_16x16x4_f32 v[102:105], v141, v226, v[102:105]
	v_pk_fma_f32 v[180:181], v[10:11], v[176:177], v[180:181] op_sel:[0,1,0]
	v_pk_fma_f32 v[192:193], v[12:13], v[176:177], v[192:193] op_sel:[0,1,0]
	v_pk_fma_f32 v[180:181], v[6:7], v[178:179], v[180:181] op_sel_hi:[1,0,1]
	v_pk_fma_f32 v[192:193], v[8:9], v[178:179], v[192:193] op_sel_hi:[1,0,1]
	v_mfma_f32_16x16x4_f32 v[98:101], v141, v227, v[98:101]
	v_pk_fma_f32 v[180:181], v[2:3], v[178:179], v[180:181] op_sel:[0,1,0]
	v_pk_fma_f32 v[192:193], v[4:5], v[178:179], v[192:193] op_sel:[0,1,0]
	v_pk_mul_f32 v[180:181], v[146:147], v[180:181]
	v_pk_mul_f32 v[192:193], v[146:147], v[192:193]
	v_pk_fma_f32 v[236:237], v[144:145], v[224:225], v[180:181]
	v_pk_fma_f32 v[238:239], v[144:145], v[226:227], v[192:193]
	global_store_dwordx4 v[150:151], v[236:239], off nt
	v_lshl_add_u64 v[150:151], v[150:151], 0, s[58:59]
	global_load_dwordx4 v[224:227], v[148:149], off nt
	v_lshl_add_u64 v[148:149], v[148:149], 0, s[58:59]
	ds_read_b32 v141, v160 offset:320
	ds_read_b128 v[114:117], v161 offset:2560
	ds_read_b128 v[176:179], v161 offset:2576
	s_waitcnt vmcnt(38)
; #define RS_LOAD(dst, it0) do { _Pragma("unroll") for (int u = 0; u < 8; ++u) dst[u] = __builtin_nontemporal_load((const f32x4*)(S0 + (size_t)(4 * ((it0) + u)) * DV)); } while (0)
; __device__ __forceinline__ void ret_sample_item(Frame& F, int item) {
;     ...
;     for (int it0 = 0; it0 < 64; it0 += 16) {
;         RS_LOAD(sb, it0 + 8);
;         RS_PROC(sa, it0);
;         { const int itn = it0 + 16 < 64 ? it0 + 16 : it0; RS_LOAD(sa, itn); }
;         RS_PROC(sb, it0 + 8);
;     }
	s_waitcnt lgkmcnt(3)
	v_cndmask_b32_e64 v143, 0, v143, s[6:7]
	v_pk_mul_f32 v[180:181], v[26:27], v[172:173] op_sel:[0,1]
	v_pk_mul_f32 v[192:193], v[28:29], v[172:173] op_sel:[0,1]
	v_mfma_f32_16x16x4_f32 v[110:113], v143, v228, v[110:113]
	v_pk_fma_f32 v[180:181], v[30:31], v[172:173], v[180:181] op_sel_hi:[1,0,1]
	v_pk_fma_f32 v[192:193], v[32:33], v[172:173], v[192:193] op_sel_hi:[1,0,1]
	v_pk_fma_f32 v[180:181], v[22:23], v[174:175], v[180:181] op_sel_hi:[1,0,1]
	v_pk_fma_f32 v[192:193], v[24:25], v[174:175], v[192:193] op_sel_hi:[1,0,1]
	v_mfma_f32_16x16x4_f32 v[106:109], v143, v229, v[106:109]
	v_pk_fma_f32 v[180:181], v[18:19], v[174:175], v[180:181] op_sel:[0,1,0]
	v_pk_fma_f32 v[192:193], v[20:21], v[174:175], v[192:193] op_sel:[0,1,0]
	v_pk_fma_f32 v[180:181], v[14:15], v[232:233], v[180:181] op_sel_hi:[1,0,1]
	v_pk_fma_f32 v[192:193], v[16:17], v[232:233], v[192:193] op_sel_hi:[1,0,1]
	v_mfma_f32_16x16x4_f32 v[102:105], v143, v230, v[102:105]
	v_pk_fma_f32 v[180:181], v[10:11], v[232:233], v[180:181] op_sel:[0,1,0]
	v_pk_fma_f32 v[192:193], v[12:13], v[232:233], v[192:193] op_sel:[0,1,0]
	v_pk_fma_f32 v[180:181], v[6:7], v[234:235], v[180:181] op_sel_hi:[1,0,1]
	v_pk_fma_f32 v[192:193], v[8:9], v[234:235], v[192:193] op_sel_hi:[1,0,1]
	v_mfma_f32_16x16x4_f32 v[98:101], v143, v231, v[98:101]
	v_pk_fma_f32 v[180:181], v[2:3], v[234:235], v[180:181] op_sel:[0,1,0]
	v_pk_fma_f32 v[192:193], v[4:5], v[234:235], v[192:193] op_sel:[0,1,0]
	v_pk_mul_f32 v[180:181], v[146:147], v[180:181]
	v_pk_mul_f32 v[192:193], v[146:147], v[192:193]
	v_pk_fma_f32 v[236:237], v[144:145], v[228:229], v[180:181]
	v_pk_fma_f32 v[238:239], v[144:145], v[230:231], v[192:193]
	global_store_dwordx4 v[150:151], v[236:239], off nt
	v_lshl_add_u64 v[150:151], v[150:151], 0, s[58:59]
	global_load_dwordx4 v[228:231], v[148:149], off nt
	v_lshl_add_u64 v[148:149], v[148:149], 0, s[58:59]
	ds_read_b32 v143, v160 offset:336
	ds_read_b128 v[172:175], v161 offset:2688
	ds_read_b128 v[232:235], v161 offset:2704
	s_waitcnt vmcnt(38)
	s_waitcnt lgkmcnt(3)
	v_cndmask_b32_e64 v141, 0, v141, s[6:7]
	v_pk_mul_f32 v[180:181], v[26:27], v[114:115] op_sel:[0,1]
	v_pk_mul_f32 v[192:193], v[28:29], v[114:115] op_sel:[0,1]
	v_mfma_f32_16x16x4_f32 v[110:113], v141, v70, v[110:113]
	v_pk_fma_f32 v[180:181], v[30:31], v[114:115], v[180:181] op_sel_hi:[1,0,1]
	v_pk_fma_f32 v[192:193], v[32:33], v[114:115], v[192:193] op_sel_hi:[1,0,1]
	v_pk_fma_f32 v[180:181], v[22:23], v[116:117], v[180:181] op_sel_hi:[1,0,1]
	v_pk_fma_f32 v[192:193], v[24:25], v[116:117], v[192:193] op_sel_hi:[1,0,1]
	v_mfma_f32_16x16x4_f32 v[106:109], v141, v71, v[106:109]
	v_pk_fma_f32 v[180:181], v[18:19], v[116:117], v[180:181] op_sel:[0,1,0]
	v_pk_fma_f32 v[192:193], v[20:21], v[116:117], v[192:193] op_sel:[0,1,0]
	v_pk_fma_f32 v[180:181], v[14:15], v[176:177], v[180:181] op_sel_hi:[1,0,1]
	v_pk_fma_f32 v[192:193], v[16:17], v[176:177], v[192:193] op_sel_hi:[1,0,1]
	v_mfma_f32_16x16x4_f32 v[102:105], v141, v72, v[102:105]
	v_pk_fma_f32 v[180:181], v[10:11], v[176:177], v[180:181] op_sel:[0,1,0]
	v_pk_fma_f32 v[192:193], v[12:13], v[176:177], v[192:193] op_sel:[0,1,0]
	v_pk_fma_f32 v[180:181], v[6:7], v[178:179], v[180:181] op_sel_hi:[1,0,1]
	v_pk_fma_f32 v[192:193], v[8:9], v[178:179], v[192:193] op_sel_hi:[1,0,1]
	v_mfma_f32_16x16x4_f32 v[98:101], v141, v73, v[98:101]
	v_pk_fma_f32 v[180:181], v[2:3], v[178:179], v[180:181] op_sel:[0,1,0]
	v_pk_fma_f32 v[192:193], v[4:5], v[178:179], v[192:193] op_sel:[0,1,0]
	v_pk_mul_f32 v[180:181], v[146:147], v[180:181]
	v_pk_mul_f32 v[192:193], v[146:147], v[192:193]
	v_pk_fma_f32 v[236:237], v[144:145], v[70:71], v[180:181]
	v_pk_fma_f32 v[238:239], v[144:145], v[72:73], v[192:193]
	global_store_dwordx4 v[150:151], v[236:239], off nt
	v_lshl_add_u64 v[150:151], v[150:151], 0, s[58:59]
	global_load_dwordx4 v[70:73], v[148:149], off nt
	v_lshl_add_u64 v[148:149], v[148:149], 0, s[58:59]
	ds_read_b32 v141, v160 offset:352
	ds_read_b128 v[114:117], v161 offset:2816
	ds_read_b128 v[176:179], v161 offset:2832
	s_waitcnt vmcnt(38)
	s_waitcnt lgkmcnt(3)
	v_cndmask_b32_e64 v143, 0, v143, s[6:7]
	v_pk_mul_f32 v[180:181], v[26:27], v[172:173] op_sel:[0,1]
	v_pk_mul_f32 v[192:193], v[28:29], v[172:173] op_sel:[0,1]
	v_mfma_f32_16x16x4_f32 v[110:113], v143, v62, v[110:113]
	v_pk_fma_f32 v[180:181], v[30:31], v[172:173], v[180:181] op_sel_hi:[1,0,1]
	v_pk_fma_f32 v[192:193], v[32:33], v[172:173], v[192:193] op_sel_hi:[1,0,1]
	v_pk_fma_f32 v[180:181], v[22:23], v[174:175], v[180:181] op_sel_hi:[1,0,1]
	v_pk_fma_f32 v[192:193], v[24:25], v[174:175], v[192:193] op_sel_hi:[1,0,1]
	v_mfma_f32_16x16x4_f32 v[106:109], v143, v63, v[106:109]
	v_pk_fma_f32 v[180:181], v[18:19], v[174:175], v[180:181] op_sel:[0,1,0]
	v_pk_fma_f32 v[192:193], v[20:21], v[174:175], v[192:193] op_sel:[0,1,0]
	v_pk_fma_f32 v[180:181], v[14:15], v[232:233], v[180:181] op_sel_hi:[1,0,1]
	v_pk_fma_f32 v[192:193], v[16:17], v[232:233], v[192:193] op_sel_hi:[1,0,1]
	v_mfma_f32_16x16x4_f32 v[102:105], v143, v64, v[102:105]
	v_pk_fma_f32 v[180:181], v[10:11], v[232:233], v[180:181] op_sel:[0,1,0]
	v_pk_fma_f32 v[192:193], v[12:13], v[232:233], v[192:193] op_sel:[0,1,0]
	v_pk_fma_f32 v[180:181], v[6:7], v[234:235], v[180:181] op_sel_hi:[1,0,1]
	v_pk_fma_f32 v[192:193], v[8:9], v[234:235], v[192:193] op_sel_hi:[1,0,1]
	v_mfma_f32_16x16x4_f32 v[98:101], v143, v65, v[98:101]
	v_pk_fma_f32 v[180:181], v[2:3], v[234:235], v[180:181] op_sel:[0,1,0]
	v_pk_fma_f32 v[192:193], v[4:5], v[234:235], v[192:193] op_sel:[0,1,0]
	v_pk_mul_f32 v[180:181], v[146:147], v[180:181]
	v_pk_mul_f32 v[192:193], v[146:147], v[192:193]
	v_pk_fma_f32 v[236:237], v[144:145], v[62:63], v[180:181]
	v_pk_fma_f32 v[238:239], v[144:145], v[64:65], v[192:193]
	global_store_dwordx4 v[150:151], v[236:239], off nt
	v_lshl_add_u64 v[150:151], v[150:151], 0, s[58:59]
	global_load_dwordx4 v[62:65], v[148:149], off nt
	v_lshl_add_u64 v[148:149], v[148:149], 0, s[58:59]
	ds_read_b32 v143, v160 offset:368
	ds_read_b128 v[172:175], v161 offset:2944
	ds_read_b128 v[232:235], v161 offset:2960
	s_waitcnt vmcnt(38)
; #define RS_LOAD(dst, it0) do { _Pragma("unroll") for (int u = 0; u < 8; ++u) dst[u] = __builtin_nontemporal_load((const f32x4*)(S0 + (size_t)(4 * ((it0) + u)) * DV)); } while (0)
; __device__ __forceinline__ void ret_sample_item(Frame& F, int item) {
;     ...
;     for (int it0 = 0; it0 < 64; it0 += 16) {
;         RS_LOAD(sb, it0 + 8);
;         RS_PROC(sa, it0);
;         { const int itn = it0 + 16 < 64 ? it0 + 16 : it0; RS_LOAD(sa, itn); }
;         RS_PROC(sb, it0 + 8);
;     }
	s_waitcnt lgkmcnt(3)
	v_cndmask_b32_e64 v141, 0, v141, s[6:7]
	v_pk_mul_f32 v[180:181], v[26:27], v[114:115] op_sel:[0,1]
	v_pk_mul_f32 v[192:193], v[28:29], v[114:115] op_sel:[0,1]
	v_mfma_f32_16x16x4_f32 v[110:113], v141, v54, v[110:113]
	v_pk_fma_f32 v[180:181], v[30:31], v[114:115], v[180:181] op_sel_hi:[1,0,1]
	v_pk_fma_f32 v[192:193], v[32:33], v[114:115], v[192:193] op_sel_hi:[1,0,1]
	v_pk_fma_f32 v[180:181], v[22:23], v[116:117], v[180:181] op_sel_hi:[1,0,1]
	v_pk_fma_f32 v[192:193], v[24:25], v[116:117], v[192:193] op_sel_hi:[1,0,1]
	v_mfma_f32_16x16x4_f32 v[106:109], v141, v55, v[106:109]
	v_pk_fma_f32 v[180:181], v[18:19], v[116:117], v[180:181] op_sel:[0,1,0]
	v_pk_fma_f32 v[192:193], v[20:21], v[116:117], v[192:193] op_sel:[0,1,0]
	v_pk_fma_f32 v[180:181], v[14:15], v[176:177], v[180:181] op_sel_hi:[1,0,1]
	v_pk_fma_f32 v[192:193], v[16:17], v[176:177], v[192:193] op_sel_hi:[1,0,1]
	v_mfma_f32_16x16x4_f32 v[102:105], v141, v56, v[102:105]
	v_pk_fma_f32 v[180:181], v[10:11], v[176:177], v[180:181] op_sel:[0,1,0]
	v_pk_fma_f32 v[192:193], v[12:13], v[176:177], v[192:193] op_sel:[0,1,0]
	v_pk_fma_f32 v[180:181], v[6:7], v[178:179], v[180:181] op_sel_hi:[1,0,1]
	v_pk_fma_f32 v[192:193], v[8:9], v[178:179], v[192:193] op_sel_hi:[1,0,1]
	v_mfma_f32_16x16x4_f32 v[98:101], v141, v57, v[98:101]
	v_pk_fma_f32 v[180:181], v[2:3], v[178:179], v[180:181] op_sel:[0,1,0]
	v_pk_fma_f32 v[192:193], v[4:5], v[178:179], v[192:193] op_sel:[0,1,0]
	v_pk_mul_f32 v[180:181], v[146:147], v[180:181]
	v_pk_mul_f32 v[192:193], v[146:147], v[192:193]
	v_pk_fma_f32 v[236:237], v[144:145], v[54:55], v[180:181]
	v_pk_fma_f32 v[238:239], v[144:145], v[56:57], v[192:193]
	global_store_dwordx4 v[150:151], v[236:239], off nt
	v_lshl_add_u64 v[150:151], v[150:151], 0, s[58:59]
	global_load_dwordx4 v[54:57], v[148:149], off nt
	v_lshl_add_u64 v[148:149], v[148:149], 0, s[58:59]
	ds_read_b32 v141, v160 offset:384
	ds_read_b128 v[114:117], v161 offset:3072
	ds_read_b128 v[176:179], v161 offset:3088
	s_waitcnt vmcnt(38)
	s_waitcnt lgkmcnt(3)
	v_cndmask_b32_e64 v143, 0, v143, s[6:7]
	v_pk_mul_f32 v[180:181], v[26:27], v[172:173] op_sel:[0,1]
	v_pk_mul_f32 v[192:193], v[28:29], v[172:173] op_sel:[0,1]
	v_mfma_f32_16x16x4_f32 v[110:113], v143, v50, v[110:113]
	v_pk_fma_f32 v[180:181], v[30:31], v[172:173], v[180:181] op_sel_hi:[1,0,1]
	v_pk_fma_f32 v[192:193], v[32:33], v[172:173], v[192:193] op_sel_hi:[1,0,1]
	v_pk_fma_f32 v[180:181], v[22:23], v[174:175], v[180:181] op_sel_hi:[1,0,1]
	v_pk_fma_f32 v[192:193], v[24:25], v[174:175], v[192:193] op_sel_hi:[1,0,1]
	v_mfma_f32_16x16x4_f32 v[106:109], v143, v51, v[106:109]
	v_pk_fma_f32 v[180:181], v[18:19], v[174:175], v[180:181] op_sel:[0,1,0]
	v_pk_fma_f32 v[192:193], v[20:21], v[174:175], v[192:193] op_sel:[0,1,0]
	v_pk_fma_f32 v[180:181], v[14:15], v[232:233], v[180:181] op_sel_hi:[1,0,1]
	v_pk_fma_f32 v[192:193], v[16:17], v[232:233], v[192:193] op_sel_hi:[1,0,1]
	v_mfma_f32_16x16x4_f32 v[102:105], v143, v52, v[102:105]
	v_pk_fma_f32 v[180:181], v[10:11], v[232:233], v[180:181] op_sel:[0,1,0]
	v_pk_fma_f32 v[192:193], v[12:13], v[232:233], v[192:193] op_sel:[0,1,0]
	v_pk_fma_f32 v[180:181], v[6:7], v[234:235], v[180:181] op_sel_hi:[1,0,1]
	v_pk_fma_f32 v[192:193], v[8:9], v[234:235], v[192:193] op_sel_hi:[1,0,1]
	v_mfma_f32_16x16x4_f32 v[98:101], v143, v53, v[98:101]
	v_pk_fma_f32 v[180:181], v[2:3], v[234:235], v[180:181] op_sel:[0,1,0]
	v_pk_fma_f32 v[192:193], v[4:5], v[234:235], v[192:193] op_sel:[0,1,0]
	v_pk_mul_f32 v[180:181], v[146:147], v[180:181]
	v_pk_mul_f32 v[192:193], v[146:147], v[192:193]
	v_pk_fma_f32 v[236:237], v[144:145], v[50:51], v[180:181]
	v_pk_fma_f32 v[238:239], v[144:145], v[52:53], v[192:193]
	global_store_dwordx4 v[150:151], v[236:239], off nt
	v_lshl_add_u64 v[150:151], v[150:151], 0, s[58:59]
	global_load_dwordx4 v[50:53], v[148:149], off nt
	v_lshl_add_u64 v[148:149], v[148:149], 0, s[58:59]
	ds_read_b32 v143, v160 offset:400
	ds_read_b128 v[172:175], v161 offset:3200
	ds_read_b128 v[232:235], v161 offset:3216
	s_waitcnt vmcnt(38)
	s_waitcnt lgkmcnt(3)
	v_cndmask_b32_e64 v141, 0, v141, s[6:7]
	v_pk_mul_f32 v[180:181], v[26:27], v[114:115] op_sel:[0,1]
	v_pk_mul_f32 v[192:193], v[28:29], v[114:115] op_sel:[0,1]
	v_mfma_f32_16x16x4_f32 v[110:113], v141, v46, v[110:113]
	v_pk_fma_f32 v[180:181], v[30:31], v[114:115], v[180:181] op_sel_hi:[1,0,1]
	v_pk_fma_f32 v[192:193], v[32:33], v[114:115], v[192:193] op_sel_hi:[1,0,1]
	v_pk_fma_f32 v[180:181], v[22:23], v[116:117], v[180:181] op_sel_hi:[1,0,1]
	v_pk_fma_f32 v[192:193], v[24:25], v[116:117], v[192:193] op_sel_hi:[1,0,1]
	v_mfma_f32_16x16x4_f32 v[106:109], v141, v47, v[106:109]
	v_pk_fma_f32 v[180:181], v[18:19], v[116:117], v[180:181] op_sel:[0,1,0]
	v_pk_fma_f32 v[192:193], v[20:21], v[116:117], v[192:193] op_sel:[0,1,0]
	v_pk_fma_f32 v[180:181], v[14:15], v[176:177], v[180:181] op_sel_hi:[1,0,1]
	v_pk_fma_f32 v[192:193], v[16:17], v[176:177], v[192:193] op_sel_hi:[1,0,1]
	v_mfma_f32_16x16x4_f32 v[102:105], v141, v48, v[102:105]
	v_pk_fma_f32 v[180:181], v[10:11], v[176:177], v[180:181] op_sel:[0,1,0]
	v_pk_fma_f32 v[192:193], v[12:13], v[176:177], v[192:193] op_sel:[0,1,0]
	v_pk_fma_f32 v[180:181], v[6:7], v[178:179], v[180:181] op_sel_hi:[1,0,1]
	v_pk_fma_f32 v[192:193], v[8:9], v[178:179], v[192:193] op_sel_hi:[1,0,1]
	v_mfma_f32_16x16x4_f32 v[98:101], v141, v49, v[98:101]
	v_pk_fma_f32 v[180:181], v[2:3], v[178:179], v[180:181] op_sel:[0,1,0]
	v_pk_fma_f32 v[192:193], v[4:5], v[178:179], v[192:193] op_sel:[0,1,0]
	v_pk_mul_f32 v[180:181], v[146:147], v[180:181]
	v_pk_mul_f32 v[192:193], v[146:147], v[192:193]
	v_pk_fma_f32 v[236:237], v[144:145], v[46:47], v[180:181]
	v_pk_fma_f32 v[238:239], v[144:145], v[48:49], v[192:193]
	global_store_dwordx4 v[150:151], v[236:239], off nt
	v_lshl_add_u64 v[150:151], v[150:151], 0, s[58:59]
	global_load_dwordx4 v[46:49], v[148:149], off nt
	v_lshl_add_u64 v[148:149], v[148:149], 0, s[58:59]
	ds_read_b32 v141, v160 offset:416
	ds_read_b128 v[114:117], v161 offset:3328
	ds_read_b128 v[176:179], v161 offset:3344
	s_waitcnt vmcnt(38)
; #define RS_LOAD(dst, it0) do { _Pragma("unroll") for (int u = 0; u < 8; ++u) dst[u] = __builtin_nontemporal_load((const f32x4*)(S0 + (size_t)(4 * ((it0) + u)) * DV)); } while (0)
; __device__ __forceinline__ void ret_sample_item(Frame& F, int item) {
;     ...
;     for (int it0 = 0; it0 < 64; it0 += 16) {
;         RS_LOAD(sb, it0 + 8);
;         RS_PROC(sa, it0);
;         { const int itn = it0 + 16 < 64 ? it0 + 16 : it0; RS_LOAD(sa, itn); }
;         RS_PROC(sb, it0 + 8);
;     }
	s_waitcnt lgkmcnt(3)
	v_cndmask_b32_e64 v143, 0, v143, s[6:7]
	v_pk_mul_f32 v[180:181], v[26:27], v[172:173] op_sel:[0,1]
	v_pk_mul_f32 v[192:193], v[28:29], v[172:173] op_sel:[0,1]
	v_mfma_f32_16x16x4_f32 v[110:113], v143, v42, v[110:113]
	v_pk_fma_f32 v[180:181], v[30:31], v[172:173], v[180:181] op_sel_hi:[1,0,1]
	v_pk_fma_f32 v[192:193], v[32:33], v[172:173], v[192:193] op_sel_hi:[1,0,1]
	v_pk_fma_f32 v[180:181], v[22:23], v[174:175], v[180:181] op_sel_hi:[1,0,1]
	v_pk_fma_f32 v[192:193], v[24:25], v[174:175], v[192:193] op_sel_hi:[1,0,1]
	v_mfma_f32_16x16x4_f32 v[106:109], v143, v43, v[106:109]
	v_pk_fma_f32 v[180:181], v[18:19], v[174:175], v[180:181] op_sel:[0,1,0]
	v_pk_fma_f32 v[192:193], v[20:21], v[174:175], v[192:193] op_sel:[0,1,0]
	v_pk_fma_f32 v[180:181], v[14:15], v[232:233], v[180:181] op_sel_hi:[1,0,1]
	v_pk_fma_f32 v[192:193], v[16:17], v[232:233], v[192:193] op_sel_hi:[1,0,1]
	v_mfma_f32_16x16x4_f32 v[102:105], v143, v44, v[102:105]
	v_pk_fma_f32 v[180:181], v[10:11], v[232:233], v[180:181] op_sel:[0,1,0]
	v_pk_fma_f32 v[192:193], v[12:13], v[232:233], v[192:193] op_sel:[0,1,0]
	v_pk_fma_f32 v[180:181], v[6:7], v[234:235], v[180:181] op_sel_hi:[1,0,1]
	v_pk_fma_f32 v[192:193], v[8:9], v[234:235], v[192:193] op_sel_hi:[1,0,1]
	v_mfma_f32_16x16x4_f32 v[98:101], v143, v45, v[98:101]
	v_pk_fma_f32 v[180:181], v[2:3], v[234:235], v[180:181] op_sel:[0,1,0]
	v_pk_fma_f32 v[192:193], v[4:5], v[234:235], v[192:193] op_sel:[0,1,0]
	v_pk_mul_f32 v[180:181], v[146:147], v[180:181]
	v_pk_mul_f32 v[192:193], v[146:147], v[192:193]
	v_pk_fma_f32 v[236:237], v[144:145], v[42:43], v[180:181]
	v_pk_fma_f32 v[238:239], v[144:145], v[44:45], v[192:193]
	global_store_dwordx4 v[150:151], v[236:239], off nt
	v_lshl_add_u64 v[150:151], v[150:151], 0, s[58:59]
	global_load_dwordx4 v[42:45], v[148:149], off nt
	v_lshl_add_u64 v[148:149], v[148:149], 0, s[58:59]
	ds_read_b32 v143, v160 offset:432
	ds_read_b128 v[172:175], v161 offset:3456
	ds_read_b128 v[232:235], v161 offset:3472
	s_waitcnt vmcnt(38)
	s_waitcnt lgkmcnt(3)
	v_cndmask_b32_e64 v141, 0, v141, s[6:7]
	v_pk_mul_f32 v[180:181], v[26:27], v[114:115] op_sel:[0,1]
	v_pk_mul_f32 v[192:193], v[28:29], v[114:115] op_sel:[0,1]
	v_mfma_f32_16x16x4_f32 v[110:113], v141, v38, v[110:113]
	v_pk_fma_f32 v[180:181], v[30:31], v[114:115], v[180:181] op_sel_hi:[1,0,1]
	v_pk_fma_f32 v[192:193], v[32:33], v[114:115], v[192:193] op_sel_hi:[1,0,1]
	v_pk_fma_f32 v[180:181], v[22:23], v[116:117], v[180:181] op_sel_hi:[1,0,1]
	v_pk_fma_f32 v[192:193], v[24:25], v[116:117], v[192:193] op_sel_hi:[1,0,1]
	v_mfma_f32_16x16x4_f32 v[106:109], v141, v39, v[106:109]
	v_pk_fma_f32 v[180:181], v[18:19], v[116:117], v[180:181] op_sel:[0,1,0]
	v_pk_fma_f32 v[192:193], v[20:21], v[116:117], v[192:193] op_sel:[0,1,0]
	v_pk_fma_f32 v[180:181], v[14:15], v[176:177], v[180:181] op_sel_hi:[1,0,1]
	v_pk_fma_f32 v[192:193], v[16:17], v[176:177], v[192:193] op_sel_hi:[1,0,1]
	v_mfma_f32_16x16x4_f32 v[102:105], v141, v40, v[102:105]
	v_pk_fma_f32 v[180:181], v[10:11], v[176:177], v[180:181] op_sel:[0,1,0]
	v_pk_fma_f32 v[192:193], v[12:13], v[176:177], v[192:193] op_sel:[0,1,0]
	v_pk_fma_f32 v[180:181], v[6:7], v[178:179], v[180:181] op_sel_hi:[1,0,1]
	v_pk_fma_f32 v[192:193], v[8:9], v[178:179], v[192:193] op_sel_hi:[1,0,1]
	v_mfma_f32_16x16x4_f32 v[98:101], v141, v41, v[98:101]
	v_pk_fma_f32 v[180:181], v[2:3], v[178:179], v[180:181] op_sel:[0,1,0]
	v_pk_fma_f32 v[192:193], v[4:5], v[178:179], v[192:193] op_sel:[0,1,0]
	v_pk_mul_f32 v[180:181], v[146:147], v[180:181]
	v_pk_mul_f32 v[192:193], v[146:147], v[192:193]
	v_pk_fma_f32 v[236:237], v[144:145], v[38:39], v[180:181]
	v_pk_fma_f32 v[238:239], v[144:145], v[40:41], v[192:193]
	global_store_dwordx4 v[150:151], v[236:239], off nt
	v_lshl_add_u64 v[150:151], v[150:151], 0, s[58:59]
	global_load_dwordx4 v[38:41], v[148:149], off nt
	v_lshl_add_u64 v[148:149], v[148:149], 0, s[58:59]
	ds_read_b32 v141, v160 offset:448
	ds_read_b128 v[114:117], v161 offset:3584
	ds_read_b128 v[176:179], v161 offset:3600
	s_waitcnt vmcnt(38)
	s_waitcnt lgkmcnt(3)
	v_cndmask_b32_e64 v143, 0, v143, s[6:7]
	v_pk_mul_f32 v[180:181], v[26:27], v[172:173] op_sel:[0,1]
	v_pk_mul_f32 v[192:193], v[28:29], v[172:173] op_sel:[0,1]
	v_mfma_f32_16x16x4_f32 v[110:113], v143, v34, v[110:113]
	v_pk_fma_f32 v[180:181], v[30:31], v[172:173], v[180:181] op_sel_hi:[1,0,1]
	v_pk_fma_f32 v[192:193], v[32:33], v[172:173], v[192:193] op_sel_hi:[1,0,1]
	v_pk_fma_f32 v[180:181], v[22:23], v[174:175], v[180:181] op_sel_hi:[1,0,1]
	v_pk_fma_f32 v[192:193], v[24:25], v[174:175], v[192:193] op_sel_hi:[1,0,1]
	v_mfma_f32_16x16x4_f32 v[106:109], v143, v35, v[106:109]
	v_pk_fma_f32 v[180:181], v[18:19], v[174:175], v[180:181] op_sel:[0,1,0]
	v_pk_fma_f32 v[192:193], v[20:21], v[174:175], v[192:193] op_sel:[0,1,0]
	v_pk_fma_f32 v[180:181], v[14:15], v[232:233], v[180:181] op_sel_hi:[1,0,1]
	v_pk_fma_f32 v[192:193], v[16:17], v[232:233], v[192:193] op_sel_hi:[1,0,1]
	v_mfma_f32_16x16x4_f32 v[102:105], v143, v36, v[102:105]
	v_pk_fma_f32 v[180:181], v[10:11], v[232:233], v[180:181] op_sel:[0,1,0]
	v_pk_fma_f32 v[192:193], v[12:13], v[232:233], v[192:193] op_sel:[0,1,0]
	v_pk_fma_f32 v[180:181], v[6:7], v[234:235], v[180:181] op_sel_hi:[1,0,1]
	v_pk_fma_f32 v[192:193], v[8:9], v[234:235], v[192:193] op_sel_hi:[1,0,1]
	v_mfma_f32_16x16x4_f32 v[98:101], v143, v37, v[98:101]
	v_pk_fma_f32 v[180:181], v[2:3], v[234:235], v[180:181] op_sel:[0,1,0]
	v_pk_fma_f32 v[192:193], v[4:5], v[234:235], v[192:193] op_sel:[0,1,0]
	v_pk_mul_f32 v[180:181], v[146:147], v[180:181]
	v_pk_mul_f32 v[192:193], v[146:147], v[192:193]
	v_pk_fma_f32 v[236:237], v[144:145], v[34:35], v[180:181]
	v_pk_fma_f32 v[238:239], v[144:145], v[36:37], v[192:193]
	global_store_dwordx4 v[150:151], v[236:239], off nt
	v_lshl_add_u64 v[150:151], v[150:151], 0, s[58:59]
	global_load_dwordx4 v[34:37], v[148:149], off nt
	v_lshl_add_u64 v[148:149], v[148:149], 0, s[58:59]
	ds_read_b32 v143, v160 offset:464
	ds_read_b128 v[172:175], v161 offset:3712
	ds_read_b128 v[232:235], v161 offset:3728
	s_waitcnt vmcnt(38)
; #define RS_LOAD(dst, it0) do { _Pragma("unroll") for (int u = 0; u < 8; ++u) dst[u] = __builtin_nontemporal_load((const f32x4*)(S0 + (size_t)(4 * ((it0) + u)) * DV)); } while (0)
; __device__ __forceinline__ void ret_sample_item(Frame& F, int item) {
;     ...
;     for (int it0 = 0; it0 < 64; it0 += 16) {
;         RS_LOAD(sb, it0 + 8);
;         RS_PROC(sa, it0);
;         { const int itn = it0 + 16 < 64 ? it0 + 16 : it0; RS_LOAD(sa, itn); }
;         RS_PROC(sb, it0 + 8);
;     }
	s_waitcnt lgkmcnt(3)
	v_cndmask_b32_e64 v141, 0, v141, s[6:7]
	v_pk_mul_f32 v[180:181], v[26:27], v[114:115] op_sel:[0,1]
	v_pk_mul_f32 v[192:193], v[28:29], v[114:115] op_sel:[0,1]
	v_mfma_f32_16x16x4_f32 v[110:113], v141, v58, v[110:113]
	v_pk_fma_f32 v[180:181], v[30:31], v[114:115], v[180:181] op_sel_hi:[1,0,1]
	v_pk_fma_f32 v[192:193], v[32:33], v[114:115], v[192:193] op_sel_hi:[1,0,1]
	v_pk_fma_f32 v[180:181], v[22:23], v[116:117], v[180:181] op_sel_hi:[1,0,1]
	v_pk_fma_f32 v[192:193], v[24:25], v[116:117], v[192:193] op_sel_hi:[1,0,1]
	v_mfma_f32_16x16x4_f32 v[106:109], v141, v59, v[106:109]
	v_pk_fma_f32 v[180:181], v[18:19], v[116:117], v[180:181] op_sel:[0,1,0]
	v_pk_fma_f32 v[192:193], v[20:21], v[116:117], v[192:193] op_sel:[0,1,0]
	v_pk_fma_f32 v[180:181], v[14:15], v[176:177], v[180:181] op_sel_hi:[1,0,1]
	v_pk_fma_f32 v[192:193], v[16:17], v[176:177], v[192:193] op_sel_hi:[1,0,1]
	v_mfma_f32_16x16x4_f32 v[102:105], v141, v60, v[102:105]
	v_pk_fma_f32 v[180:181], v[10:11], v[176:177], v[180:181] op_sel:[0,1,0]
	v_pk_fma_f32 v[192:193], v[12:13], v[176:177], v[192:193] op_sel:[0,1,0]
	v_pk_fma_f32 v[180:181], v[6:7], v[178:179], v[180:181] op_sel_hi:[1,0,1]
	v_pk_fma_f32 v[192:193], v[8:9], v[178:179], v[192:193] op_sel_hi:[1,0,1]
	v_mfma_f32_16x16x4_f32 v[98:101], v141, v61, v[98:101]
	v_pk_fma_f32 v[180:181], v[2:3], v[178:179], v[180:181] op_sel:[0,1,0]
	v_pk_fma_f32 v[192:193], v[4:5], v[178:179], v[192:193] op_sel:[0,1,0]
	v_pk_mul_f32 v[180:181], v[146:147], v[180:181]
	v_pk_mul_f32 v[192:193], v[146:147], v[192:193]
	v_pk_fma_f32 v[236:237], v[144:145], v[58:59], v[180:181]
	v_pk_fma_f32 v[238:239], v[144:145], v[60:61], v[192:193]
	global_store_dwordx4 v[150:151], v[236:239], off nt
	v_lshl_add_u64 v[150:151], v[150:151], 0, s[58:59]
	global_load_dwordx4 v[58:61], v[148:149], off nt
	v_lshl_add_u64 v[148:149], v[148:149], 0, s[58:59]
	ds_read_b32 v141, v160 offset:480
	ds_read_b128 v[114:117], v161 offset:3840
	ds_read_b128 v[176:179], v161 offset:3856
	s_waitcnt vmcnt(38)
	s_waitcnt lgkmcnt(3)
	v_cndmask_b32_e64 v143, 0, v143, s[6:7]
	v_pk_mul_f32 v[180:181], v[26:27], v[172:173] op_sel:[0,1]
	v_pk_mul_f32 v[192:193], v[28:29], v[172:173] op_sel:[0,1]
	v_mfma_f32_16x16x4_f32 v[110:113], v143, v66, v[110:113]
	v_pk_fma_f32 v[180:181], v[30:31], v[172:173], v[180:181] op_sel_hi:[1,0,1]
	v_pk_fma_f32 v[192:193], v[32:33], v[172:173], v[192:193] op_sel_hi:[1,0,1]
	v_pk_fma_f32 v[180:181], v[22:23], v[174:175], v[180:181] op_sel_hi:[1,0,1]
	v_pk_fma_f32 v[192:193], v[24:25], v[174:175], v[192:193] op_sel_hi:[1,0,1]
	v_mfma_f32_16x16x4_f32 v[106:109], v143, v67, v[106:109]
	v_pk_fma_f32 v[180:181], v[18:19], v[174:175], v[180:181] op_sel:[0,1,0]
	v_pk_fma_f32 v[192:193], v[20:21], v[174:175], v[192:193] op_sel:[0,1,0]
	v_pk_fma_f32 v[180:181], v[14:15], v[232:233], v[180:181] op_sel_hi:[1,0,1]
	v_pk_fma_f32 v[192:193], v[16:17], v[232:233], v[192:193] op_sel_hi:[1,0,1]
	v_mfma_f32_16x16x4_f32 v[102:105], v143, v68, v[102:105]
	v_pk_fma_f32 v[180:181], v[10:11], v[232:233], v[180:181] op_sel:[0,1,0]
	v_pk_fma_f32 v[192:193], v[12:13], v[232:233], v[192:193] op_sel:[0,1,0]
	v_pk_fma_f32 v[180:181], v[6:7], v[234:235], v[180:181] op_sel_hi:[1,0,1]
	v_pk_fma_f32 v[192:193], v[8:9], v[234:235], v[192:193] op_sel_hi:[1,0,1]
	v_mfma_f32_16x16x4_f32 v[98:101], v143, v69, v[98:101]
	v_pk_fma_f32 v[180:181], v[2:3], v[234:235], v[180:181] op_sel:[0,1,0]
	v_pk_fma_f32 v[192:193], v[4:5], v[234:235], v[192:193] op_sel:[0,1,0]
	v_pk_mul_f32 v[180:181], v[146:147], v[180:181]
	v_pk_mul_f32 v[192:193], v[146:147], v[192:193]
	v_pk_fma_f32 v[236:237], v[144:145], v[66:67], v[180:181]
	v_pk_fma_f32 v[238:239], v[144:145], v[68:69], v[192:193]
	global_store_dwordx4 v[150:151], v[236:239], off nt
	v_lshl_add_u64 v[150:151], v[150:151], 0, s[58:59]
	global_load_dwordx4 v[66:69], v[148:149], off nt
	v_lshl_add_u64 v[148:149], v[148:149], 0, s[58:59]
	ds_read_b32 v143, v160 offset:496
	ds_read_b128 v[172:175], v161 offset:3968
	ds_read_b128 v[232:235], v161 offset:3984
	s_waitcnt vmcnt(38)
	s_waitcnt lgkmcnt(3)
	v_cndmask_b32_e64 v141, 0, v141, s[6:7]
	v_pk_mul_f32 v[180:181], v[26:27], v[114:115] op_sel:[0,1]
	v_pk_mul_f32 v[192:193], v[28:29], v[114:115] op_sel:[0,1]
	v_mfma_f32_16x16x4_f32 v[110:113], v141, v74, v[110:113]
	v_pk_fma_f32 v[180:181], v[30:31], v[114:115], v[180:181] op_sel_hi:[1,0,1]
	v_pk_fma_f32 v[192:193], v[32:33], v[114:115], v[192:193] op_sel_hi:[1,0,1]
	v_pk_fma_f32 v[180:181], v[22:23], v[116:117], v[180:181] op_sel_hi:[1,0,1]
	v_pk_fma_f32 v[192:193], v[24:25], v[116:117], v[192:193] op_sel_hi:[1,0,1]
	v_mfma_f32_16x16x4_f32 v[106:109], v141, v75, v[106:109]
	v_pk_fma_f32 v[180:181], v[18:19], v[116:117], v[180:181] op_sel:[0,1,0]
	v_pk_fma_f32 v[192:193], v[20:21], v[116:117], v[192:193] op_sel:[0,1,0]
	v_pk_fma_f32 v[180:181], v[14:15], v[176:177], v[180:181] op_sel_hi:[1,0,1]
	v_pk_fma_f32 v[192:193], v[16:17], v[176:177], v[192:193] op_sel_hi:[1,0,1]
	v_mfma_f32_16x16x4_f32 v[102:105], v141, v76, v[102:105]
	v_pk_fma_f32 v[180:181], v[10:11], v[176:177], v[180:181] op_sel:[0,1,0]
	v_pk_fma_f32 v[192:193], v[12:13], v[176:177], v[192:193] op_sel:[0,1,0]
	v_pk_fma_f32 v[180:181], v[6:7], v[178:179], v[180:181] op_sel_hi:[1,0,1]
	v_pk_fma_f32 v[192:193], v[8:9], v[178:179], v[192:193] op_sel_hi:[1,0,1]
	v_mfma_f32_16x16x4_f32 v[98:101], v141, v77, v[98:101]
	v_pk_fma_f32 v[180:181], v[2:3], v[178:179], v[180:181] op_sel:[0,1,0]
	v_pk_fma_f32 v[192:193], v[4:5], v[178:179], v[192:193] op_sel:[0,1,0]
	v_pk_mul_f32 v[180:181], v[146:147], v[180:181]
	v_pk_mul_f32 v[192:193], v[146:147], v[192:193]
	v_pk_fma_f32 v[236:237], v[144:145], v[74:75], v[180:181]
	v_pk_fma_f32 v[238:239], v[144:145], v[76:77], v[192:193]
	global_store_dwordx4 v[150:151], v[236:239], off nt
	v_lshl_add_u64 v[150:151], v[150:151], 0, s[58:59]
	global_load_dwordx4 v[74:77], v[148:149], off nt
	v_lshl_add_u64 v[148:149], v[148:149], 0, s[58:59]
	ds_read_b32 v141, v160 offset:512
	ds_read_b128 v[114:117], v161 offset:4096
	ds_read_b128 v[176:179], v161 offset:4112
	s_waitcnt vmcnt(38)
; #define RS_LOAD(dst, it0) do { _Pragma("unroll") for (int u = 0; u < 8; ++u) dst[u] = __builtin_nontemporal_load((const f32x4*)(S0 + (size_t)(4 * ((it0) + u)) * DV)); } while (0)
; __device__ __forceinline__ void ret_sample_item(Frame& F, int item) {
;     ...
;     for (int it0 = 0; it0 < 64; it0 += 16) {
;         RS_LOAD(sb, it0 + 8);
;         RS_PROC(sa, it0);
;         { const int itn = it0 + 16 < 64 ? it0 + 16 : it0; RS_LOAD(sa, itn); }
;         RS_PROC(sb, it0 + 8);
;     }
	s_waitcnt lgkmcnt(3)
	v_cndmask_b32_e64 v143, 0, v143, s[6:7]
	v_pk_mul_f32 v[180:181], v[26:27], v[172:173] op_sel:[0,1]
	v_pk_mul_f32 v[192:193], v[28:29], v[172:173] op_sel:[0,1]
	v_mfma_f32_16x16x4_f32 v[110:113], v143, v78, v[110:113]
	v_pk_fma_f32 v[180:181], v[30:31], v[172:173], v[180:181] op_sel_hi:[1,0,1]
	v_pk_fma_f32 v[192:193], v[32:33], v[172:173], v[192:193] op_sel_hi:[1,0,1]
	v_pk_fma_f32 v[180:181], v[22:23], v[174:175], v[180:181] op_sel_hi:[1,0,1]
	v_pk_fma_f32 v[192:193], v[24:25], v[174:175], v[192:193] op_sel_hi:[1,0,1]
	v_mfma_f32_16x16x4_f32 v[106:109], v143, v79, v[106:109]
	v_pk_fma_f32 v[180:181], v[18:19], v[174:175], v[180:181] op_sel:[0,1,0]
	v_pk_fma_f32 v[192:193], v[20:21], v[174:175], v[192:193] op_sel:[0,1,0]
	v_pk_fma_f32 v[180:181], v[14:15], v[232:233], v[180:181] op_sel_hi:[1,0,1]
	v_pk_fma_f32 v[192:193], v[16:17], v[232:233], v[192:193] op_sel_hi:[1,0,1]
	v_mfma_f32_16x16x4_f32 v[102:105], v143, v80, v[102:105]
	v_pk_fma_f32 v[180:181], v[10:11], v[232:233], v[180:181] op_sel:[0,1,0]
	v_pk_fma_f32 v[192:193], v[12:13], v[232:233], v[192:193] op_sel:[0,1,0]
	v_pk_fma_f32 v[180:181], v[6:7], v[234:235], v[180:181] op_sel_hi:[1,0,1]
	v_pk_fma_f32 v[192:193], v[8:9], v[234:235], v[192:193] op_sel_hi:[1,0,1]
	v_mfma_f32_16x16x4_f32 v[98:101], v143, v81, v[98:101]
	v_pk_fma_f32 v[180:181], v[2:3], v[234:235], v[180:181] op_sel:[0,1,0]
	v_pk_fma_f32 v[192:193], v[4:5], v[234:235], v[192:193] op_sel:[0,1,0]
	v_pk_mul_f32 v[180:181], v[146:147], v[180:181]
	v_pk_mul_f32 v[192:193], v[146:147], v[192:193]
	v_pk_fma_f32 v[236:237], v[144:145], v[78:79], v[180:181]
	v_pk_fma_f32 v[238:239], v[144:145], v[80:81], v[192:193]
	global_store_dwordx4 v[150:151], v[236:239], off nt
	v_lshl_add_u64 v[150:151], v[150:151], 0, s[58:59]
	global_load_dwordx4 v[78:81], v[148:149], off nt
	v_lshl_add_u64 v[148:149], v[148:149], 0, s[58:59]
	ds_read_b32 v143, v160 offset:528
	ds_read_b128 v[172:175], v161 offset:4224
	ds_read_b128 v[232:235], v161 offset:4240
	s_waitcnt vmcnt(38)
	s_waitcnt lgkmcnt(3)
	v_cndmask_b32_e64 v141, 0, v141, s[6:7]
	v_pk_mul_f32 v[180:181], v[26:27], v[114:115] op_sel:[0,1]
	v_pk_mul_f32 v[192:193], v[28:29], v[114:115] op_sel:[0,1]
	v_mfma_f32_16x16x4_f32 v[110:113], v141, v82, v[110:113]
	v_pk_fma_f32 v[180:181], v[30:31], v[114:115], v[180:181] op_sel_hi:[1,0,1]
	v_pk_fma_f32 v[192:193], v[32:33], v[114:115], v[192:193] op_sel_hi:[1,0,1]
	v_pk_fma_f32 v[180:181], v[22:23], v[116:117], v[180:181] op_sel_hi:[1,0,1]
	v_pk_fma_f32 v[192:193], v[24:25], v[116:117], v[192:193] op_sel_hi:[1,0,1]
	v_mfma_f32_16x16x4_f32 v[106:109], v141, v83, v[106:109]
	v_pk_fma_f32 v[180:181], v[18:19], v[116:117], v[180:181] op_sel:[0,1,0]
	v_pk_fma_f32 v[192:193], v[20:21], v[116:117], v[192:193] op_sel:[0,1,0]
	v_pk_fma_f32 v[180:181], v[14:15], v[176:177], v[180:181] op_sel_hi:[1,0,1]
	v_pk_fma_f32 v[192:193], v[16:17], v[176:177], v[192:193] op_sel_hi:[1,0,1]
	v_mfma_f32_16x16x4_f32 v[102:105], v141, v84, v[102:105]
	v_pk_fma_f32 v[180:181], v[10:11], v[176:177], v[180:181] op_sel:[0,1,0]
	v_pk_fma_f32 v[192:193], v[12:13], v[176:177], v[192:193] op_sel:[0,1,0]
	v_pk_fma_f32 v[180:181], v[6:7], v[178:179], v[180:181] op_sel_hi:[1,0,1]
	v_pk_fma_f32 v[192:193], v[8:9], v[178:179], v[192:193] op_sel_hi:[1,0,1]
	v_mfma_f32_16x16x4_f32 v[98:101], v141, v85, v[98:101]
	v_pk_fma_f32 v[180:181], v[2:3], v[178:179], v[180:181] op_sel:[0,1,0]
	v_pk_fma_f32 v[192:193], v[4:5], v[178:179], v[192:193] op_sel:[0,1,0]
	v_pk_mul_f32 v[180:181], v[146:147], v[180:181]
	v_pk_mul_f32 v[192:193], v[146:147], v[192:193]
	v_pk_fma_f32 v[236:237], v[144:145], v[82:83], v[180:181]
	v_pk_fma_f32 v[238:239], v[144:145], v[84:85], v[192:193]
	global_store_dwordx4 v[150:151], v[236:239], off nt
	v_lshl_add_u64 v[150:151], v[150:151], 0, s[58:59]
	global_load_dwordx4 v[82:85], v[148:149], off nt
	v_lshl_add_u64 v[148:149], v[148:149], 0, s[58:59]
	ds_read_b32 v141, v160 offset:544
	ds_read_b128 v[114:117], v161 offset:4352
	ds_read_b128 v[176:179], v161 offset:4368
	s_waitcnt vmcnt(38)
	s_waitcnt lgkmcnt(3)
	v_cndmask_b32_e64 v143, 0, v143, s[6:7]
	v_pk_mul_f32 v[180:181], v[26:27], v[172:173] op_sel:[0,1]
	v_pk_mul_f32 v[192:193], v[28:29], v[172:173] op_sel:[0,1]
	v_mfma_f32_16x16x4_f32 v[110:113], v143, v86, v[110:113]
	v_pk_fma_f32 v[180:181], v[30:31], v[172:173], v[180:181] op_sel_hi:[1,0,1]
	v_pk_fma_f32 v[192:193], v[32:33], v[172:173], v[192:193] op_sel_hi:[1,0,1]
	v_pk_fma_f32 v[180:181], v[22:23], v[174:175], v[180:181] op_sel_hi:[1,0,1]
	v_pk_fma_f32 v[192:193], v[24:25], v[174:175], v[192:193] op_sel_hi:[1,0,1]
	v_mfma_f32_16x16x4_f32 v[106:109], v143, v87, v[106:109]
	v_pk_fma_f32 v[180:181], v[18:19], v[174:175], v[180:181] op_sel:[0,1,0]
	v_pk_fma_f32 v[192:193], v[20:21], v[174:175], v[192:193] op_sel:[0,1,0]
	v_pk_fma_f32 v[180:181], v[14:15], v[232:233], v[180:181] op_sel_hi:[1,0,1]
	v_pk_fma_f32 v[192:193], v[16:17], v[232:233], v[192:193] op_sel_hi:[1,0,1]
	v_mfma_f32_16x16x4_f32 v[102:105], v143, v88, v[102:105]
	v_pk_fma_f32 v[180:181], v[10:11], v[232:233], v[180:181] op_sel:[0,1,0]
	v_pk_fma_f32 v[192:193], v[12:13], v[232:233], v[192:193] op_sel:[0,1,0]
	v_pk_fma_f32 v[180:181], v[6:7], v[234:235], v[180:181] op_sel_hi:[1,0,1]
	v_pk_fma_f32 v[192:193], v[8:9], v[234:235], v[192:193] op_sel_hi:[1,0,1]
	v_mfma_f32_16x16x4_f32 v[98:101], v143, v89, v[98:101]
	v_pk_fma_f32 v[180:181], v[2:3], v[234:235], v[180:181] op_sel:[0,1,0]
	v_pk_fma_f32 v[192:193], v[4:5], v[234:235], v[192:193] op_sel:[0,1,0]
	v_pk_mul_f32 v[180:181], v[146:147], v[180:181]
	v_pk_mul_f32 v[192:193], v[146:147], v[192:193]
	v_pk_fma_f32 v[236:237], v[144:145], v[86:87], v[180:181]
	v_pk_fma_f32 v[238:239], v[144:145], v[88:89], v[192:193]
	global_store_dwordx4 v[150:151], v[236:239], off nt
	v_lshl_add_u64 v[150:151], v[150:151], 0, s[58:59]
	global_load_dwordx4 v[86:89], v[148:149], off nt
	v_lshl_add_u64 v[148:149], v[148:149], 0, s[58:59]
	ds_read_b32 v143, v160 offset:560
	ds_read_b128 v[172:175], v161 offset:4480
	ds_read_b128 v[232:235], v161 offset:4496
	s_waitcnt vmcnt(38)
; #define RS_LOAD(dst, it0) do { _Pragma("unroll") for (int u = 0; u < 8; ++u) dst[u] = __builtin_nontemporal_load((const f32x4*)(S0 + (size_t)(4 * ((it0) + u)) * DV)); } while (0)
; __device__ __forceinline__ void ret_sample_item(Frame& F, int item) {
;     ...
;     for (int it0 = 0; it0 < 64; it0 += 16) {
;         RS_LOAD(sb, it0 + 8);
;         RS_PROC(sa, it0);
;         { const int itn = it0 + 16 < 64 ? it0 + 16 : it0; RS_LOAD(sa, itn); }
;         RS_PROC(sb, it0 + 8);
;     }
	s_waitcnt lgkmcnt(3)
	v_cndmask_b32_e64 v141, 0, v141, s[6:7]
	v_pk_mul_f32 v[180:181], v[26:27], v[114:115] op_sel:[0,1]
	v_pk_mul_f32 v[192:193], v[28:29], v[114:115] op_sel:[0,1]
	v_mfma_f32_16x16x4_f32 v[110:113], v141, v90, v[110:113]
	v_pk_fma_f32 v[180:181], v[30:31], v[114:115], v[180:181] op_sel_hi:[1,0,1]
	v_pk_fma_f32 v[192:193], v[32:33], v[114:115], v[192:193] op_sel_hi:[1,0,1]
	v_pk_fma_f32 v[180:181], v[22:23], v[116:117], v[180:181] op_sel_hi:[1,0,1]
	v_pk_fma_f32 v[192:193], v[24:25], v[116:117], v[192:193] op_sel_hi:[1,0,1]
	v_mfma_f32_16x16x4_f32 v[106:109], v141, v91, v[106:109]
	v_pk_fma_f32 v[180:181], v[18:19], v[116:117], v[180:181] op_sel:[0,1,0]
	v_pk_fma_f32 v[192:193], v[20:21], v[116:117], v[192:193] op_sel:[0,1,0]
	v_pk_fma_f32 v[180:181], v[14:15], v[176:177], v[180:181] op_sel_hi:[1,0,1]
	v_pk_fma_f32 v[192:193], v[16:17], v[176:177], v[192:193] op_sel_hi:[1,0,1]
	v_mfma_f32_16x16x4_f32 v[102:105], v141, v92, v[102:105]
	v_pk_fma_f32 v[180:181], v[10:11], v[176:177], v[180:181] op_sel:[0,1,0]
	v_pk_fma_f32 v[192:193], v[12:13], v[176:177], v[192:193] op_sel:[0,1,0]
	v_pk_fma_f32 v[180:181], v[6:7], v[178:179], v[180:181] op_sel_hi:[1,0,1]
	v_pk_fma_f32 v[192:193], v[8:9], v[178:179], v[192:193] op_sel_hi:[1,0,1]
	v_mfma_f32_16x16x4_f32 v[98:101], v141, v93, v[98:101]
	v_pk_fma_f32 v[180:181], v[2:3], v[178:179], v[180:181] op_sel:[0,1,0]
	v_pk_fma_f32 v[192:193], v[4:5], v[178:179], v[192:193] op_sel:[0,1,0]
	v_pk_mul_f32 v[180:181], v[146:147], v[180:181]
	v_pk_mul_f32 v[192:193], v[146:147], v[192:193]
	v_pk_fma_f32 v[236:237], v[144:145], v[90:91], v[180:181]
	v_pk_fma_f32 v[238:239], v[144:145], v[92:93], v[192:193]
	global_store_dwordx4 v[150:151], v[236:239], off nt
	v_lshl_add_u64 v[150:151], v[150:151], 0, s[58:59]
	global_load_dwordx4 v[90:93], v[148:149], off nt
	v_lshl_add_u64 v[148:149], v[148:149], 0, s[58:59]
	ds_read_b32 v141, v160 offset:576
	ds_read_b128 v[114:117], v161 offset:4608
	ds_read_b128 v[176:179], v161 offset:4624
	s_waitcnt vmcnt(38)
	s_waitcnt lgkmcnt(3)
	v_cndmask_b32_e64 v143, 0, v143, s[6:7]
	v_pk_mul_f32 v[180:181], v[26:27], v[172:173] op_sel:[0,1]
	v_pk_mul_f32 v[192:193], v[28:29], v[172:173] op_sel:[0,1]
	v_mfma_f32_16x16x4_f32 v[110:113], v143, v94, v[110:113]
	v_pk_fma_f32 v[180:181], v[30:31], v[172:173], v[180:181] op_sel_hi:[1,0,1]
	v_pk_fma_f32 v[192:193], v[32:33], v[172:173], v[192:193] op_sel_hi:[1,0,1]
	v_pk_fma_f32 v[180:181], v[22:23], v[174:175], v[180:181] op_sel_hi:[1,0,1]
	v_pk_fma_f32 v[192:193], v[24:25], v[174:175], v[192:193] op_sel_hi:[1,0,1]
	v_mfma_f32_16x16x4_f32 v[106:109], v143, v95, v[106:109]
	v_pk_fma_f32 v[180:181], v[18:19], v[174:175], v[180:181] op_sel:[0,1,0]
	v_pk_fma_f32 v[192:193], v[20:21], v[174:175], v[192:193] op_sel:[0,1,0]
	v_pk_fma_f32 v[180:181], v[14:15], v[232:233], v[180:181] op_sel_hi:[1,0,1]
	v_pk_fma_f32 v[192:193], v[16:17], v[232:233], v[192:193] op_sel_hi:[1,0,1]
	v_mfma_f32_16x16x4_f32 v[102:105], v143, v96, v[102:105]
	v_pk_fma_f32 v[180:181], v[10:11], v[232:233], v[180:181] op_sel:[0,1,0]
	v_pk_fma_f32 v[192:193], v[12:13], v[232:233], v[192:193] op_sel:[0,1,0]
	v_pk_fma_f32 v[180:181], v[6:7], v[234:235], v[180:181] op_sel_hi:[1,0,1]
	v_pk_fma_f32 v[192:193], v[8:9], v[234:235], v[192:193] op_sel_hi:[1,0,1]
	v_mfma_f32_16x16x4_f32 v[98:101], v143, v97, v[98:101]
	v_pk_fma_f32 v[180:181], v[2:3], v[234:235], v[180:181] op_sel:[0,1,0]
	v_pk_fma_f32 v[192:193], v[4:5], v[234:235], v[192:193] op_sel:[0,1,0]
	v_pk_mul_f32 v[180:181], v[146:147], v[180:181]
	v_pk_mul_f32 v[192:193], v[146:147], v[192:193]
	v_pk_fma_f32 v[236:237], v[144:145], v[94:95], v[180:181]
	v_pk_fma_f32 v[238:239], v[144:145], v[96:97], v[192:193]
	global_store_dwordx4 v[150:151], v[236:239], off nt
	v_lshl_add_u64 v[150:151], v[150:151], 0, s[58:59]
	global_load_dwordx4 v[94:97], v[148:149], off nt
	v_lshl_add_u64 v[148:149], v[148:149], 0, s[58:59]
	ds_read_b32 v143, v160 offset:592
	ds_read_b128 v[172:175], v161 offset:4736
	ds_read_b128 v[232:235], v161 offset:4752
	s_waitcnt vmcnt(38)
	s_waitcnt lgkmcnt(3)
	v_cndmask_b32_e64 v141, 0, v141, s[6:7]
	v_pk_mul_f32 v[180:181], v[26:27], v[114:115] op_sel:[0,1]
	v_pk_mul_f32 v[192:193], v[28:29], v[114:115] op_sel:[0,1]
	v_mfma_f32_16x16x4_f32 v[110:113], v141, v212, v[110:113]
	v_pk_fma_f32 v[180:181], v[30:31], v[114:115], v[180:181] op_sel_hi:[1,0,1]
	v_pk_fma_f32 v[192:193], v[32:33], v[114:115], v[192:193] op_sel_hi:[1,0,1]
	v_pk_fma_f32 v[180:181], v[22:23], v[116:117], v[180:181] op_sel_hi:[1,0,1]
	v_pk_fma_f32 v[192:193], v[24:25], v[116:117], v[192:193] op_sel_hi:[1,0,1]
	v_mfma_f32_16x16x4_f32 v[106:109], v141, v213, v[106:109]
	v_pk_fma_f32 v[180:181], v[18:19], v[116:117], v[180:181] op_sel:[0,1,0]
	v_pk_fma_f32 v[192:193], v[20:21], v[116:117], v[192:193] op_sel:[0,1,0]
	v_pk_fma_f32 v[180:181], v[14:15], v[176:177], v[180:181] op_sel_hi:[1,0,1]
	v_pk_fma_f32 v[192:193], v[16:17], v[176:177], v[192:193] op_sel_hi:[1,0,1]
	v_mfma_f32_16x16x4_f32 v[102:105], v141, v214, v[102:105]
	v_pk_fma_f32 v[180:181], v[10:11], v[176:177], v[180:181] op_sel:[0,1,0]
	v_pk_fma_f32 v[192:193], v[12:13], v[176:177], v[192:193] op_sel:[0,1,0]
	v_pk_fma_f32 v[180:181], v[6:7], v[178:179], v[180:181] op_sel_hi:[1,0,1]
	v_pk_fma_f32 v[192:193], v[8:9], v[178:179], v[192:193] op_sel_hi:[1,0,1]
	v_mfma_f32_16x16x4_f32 v[98:101], v141, v215, v[98:101]
	v_pk_fma_f32 v[180:181], v[2:3], v[178:179], v[180:181] op_sel:[0,1,0]
	v_pk_fma_f32 v[192:193], v[4:5], v[178:179], v[192:193] op_sel:[0,1,0]
	v_pk_mul_f32 v[180:181], v[146:147], v[180:181]
	v_pk_mul_f32 v[192:193], v[146:147], v[192:193]
	v_pk_fma_f32 v[236:237], v[144:145], v[212:213], v[180:181]
	v_pk_fma_f32 v[238:239], v[144:145], v[214:215], v[192:193]
	global_store_dwordx4 v[150:151], v[236:239], off nt
	v_lshl_add_u64 v[150:151], v[150:151], 0, s[58:59]
	global_load_dwordx4 v[212:215], v[148:149], off nt
	v_lshl_add_u64 v[148:149], v[148:149], 0, s[58:59]
	ds_read_b32 v141, v160 offset:608
	ds_read_b128 v[114:117], v161 offset:4864
	ds_read_b128 v[176:179], v161 offset:4880
	s_waitcnt vmcnt(38)
; #define RS_LOAD(dst, it0) do { _Pragma("unroll") for (int u = 0; u < 8; ++u) dst[u] = __builtin_nontemporal_load((const f32x4*)(S0 + (size_t)(4 * ((it0) + u)) * DV)); } while (0)
; __device__ __forceinline__ void ret_sample_item(Frame& F, int item) {
;     ...
;     for (int it0 = 0; it0 < 64; it0 += 16) {
;         RS_LOAD(sb, it0 + 8);
;         RS_PROC(sa, it0);
;         { const int itn = it0 + 16 < 64 ? it0 + 16 : it0; RS_LOAD(sa, itn); }
;         RS_PROC(sb, it0 + 8);
;     }
	s_waitcnt lgkmcnt(3)
	v_cndmask_b32_e64 v143, 0, v143, s[6:7]
	v_pk_mul_f32 v[180:181], v[26:27], v[172:173] op_sel:[0,1]
	v_pk_mul_f32 v[192:193], v[28:29], v[172:173] op_sel:[0,1]
	v_mfma_f32_16x16x4_f32 v[110:113], v143, v216, v[110:113]
	v_pk_fma_f32 v[180:181], v[30:31], v[172:173], v[180:181] op_sel_hi:[1,0,1]
	v_pk_fma_f32 v[192:193], v[32:33], v[172:173], v[192:193] op_sel_hi:[1,0,1]
	v_pk_fma_f32 v[180:181], v[22:23], v[174:175], v[180:181] op_sel_hi:[1,0,1]
	v_pk_fma_f32 v[192:193], v[24:25], v[174:175], v[192:193] op_sel_hi:[1,0,1]
	v_mfma_f32_16x16x4_f32 v[106:109], v143, v217, v[106:109]
	v_pk_fma_f32 v[180:181], v[18:19], v[174:175], v[180:181] op_sel:[0,1,0]
	v_pk_fma_f32 v[192:193], v[20:21], v[174:175], v[192:193] op_sel:[0,1,0]
	v_pk_fma_f32 v[180:181], v[14:15], v[232:233], v[180:181] op_sel_hi:[1,0,1]
	v_pk_fma_f32 v[192:193], v[16:17], v[232:233], v[192:193] op_sel_hi:[1,0,1]
	v_mfma_f32_16x16x4_f32 v[102:105], v143, v218, v[102:105]
	v_pk_fma_f32 v[180:181], v[10:11], v[232:233], v[180:181] op_sel:[0,1,0]
	v_pk_fma_f32 v[192:193], v[12:13], v[232:233], v[192:193] op_sel:[0,1,0]
	v_pk_fma_f32 v[180:181], v[6:7], v[234:235], v[180:181] op_sel_hi:[1,0,1]
	v_pk_fma_f32 v[192:193], v[8:9], v[234:235], v[192:193] op_sel_hi:[1,0,1]
	v_mfma_f32_16x16x4_f32 v[98:101], v143, v219, v[98:101]
	v_pk_fma_f32 v[180:181], v[2:3], v[234:235], v[180:181] op_sel:[0,1,0]
	v_pk_fma_f32 v[192:193], v[4:5], v[234:235], v[192:193] op_sel:[0,1,0]
	v_pk_mul_f32 v[180:181], v[146:147], v[180:181]
	v_pk_mul_f32 v[192:193], v[146:147], v[192:193]
	v_pk_fma_f32 v[236:237], v[144:145], v[216:217], v[180:181]
	v_pk_fma_f32 v[238:239], v[144:145], v[218:219], v[192:193]
	global_store_dwordx4 v[150:151], v[236:239], off nt
	v_lshl_add_u64 v[150:151], v[150:151], 0, s[58:59]
	global_load_dwordx4 v[216:219], v[148:149], off nt
	v_lshl_add_u64 v[148:149], v[148:149], 0, s[58:59]
	ds_read_b32 v143, v160 offset:624
	ds_read_b128 v[172:175], v161 offset:4992
	ds_read_b128 v[232:235], v161 offset:5008
	s_waitcnt vmcnt(38)
	s_waitcnt lgkmcnt(3)
	v_cndmask_b32_e64 v141, 0, v141, s[6:7]
	v_pk_mul_f32 v[180:181], v[26:27], v[114:115] op_sel:[0,1]
	v_pk_mul_f32 v[192:193], v[28:29], v[114:115] op_sel:[0,1]
	v_mfma_f32_16x16x4_f32 v[110:113], v141, v224, v[110:113]
	v_pk_fma_f32 v[180:181], v[30:31], v[114:115], v[180:181] op_sel_hi:[1,0,1]
	v_pk_fma_f32 v[192:193], v[32:33], v[114:115], v[192:193] op_sel_hi:[1,0,1]
	v_pk_fma_f32 v[180:181], v[22:23], v[116:117], v[180:181] op_sel_hi:[1,0,1]
	v_pk_fma_f32 v[192:193], v[24:25], v[116:117], v[192:193] op_sel_hi:[1,0,1]
	v_mfma_f32_16x16x4_f32 v[106:109], v141, v225, v[106:109]
	v_pk_fma_f32 v[180:181], v[18:19], v[116:117], v[180:181] op_sel:[0,1,0]
	v_pk_fma_f32 v[192:193], v[20:21], v[116:117], v[192:193] op_sel:[0,1,0]
	v_pk_fma_f32 v[180:181], v[14:15], v[176:177], v[180:181] op_sel_hi:[1,0,1]
	v_pk_fma_f32 v[192:193], v[16:17], v[176:177], v[192:193] op_sel_hi:[1,0,1]
	v_mfma_f32_16x16x4_f32 v[102:105], v141, v226, v[102:105]
	v_pk_fma_f32 v[180:181], v[10:11], v[176:177], v[180:181] op_sel:[0,1,0]
	v_pk_fma_f32 v[192:193], v[12:13], v[176:177], v[192:193] op_sel:[0,1,0]
	v_pk_fma_f32 v[180:181], v[6:7], v[178:179], v[180:181] op_sel_hi:[1,0,1]
	v_pk_fma_f32 v[192:193], v[8:9], v[178:179], v[192:193] op_sel_hi:[1,0,1]
	v_mfma_f32_16x16x4_f32 v[98:101], v141, v227, v[98:101]
	v_pk_fma_f32 v[180:181], v[2:3], v[178:179], v[180:181] op_sel:[0,1,0]
	v_pk_fma_f32 v[192:193], v[4:5], v[178:179], v[192:193] op_sel:[0,1,0]
	v_pk_mul_f32 v[180:181], v[146:147], v[180:181]
	v_pk_mul_f32 v[192:193], v[146:147], v[192:193]
	v_pk_fma_f32 v[236:237], v[144:145], v[224:225], v[180:181]
	v_pk_fma_f32 v[238:239], v[144:145], v[226:227], v[192:193]
	global_store_dwordx4 v[150:151], v[236:239], off nt
	v_lshl_add_u64 v[150:151], v[150:151], 0, s[58:59]
	global_load_dwordx4 v[224:227], v[148:149], off nt
	v_lshl_add_u64 v[148:149], v[148:149], 0, s[58:59]
	ds_read_b32 v141, v160 offset:640
	ds_read_b128 v[114:117], v161 offset:5120
	ds_read_b128 v[176:179], v161 offset:5136
	s_waitcnt vmcnt(38)
	s_waitcnt lgkmcnt(3)
	v_cndmask_b32_e64 v143, 0, v143, s[6:7]
	v_pk_mul_f32 v[180:181], v[26:27], v[172:173] op_sel:[0,1]
	v_pk_mul_f32 v[192:193], v[28:29], v[172:173] op_sel:[0,1]
	v_mfma_f32_16x16x4_f32 v[110:113], v143, v228, v[110:113]
	v_pk_fma_f32 v[180:181], v[30:31], v[172:173], v[180:181] op_sel_hi:[1,0,1]
	v_pk_fma_f32 v[192:193], v[32:33], v[172:173], v[192:193] op_sel_hi:[1,0,1]
	v_pk_fma_f32 v[180:181], v[22:23], v[174:175], v[180:181] op_sel_hi:[1,0,1]
	v_pk_fma_f32 v[192:193], v[24:25], v[174:175], v[192:193] op_sel_hi:[1,0,1]
	v_mfma_f32_16x16x4_f32 v[106:109], v143, v229, v[106:109]
	v_pk_fma_f32 v[180:181], v[18:19], v[174:175], v[180:181] op_sel:[0,1,0]
	v_pk_fma_f32 v[192:193], v[20:21], v[174:175], v[192:193] op_sel:[0,1,0]
	v_pk_fma_f32 v[180:181], v[14:15], v[232:233], v[180:181] op_sel_hi:[1,0,1]
	v_pk_fma_f32 v[192:193], v[16:17], v[232:233], v[192:193] op_sel_hi:[1,0,1]
	v_mfma_f32_16x16x4_f32 v[102:105], v143, v230, v[102:105]
	v_pk_fma_f32 v[180:181], v[10:11], v[232:233], v[180:181] op_sel:[0,1,0]
	v_pk_fma_f32 v[192:193], v[12:13], v[232:233], v[192:193] op_sel:[0,1,0]
	v_pk_fma_f32 v[180:181], v[6:7], v[234:235], v[180:181] op_sel_hi:[1,0,1]
	v_pk_fma_f32 v[192:193], v[8:9], v[234:235], v[192:193] op_sel_hi:[1,0,1]
	v_mfma_f32_16x16x4_f32 v[98:101], v143, v231, v[98:101]
	v_pk_fma_f32 v[180:181], v[2:3], v[234:235], v[180:181] op_sel:[0,1,0]
	v_pk_fma_f32 v[192:193], v[4:5], v[234:235], v[192:193] op_sel:[0,1,0]
	v_pk_mul_f32 v[180:181], v[146:147], v[180:181]
	v_pk_mul_f32 v[192:193], v[146:147], v[192:193]
	v_pk_fma_f32 v[236:237], v[144:145], v[228:229], v[180:181]
	v_pk_fma_f32 v[238:239], v[144:145], v[230:231], v[192:193]
	global_store_dwordx4 v[150:151], v[236:239], off nt
	v_lshl_add_u64 v[150:151], v[150:151], 0, s[58:59]
	global_load_dwordx4 v[228:231], v[148:149], off nt
	v_lshl_add_u64 v[148:149], v[148:149], 0, s[58:59]
	ds_read_b32 v143, v160 offset:656
	ds_read_b128 v[172:175], v161 offset:5248
	ds_read_b128 v[232:235], v161 offset:5264
	s_waitcnt vmcnt(38)
; #define RS_LOAD(dst, it0) do { _Pragma("unroll") for (int u = 0; u < 8; ++u) dst[u] = __builtin_nontemporal_load((const f32x4*)(S0 + (size_t)(4 * ((it0) + u)) * DV)); } while (0)
; __device__ __forceinline__ void ret_sample_item(Frame& F, int item) {
;     ...
;     for (int it0 = 0; it0 < 64; it0 += 16) {
;         RS_LOAD(sb, it0 + 8);
;         RS_PROC(sa, it0);
;         { const int itn = it0 + 16 < 64 ? it0 + 16 : it0; RS_LOAD(sa, itn); }
;         RS_PROC(sb, it0 + 8);
;     }
	s_waitcnt lgkmcnt(3)
	v_cndmask_b32_e64 v141, 0, v141, s[6:7]
	v_pk_mul_f32 v[180:181], v[26:27], v[114:115] op_sel:[0,1]
	v_pk_mul_f32 v[192:193], v[28:29], v[114:115] op_sel:[0,1]
	v_mfma_f32_16x16x4_f32 v[110:113], v141, v70, v[110:113]
	v_pk_fma_f32 v[180:181], v[30:31], v[114:115], v[180:181] op_sel_hi:[1,0,1]
	v_pk_fma_f32 v[192:193], v[32:33], v[114:115], v[192:193] op_sel_hi:[1,0,1]
	v_pk_fma_f32 v[180:181], v[22:23], v[116:117], v[180:181] op_sel_hi:[1,0,1]
	v_pk_fma_f32 v[192:193], v[24:25], v[116:117], v[192:193] op_sel_hi:[1,0,1]
	v_mfma_f32_16x16x4_f32 v[106:109], v141, v71, v[106:109]
	v_pk_fma_f32 v[180:181], v[18:19], v[116:117], v[180:181] op_sel:[0,1,0]
	v_pk_fma_f32 v[192:193], v[20:21], v[116:117], v[192:193] op_sel:[0,1,0]
	v_pk_fma_f32 v[180:181], v[14:15], v[176:177], v[180:181] op_sel_hi:[1,0,1]
	v_pk_fma_f32 v[192:193], v[16:17], v[176:177], v[192:193] op_sel_hi:[1,0,1]
	v_mfma_f32_16x16x4_f32 v[102:105], v141, v72, v[102:105]
	v_pk_fma_f32 v[180:181], v[10:11], v[176:177], v[180:181] op_sel:[0,1,0]
	v_pk_fma_f32 v[192:193], v[12:13], v[176:177], v[192:193] op_sel:[0,1,0]
	v_pk_fma_f32 v[180:181], v[6:7], v[178:179], v[180:181] op_sel_hi:[1,0,1]
	v_pk_fma_f32 v[192:193], v[8:9], v[178:179], v[192:193] op_sel_hi:[1,0,1]
	v_mfma_f32_16x16x4_f32 v[98:101], v141, v73, v[98:101]
	v_pk_fma_f32 v[180:181], v[2:3], v[178:179], v[180:181] op_sel:[0,1,0]
	v_pk_fma_f32 v[192:193], v[4:5], v[178:179], v[192:193] op_sel:[0,1,0]
	v_pk_mul_f32 v[180:181], v[146:147], v[180:181]
	v_pk_mul_f32 v[192:193], v[146:147], v[192:193]
	v_pk_fma_f32 v[236:237], v[144:145], v[70:71], v[180:181]
	v_pk_fma_f32 v[238:239], v[144:145], v[72:73], v[192:193]
	global_store_dwordx4 v[150:151], v[236:239], off nt
	v_lshl_add_u64 v[150:151], v[150:151], 0, s[58:59]
	global_load_dwordx4 v[70:73], v[148:149], off nt
	v_lshl_add_u64 v[148:149], v[148:149], 0, s[58:59]
	ds_read_b32 v141, v160 offset:672
	ds_read_b128 v[114:117], v161 offset:5376
	ds_read_b128 v[176:179], v161 offset:5392
	s_waitcnt vmcnt(38)
	s_waitcnt lgkmcnt(3)
	v_cndmask_b32_e64 v143, 0, v143, s[6:7]
	v_pk_mul_f32 v[180:181], v[26:27], v[172:173] op_sel:[0,1]
	v_pk_mul_f32 v[192:193], v[28:29], v[172:173] op_sel:[0,1]
	v_mfma_f32_16x16x4_f32 v[110:113], v143, v62, v[110:113]
	v_pk_fma_f32 v[180:181], v[30:31], v[172:173], v[180:181] op_sel_hi:[1,0,1]
	v_pk_fma_f32 v[192:193], v[32:33], v[172:173], v[192:193] op_sel_hi:[1,0,1]
	v_pk_fma_f32 v[180:181], v[22:23], v[174:175], v[180:181] op_sel_hi:[1,0,1]
	v_pk_fma_f32 v[192:193], v[24:25], v[174:175], v[192:193] op_sel_hi:[1,0,1]
	v_mfma_f32_16x16x4_f32 v[106:109], v143, v63, v[106:109]
	v_pk_fma_f32 v[180:181], v[18:19], v[174:175], v[180:181] op_sel:[0,1,0]
	v_pk_fma_f32 v[192:193], v[20:21], v[174:175], v[192:193] op_sel:[0,1,0]
	v_pk_fma_f32 v[180:181], v[14:15], v[232:233], v[180:181] op_sel_hi:[1,0,1]
	v_pk_fma_f32 v[192:193], v[16:17], v[232:233], v[192:193] op_sel_hi:[1,0,1]
	v_mfma_f32_16x16x4_f32 v[102:105], v143, v64, v[102:105]
	v_pk_fma_f32 v[180:181], v[10:11], v[232:233], v[180:181] op_sel:[0,1,0]
	v_pk_fma_f32 v[192:193], v[12:13], v[232:233], v[192:193] op_sel:[0,1,0]
	v_pk_fma_f32 v[180:181], v[6:7], v[234:235], v[180:181] op_sel_hi:[1,0,1]
	v_pk_fma_f32 v[192:193], v[8:9], v[234:235], v[192:193] op_sel_hi:[1,0,1]
	v_mfma_f32_16x16x4_f32 v[98:101], v143, v65, v[98:101]
	v_pk_fma_f32 v[180:181], v[2:3], v[234:235], v[180:181] op_sel:[0,1,0]
	v_pk_fma_f32 v[192:193], v[4:5], v[234:235], v[192:193] op_sel:[0,1,0]
	v_pk_mul_f32 v[180:181], v[146:147], v[180:181]
	v_pk_mul_f32 v[192:193], v[146:147], v[192:193]
	v_pk_fma_f32 v[236:237], v[144:145], v[62:63], v[180:181]
	v_pk_fma_f32 v[238:239], v[144:145], v[64:65], v[192:193]
	global_store_dwordx4 v[150:151], v[236:239], off nt
	v_lshl_add_u64 v[150:151], v[150:151], 0, s[58:59]
	global_load_dwordx4 v[62:65], v[148:149], off nt
	v_lshl_add_u64 v[148:149], v[148:149], 0, s[58:59]
	ds_read_b32 v143, v160 offset:688
	ds_read_b128 v[172:175], v161 offset:5504
	ds_read_b128 v[232:235], v161 offset:5520
	s_waitcnt vmcnt(38)
	s_waitcnt lgkmcnt(3)
	v_cndmask_b32_e64 v141, 0, v141, s[6:7]
	v_pk_mul_f32 v[180:181], v[26:27], v[114:115] op_sel:[0,1]
	v_pk_mul_f32 v[192:193], v[28:29], v[114:115] op_sel:[0,1]
	v_mfma_f32_16x16x4_f32 v[110:113], v141, v54, v[110:113]
	v_pk_fma_f32 v[180:181], v[30:31], v[114:115], v[180:181] op_sel_hi:[1,0,1]
	v_pk_fma_f32 v[192:193], v[32:33], v[114:115], v[192:193] op_sel_hi:[1,0,1]
	v_pk_fma_f32 v[180:181], v[22:23], v[116:117], v[180:181] op_sel_hi:[1,0,1]
	v_pk_fma_f32 v[192:193], v[24:25], v[116:117], v[192:193] op_sel_hi:[1,0,1]
	v_mfma_f32_16x16x4_f32 v[106:109], v141, v55, v[106:109]
	v_pk_fma_f32 v[180:181], v[18:19], v[116:117], v[180:181] op_sel:[0,1,0]
	v_pk_fma_f32 v[192:193], v[20:21], v[116:117], v[192:193] op_sel:[0,1,0]
	v_pk_fma_f32 v[180:181], v[14:15], v[176:177], v[180:181] op_sel_hi:[1,0,1]
	v_pk_fma_f32 v[192:193], v[16:17], v[176:177], v[192:193] op_sel_hi:[1,0,1]
	v_mfma_f32_16x16x4_f32 v[102:105], v141, v56, v[102:105]
	v_pk_fma_f32 v[180:181], v[10:11], v[176:177], v[180:181] op_sel:[0,1,0]
	v_pk_fma_f32 v[192:193], v[12:13], v[176:177], v[192:193] op_sel:[0,1,0]
	v_pk_fma_f32 v[180:181], v[6:7], v[178:179], v[180:181] op_sel_hi:[1,0,1]
	v_pk_fma_f32 v[192:193], v[8:9], v[178:179], v[192:193] op_sel_hi:[1,0,1]
	v_mfma_f32_16x16x4_f32 v[98:101], v141, v57, v[98:101]
	v_pk_fma_f32 v[180:181], v[2:3], v[178:179], v[180:181] op_sel:[0,1,0]
	v_pk_fma_f32 v[192:193], v[4:5], v[178:179], v[192:193] op_sel:[0,1,0]
	v_pk_mul_f32 v[180:181], v[146:147], v[180:181]
	v_pk_mul_f32 v[192:193], v[146:147], v[192:193]
	v_pk_fma_f32 v[236:237], v[144:145], v[54:55], v[180:181]
	v_pk_fma_f32 v[238:239], v[144:145], v[56:57], v[192:193]
	global_store_dwordx4 v[150:151], v[236:239], off nt
	v_lshl_add_u64 v[150:151], v[150:151], 0, s[58:59]
	global_load_dwordx4 v[54:57], v[148:149], off nt
	v_lshl_add_u64 v[148:149], v[148:149], 0, s[58:59]
	ds_read_b32 v141, v160 offset:704
	ds_read_b128 v[114:117], v161 offset:5632
	ds_read_b128 v[176:179], v161 offset:5648
	s_waitcnt vmcnt(38)
; #define RS_LOAD(dst, it0) do { _Pragma("unroll") for (int u = 0; u < 8; ++u) dst[u] = __builtin_nontemporal_load((const f32x4*)(S0 + (size_t)(4 * ((it0) + u)) * DV)); } while (0)
; __device__ __forceinline__ void ret_sample_item(Frame& F, int item) {
;     ...
;     for (int it0 = 0; it0 < 64; it0 += 16) {
;         RS_LOAD(sb, it0 + 8);
;         RS_PROC(sa, it0);
;         { const int itn = it0 + 16 < 64 ? it0 + 16 : it0; RS_LOAD(sa, itn); }
;         RS_PROC(sb, it0 + 8);
;     }
	s_waitcnt lgkmcnt(3)
	v_cndmask_b32_e64 v143, 0, v143, s[6:7]
	v_pk_mul_f32 v[180:181], v[26:27], v[172:173] op_sel:[0,1]
	v_pk_mul_f32 v[192:193], v[28:29], v[172:173] op_sel:[0,1]
	v_mfma_f32_16x16x4_f32 v[110:113], v143, v50, v[110:113]
	v_pk_fma_f32 v[180:181], v[30:31], v[172:173], v[180:181] op_sel_hi:[1,0,1]
	v_pk_fma_f32 v[192:193], v[32:33], v[172:173], v[192:193] op_sel_hi:[1,0,1]
	v_pk_fma_f32 v[180:181], v[22:23], v[174:175], v[180:181] op_sel_hi:[1,0,1]
	v_pk_fma_f32 v[192:193], v[24:25], v[174:175], v[192:193] op_sel_hi:[1,0,1]
	v_mfma_f32_16x16x4_f32 v[106:109], v143, v51, v[106:109]
	v_pk_fma_f32 v[180:181], v[18:19], v[174:175], v[180:181] op_sel:[0,1,0]
	v_pk_fma_f32 v[192:193], v[20:21], v[174:175], v[192:193] op_sel:[0,1,0]
	v_pk_fma_f32 v[180:181], v[14:15], v[232:233], v[180:181] op_sel_hi:[1,0,1]
	v_pk_fma_f32 v[192:193], v[16:17], v[232:233], v[192:193] op_sel_hi:[1,0,1]
	v_mfma_f32_16x16x4_f32 v[102:105], v143, v52, v[102:105]
	v_pk_fma_f32 v[180:181], v[10:11], v[232:233], v[180:181] op_sel:[0,1,0]
	v_pk_fma_f32 v[192:193], v[12:13], v[232:233], v[192:193] op_sel:[0,1,0]
	v_pk_fma_f32 v[180:181], v[6:7], v[234:235], v[180:181] op_sel_hi:[1,0,1]
	v_pk_fma_f32 v[192:193], v[8:9], v[234:235], v[192:193] op_sel_hi:[1,0,1]
	v_mfma_f32_16x16x4_f32 v[98:101], v143, v53, v[98:101]
	v_pk_fma_f32 v[180:181], v[2:3], v[234:235], v[180:181] op_sel:[0,1,0]
	v_pk_fma_f32 v[192:193], v[4:5], v[234:235], v[192:193] op_sel:[0,1,0]
	v_pk_mul_f32 v[180:181], v[146:147], v[180:181]
	v_pk_mul_f32 v[192:193], v[146:147], v[192:193]
	v_pk_fma_f32 v[236:237], v[144:145], v[50:51], v[180:181]
	v_pk_fma_f32 v[238:239], v[144:145], v[52:53], v[192:193]
	global_store_dwordx4 v[150:151], v[236:239], off nt
	v_lshl_add_u64 v[150:151], v[150:151], 0, s[58:59]
	global_load_dwordx4 v[50:53], v[148:149], off nt
	v_lshl_add_u64 v[148:149], v[148:149], 0, s[58:59]
	ds_read_b32 v143, v160 offset:720
	ds_read_b128 v[172:175], v161 offset:5760
	ds_read_b128 v[232:235], v161 offset:5776
	s_waitcnt vmcnt(38)
	s_waitcnt lgkmcnt(3)
	v_cndmask_b32_e64 v141, 0, v141, s[6:7]
	v_pk_mul_f32 v[180:181], v[26:27], v[114:115] op_sel:[0,1]
	v_pk_mul_f32 v[192:193], v[28:29], v[114:115] op_sel:[0,1]
	v_mfma_f32_16x16x4_f32 v[110:113], v141, v46, v[110:113]
	v_pk_fma_f32 v[180:181], v[30:31], v[114:115], v[180:181] op_sel_hi:[1,0,1]
	v_pk_fma_f32 v[192:193], v[32:33], v[114:115], v[192:193] op_sel_hi:[1,0,1]
	v_pk_fma_f32 v[180:181], v[22:23], v[116:117], v[180:181] op_sel_hi:[1,0,1]
	v_pk_fma_f32 v[192:193], v[24:25], v[116:117], v[192:193] op_sel_hi:[1,0,1]
	v_mfma_f32_16x16x4_f32 v[106:109], v141, v47, v[106:109]
	v_pk_fma_f32 v[180:181], v[18:19], v[116:117], v[180:181] op_sel:[0,1,0]
	v_pk_fma_f32 v[192:193], v[20:21], v[116:117], v[192:193] op_sel:[0,1,0]
	v_pk_fma_f32 v[180:181], v[14:15], v[176:177], v[180:181] op_sel_hi:[1,0,1]
	v_pk_fma_f32 v[192:193], v[16:17], v[176:177], v[192:193] op_sel_hi:[1,0,1]
	v_mfma_f32_16x16x4_f32 v[102:105], v141, v48, v[102:105]
	v_pk_fma_f32 v[180:181], v[10:11], v[176:177], v[180:181] op_sel:[0,1,0]
	v_pk_fma_f32 v[192:193], v[12:13], v[176:177], v[192:193] op_sel:[0,1,0]
	v_pk_fma_f32 v[180:181], v[6:7], v[178:179], v[180:181] op_sel_hi:[1,0,1]
	v_pk_fma_f32 v[192:193], v[8:9], v[178:179], v[192:193] op_sel_hi:[1,0,1]
	v_mfma_f32_16x16x4_f32 v[98:101], v141, v49, v[98:101]
	v_pk_fma_f32 v[180:181], v[2:3], v[178:179], v[180:181] op_sel:[0,1,0]
	v_pk_fma_f32 v[192:193], v[4:5], v[178:179], v[192:193] op_sel:[0,1,0]
	v_pk_mul_f32 v[180:181], v[146:147], v[180:181]
	v_pk_mul_f32 v[192:193], v[146:147], v[192:193]
	v_pk_fma_f32 v[236:237], v[144:145], v[46:47], v[180:181]
	v_pk_fma_f32 v[238:239], v[144:145], v[48:49], v[192:193]
	global_store_dwordx4 v[150:151], v[236:239], off nt
	v_lshl_add_u64 v[150:151], v[150:151], 0, s[58:59]
	ds_read_b32 v141, v160 offset:736
	ds_read_b128 v[114:117], v161 offset:5888
	ds_read_b128 v[176:179], v161 offset:5904
	s_waitcnt vmcnt(37)
	s_waitcnt lgkmcnt(3)
	v_cndmask_b32_e64 v143, 0, v143, s[6:7]
	v_pk_mul_f32 v[180:181], v[26:27], v[172:173] op_sel:[0,1]
	v_pk_mul_f32 v[192:193], v[28:29], v[172:173] op_sel:[0,1]
	v_mfma_f32_16x16x4_f32 v[110:113], v143, v42, v[110:113]
	v_pk_fma_f32 v[180:181], v[30:31], v[172:173], v[180:181] op_sel_hi:[1,0,1]
	v_pk_fma_f32 v[192:193], v[32:33], v[172:173], v[192:193] op_sel_hi:[1,0,1]
	v_pk_fma_f32 v[180:181], v[22:23], v[174:175], v[180:181] op_sel_hi:[1,0,1]
	v_pk_fma_f32 v[192:193], v[24:25], v[174:175], v[192:193] op_sel_hi:[1,0,1]
	v_mfma_f32_16x16x4_f32 v[106:109], v143, v43, v[106:109]
	v_pk_fma_f32 v[180:181], v[18:19], v[174:175], v[180:181] op_sel:[0,1,0]
	v_pk_fma_f32 v[192:193], v[20:21], v[174:175], v[192:193] op_sel:[0,1,0]
	v_pk_fma_f32 v[180:181], v[14:15], v[232:233], v[180:181] op_sel_hi:[1,0,1]
	v_pk_fma_f32 v[192:193], v[16:17], v[232:233], v[192:193] op_sel_hi:[1,0,1]
	v_mfma_f32_16x16x4_f32 v[102:105], v143, v44, v[102:105]
	v_pk_fma_f32 v[180:181], v[10:11], v[232:233], v[180:181] op_sel:[0,1,0]
	v_pk_fma_f32 v[192:193], v[12:13], v[232:233], v[192:193] op_sel:[0,1,0]
	v_pk_fma_f32 v[180:181], v[6:7], v[234:235], v[180:181] op_sel_hi:[1,0,1]
	v_pk_fma_f32 v[192:193], v[8:9], v[234:235], v[192:193] op_sel_hi:[1,0,1]
	v_mfma_f32_16x16x4_f32 v[98:101], v143, v45, v[98:101]
	v_pk_fma_f32 v[180:181], v[2:3], v[234:235], v[180:181] op_sel:[0,1,0]
	v_pk_fma_f32 v[192:193], v[4:5], v[234:235], v[192:193] op_sel:[0,1,0]
	v_pk_mul_f32 v[180:181], v[146:147], v[180:181]
	v_pk_mul_f32 v[192:193], v[146:147], v[192:193]
	v_pk_fma_f32 v[236:237], v[144:145], v[42:43], v[180:181]
	v_pk_fma_f32 v[238:239], v[144:145], v[44:45], v[192:193]
	global_store_dwordx4 v[150:151], v[236:239], off nt
	v_lshl_add_u64 v[150:151], v[150:151], 0, s[58:59]
	ds_read_b32 v143, v160 offset:752
	ds_read_b128 v[172:175], v161 offset:6016
	ds_read_b128 v[232:235], v161 offset:6032
	s_waitcnt vmcnt(36)
; #define RS_LOAD(dst, it0) do { _Pragma("unroll") for (int u = 0; u < 8; ++u) dst[u] = __builtin_nontemporal_load((const f32x4*)(S0 + (size_t)(4 * ((it0) + u)) * DV)); } while (0)
; __device__ __forceinline__ void ret_sample_item(Frame& F, int item) {
;     ...
;     for (int it0 = 0; it0 < 64; it0 += 16) {
;         RS_LOAD(sb, it0 + 8);
;         RS_PROC(sa, it0);
;         { const int itn = it0 + 16 < 64 ? it0 + 16 : it0; RS_LOAD(sa, itn); }
;         RS_PROC(sb, it0 + 8);
;     }
	s_waitcnt lgkmcnt(3)
	v_cndmask_b32_e64 v141, 0, v141, s[6:7]
	v_pk_mul_f32 v[180:181], v[26:27], v[114:115] op_sel:[0,1]
	v_pk_mul_f32 v[192:193], v[28:29], v[114:115] op_sel:[0,1]
	v_mfma_f32_16x16x4_f32 v[110:113], v141, v38, v[110:113]
	v_pk_fma_f32 v[180:181], v[30:31], v[114:115], v[180:181] op_sel_hi:[1,0,1]
	v_pk_fma_f32 v[192:193], v[32:33], v[114:115], v[192:193] op_sel_hi:[1,0,1]
	v_pk_fma_f32 v[180:181], v[22:23], v[116:117], v[180:181] op_sel_hi:[1,0,1]
	v_pk_fma_f32 v[192:193], v[24:25], v[116:117], v[192:193] op_sel_hi:[1,0,1]
	v_mfma_f32_16x16x4_f32 v[106:109], v141, v39, v[106:109]
	v_pk_fma_f32 v[180:181], v[18:19], v[116:117], v[180:181] op_sel:[0,1,0]
	v_pk_fma_f32 v[192:193], v[20:21], v[116:117], v[192:193] op_sel:[0,1,0]
	v_pk_fma_f32 v[180:181], v[14:15], v[176:177], v[180:181] op_sel_hi:[1,0,1]
	v_pk_fma_f32 v[192:193], v[16:17], v[176:177], v[192:193] op_sel_hi:[1,0,1]
	v_mfma_f32_16x16x4_f32 v[102:105], v141, v40, v[102:105]
	v_pk_fma_f32 v[180:181], v[10:11], v[176:177], v[180:181] op_sel:[0,1,0]
	v_pk_fma_f32 v[192:193], v[12:13], v[176:177], v[192:193] op_sel:[0,1,0]
	v_pk_fma_f32 v[180:181], v[6:7], v[178:179], v[180:181] op_sel_hi:[1,0,1]
	v_pk_fma_f32 v[192:193], v[8:9], v[178:179], v[192:193] op_sel_hi:[1,0,1]
	v_mfma_f32_16x16x4_f32 v[98:101], v141, v41, v[98:101]
	v_pk_fma_f32 v[180:181], v[2:3], v[178:179], v[180:181] op_sel:[0,1,0]
	v_pk_fma_f32 v[192:193], v[4:5], v[178:179], v[192:193] op_sel:[0,1,0]
	v_pk_mul_f32 v[180:181], v[146:147], v[180:181]
	v_pk_mul_f32 v[192:193], v[146:147], v[192:193]
	v_pk_fma_f32 v[236:237], v[144:145], v[38:39], v[180:181]
	v_pk_fma_f32 v[238:239], v[144:145], v[40:41], v[192:193]
	global_store_dwordx4 v[150:151], v[236:239], off nt
	v_lshl_add_u64 v[150:151], v[150:151], 0, s[58:59]
	ds_read_b32 v141, v160 offset:768
	ds_read_b128 v[114:117], v161 offset:6144
	ds_read_b128 v[176:179], v161 offset:6160
	s_waitcnt vmcnt(35)
	s_waitcnt lgkmcnt(3)
	v_cndmask_b32_e64 v143, 0, v143, s[6:7]
	v_pk_mul_f32 v[180:181], v[26:27], v[172:173] op_sel:[0,1]
	v_pk_mul_f32 v[192:193], v[28:29], v[172:173] op_sel:[0,1]
	v_mfma_f32_16x16x4_f32 v[110:113], v143, v34, v[110:113]
	v_pk_fma_f32 v[180:181], v[30:31], v[172:173], v[180:181] op_sel_hi:[1,0,1]
	v_pk_fma_f32 v[192:193], v[32:33], v[172:173], v[192:193] op_sel_hi:[1,0,1]
	v_pk_fma_f32 v[180:181], v[22:23], v[174:175], v[180:181] op_sel_hi:[1,0,1]
	v_pk_fma_f32 v[192:193], v[24:25], v[174:175], v[192:193] op_sel_hi:[1,0,1]
	v_mfma_f32_16x16x4_f32 v[106:109], v143, v35, v[106:109]
	v_pk_fma_f32 v[180:181], v[18:19], v[174:175], v[180:181] op_sel:[0,1,0]
	v_pk_fma_f32 v[192:193], v[20:21], v[174:175], v[192:193] op_sel:[0,1,0]
	v_pk_fma_f32 v[180:181], v[14:15], v[232:233], v[180:181] op_sel_hi:[1,0,1]
	v_pk_fma_f32 v[192:193], v[16:17], v[232:233], v[192:193] op_sel_hi:[1,0,1]
	v_mfma_f32_16x16x4_f32 v[102:105], v143, v36, v[102:105]
	v_pk_fma_f32 v[180:181], v[10:11], v[232:233], v[180:181] op_sel:[0,1,0]
	v_pk_fma_f32 v[192:193], v[12:13], v[232:233], v[192:193] op_sel:[0,1,0]
	v_pk_fma_f32 v[180:181], v[6:7], v[234:235], v[180:181] op_sel_hi:[1,0,1]
	v_pk_fma_f32 v[192:193], v[8:9], v[234:235], v[192:193] op_sel_hi:[1,0,1]
	v_mfma_f32_16x16x4_f32 v[98:101], v143, v37, v[98:101]
	v_pk_fma_f32 v[180:181], v[2:3], v[234:235], v[180:181] op_sel:[0,1,0]
	v_pk_fma_f32 v[192:193], v[4:5], v[234:235], v[192:193] op_sel:[0,1,0]
	v_pk_mul_f32 v[180:181], v[146:147], v[180:181]
	v_pk_mul_f32 v[192:193], v[146:147], v[192:193]
	v_pk_fma_f32 v[236:237], v[144:145], v[34:35], v[180:181]
	v_pk_fma_f32 v[238:239], v[144:145], v[36:37], v[192:193]
	global_store_dwordx4 v[150:151], v[236:239], off nt
	v_lshl_add_u64 v[150:151], v[150:151], 0, s[58:59]
	ds_read_b32 v143, v160 offset:784
	ds_read_b128 v[172:175], v161 offset:6272
	ds_read_b128 v[232:235], v161 offset:6288
	s_waitcnt vmcnt(34)
	s_waitcnt lgkmcnt(3)
	v_cndmask_b32_e64 v141, 0, v141, s[6:7]
	v_pk_mul_f32 v[180:181], v[26:27], v[114:115] op_sel:[0,1]
	v_pk_mul_f32 v[192:193], v[28:29], v[114:115] op_sel:[0,1]
	v_mfma_f32_16x16x4_f32 v[110:113], v141, v58, v[110:113]
	v_pk_fma_f32 v[180:181], v[30:31], v[114:115], v[180:181] op_sel_hi:[1,0,1]
	v_pk_fma_f32 v[192:193], v[32:33], v[114:115], v[192:193] op_sel_hi:[1,0,1]
	v_pk_fma_f32 v[180:181], v[22:23], v[116:117], v[180:181] op_sel_hi:[1,0,1]
	v_pk_fma_f32 v[192:193], v[24:25], v[116:117], v[192:193] op_sel_hi:[1,0,1]
	v_mfma_f32_16x16x4_f32 v[106:109], v141, v59, v[106:109]
	v_pk_fma_f32 v[180:181], v[18:19], v[116:117], v[180:181] op_sel:[0,1,0]
	v_pk_fma_f32 v[192:193], v[20:21], v[116:117], v[192:193] op_sel:[0,1,0]
	v_pk_fma_f32 v[180:181], v[14:15], v[176:177], v[180:181] op_sel_hi:[1,0,1]
	v_pk_fma_f32 v[192:193], v[16:17], v[176:177], v[192:193] op_sel_hi:[1,0,1]
	v_mfma_f32_16x16x4_f32 v[102:105], v141, v60, v[102:105]
	v_pk_fma_f32 v[180:181], v[10:11], v[176:177], v[180:181] op_sel:[0,1,0]
	v_pk_fma_f32 v[192:193], v[12:13], v[176:177], v[192:193] op_sel:[0,1,0]
	v_pk_fma_f32 v[180:181], v[6:7], v[178:179], v[180:181] op_sel_hi:[1,0,1]
	v_pk_fma_f32 v[192:193], v[8:9], v[178:179], v[192:193] op_sel_hi:[1,0,1]
	v_mfma_f32_16x16x4_f32 v[98:101], v141, v61, v[98:101]
	v_pk_fma_f32 v[180:181], v[2:3], v[178:179], v[180:181] op_sel:[0,1,0]
	v_pk_fma_f32 v[192:193], v[4:5], v[178:179], v[192:193] op_sel:[0,1,0]
	v_pk_mul_f32 v[180:181], v[146:147], v[180:181]
	v_pk_mul_f32 v[192:193], v[146:147], v[192:193]
	v_pk_fma_f32 v[236:237], v[144:145], v[58:59], v[180:181]
	v_pk_fma_f32 v[238:239], v[144:145], v[60:61], v[192:193]
	global_store_dwordx4 v[150:151], v[236:239], off nt
	v_lshl_add_u64 v[150:151], v[150:151], 0, s[58:59]
	ds_read_b32 v141, v160 offset:800
	ds_read_b128 v[114:117], v161 offset:6400
	ds_read_b128 v[176:179], v161 offset:6416
	s_waitcnt vmcnt(33)
; #define RS_LOAD(dst, it0) do { _Pragma("unroll") for (int u = 0; u < 8; ++u) dst[u] = __builtin_nontemporal_load((const f32x4*)(S0 + (size_t)(4 * ((it0) + u)) * DV)); } while (0)
; __device__ __forceinline__ void ret_sample_item(Frame& F, int item) {
;     ...
;     for (int it0 = 0; it0 < 64; it0 += 16) {
;         RS_LOAD(sb, it0 + 8);
;         RS_PROC(sa, it0);
;         { const int itn = it0 + 16 < 64 ? it0 + 16 : it0; RS_LOAD(sa, itn); }
;         RS_PROC(sb, it0 + 8);
;     }
	s_waitcnt lgkmcnt(3)
	v_cndmask_b32_e64 v143, 0, v143, s[6:7]
	v_pk_mul_f32 v[180:181], v[26:27], v[172:173] op_sel:[0,1]
	v_pk_mul_f32 v[192:193], v[28:29], v[172:173] op_sel:[0,1]
	v_mfma_f32_16x16x4_f32 v[110:113], v143, v66, v[110:113]
	v_pk_fma_f32 v[180:181], v[30:31], v[172:173], v[180:181] op_sel_hi:[1,0,1]
	v_pk_fma_f32 v[192:193], v[32:33], v[172:173], v[192:193] op_sel_hi:[1,0,1]
	v_pk_fma_f32 v[180:181], v[22:23], v[174:175], v[180:181] op_sel_hi:[1,0,1]
	v_pk_fma_f32 v[192:193], v[24:25], v[174:175], v[192:193] op_sel_hi:[1,0,1]
	v_mfma_f32_16x16x4_f32 v[106:109], v143, v67, v[106:109]
	v_pk_fma_f32 v[180:181], v[18:19], v[174:175], v[180:181] op_sel:[0,1,0]
	v_pk_fma_f32 v[192:193], v[20:21], v[174:175], v[192:193] op_sel:[0,1,0]
	v_pk_fma_f32 v[180:181], v[14:15], v[232:233], v[180:181] op_sel_hi:[1,0,1]
	v_pk_fma_f32 v[192:193], v[16:17], v[232:233], v[192:193] op_sel_hi:[1,0,1]
	v_mfma_f32_16x16x4_f32 v[102:105], v143, v68, v[102:105]
	v_pk_fma_f32 v[180:181], v[10:11], v[232:233], v[180:181] op_sel:[0,1,0]
	v_pk_fma_f32 v[192:193], v[12:13], v[232:233], v[192:193] op_sel:[0,1,0]
	v_pk_fma_f32 v[180:181], v[6:7], v[234:235], v[180:181] op_sel_hi:[1,0,1]
	v_pk_fma_f32 v[192:193], v[8:9], v[234:235], v[192:193] op_sel_hi:[1,0,1]
	v_mfma_f32_16x16x4_f32 v[98:101], v143, v69, v[98:101]
	v_pk_fma_f32 v[180:181], v[2:3], v[234:235], v[180:181] op_sel:[0,1,0]
	v_pk_fma_f32 v[192:193], v[4:5], v[234:235], v[192:193] op_sel:[0,1,0]
	v_pk_mul_f32 v[180:181], v[146:147], v[180:181]
	v_pk_mul_f32 v[192:193], v[146:147], v[192:193]
	v_pk_fma_f32 v[236:237], v[144:145], v[66:67], v[180:181]
	v_pk_fma_f32 v[238:239], v[144:145], v[68:69], v[192:193]
	global_store_dwordx4 v[150:151], v[236:239], off nt
	v_lshl_add_u64 v[150:151], v[150:151], 0, s[58:59]
	ds_read_b32 v143, v160 offset:816
	ds_read_b128 v[172:175], v161 offset:6528
	ds_read_b128 v[232:235], v161 offset:6544
	s_waitcnt vmcnt(32)
	s_waitcnt lgkmcnt(3)
	v_cndmask_b32_e64 v141, 0, v141, s[6:7]
	v_pk_mul_f32 v[180:181], v[26:27], v[114:115] op_sel:[0,1]
	v_pk_mul_f32 v[192:193], v[28:29], v[114:115] op_sel:[0,1]
	v_mfma_f32_16x16x4_f32 v[110:113], v141, v74, v[110:113]
	v_pk_fma_f32 v[180:181], v[30:31], v[114:115], v[180:181] op_sel_hi:[1,0,1]
	v_pk_fma_f32 v[192:193], v[32:33], v[114:115], v[192:193] op_sel_hi:[1,0,1]
	v_pk_fma_f32 v[180:181], v[22:23], v[116:117], v[180:181] op_sel_hi:[1,0,1]
	v_pk_fma_f32 v[192:193], v[24:25], v[116:117], v[192:193] op_sel_hi:[1,0,1]
	v_mfma_f32_16x16x4_f32 v[106:109], v141, v75, v[106:109]
	v_pk_fma_f32 v[180:181], v[18:19], v[116:117], v[180:181] op_sel:[0,1,0]
	v_pk_fma_f32 v[192:193], v[20:21], v[116:117], v[192:193] op_sel:[0,1,0]
	v_pk_fma_f32 v[180:181], v[14:15], v[176:177], v[180:181] op_sel_hi:[1,0,1]
	v_pk_fma_f32 v[192:193], v[16:17], v[176:177], v[192:193] op_sel_hi:[1,0,1]
	v_mfma_f32_16x16x4_f32 v[102:105], v141, v76, v[102:105]
	v_pk_fma_f32 v[180:181], v[10:11], v[176:177], v[180:181] op_sel:[0,1,0]
	v_pk_fma_f32 v[192:193], v[12:13], v[176:177], v[192:193] op_sel:[0,1,0]
	v_pk_fma_f32 v[180:181], v[6:7], v[178:179], v[180:181] op_sel_hi:[1,0,1]
	v_pk_fma_f32 v[192:193], v[8:9], v[178:179], v[192:193] op_sel_hi:[1,0,1]
	v_mfma_f32_16x16x4_f32 v[98:101], v141, v77, v[98:101]
	v_pk_fma_f32 v[180:181], v[2:3], v[178:179], v[180:181] op_sel:[0,1,0]
	v_pk_fma_f32 v[192:193], v[4:5], v[178:179], v[192:193] op_sel:[0,1,0]
	v_pk_mul_f32 v[180:181], v[146:147], v[180:181]
	v_pk_mul_f32 v[192:193], v[146:147], v[192:193]
	v_pk_fma_f32 v[236:237], v[144:145], v[74:75], v[180:181]
	v_pk_fma_f32 v[238:239], v[144:145], v[76:77], v[192:193]
	global_store_dwordx4 v[150:151], v[236:239], off nt
	v_lshl_add_u64 v[150:151], v[150:151], 0, s[58:59]
	ds_read_b32 v141, v160 offset:832
	ds_read_b128 v[114:117], v161 offset:6656
	ds_read_b128 v[176:179], v161 offset:6672
	s_waitcnt vmcnt(31)
	s_waitcnt lgkmcnt(3)
	v_cndmask_b32_e64 v143, 0, v143, s[6:7]
	v_pk_mul_f32 v[180:181], v[26:27], v[172:173] op_sel:[0,1]
	v_pk_mul_f32 v[192:193], v[28:29], v[172:173] op_sel:[0,1]
	v_mfma_f32_16x16x4_f32 v[110:113], v143, v78, v[110:113]
	v_pk_fma_f32 v[180:181], v[30:31], v[172:173], v[180:181] op_sel_hi:[1,0,1]
	v_pk_fma_f32 v[192:193], v[32:33], v[172:173], v[192:193] op_sel_hi:[1,0,1]
	v_pk_fma_f32 v[180:181], v[22:23], v[174:175], v[180:181] op_sel_hi:[1,0,1]
	v_pk_fma_f32 v[192:193], v[24:25], v[174:175], v[192:193] op_sel_hi:[1,0,1]
	v_mfma_f32_16x16x4_f32 v[106:109], v143, v79, v[106:109]
	v_pk_fma_f32 v[180:181], v[18:19], v[174:175], v[180:181] op_sel:[0,1,0]
	v_pk_fma_f32 v[192:193], v[20:21], v[174:175], v[192:193] op_sel:[0,1,0]
	v_pk_fma_f32 v[180:181], v[14:15], v[232:233], v[180:181] op_sel_hi:[1,0,1]
	v_pk_fma_f32 v[192:193], v[16:17], v[232:233], v[192:193] op_sel_hi:[1,0,1]
	v_mfma_f32_16x16x4_f32 v[102:105], v143, v80, v[102:105]
	v_pk_fma_f32 v[180:181], v[10:11], v[232:233], v[180:181] op_sel:[0,1,0]
	v_pk_fma_f32 v[192:193], v[12:13], v[232:233], v[192:193] op_sel:[0,1,0]
	v_pk_fma_f32 v[180:181], v[6:7], v[234:235], v[180:181] op_sel_hi:[1,0,1]
	v_pk_fma_f32 v[192:193], v[8:9], v[234:235], v[192:193] op_sel_hi:[1,0,1]
	v_mfma_f32_16x16x4_f32 v[98:101], v143, v81, v[98:101]
	v_pk_fma_f32 v[180:181], v[2:3], v[234:235], v[180:181] op_sel:[0,1,0]
	v_pk_fma_f32 v[192:193], v[4:5], v[234:235], v[192:193] op_sel:[0,1,0]
	v_pk_mul_f32 v[180:181], v[146:147], v[180:181]
	v_pk_mul_f32 v[192:193], v[146:147], v[192:193]
	v_pk_fma_f32 v[236:237], v[144:145], v[78:79], v[180:181]
	v_pk_fma_f32 v[238:239], v[144:145], v[80:81], v[192:193]
	global_store_dwordx4 v[150:151], v[236:239], off nt
	v_lshl_add_u64 v[150:151], v[150:151], 0, s[58:59]
	ds_read_b32 v143, v160 offset:848
	ds_read_b128 v[172:175], v161 offset:6784
	ds_read_b128 v[232:235], v161 offset:6800
	s_waitcnt vmcnt(30)
; #define RS_LOAD(dst, it0) do { _Pragma("unroll") for (int u = 0; u < 8; ++u) dst[u] = __builtin_nontemporal_load((const f32x4*)(S0 + (size_t)(4 * ((it0) + u)) * DV)); } while (0)
; __device__ __forceinline__ void ret_sample_item(Frame& F, int item) {
;     ...
;     for (int it0 = 0; it0 < 64; it0 += 16) {
;         RS_LOAD(sb, it0 + 8);
;         RS_PROC(sa, it0);
;         { const int itn = it0 + 16 < 64 ? it0 + 16 : it0; RS_LOAD(sa, itn); }
;         RS_PROC(sb, it0 + 8);
;     }
	s_waitcnt lgkmcnt(3)
	v_cndmask_b32_e64 v141, 0, v141, s[6:7]
	v_pk_mul_f32 v[180:181], v[26:27], v[114:115] op_sel:[0,1]
	v_pk_mul_f32 v[192:193], v[28:29], v[114:115] op_sel:[0,1]
	v_mfma_f32_16x16x4_f32 v[110:113], v141, v82, v[110:113]
	v_pk_fma_f32 v[180:181], v[30:31], v[114:115], v[180:181] op_sel_hi:[1,0,1]
	v_pk_fma_f32 v[192:193], v[32:33], v[114:115], v[192:193] op_sel_hi:[1,0,1]
	v_pk_fma_f32 v[180:181], v[22:23], v[116:117], v[180:181] op_sel_hi:[1,0,1]
	v_pk_fma_f32 v[192:193], v[24:25], v[116:117], v[192:193] op_sel_hi:[1,0,1]
	v_mfma_f32_16x16x4_f32 v[106:109], v141, v83, v[106:109]
	v_pk_fma_f32 v[180:181], v[18:19], v[116:117], v[180:181] op_sel:[0,1,0]
	v_pk_fma_f32 v[192:193], v[20:21], v[116:117], v[192:193] op_sel:[0,1,0]
	v_pk_fma_f32 v[180:181], v[14:15], v[176:177], v[180:181] op_sel_hi:[1,0,1]
	v_pk_fma_f32 v[192:193], v[16:17], v[176:177], v[192:193] op_sel_hi:[1,0,1]
	v_mfma_f32_16x16x4_f32 v[102:105], v141, v84, v[102:105]
	v_pk_fma_f32 v[180:181], v[10:11], v[176:177], v[180:181] op_sel:[0,1,0]
	v_pk_fma_f32 v[192:193], v[12:13], v[176:177], v[192:193] op_sel:[0,1,0]
	v_pk_fma_f32 v[180:181], v[6:7], v[178:179], v[180:181] op_sel_hi:[1,0,1]
	v_pk_fma_f32 v[192:193], v[8:9], v[178:179], v[192:193] op_sel_hi:[1,0,1]
	v_mfma_f32_16x16x4_f32 v[98:101], v141, v85, v[98:101]
	v_pk_fma_f32 v[180:181], v[2:3], v[178:179], v[180:181] op_sel:[0,1,0]
	v_pk_fma_f32 v[192:193], v[4:5], v[178:179], v[192:193] op_sel:[0,1,0]
	v_pk_mul_f32 v[180:181], v[146:147], v[180:181]
	v_pk_mul_f32 v[192:193], v[146:147], v[192:193]
	v_pk_fma_f32 v[236:237], v[144:145], v[82:83], v[180:181]
	v_pk_fma_f32 v[238:239], v[144:145], v[84:85], v[192:193]
	global_store_dwordx4 v[150:151], v[236:239], off nt
	v_lshl_add_u64 v[150:151], v[150:151], 0, s[58:59]
	ds_read_b32 v141, v160 offset:864
	ds_read_b128 v[114:117], v161 offset:6912
	ds_read_b128 v[176:179], v161 offset:6928
	s_waitcnt vmcnt(29)
	s_waitcnt lgkmcnt(3)
	v_cndmask_b32_e64 v143, 0, v143, s[6:7]
	v_pk_mul_f32 v[180:181], v[26:27], v[172:173] op_sel:[0,1]
	v_pk_mul_f32 v[192:193], v[28:29], v[172:173] op_sel:[0,1]
	v_mfma_f32_16x16x4_f32 v[110:113], v143, v86, v[110:113]
	v_pk_fma_f32 v[180:181], v[30:31], v[172:173], v[180:181] op_sel_hi:[1,0,1]
	v_pk_fma_f32 v[192:193], v[32:33], v[172:173], v[192:193] op_sel_hi:[1,0,1]
	v_pk_fma_f32 v[180:181], v[22:23], v[174:175], v[180:181] op_sel_hi:[1,0,1]
	v_pk_fma_f32 v[192:193], v[24:25], v[174:175], v[192:193] op_sel_hi:[1,0,1]
	v_mfma_f32_16x16x4_f32 v[106:109], v143, v87, v[106:109]
	v_pk_fma_f32 v[180:181], v[18:19], v[174:175], v[180:181] op_sel:[0,1,0]
	v_pk_fma_f32 v[192:193], v[20:21], v[174:175], v[192:193] op_sel:[0,1,0]
	v_pk_fma_f32 v[180:181], v[14:15], v[232:233], v[180:181] op_sel_hi:[1,0,1]
	v_pk_fma_f32 v[192:193], v[16:17], v[232:233], v[192:193] op_sel_hi:[1,0,1]
	v_mfma_f32_16x16x4_f32 v[102:105], v143, v88, v[102:105]
	v_pk_fma_f32 v[180:181], v[10:11], v[232:233], v[180:181] op_sel:[0,1,0]
	v_pk_fma_f32 v[192:193], v[12:13], v[232:233], v[192:193] op_sel:[0,1,0]
	v_pk_fma_f32 v[180:181], v[6:7], v[234:235], v[180:181] op_sel_hi:[1,0,1]
	v_pk_fma_f32 v[192:193], v[8:9], v[234:235], v[192:193] op_sel_hi:[1,0,1]
	v_mfma_f32_16x16x4_f32 v[98:101], v143, v89, v[98:101]
	v_pk_fma_f32 v[180:181], v[2:3], v[234:235], v[180:181] op_sel:[0,1,0]
	v_pk_fma_f32 v[192:193], v[4:5], v[234:235], v[192:193] op_sel:[0,1,0]
	v_pk_mul_f32 v[180:181], v[146:147], v[180:181]
	v_pk_mul_f32 v[192:193], v[146:147], v[192:193]
	v_pk_fma_f32 v[236:237], v[144:145], v[86:87], v[180:181]
	v_pk_fma_f32 v[238:239], v[144:145], v[88:89], v[192:193]
	global_store_dwordx4 v[150:151], v[236:239], off nt
	v_lshl_add_u64 v[150:151], v[150:151], 0, s[58:59]
	ds_read_b32 v143, v160 offset:880
	ds_read_b128 v[172:175], v161 offset:7040
	ds_read_b128 v[232:235], v161 offset:7056
	s_waitcnt vmcnt(28)
	s_waitcnt lgkmcnt(3)
	v_cndmask_b32_e64 v141, 0, v141, s[6:7]
	v_pk_mul_f32 v[180:181], v[26:27], v[114:115] op_sel:[0,1]
	v_pk_mul_f32 v[192:193], v[28:29], v[114:115] op_sel:[0,1]
	v_mfma_f32_16x16x4_f32 v[110:113], v141, v90, v[110:113]
	v_pk_fma_f32 v[180:181], v[30:31], v[114:115], v[180:181] op_sel_hi:[1,0,1]
	v_pk_fma_f32 v[192:193], v[32:33], v[114:115], v[192:193] op_sel_hi:[1,0,1]
	v_pk_fma_f32 v[180:181], v[22:23], v[116:117], v[180:181] op_sel_hi:[1,0,1]
	v_pk_fma_f32 v[192:193], v[24:25], v[116:117], v[192:193] op_sel_hi:[1,0,1]
	v_mfma_f32_16x16x4_f32 v[106:109], v141, v91, v[106:109]
	v_pk_fma_f32 v[180:181], v[18:19], v[116:117], v[180:181] op_sel:[0,1,0]
	v_pk_fma_f32 v[192:193], v[20:21], v[116:117], v[192:193] op_sel:[0,1,0]
	v_pk_fma_f32 v[180:181], v[14:15], v[176:177], v[180:181] op_sel_hi:[1,0,1]
	v_pk_fma_f32 v[192:193], v[16:17], v[176:177], v[192:193] op_sel_hi:[1,0,1]
	v_mfma_f32_16x16x4_f32 v[102:105], v141, v92, v[102:105]
	v_pk_fma_f32 v[180:181], v[10:11], v[176:177], v[180:181] op_sel:[0,1,0]
	v_pk_fma_f32 v[192:193], v[12:13], v[176:177], v[192:193] op_sel:[0,1,0]
	v_pk_fma_f32 v[180:181], v[6:7], v[178:179], v[180:181] op_sel_hi:[1,0,1]
	v_pk_fma_f32 v[192:193], v[8:9], v[178:179], v[192:193] op_sel_hi:[1,0,1]
	v_mfma_f32_16x16x4_f32 v[98:101], v141, v93, v[98:101]
	v_pk_fma_f32 v[180:181], v[2:3], v[178:179], v[180:181] op_sel:[0,1,0]
	v_pk_fma_f32 v[192:193], v[4:5], v[178:179], v[192:193] op_sel:[0,1,0]
	v_pk_mul_f32 v[180:181], v[146:147], v[180:181]
	v_pk_mul_f32 v[192:193], v[146:147], v[192:193]
	v_pk_fma_f32 v[236:237], v[144:145], v[90:91], v[180:181]
	v_pk_fma_f32 v[238:239], v[144:145], v[92:93], v[192:193]
	global_store_dwordx4 v[150:151], v[236:239], off nt
	v_lshl_add_u64 v[150:151], v[150:151], 0, s[58:59]
	ds_read_b32 v141, v160 offset:896
	ds_read_b128 v[114:117], v161 offset:7168
	ds_read_b128 v[176:179], v161 offset:7184
	s_waitcnt vmcnt(27)
; #define RS_LOAD(dst, it0) do { _Pragma("unroll") for (int u = 0; u < 8; ++u) dst[u] = __builtin_nontemporal_load((const f32x4*)(S0 + (size_t)(4 * ((it0) + u)) * DV)); } while (0)
; __device__ __forceinline__ void ret_sample_item(Frame& F, int item) {
;     ...
;     for (int it0 = 0; it0 < 64; it0 += 16) {
;         RS_LOAD(sb, it0 + 8);
;         RS_PROC(sa, it0);
;         { const int itn = it0 + 16 < 64 ? it0 + 16 : it0; RS_LOAD(sa, itn); }
;         RS_PROC(sb, it0 + 8);
;     }
	s_waitcnt lgkmcnt(3)
	v_cndmask_b32_e64 v143, 0, v143, s[6:7]
	v_pk_mul_f32 v[180:181], v[26:27], v[172:173] op_sel:[0,1]
	v_pk_mul_f32 v[192:193], v[28:29], v[172:173] op_sel:[0,1]
	v_mfma_f32_16x16x4_f32 v[110:113], v143, v94, v[110:113]
	v_pk_fma_f32 v[180:181], v[30:31], v[172:173], v[180:181] op_sel_hi:[1,0,1]
	v_pk_fma_f32 v[192:193], v[32:33], v[172:173], v[192:193] op_sel_hi:[1,0,1]
	v_pk_fma_f32 v[180:181], v[22:23], v[174:175], v[180:181] op_sel_hi:[1,0,1]
	v_pk_fma_f32 v[192:193], v[24:25], v[174:175], v[192:193] op_sel_hi:[1,0,1]
	v_mfma_f32_16x16x4_f32 v[106:109], v143, v95, v[106:109]
	v_pk_fma_f32 v[180:181], v[18:19], v[174:175], v[180:181] op_sel:[0,1,0]
	v_pk_fma_f32 v[192:193], v[20:21], v[174:175], v[192:193] op_sel:[0,1,0]
	v_pk_fma_f32 v[180:181], v[14:15], v[232:233], v[180:181] op_sel_hi:[1,0,1]
	v_pk_fma_f32 v[192:193], v[16:17], v[232:233], v[192:193] op_sel_hi:[1,0,1]
	v_mfma_f32_16x16x4_f32 v[102:105], v143, v96, v[102:105]
	v_pk_fma_f32 v[180:181], v[10:11], v[232:233], v[180:181] op_sel:[0,1,0]
	v_pk_fma_f32 v[192:193], v[12:13], v[232:233], v[192:193] op_sel:[0,1,0]
	v_pk_fma_f32 v[180:181], v[6:7], v[234:235], v[180:181] op_sel_hi:[1,0,1]
	v_pk_fma_f32 v[192:193], v[8:9], v[234:235], v[192:193] op_sel_hi:[1,0,1]
	v_mfma_f32_16x16x4_f32 v[98:101], v143, v97, v[98:101]
	v_pk_fma_f32 v[180:181], v[2:3], v[234:235], v[180:181] op_sel:[0,1,0]
	v_pk_fma_f32 v[192:193], v[4:5], v[234:235], v[192:193] op_sel:[0,1,0]
	v_pk_mul_f32 v[180:181], v[146:147], v[180:181]
	v_pk_mul_f32 v[192:193], v[146:147], v[192:193]
	v_pk_fma_f32 v[236:237], v[144:145], v[94:95], v[180:181]
	v_pk_fma_f32 v[238:239], v[144:145], v[96:97], v[192:193]
	global_store_dwordx4 v[150:151], v[236:239], off nt
	v_lshl_add_u64 v[150:151], v[150:151], 0, s[58:59]
	ds_read_b32 v143, v160 offset:912
	ds_read_b128 v[172:175], v161 offset:7296
	ds_read_b128 v[232:235], v161 offset:7312
	s_waitcnt vmcnt(26)
	s_waitcnt lgkmcnt(3)
	v_cndmask_b32_e64 v141, 0, v141, s[6:7]
	v_pk_mul_f32 v[180:181], v[26:27], v[114:115] op_sel:[0,1]
	v_pk_mul_f32 v[192:193], v[28:29], v[114:115] op_sel:[0,1]
	v_mfma_f32_16x16x4_f32 v[110:113], v141, v212, v[110:113]
	v_pk_fma_f32 v[180:181], v[30:31], v[114:115], v[180:181] op_sel_hi:[1,0,1]
	v_pk_fma_f32 v[192:193], v[32:33], v[114:115], v[192:193] op_sel_hi:[1,0,1]
	v_pk_fma_f32 v[180:181], v[22:23], v[116:117], v[180:181] op_sel_hi:[1,0,1]
	v_pk_fma_f32 v[192:193], v[24:25], v[116:117], v[192:193] op_sel_hi:[1,0,1]
	v_mfma_f32_16x16x4_f32 v[106:109], v141, v213, v[106:109]
	v_pk_fma_f32 v[180:181], v[18:19], v[116:117], v[180:181] op_sel:[0,1,0]
	v_pk_fma_f32 v[192:193], v[20:21], v[116:117], v[192:193] op_sel:[0,1,0]
	v_pk_fma_f32 v[180:181], v[14:15], v[176:177], v[180:181] op_sel_hi:[1,0,1]
	v_pk_fma_f32 v[192:193], v[16:17], v[176:177], v[192:193] op_sel_hi:[1,0,1]
	v_mfma_f32_16x16x4_f32 v[102:105], v141, v214, v[102:105]
	v_pk_fma_f32 v[180:181], v[10:11], v[176:177], v[180:181] op_sel:[0,1,0]
	v_pk_fma_f32 v[192:193], v[12:13], v[176:177], v[192:193] op_sel:[0,1,0]
	v_pk_fma_f32 v[180:181], v[6:7], v[178:179], v[180:181] op_sel_hi:[1,0,1]
	v_pk_fma_f32 v[192:193], v[8:9], v[178:179], v[192:193] op_sel_hi:[1,0,1]
	v_mfma_f32_16x16x4_f32 v[98:101], v141, v215, v[98:101]
	v_pk_fma_f32 v[180:181], v[2:3], v[178:179], v[180:181] op_sel:[0,1,0]
	v_pk_fma_f32 v[192:193], v[4:5], v[178:179], v[192:193] op_sel:[0,1,0]
	v_pk_mul_f32 v[180:181], v[146:147], v[180:181]
	v_pk_mul_f32 v[192:193], v[146:147], v[192:193]
	v_pk_fma_f32 v[236:237], v[144:145], v[212:213], v[180:181]
	v_pk_fma_f32 v[238:239], v[144:145], v[214:215], v[192:193]
	global_store_dwordx4 v[150:151], v[236:239], off nt
	v_lshl_add_u64 v[150:151], v[150:151], 0, s[58:59]
	ds_read_b32 v141, v160 offset:928
	ds_read_b128 v[114:117], v161 offset:7424
	ds_read_b128 v[176:179], v161 offset:7440
	s_waitcnt vmcnt(25)
	s_waitcnt lgkmcnt(3)
	v_cndmask_b32_e64 v143, 0, v143, s[6:7]
	v_pk_mul_f32 v[180:181], v[26:27], v[172:173] op_sel:[0,1]
	v_pk_mul_f32 v[192:193], v[28:29], v[172:173] op_sel:[0,1]
	v_mfma_f32_16x16x4_f32 v[110:113], v143, v216, v[110:113]
	v_pk_fma_f32 v[180:181], v[30:31], v[172:173], v[180:181] op_sel_hi:[1,0,1]
	v_pk_fma_f32 v[192:193], v[32:33], v[172:173], v[192:193] op_sel_hi:[1,0,1]
	v_pk_fma_f32 v[180:181], v[22:23], v[174:175], v[180:181] op_sel_hi:[1,0,1]
	v_pk_fma_f32 v[192:193], v[24:25], v[174:175], v[192:193] op_sel_hi:[1,0,1]
	v_mfma_f32_16x16x4_f32 v[106:109], v143, v217, v[106:109]
	v_pk_fma_f32 v[180:181], v[18:19], v[174:175], v[180:181] op_sel:[0,1,0]
	v_pk_fma_f32 v[192:193], v[20:21], v[174:175], v[192:193] op_sel:[0,1,0]
	v_pk_fma_f32 v[180:181], v[14:15], v[232:233], v[180:181] op_sel_hi:[1,0,1]
	v_pk_fma_f32 v[192:193], v[16:17], v[232:233], v[192:193] op_sel_hi:[1,0,1]
	v_mfma_f32_16x16x4_f32 v[102:105], v143, v218, v[102:105]
	v_pk_fma_f32 v[180:181], v[10:11], v[232:233], v[180:181] op_sel:[0,1,0]
	v_pk_fma_f32 v[192:193], v[12:13], v[232:233], v[192:193] op_sel:[0,1,0]
	v_pk_fma_f32 v[180:181], v[6:7], v[234:235], v[180:181] op_sel_hi:[1,0,1]
	v_pk_fma_f32 v[192:193], v[8:9], v[234:235], v[192:193] op_sel_hi:[1,0,1]
	v_mfma_f32_16x16x4_f32 v[98:101], v143, v219, v[98:101]
	v_pk_fma_f32 v[180:181], v[2:3], v[234:235], v[180:181] op_sel:[0,1,0]
	v_pk_fma_f32 v[192:193], v[4:5], v[234:235], v[192:193] op_sel:[0,1,0]
	v_pk_mul_f32 v[180:181], v[146:147], v[180:181]
	v_pk_mul_f32 v[192:193], v[146:147], v[192:193]
	v_pk_fma_f32 v[236:237], v[144:145], v[216:217], v[180:181]
	v_pk_fma_f32 v[238:239], v[144:145], v[218:219], v[192:193]
	global_store_dwordx4 v[150:151], v[236:239], off nt
	v_lshl_add_u64 v[150:151], v[150:151], 0, s[58:59]
	ds_read_b32 v143, v160 offset:944
	ds_read_b128 v[172:175], v161 offset:7552
	ds_read_b128 v[232:235], v161 offset:7568
	s_waitcnt vmcnt(24)
; #define RS_LOAD(dst, it0) do { _Pragma("unroll") for (int u = 0; u < 8; ++u) dst[u] = __builtin_nontemporal_load((const f32x4*)(S0 + (size_t)(4 * ((it0) + u)) * DV)); } while (0)
; __device__ __forceinline__ void ret_sample_item(Frame& F, int item) {
;     ...
;     for (int it0 = 0; it0 < 64; it0 += 16) {
;         RS_LOAD(sb, it0 + 8);
;         RS_PROC(sa, it0);
;         { const int itn = it0 + 16 < 64 ? it0 + 16 : it0; RS_LOAD(sa, itn); }
;         RS_PROC(sb, it0 + 8);
;     }
	s_waitcnt lgkmcnt(3)
	v_cndmask_b32_e64 v141, 0, v141, s[6:7]
	v_pk_mul_f32 v[180:181], v[26:27], v[114:115] op_sel:[0,1]
	v_pk_mul_f32 v[192:193], v[28:29], v[114:115] op_sel:[0,1]
	v_mfma_f32_16x16x4_f32 v[110:113], v141, v224, v[110:113]
	v_pk_fma_f32 v[180:181], v[30:31], v[114:115], v[180:181] op_sel_hi:[1,0,1]
	v_pk_fma_f32 v[192:193], v[32:33], v[114:115], v[192:193] op_sel_hi:[1,0,1]
	v_pk_fma_f32 v[180:181], v[22:23], v[116:117], v[180:181] op_sel_hi:[1,0,1]
	v_pk_fma_f32 v[192:193], v[24:25], v[116:117], v[192:193] op_sel_hi:[1,0,1]
	v_mfma_f32_16x16x4_f32 v[106:109], v141, v225, v[106:109]
	v_pk_fma_f32 v[180:181], v[18:19], v[116:117], v[180:181] op_sel:[0,1,0]
	v_pk_fma_f32 v[192:193], v[20:21], v[116:117], v[192:193] op_sel:[0,1,0]
	v_pk_fma_f32 v[180:181], v[14:15], v[176:177], v[180:181] op_sel_hi:[1,0,1]
	v_pk_fma_f32 v[192:193], v[16:17], v[176:177], v[192:193] op_sel_hi:[1,0,1]
	v_mfma_f32_16x16x4_f32 v[102:105], v141, v226, v[102:105]
	v_pk_fma_f32 v[180:181], v[10:11], v[176:177], v[180:181] op_sel:[0,1,0]
	v_pk_fma_f32 v[192:193], v[12:13], v[176:177], v[192:193] op_sel:[0,1,0]
	v_pk_fma_f32 v[180:181], v[6:7], v[178:179], v[180:181] op_sel_hi:[1,0,1]
	v_pk_fma_f32 v[192:193], v[8:9], v[178:179], v[192:193] op_sel_hi:[1,0,1]
	v_mfma_f32_16x16x4_f32 v[98:101], v141, v227, v[98:101]
	v_pk_fma_f32 v[180:181], v[2:3], v[178:179], v[180:181] op_sel:[0,1,0]
	v_pk_fma_f32 v[192:193], v[4:5], v[178:179], v[192:193] op_sel:[0,1,0]
	v_pk_mul_f32 v[180:181], v[146:147], v[180:181]
	v_pk_mul_f32 v[192:193], v[146:147], v[192:193]
	v_pk_fma_f32 v[236:237], v[144:145], v[224:225], v[180:181]
	v_pk_fma_f32 v[238:239], v[144:145], v[226:227], v[192:193]
	global_store_dwordx4 v[150:151], v[236:239], off nt
	v_lshl_add_u64 v[150:151], v[150:151], 0, s[58:59]
	ds_read_b32 v141, v160 offset:960
	ds_read_b128 v[114:117], v161 offset:7680
	ds_read_b128 v[176:179], v161 offset:7696
	s_waitcnt vmcnt(23)
	s_waitcnt lgkmcnt(3)
	v_cndmask_b32_e64 v143, 0, v143, s[6:7]
	v_pk_mul_f32 v[180:181], v[26:27], v[172:173] op_sel:[0,1]
	v_pk_mul_f32 v[192:193], v[28:29], v[172:173] op_sel:[0,1]
	v_mfma_f32_16x16x4_f32 v[110:113], v143, v228, v[110:113]
	v_pk_fma_f32 v[180:181], v[30:31], v[172:173], v[180:181] op_sel_hi:[1,0,1]
	v_pk_fma_f32 v[192:193], v[32:33], v[172:173], v[192:193] op_sel_hi:[1,0,1]
	v_pk_fma_f32 v[180:181], v[22:23], v[174:175], v[180:181] op_sel_hi:[1,0,1]
	v_pk_fma_f32 v[192:193], v[24:25], v[174:175], v[192:193] op_sel_hi:[1,0,1]
	v_mfma_f32_16x16x4_f32 v[106:109], v143, v229, v[106:109]
	v_pk_fma_f32 v[180:181], v[18:19], v[174:175], v[180:181] op_sel:[0,1,0]
	v_pk_fma_f32 v[192:193], v[20:21], v[174:175], v[192:193] op_sel:[0,1,0]
	v_pk_fma_f32 v[180:181], v[14:15], v[232:233], v[180:181] op_sel_hi:[1,0,1]
	v_pk_fma_f32 v[192:193], v[16:17], v[232:233], v[192:193] op_sel_hi:[1,0,1]
	v_mfma_f32_16x16x4_f32 v[102:105], v143, v230, v[102:105]
	v_pk_fma_f32 v[180:181], v[10:11], v[232:233], v[180:181] op_sel:[0,1,0]
	v_pk_fma_f32 v[192:193], v[12:13], v[232:233], v[192:193] op_sel:[0,1,0]
	v_pk_fma_f32 v[180:181], v[6:7], v[234:235], v[180:181] op_sel_hi:[1,0,1]
	v_pk_fma_f32 v[192:193], v[8:9], v[234:235], v[192:193] op_sel_hi:[1,0,1]
	v_mfma_f32_16x16x4_f32 v[98:101], v143, v231, v[98:101]
	v_pk_fma_f32 v[180:181], v[2:3], v[234:235], v[180:181] op_sel:[0,1,0]
	v_pk_fma_f32 v[192:193], v[4:5], v[234:235], v[192:193] op_sel:[0,1,0]
	v_pk_mul_f32 v[180:181], v[146:147], v[180:181]
	v_pk_mul_f32 v[192:193], v[146:147], v[192:193]
	v_pk_fma_f32 v[236:237], v[144:145], v[228:229], v[180:181]
	v_pk_fma_f32 v[238:239], v[144:145], v[230:231], v[192:193]
	global_store_dwordx4 v[150:151], v[236:239], off nt
	v_lshl_add_u64 v[150:151], v[150:151], 0, s[58:59]
	ds_read_b32 v143, v160 offset:976
	ds_read_b128 v[172:175], v161 offset:7808
	ds_read_b128 v[232:235], v161 offset:7824
	s_waitcnt vmcnt(22)
	s_waitcnt lgkmcnt(3)
	v_cndmask_b32_e64 v141, 0, v141, s[6:7]
	v_pk_mul_f32 v[180:181], v[26:27], v[114:115] op_sel:[0,1]
	v_pk_mul_f32 v[192:193], v[28:29], v[114:115] op_sel:[0,1]
	v_mfma_f32_16x16x4_f32 v[110:113], v141, v70, v[110:113]
	v_pk_fma_f32 v[180:181], v[30:31], v[114:115], v[180:181] op_sel_hi:[1,0,1]
	v_pk_fma_f32 v[192:193], v[32:33], v[114:115], v[192:193] op_sel_hi:[1,0,1]
	v_pk_fma_f32 v[180:181], v[22:23], v[116:117], v[180:181] op_sel_hi:[1,0,1]
	v_pk_fma_f32 v[192:193], v[24:25], v[116:117], v[192:193] op_sel_hi:[1,0,1]
	v_mfma_f32_16x16x4_f32 v[106:109], v141, v71, v[106:109]
	v_pk_fma_f32 v[180:181], v[18:19], v[116:117], v[180:181] op_sel:[0,1,0]
	v_pk_fma_f32 v[192:193], v[20:21], v[116:117], v[192:193] op_sel:[0,1,0]
	v_pk_fma_f32 v[180:181], v[14:15], v[176:177], v[180:181] op_sel_hi:[1,0,1]
	v_pk_fma_f32 v[192:193], v[16:17], v[176:177], v[192:193] op_sel_hi:[1,0,1]
	v_mfma_f32_16x16x4_f32 v[102:105], v141, v72, v[102:105]
	v_pk_fma_f32 v[180:181], v[10:11], v[176:177], v[180:181] op_sel:[0,1,0]
	v_pk_fma_f32 v[192:193], v[12:13], v[176:177], v[192:193] op_sel:[0,1,0]
	v_pk_fma_f32 v[180:181], v[6:7], v[178:179], v[180:181] op_sel_hi:[1,0,1]
	v_pk_fma_f32 v[192:193], v[8:9], v[178:179], v[192:193] op_sel_hi:[1,0,1]
	v_mfma_f32_16x16x4_f32 v[98:101], v141, v73, v[98:101]
	v_pk_fma_f32 v[180:181], v[2:3], v[178:179], v[180:181] op_sel:[0,1,0]
	v_pk_fma_f32 v[192:193], v[4:5], v[178:179], v[192:193] op_sel:[0,1,0]
	v_pk_mul_f32 v[180:181], v[146:147], v[180:181]
	v_pk_mul_f32 v[192:193], v[146:147], v[192:193]
	v_pk_fma_f32 v[236:237], v[144:145], v[70:71], v[180:181]
	v_pk_fma_f32 v[238:239], v[144:145], v[72:73], v[192:193]
	global_store_dwordx4 v[150:151], v[236:239], off nt
	v_lshl_add_u64 v[150:151], v[150:151], 0, s[58:59]
	ds_read_b32 v141, v160 offset:992
	ds_read_b128 v[114:117], v161 offset:7936
	ds_read_b128 v[176:179], v161 offset:7952
	s_waitcnt vmcnt(21)
; #define RS_LOAD(dst, it0) do { _Pragma("unroll") for (int u = 0; u < 8; ++u) dst[u] = __builtin_nontemporal_load((const f32x4*)(S0 + (size_t)(4 * ((it0) + u)) * DV)); } while (0)
; __device__ __forceinline__ void ret_sample_item(Frame& F, int item) {
;     ...
;     for (int it0 = 0; it0 < 64; it0 += 16) {
;         RS_LOAD(sb, it0 + 8);
;         RS_PROC(sa, it0);
;         { const int itn = it0 + 16 < 64 ? it0 + 16 : it0; RS_LOAD(sa, itn); }
;         RS_PROC(sb, it0 + 8);
;     }
	s_waitcnt lgkmcnt(3)
	v_cndmask_b32_e64 v143, 0, v143, s[6:7]
	v_pk_mul_f32 v[180:181], v[26:27], v[172:173] op_sel:[0,1]
	v_pk_mul_f32 v[192:193], v[28:29], v[172:173] op_sel:[0,1]
	v_mfma_f32_16x16x4_f32 v[110:113], v143, v62, v[110:113]
	v_pk_fma_f32 v[180:181], v[30:31], v[172:173], v[180:181] op_sel_hi:[1,0,1]
	v_pk_fma_f32 v[192:193], v[32:33], v[172:173], v[192:193] op_sel_hi:[1,0,1]
	v_pk_fma_f32 v[180:181], v[22:23], v[174:175], v[180:181] op_sel_hi:[1,0,1]
	v_pk_fma_f32 v[192:193], v[24:25], v[174:175], v[192:193] op_sel_hi:[1,0,1]
	v_mfma_f32_16x16x4_f32 v[106:109], v143, v63, v[106:109]
	v_pk_fma_f32 v[180:181], v[18:19], v[174:175], v[180:181] op_sel:[0,1,0]
	v_pk_fma_f32 v[192:193], v[20:21], v[174:175], v[192:193] op_sel:[0,1,0]
	v_pk_fma_f32 v[180:181], v[14:15], v[232:233], v[180:181] op_sel_hi:[1,0,1]
	v_pk_fma_f32 v[192:193], v[16:17], v[232:233], v[192:193] op_sel_hi:[1,0,1]
	v_mfma_f32_16x16x4_f32 v[102:105], v143, v64, v[102:105]
	v_pk_fma_f32 v[180:181], v[10:11], v[232:233], v[180:181] op_sel:[0,1,0]
	v_pk_fma_f32 v[192:193], v[12:13], v[232:233], v[192:193] op_sel:[0,1,0]
	v_pk_fma_f32 v[180:181], v[6:7], v[234:235], v[180:181] op_sel_hi:[1,0,1]
	v_pk_fma_f32 v[192:193], v[8:9], v[234:235], v[192:193] op_sel_hi:[1,0,1]
	v_mfma_f32_16x16x4_f32 v[98:101], v143, v65, v[98:101]
	v_pk_fma_f32 v[180:181], v[2:3], v[234:235], v[180:181] op_sel:[0,1,0]
	v_pk_fma_f32 v[192:193], v[4:5], v[234:235], v[192:193] op_sel:[0,1,0]
	v_pk_mul_f32 v[180:181], v[146:147], v[180:181]
	v_pk_mul_f32 v[192:193], v[146:147], v[192:193]
	v_pk_fma_f32 v[236:237], v[144:145], v[62:63], v[180:181]
	v_pk_fma_f32 v[238:239], v[144:145], v[64:65], v[192:193]
	global_store_dwordx4 v[150:151], v[236:239], off nt
	v_lshl_add_u64 v[150:151], v[150:151], 0, s[58:59]
	ds_read_b32 v143, v160 offset:1008
	ds_read_b128 v[172:175], v161 offset:8064
	ds_read_b128 v[232:235], v161 offset:8080
	s_waitcnt vmcnt(20)
	s_waitcnt lgkmcnt(3)
	v_cndmask_b32_e64 v141, 0, v141, s[6:7]
	v_pk_mul_f32 v[180:181], v[26:27], v[114:115] op_sel:[0,1]
	v_pk_mul_f32 v[192:193], v[28:29], v[114:115] op_sel:[0,1]
	v_mfma_f32_16x16x4_f32 v[110:113], v141, v54, v[110:113]
	v_pk_fma_f32 v[180:181], v[30:31], v[114:115], v[180:181] op_sel_hi:[1,0,1]
	v_pk_fma_f32 v[192:193], v[32:33], v[114:115], v[192:193] op_sel_hi:[1,0,1]
	v_pk_fma_f32 v[180:181], v[22:23], v[116:117], v[180:181] op_sel_hi:[1,0,1]
	v_pk_fma_f32 v[192:193], v[24:25], v[116:117], v[192:193] op_sel_hi:[1,0,1]
	v_mfma_f32_16x16x4_f32 v[106:109], v141, v55, v[106:109]
	v_pk_fma_f32 v[180:181], v[18:19], v[116:117], v[180:181] op_sel:[0,1,0]
	v_pk_fma_f32 v[192:193], v[20:21], v[116:117], v[192:193] op_sel:[0,1,0]
	v_pk_fma_f32 v[180:181], v[14:15], v[176:177], v[180:181] op_sel_hi:[1,0,1]
	v_pk_fma_f32 v[192:193], v[16:17], v[176:177], v[192:193] op_sel_hi:[1,0,1]
	v_mfma_f32_16x16x4_f32 v[102:105], v141, v56, v[102:105]
	v_pk_fma_f32 v[180:181], v[10:11], v[176:177], v[180:181] op_sel:[0,1,0]
	v_pk_fma_f32 v[192:193], v[12:13], v[176:177], v[192:193] op_sel:[0,1,0]
	v_pk_fma_f32 v[180:181], v[6:7], v[178:179], v[180:181] op_sel_hi:[1,0,1]
	v_pk_fma_f32 v[192:193], v[8:9], v[178:179], v[192:193] op_sel_hi:[1,0,1]
	v_mfma_f32_16x16x4_f32 v[98:101], v141, v57, v[98:101]
	v_pk_fma_f32 v[180:181], v[2:3], v[178:179], v[180:181] op_sel:[0,1,0]
	v_pk_fma_f32 v[192:193], v[4:5], v[178:179], v[192:193] op_sel:[0,1,0]
	v_pk_mul_f32 v[180:181], v[146:147], v[180:181]
	v_pk_mul_f32 v[192:193], v[146:147], v[192:193]
	v_pk_fma_f32 v[236:237], v[144:145], v[54:55], v[180:181]
	v_pk_fma_f32 v[238:239], v[144:145], v[56:57], v[192:193]
	global_store_dwordx4 v[150:151], v[236:239], off nt
	v_lshl_add_u64 v[150:151], v[150:151], 0, s[58:59]
	s_waitcnt vmcnt(19)
	s_waitcnt lgkmcnt(0)
	v_cndmask_b32_e64 v143, 0, v143, s[6:7]
	v_pk_mul_f32 v[180:181], v[26:27], v[172:173] op_sel:[0,1]
	v_pk_mul_f32 v[192:193], v[28:29], v[172:173] op_sel:[0,1]
	v_mfma_f32_16x16x4_f32 v[110:113], v143, v50, v[110:113]
	v_pk_fma_f32 v[180:181], v[30:31], v[172:173], v[180:181] op_sel_hi:[1,0,1]
	v_pk_fma_f32 v[192:193], v[32:33], v[172:173], v[192:193] op_sel_hi:[1,0,1]
	v_pk_fma_f32 v[180:181], v[22:23], v[174:175], v[180:181] op_sel_hi:[1,0,1]
	v_pk_fma_f32 v[192:193], v[24:25], v[174:175], v[192:193] op_sel_hi:[1,0,1]
	v_mfma_f32_16x16x4_f32 v[106:109], v143, v51, v[106:109]
	v_pk_fma_f32 v[180:181], v[18:19], v[174:175], v[180:181] op_sel:[0,1,0]
	v_pk_fma_f32 v[192:193], v[20:21], v[174:175], v[192:193] op_sel:[0,1,0]
	v_pk_fma_f32 v[180:181], v[14:15], v[232:233], v[180:181] op_sel_hi:[1,0,1]
	v_pk_fma_f32 v[192:193], v[16:17], v[232:233], v[192:193] op_sel_hi:[1,0,1]
	v_mfma_f32_16x16x4_f32 v[102:105], v143, v52, v[102:105]
	v_pk_fma_f32 v[180:181], v[10:11], v[232:233], v[180:181] op_sel:[0,1,0]
	v_pk_fma_f32 v[192:193], v[12:13], v[232:233], v[192:193] op_sel:[0,1,0]
	v_pk_fma_f32 v[180:181], v[6:7], v[234:235], v[180:181] op_sel_hi:[1,0,1]
	v_pk_fma_f32 v[192:193], v[8:9], v[234:235], v[192:193] op_sel_hi:[1,0,1]
	v_mfma_f32_16x16x4_f32 v[98:101], v143, v53, v[98:101]
	v_pk_fma_f32 v[180:181], v[2:3], v[234:235], v[180:181] op_sel:[0,1,0]
	v_pk_fma_f32 v[192:193], v[4:5], v[234:235], v[192:193] op_sel:[0,1,0]
	v_pk_mul_f32 v[180:181], v[146:147], v[180:181]
	v_pk_mul_f32 v[192:193], v[146:147], v[192:193]
	v_pk_fma_f32 v[236:237], v[144:145], v[50:51], v[180:181]
	v_pk_fma_f32 v[238:239], v[144:145], v[52:53], v[192:193]
	global_store_dwordx4 v[150:151], v[236:239], off nt
	v_lshl_add_u64 v[150:151], v[150:151], 0, s[58:59]
	s_nop 7
	s_nop 3
	s_branch .LBB0_677
	s_nop 0
	s_nop 0
	s_nop 0
	s_nop 0
	s_nop 0
	s_nop 0
	s_nop 0
	s_nop 0
	s_nop 0
	s_nop 0
	s_nop 0
	s_nop 0
	s_nop 0
	s_nop 0
	s_nop 0
	s_nop 0
	s_nop 0
	s_nop 0
	s_nop 0
	s_nop 0
	s_nop 0
	s_nop 0
	s_nop 0
	s_nop 0
	s_nop 0
	s_nop 0
	s_nop 0
	s_nop 0
	s_nop 0
	s_nop 0
	s_nop 0
	s_nop 0
	s_nop 0
	s_nop 0
	s_nop 0
	s_nop 0
	s_nop 0
	s_nop 0
	s_nop 0
	s_nop 0
	s_nop 0
	s_nop 0
	s_nop 0
	s_nop 0
	s_nop 0
	s_nop 0
	s_nop 0
	s_nop 0
	s_nop 0
	s_nop 0
	s_nop 0
	s_nop 0
	s_nop 0
	s_nop 0
	s_nop 0
	s_nop 0
	s_nop 0
	s_nop 0
	s_nop 0
	s_nop 0
	s_nop 0
